# loop-invariant LDS-DMA destination bases kept in four spare SGPRs (one scalar add less per DMA group in the K-loop)
# speedup vs baseline: 1.0045x; 1.0015x over previous
; #define PG8_STAGE(bufoff, gbase, voff) do { _Pragma("unroll") for (int _i = 0; _i < 2; ++_i) \
;         __builtin_amdgcn_global_load_lds((const unsigned*)((const char*)(gbase) + (voff)[_i]), (PG8_LAS unsigned*)(lds + (bufoff) + ldsw + _i * 8192), 16, 0, 0); } while (0)
; #define PG8_LDA(dst, b, h) do { _Pragma("unroll") for (int m = 0; m < 4; ++m) _Pragma("unroll") for (int k = 0; k < 2; ++k) dst[m][k] = *(const PG8_LAS bf16x8*)(lds + PG8_SA(b, h) + aoff + m * 2048 + k * 1024); } while (0)
; #define PG8_LDB(dst, b, h) do { _Pragma("unroll") for (int n = 0; n < 2; ++n) _Pragma("unroll") for (int k = 0; k < 2; ++k) dst[n][k] = *(const PG8_LAS bf16x8*)(lds + PG8_SB(b, h) + boff + n * 2048 + k * 1024); } while (0)
; #define PG8_MMA(ai, bj, At, Bt) do { __builtin_amdgcn_s_setprio(1); _Pragma("unroll") for (int m = 0; m < 4; ++m) _Pragma("unroll") for (int n = 0; n < 2; ++n) _Pragma("unroll") for (int k = 0; k < 2; ++k) \
;         acc[ai][bj][m][n] = __builtin_amdgcn_mfma_f32_16x16x32_bf16(Bt[n][k], At[m][k], acc[ai][bj][m][n], 0, 0, 0); __builtin_amdgcn_s_setprio(0); } while (0)
; #define PG8_WAIT_V(n) asm volatile("s_waitcnt vmcnt(" #n ")" ::: "memory")
; template <class Epi, class Sched, bool ALIGN_EPI = false, bool SP2 = false>
; __device__ __forceinline__ void gemm_phase(PG8_LAS unsigned char* lds, const Gemm g, const Sched& S, const Epi& E) {
;     ...
;         const char* nA = has_next ? (const char*)g.A + (size_t)nxt.pm * tstep : cA; const char* nB = has_next ? (const char*)g.Bt + (size_t)nxt.pn * tstep : cB;
;         for (int t = 0; t < nt; t += 2) {
;             const bool last = (t == nt - 2);
;             const char* a1 = cA + (size_t)(t + 1) * kstep;
;             const char* a2 = last ? nA : cA + (size_t)(t + 2) * kstep; const char* b2 = last ? nB : cB + (size_t)(t + 2) * kstep;
;             const char* a3 = a2 + kstep; const char* b3 = b2 + kstep;
;             if (last && has_next) S.a_ready(nxt);
;             if constexpr (SP2) {
;             PG8_LDB(B0, 0, 0); PG8_LDB(B1, 0, 1); PG8_SCHED; PG8_LDA(At, 0, 0); PG8_STAGE(PG8_SA(1, 1), a1 + hstep, voffA);
;             PG8_WAIT_V(8); PG8_WAIT_L(0); PG8_BAR; PG8_MMA(0, 0, At, B0); PG8_MMA(0, 1, At, B1); PG8_BAR; PG8_SCHED;
;             PG8_LDA(At, 0, 1); PG8_STAGE(PG8_SB(0, 0), b2, voffB); PG8_STAGE(PG8_SB(0, 1), b2 + hstep, voffB); PG8_STAGE(PG8_SA(0, 0), a2, voffA);
.LBB0_128:
	s_ashr_i32 s25, s24, 31
	s_lshl_b64 s[28:29], s[24:25], 20
	v_readlane_b32 s30, v254, 51
	v_readlane_b32 s31, v254, 52
	s_add_u32 s28, s30, s28
	s_addc_u32 s29, s31, s29
	s_and_b64 s[30:31], s[26:27], exec
	s_cselect_b32 s25, s29, s9
	s_cselect_b32 s35, s28, s8
	s_ashr_i32 s23, s22, 31
	s_lshl_b64 s[30:31], s[22:23], 20
	s_add_u32 s30, s94, s30
	s_addc_u32 s31, s95, s31
	s_and_b64 s[46:47], s[26:27], exec
	s_cselect_b32 s23, s31, s45
	s_cselect_b32 s43, s30, s44
	s_add_u32 s8, s8, 0x80080
	s_addc_u32 s9, s9, 0
	s_add_u32 s48, s44, 0x100
	s_addc_u32 s49, s45, 0
	s_mov_b32 s54, -2
	s_waitcnt lgkmcnt(0)
	s_add_i32 s98, s62, 0x10000
	s_add_i32 s99, s62, 0x14000
	s_add_i32 s100, s62, 0x18000
	s_add_i32 s101, s62, 0x1c000
	ds_read_b128 v[96:99], v173
	ds_read_b128 v[100:103], v173 offset:1024
	ds_read_b128 v[104:107], v173 offset:2048
	ds_read_b128 v[112:115], v173 offset:3072
	ds_read_b128 v[178:181], v175
	ds_read_b128 v[182:185], v175 offset:1024
	ds_read_b128 v[186:189], v175 offset:2048
	ds_read_b128 v[190:193], v175 offset:3072
	s_add_u32 s44, s8, 0xfff80080
	s_addc_u32 s45, s9, -1
	s_cmp_eq_u32 s54, 28
	s_cselect_b32 s47, s25, s45
	s_cselect_b32 s46, s35, s44
	s_cselect_b32 s45, s23, s49
	s_cselect_b32 s44, s43, s48
	s_add_i32 m0, s63, 0xc000
	ds_read_b128 v[198:201], v177
	ds_read_b128 v[202:205], v177 offset:1024
	ds_read_b128 v[206:209], v177 offset:2048
	ds_read_b128 v[210:213], v177 offset:3072
	ds_read_b128 v[214:217], v177 offset:4096
	ds_read_b128 v[218:221], v177 offset:5120
	ds_read_b128 v[222:225], v177 offset:6144
	ds_read_b128 v[226:229], v177 offset:7168
	global_load_lds_dwordx4 v154, s[8:9]
	s_add_i32 m0, s63, 0xe000
	s_nop 0
	global_load_lds_dwordx4 v156, s[8:9]
	s_waitcnt lgkmcnt(0)
	s_setprio 1
	s_barrier
	v_mfma_f32_16x16x32_bf16 v[140:143], v[96:99], v[198:201], 0
	v_mfma_f32_16x16x32_bf16 v[132:135], v[104:107], v[198:201], 0
	v_mfma_f32_16x16x32_bf16 v[116:119], v[96:99], v[206:209], 0
	v_mfma_f32_16x16x32_bf16 v[124:127], v[104:107], v[206:209], 0
	v_mfma_f32_16x16x32_bf16 v[84:87], v[96:99], v[214:217], 0
	v_mfma_f32_16x16x32_bf16 v[92:95], v[104:107], v[214:217], 0
	v_mfma_f32_16x16x32_bf16 v[68:71], v[96:99], v[222:225], 0
	v_mfma_f32_16x16x32_bf16 v[76:79], v[104:107], v[222:225], 0
	v_mfma_f32_16x16x32_bf16 v[140:143], v[100:103], v[202:205], v[140:143]
	v_mfma_f32_16x16x32_bf16 v[132:135], v[112:115], v[202:205], v[132:135]
	v_mfma_f32_16x16x32_bf16 v[116:119], v[100:103], v[210:213], v[116:119]
	v_mfma_f32_16x16x32_bf16 v[124:127], v[112:115], v[210:213], v[124:127]
	v_mfma_f32_16x16x32_bf16 v[84:87], v[100:103], v[218:221], v[84:87]
	v_mfma_f32_16x16x32_bf16 v[92:95], v[112:115], v[218:221], v[92:95]
	v_mfma_f32_16x16x32_bf16 v[68:71], v[100:103], v[226:229], v[68:71]
	v_mfma_f32_16x16x32_bf16 v[76:79], v[112:115], v[226:229], v[76:79]
	v_mfma_f32_16x16x32_bf16 v[128:131], v[178:181], v[198:201], 0
	v_mfma_f32_16x16x32_bf16 v[136:139], v[186:189], v[198:201], 0
	v_mfma_f32_16x16x32_bf16 v[120:123], v[178:181], v[206:209], 0
	v_mfma_f32_16x16x32_bf16 v[108:111], v[186:189], v[206:209], 0
	v_mfma_f32_16x16x32_bf16 v[88:91], v[178:181], v[214:217], 0
	v_mfma_f32_16x16x32_bf16 v[80:83], v[186:189], v[214:217], 0
	v_mfma_f32_16x16x32_bf16 v[72:75], v[178:181], v[222:225], 0
	v_mfma_f32_16x16x32_bf16 v[64:67], v[186:189], v[222:225], 0
	v_mfma_f32_16x16x32_bf16 v[128:131], v[182:185], v[202:205], v[128:131]
	v_mfma_f32_16x16x32_bf16 v[136:139], v[190:193], v[202:205], v[136:139]
	v_mfma_f32_16x16x32_bf16 v[120:123], v[182:185], v[210:213], v[120:123]
	v_mfma_f32_16x16x32_bf16 v[108:111], v[190:193], v[210:213], v[108:111]
	v_mfma_f32_16x16x32_bf16 v[88:91], v[182:185], v[218:221], v[88:91]
	v_mfma_f32_16x16x32_bf16 v[80:83], v[190:193], v[218:221], v[80:83]
	v_mfma_f32_16x16x32_bf16 v[72:75], v[182:185], v[226:229], v[72:75]
	v_mfma_f32_16x16x32_bf16 v[64:67], v[190:193], v[226:229], v[64:67]
	s_barrier
	s_setprio 0
	v_lshl_add_u64 v[160:161], s[44:45], 0, v[144:145]
	s_mov_b32 m0, s98
	ds_read_b128 v[198:201], v177 offset:16384
	ds_read_b128 v[202:205], v177 offset:17408
	ds_read_b128 v[206:209], v177 offset:18432
	ds_read_b128 v[210:213], v177 offset:19456
	ds_read_b128 v[214:217], v177 offset:20480
	ds_read_b128 v[218:221], v177 offset:21504
	ds_read_b128 v[222:225], v177 offset:22528
	ds_read_b128 v[226:229], v177 offset:23552
	global_load_lds_dwordx4 v[160:161], off
	s_add_i32 m0, s98, 0x2000
	s_add_u32 s56, s44, 0x80000
	v_lshl_add_u64 v[164:165], s[44:45], 0, v[146:147]
	s_addc_u32 s57, s45, 0
	global_load_lds_dwordx4 v[164:165], off
	s_mov_b32 m0, s99
	v_lshl_add_u64 v[194:195], s[46:47], 0, v[146:147]
	global_load_lds_dwordx4 v144, s[56:57]
	s_add_i32 m0, s99, 0x2000
	s_nop 0
	global_load_lds_dwordx4 v146, s[56:57]
	s_mov_b32 m0, s63
	v_lshl_add_u64 v[170:171], s[46:47], 0, v[144:145]
	global_load_lds_dwordx4 v[170:171], off
	s_mov_b32 m0, s64
	s_nop 0
	global_load_lds_dwordx4 v[194:195], off
	s_waitcnt lgkmcnt(0)
	s_setprio 1
	s_barrier
; #define PG8_STAGE(bufoff, gbase, voff) do { _Pragma("unroll") for (int _i = 0; _i < 2; ++_i) \
;         __builtin_amdgcn_global_load_lds((const unsigned*)((const char*)(gbase) + (voff)[_i]), (PG8_LAS unsigned*)(lds + (bufoff) + ldsw + _i * 8192), 16, 0, 0); } while (0)
; #define PG8_LDA(dst, b, h) do { _Pragma("unroll") for (int m = 0; m < 4; ++m) _Pragma("unroll") for (int k = 0; k < 2; ++k) dst[m][k] = *(const PG8_LAS bf16x8*)(lds + PG8_SA(b, h) + aoff + m * 2048 + k * 1024); } while (0)
; #define PG8_LDB(dst, b, h) do { _Pragma("unroll") for (int n = 0; n < 2; ++n) _Pragma("unroll") for (int k = 0; k < 2; ++k) dst[n][k] = *(const PG8_LAS bf16x8*)(lds + PG8_SB(b, h) + boff + n * 2048 + k * 1024); } while (0)
; #define PG8_MMA(ai, bj, At, Bt) do { __builtin_amdgcn_s_setprio(1); _Pragma("unroll") for (int m = 0; m < 4; ++m) _Pragma("unroll") for (int n = 0; n < 2; ++n) _Pragma("unroll") for (int k = 0; k < 2; ++k) \
;         acc[ai][bj][m][n] = __builtin_amdgcn_mfma_f32_16x16x32_bf16(Bt[n][k], At[m][k], acc[ai][bj][m][n], 0, 0, 0); __builtin_amdgcn_s_setprio(0); } while (0)
; #define PG8_WAIT_V(n) asm volatile("s_waitcnt vmcnt(" #n ")" ::: "memory")
; #define PG8_WAIT_L(n) asm volatile("s_waitcnt lgkmcnt(" #n ")" ::: "memory")
; #define PG8_BAR __builtin_amdgcn_s_barrier()
; #define PG8_SCHED __builtin_amdgcn_sched_barrier(0)
; template <class Epi, class Sched, bool ALIGN_EPI = false, bool SP2 = false>
; __device__ __forceinline__ void gemm_phase(PG8_LAS unsigned char* lds, const Gemm g, const Sched& S, const Epi& E) {
;     ...
;             PG8_WAIT_V(8); PG8_WAIT_L(0); PG8_BAR; PG8_MMA(1, 0, At, B0); PG8_MMA(1, 1, At, B1); PG8_BAR; PG8_SCHED;
;             PG8_LDB(B0, 1, 0); PG8_LDB(B1, 1, 1); PG8_SCHED; PG8_LDA(At, 1, 0); PG8_STAGE(PG8_SA(0, 1), a2 + hstep, voffA);
;             PG8_WAIT_V(8); PG8_WAIT_L(0); PG8_BAR; PG8_MMA(0, 0, At, B0); PG8_MMA(0, 1, At, B1); PG8_BAR; PG8_SCHED;
	v_mfma_f32_16x16x32_bf16 v[60:63], v[96:99], v[198:201], 0
	v_mfma_f32_16x16x32_bf16 v[52:55], v[104:107], v[198:201], 0
	v_mfma_f32_16x16x32_bf16 v[36:39], v[96:99], v[206:209], 0
	v_mfma_f32_16x16x32_bf16 v[44:47], v[104:107], v[206:209], 0
	v_mfma_f32_16x16x32_bf16 v[20:23], v[96:99], v[214:217], 0
	v_mfma_f32_16x16x32_bf16 v[28:31], v[104:107], v[214:217], 0
	v_mfma_f32_16x16x32_bf16 v[4:7], v[96:99], v[222:225], 0
	v_mfma_f32_16x16x32_bf16 v[12:15], v[104:107], v[222:225], 0
	v_mfma_f32_16x16x32_bf16 v[60:63], v[100:103], v[202:205], v[60:63]
	v_mfma_f32_16x16x32_bf16 v[52:55], v[112:115], v[202:205], v[52:55]
	v_mfma_f32_16x16x32_bf16 v[36:39], v[100:103], v[210:213], v[36:39]
	v_mfma_f32_16x16x32_bf16 v[44:47], v[112:115], v[210:213], v[44:47]
	v_mfma_f32_16x16x32_bf16 v[20:23], v[100:103], v[218:221], v[20:23]
	v_mfma_f32_16x16x32_bf16 v[28:31], v[112:115], v[218:221], v[28:31]
	v_mfma_f32_16x16x32_bf16 v[4:7], v[100:103], v[226:229], v[4:7]
	v_mfma_f32_16x16x32_bf16 v[12:15], v[112:115], v[226:229], v[12:15]
	v_mfma_f32_16x16x32_bf16 v[48:51], v[178:181], v[198:201], 0
	v_mfma_f32_16x16x32_bf16 v[56:59], v[186:189], v[198:201], 0
	v_mfma_f32_16x16x32_bf16 v[40:43], v[178:181], v[206:209], 0
	v_mfma_f32_16x16x32_bf16 v[32:35], v[186:189], v[206:209], 0
	v_mfma_f32_16x16x32_bf16 v[24:27], v[178:181], v[214:217], 0
	v_mfma_f32_16x16x32_bf16 v[16:19], v[186:189], v[214:217], 0
	v_mfma_f32_16x16x32_bf16 v[8:11], v[178:181], v[222:225], 0
	v_mfma_f32_16x16x32_bf16 v[0:3], v[186:189], v[222:225], 0
	v_mfma_f32_16x16x32_bf16 v[48:51], v[182:185], v[202:205], v[48:51]
	v_mfma_f32_16x16x32_bf16 v[56:59], v[190:193], v[202:205], v[56:59]
	v_mfma_f32_16x16x32_bf16 v[40:43], v[182:185], v[210:213], v[40:43]
	v_mfma_f32_16x16x32_bf16 v[32:35], v[190:193], v[210:213], v[32:35]
	v_mfma_f32_16x16x32_bf16 v[24:27], v[182:185], v[218:221], v[24:27]
	v_mfma_f32_16x16x32_bf16 v[16:19], v[190:193], v[218:221], v[16:19]
	v_mfma_f32_16x16x32_bf16 v[8:11], v[182:185], v[226:229], v[8:11]
	v_mfma_f32_16x16x32_bf16 v[0:3], v[190:193], v[226:229], v[0:3]
	s_barrier
	s_setprio 0
	s_add_i32 s55, 0, 0x18000
	s_add_i32 s56, 0, 0x1c000
	v_add_u32_e32 v112, s55, v167
	v_add_u32_e32 v162, s56, v167
	ds_read_b128 v[96:99], v112
	ds_read_b128 v[100:103], v112 offset:1024
	ds_read_b128 v[104:107], v112 offset:2048
	ds_read_b128 v[112:115], v112 offset:3072
	ds_read_b128 v[178:181], v162
	ds_read_b128 v[182:185], v162 offset:1024
	ds_read_b128 v[186:189], v162 offset:2048
	ds_read_b128 v[190:193], v162 offset:3072
	s_add_u32 s46, s46, 0x80000
	s_addc_u32 s47, s47, 0
	s_mov_b32 m0, s65
	ds_read_b128 v[198:201], v177 offset:32768
	ds_read_b128 v[202:205], v177 offset:33792
	ds_read_b128 v[206:209], v177 offset:34816
	ds_read_b128 v[210:213], v177 offset:35840
	ds_read_b128 v[214:217], v177 offset:36864
	ds_read_b128 v[218:221], v177 offset:37888
	ds_read_b128 v[222:225], v177 offset:38912
	ds_read_b128 v[226:229], v177 offset:39936
	global_load_lds_dwordx4 v144, s[46:47]
	s_mov_b32 m0, s66
	v_lshl_add_u64 v[230:231], s[46:47], 0, v[146:147]
	global_load_lds_dwordx4 v[230:231], off
	s_waitcnt vmcnt(8) lgkmcnt(0)
	s_setprio 1
	s_barrier
	v_mfma_f32_16x16x32_bf16 v[140:143], v[96:99], v[198:201], v[140:143]
	v_mfma_f32_16x16x32_bf16 v[132:135], v[104:107], v[198:201], v[132:135]
	v_mfma_f32_16x16x32_bf16 v[116:119], v[96:99], v[206:209], v[116:119]
	v_mfma_f32_16x16x32_bf16 v[124:127], v[104:107], v[206:209], v[124:127]
	v_mfma_f32_16x16x32_bf16 v[84:87], v[96:99], v[214:217], v[84:87]
	v_mfma_f32_16x16x32_bf16 v[92:95], v[104:107], v[214:217], v[92:95]
	v_mfma_f32_16x16x32_bf16 v[68:71], v[96:99], v[222:225], v[68:71]
	v_mfma_f32_16x16x32_bf16 v[76:79], v[104:107], v[222:225], v[76:79]
	v_mfma_f32_16x16x32_bf16 v[140:143], v[100:103], v[202:205], v[140:143]
	v_mfma_f32_16x16x32_bf16 v[132:135], v[112:115], v[202:205], v[132:135]
	v_mfma_f32_16x16x32_bf16 v[116:119], v[100:103], v[210:213], v[116:119]
	v_mfma_f32_16x16x32_bf16 v[124:127], v[112:115], v[210:213], v[124:127]
	v_mfma_f32_16x16x32_bf16 v[84:87], v[100:103], v[218:221], v[84:87]
	v_mfma_f32_16x16x32_bf16 v[92:95], v[112:115], v[218:221], v[92:95]
	v_mfma_f32_16x16x32_bf16 v[68:71], v[100:103], v[226:229], v[68:71]
	v_mfma_f32_16x16x32_bf16 v[76:79], v[112:115], v[226:229], v[76:79]
	v_mfma_f32_16x16x32_bf16 v[128:131], v[178:181], v[198:201], v[128:131]
	v_mfma_f32_16x16x32_bf16 v[136:139], v[186:189], v[198:201], v[136:139]
	v_mfma_f32_16x16x32_bf16 v[120:123], v[178:181], v[206:209], v[120:123]
	v_mfma_f32_16x16x32_bf16 v[108:111], v[186:189], v[206:209], v[108:111]
	v_mfma_f32_16x16x32_bf16 v[88:91], v[178:181], v[214:217], v[88:91]
	v_mfma_f32_16x16x32_bf16 v[80:83], v[186:189], v[214:217], v[80:83]
	v_mfma_f32_16x16x32_bf16 v[72:75], v[178:181], v[222:225], v[72:75]
	v_mfma_f32_16x16x32_bf16 v[64:67], v[186:189], v[222:225], v[64:67]
	v_mfma_f32_16x16x32_bf16 v[128:131], v[182:185], v[202:205], v[128:131]
	v_mfma_f32_16x16x32_bf16 v[136:139], v[190:193], v[202:205], v[136:139]
	v_mfma_f32_16x16x32_bf16 v[120:123], v[182:185], v[210:213], v[120:123]
	v_mfma_f32_16x16x32_bf16 v[108:111], v[190:193], v[210:213], v[108:111]
	v_mfma_f32_16x16x32_bf16 v[88:91], v[182:185], v[218:221], v[88:91]
	v_mfma_f32_16x16x32_bf16 v[80:83], v[190:193], v[218:221], v[80:83]
	v_mfma_f32_16x16x32_bf16 v[72:75], v[182:185], v[226:229], v[72:75]
	v_mfma_f32_16x16x32_bf16 v[64:67], v[190:193], v[226:229], v[64:67]
	s_barrier
; #define PG8_STAGE(bufoff, gbase, voff) do { _Pragma("unroll") for (int _i = 0; _i < 2; ++_i) \
;         __builtin_amdgcn_global_load_lds((const unsigned*)((const char*)(gbase) + (voff)[_i]), (PG8_LAS unsigned*)(lds + (bufoff) + ldsw + _i * 8192), 16, 0, 0); } while (0)
; #define PG8_LDA(dst, b, h) do { _Pragma("unroll") for (int m = 0; m < 4; ++m) _Pragma("unroll") for (int k = 0; k < 2; ++k) dst[m][k] = *(const PG8_LAS bf16x8*)(lds + PG8_SA(b, h) + aoff + m * 2048 + k * 1024); } while (0)
; #define PG8_LDB(dst, b, h) do { _Pragma("unroll") for (int n = 0; n < 2; ++n) _Pragma("unroll") for (int k = 0; k < 2; ++k) dst[n][k] = *(const PG8_LAS bf16x8*)(lds + PG8_SB(b, h) + boff + n * 2048 + k * 1024); } while (0)
; #define PG8_MMA(ai, bj, At, Bt) do { __builtin_amdgcn_s_setprio(1); _Pragma("unroll") for (int m = 0; m < 4; ++m) _Pragma("unroll") for (int n = 0; n < 2; ++n) _Pragma("unroll") for (int k = 0; k < 2; ++k) \
;         acc[ai][bj][m][n] = __builtin_amdgcn_mfma_f32_16x16x32_bf16(Bt[n][k], At[m][k], acc[ai][bj][m][n], 0, 0, 0); __builtin_amdgcn_s_setprio(0); } while (0)
; #define PG8_WAIT_V(n) asm volatile("s_waitcnt vmcnt(" #n ")" ::: "memory")
; #define PG8_WAIT_L(n) asm volatile("s_waitcnt lgkmcnt(" #n ")" ::: "memory")
; #define PG8_BAR __builtin_amdgcn_s_barrier()
; #define PG8_SCHED __builtin_amdgcn_sched_barrier(0)
; template <class Epi, class Sched, bool ALIGN_EPI = false, bool SP2 = false>
; __device__ __forceinline__ void gemm_phase(PG8_LAS unsigned char* lds, const Gemm g, const Sched& S, const Epi& E) {
;     ...
;             const bool last = (t == nt - 2);
;             const char* a1 = cA + (size_t)(t + 1) * kstep;
;             const char* a2 = last ? nA : cA + (size_t)(t + 2) * kstep; const char* b2 = last ? nB : cB + (size_t)(t + 2) * kstep;
;             const char* a3 = a2 + kstep; const char* b3 = b2 + kstep;
;             if (last && has_next) S.a_ready(nxt);
;             if constexpr (SP2) {
;             PG8_LDB(B0, 0, 0); PG8_LDB(B1, 0, 1); PG8_SCHED; PG8_LDA(At, 0, 0); PG8_STAGE(PG8_SA(1, 1), a1 + hstep, voffA);
;     ...
;             PG8_LDA(At, 1, 1); PG8_STAGE(PG8_SB(1, 0), b3, voffB); PG8_STAGE(PG8_SB(1, 1), b3 + hstep, voffB); PG8_STAGE(PG8_SA(1, 0), a3, voffA);
;             PG8_WAIT_V(8); PG8_WAIT_L(0); PG8_BAR; PG8_MMA(1, 0, At, B0); PG8_MMA(1, 1, At, B1); PG8_BAR; PG8_SCHED;
	s_setprio 0
	v_lshl_add_u64 v[160:161], v[160:161], 0, s[12:13]
	s_mov_b32 m0, s100
	ds_read_b128 v[198:201], v177 offset:49152
	ds_read_b128 v[202:205], v177 offset:50176
	ds_read_b128 v[206:209], v177 offset:51200
	ds_read_b128 v[210:213], v177 offset:52224
	ds_read_b128 v[214:217], v177 offset:53248
	ds_read_b128 v[218:221], v177 offset:54272
	ds_read_b128 v[222:225], v177 offset:55296
	ds_read_b128 v[226:229], v177 offset:56320
	global_load_lds_dwordx4 v[160:161], off
	s_add_i32 m0, s100, 0x2000
	s_add_u32 s44, s44, 0x80080
	v_lshl_add_u64 v[160:161], v[164:165], 0, s[12:13]
	s_addc_u32 s45, s45, 0
	global_load_lds_dwordx4 v[160:161], off
	s_mov_b32 m0, s101
	s_nop 0
	global_load_lds_dwordx4 v144, s[44:45]
	s_add_i32 m0, s101, 0x2000
	v_lshl_add_u64 v[160:161], s[44:45], 0, v[146:147]
	global_load_lds_dwordx4 v[160:161], off
	s_mov_b32 m0, s68
	v_lshl_add_u64 v[160:161], v[170:171], 0, s[12:13]
	global_load_lds_dwordx4 v[160:161], off
	s_mov_b32 m0, s69
	v_lshl_add_u64 v[160:161], v[194:195], 0, s[12:13]
	global_load_lds_dwordx4 v[160:161], off
	s_waitcnt vmcnt(8) lgkmcnt(0)
	s_setprio 1
	s_barrier
	v_mfma_f32_16x16x32_bf16 v[60:63], v[96:99], v[198:201], v[60:63]
	v_mfma_f32_16x16x32_bf16 v[52:55], v[104:107], v[198:201], v[52:55]
	v_mfma_f32_16x16x32_bf16 v[36:39], v[96:99], v[206:209], v[36:39]
	v_mfma_f32_16x16x32_bf16 v[44:47], v[104:107], v[206:209], v[44:47]
	v_mfma_f32_16x16x32_bf16 v[20:23], v[96:99], v[214:217], v[20:23]
	v_mfma_f32_16x16x32_bf16 v[28:31], v[104:107], v[214:217], v[28:31]
	v_mfma_f32_16x16x32_bf16 v[4:7], v[96:99], v[222:225], v[4:7]
	v_mfma_f32_16x16x32_bf16 v[12:15], v[104:107], v[222:225], v[12:15]
	v_mfma_f32_16x16x32_bf16 v[60:63], v[100:103], v[202:205], v[60:63]
	v_mfma_f32_16x16x32_bf16 v[52:55], v[112:115], v[202:205], v[52:55]
	v_mfma_f32_16x16x32_bf16 v[36:39], v[100:103], v[210:213], v[36:39]
	v_mfma_f32_16x16x32_bf16 v[44:47], v[112:115], v[210:213], v[44:47]
	v_mfma_f32_16x16x32_bf16 v[20:23], v[100:103], v[218:221], v[20:23]
	v_mfma_f32_16x16x32_bf16 v[28:31], v[112:115], v[218:221], v[28:31]
	v_mfma_f32_16x16x32_bf16 v[4:7], v[100:103], v[226:229], v[4:7]
	v_mfma_f32_16x16x32_bf16 v[12:15], v[112:115], v[226:229], v[12:15]
	v_mfma_f32_16x16x32_bf16 v[48:51], v[178:181], v[198:201], v[48:51]
	v_mfma_f32_16x16x32_bf16 v[56:59], v[186:189], v[198:201], v[56:59]
	v_mfma_f32_16x16x32_bf16 v[40:43], v[178:181], v[206:209], v[40:43]
	v_mfma_f32_16x16x32_bf16 v[32:35], v[186:189], v[206:209], v[32:35]
	v_mfma_f32_16x16x32_bf16 v[24:27], v[178:181], v[214:217], v[24:27]
	v_mfma_f32_16x16x32_bf16 v[16:19], v[186:189], v[214:217], v[16:19]
	v_mfma_f32_16x16x32_bf16 v[8:11], v[178:181], v[222:225], v[8:11]
	v_mfma_f32_16x16x32_bf16 v[0:3], v[186:189], v[222:225], v[0:3]
	v_mfma_f32_16x16x32_bf16 v[48:51], v[182:185], v[202:205], v[48:51]
	v_mfma_f32_16x16x32_bf16 v[56:59], v[190:193], v[202:205], v[56:59]
	v_mfma_f32_16x16x32_bf16 v[40:43], v[182:185], v[210:213], v[40:43]
	v_mfma_f32_16x16x32_bf16 v[32:35], v[190:193], v[210:213], v[32:35]
	v_mfma_f32_16x16x32_bf16 v[24:27], v[182:185], v[218:221], v[24:27]
	v_mfma_f32_16x16x32_bf16 v[16:19], v[190:193], v[218:221], v[16:19]
	v_mfma_f32_16x16x32_bf16 v[8:11], v[182:185], v[226:229], v[8:11]
	v_mfma_f32_16x16x32_bf16 v[0:3], v[190:193], v[226:229], v[0:3]
	s_barrier
	s_setprio 0
	s_add_i32 s54, s54, 2
	s_add_u32 s8, s8, 0x100
	s_addc_u32 s9, s9, 0
	s_add_u32 s48, s48, 0x100
	s_addc_u32 s49, s49, 0
.LBB0_129:
	ds_read_b128 v[96:99], v173
	ds_read_b128 v[100:103], v173 offset:1024
	ds_read_b128 v[104:107], v173 offset:2048
	ds_read_b128 v[112:115], v173 offset:3072
	ds_read_b128 v[178:181], v175
	ds_read_b128 v[182:185], v175 offset:1024
	ds_read_b128 v[186:189], v175 offset:2048
	ds_read_b128 v[190:193], v175 offset:3072
	s_add_u32 s44, s8, 0xfff80080
	s_addc_u32 s45, s9, -1
	s_cmp_eq_u32 s54, 28
	s_cselect_b32 s47, s25, s45
	s_cselect_b32 s46, s35, s44
	s_cselect_b32 s45, s23, s49
	s_cselect_b32 s44, s43, s48
	s_add_i32 m0, s63, 0xc000
	ds_read_b128 v[198:201], v177
	ds_read_b128 v[202:205], v177 offset:1024
	ds_read_b128 v[206:209], v177 offset:2048
	ds_read_b128 v[210:213], v177 offset:3072
	ds_read_b128 v[214:217], v177 offset:4096
	ds_read_b128 v[218:221], v177 offset:5120
	ds_read_b128 v[222:225], v177 offset:6144
	ds_read_b128 v[226:229], v177 offset:7168
	global_load_lds_dwordx4 v154, s[8:9]
	s_add_i32 m0, s63, 0xe000
	s_nop 0
	global_load_lds_dwordx4 v156, s[8:9]
	s_waitcnt vmcnt(8) lgkmcnt(0)
	s_setprio 1
	s_barrier
	v_mfma_f32_16x16x32_bf16 v[140:143], v[96:99], v[198:201], v[140:143]
	v_mfma_f32_16x16x32_bf16 v[132:135], v[104:107], v[198:201], v[132:135]
	v_mfma_f32_16x16x32_bf16 v[116:119], v[96:99], v[206:209], v[116:119]
	v_mfma_f32_16x16x32_bf16 v[124:127], v[104:107], v[206:209], v[124:127]
	v_mfma_f32_16x16x32_bf16 v[84:87], v[96:99], v[214:217], v[84:87]
	v_mfma_f32_16x16x32_bf16 v[92:95], v[104:107], v[214:217], v[92:95]
	v_mfma_f32_16x16x32_bf16 v[68:71], v[96:99], v[222:225], v[68:71]
	v_mfma_f32_16x16x32_bf16 v[76:79], v[104:107], v[222:225], v[76:79]
	v_mfma_f32_16x16x32_bf16 v[140:143], v[100:103], v[202:205], v[140:143]
	v_mfma_f32_16x16x32_bf16 v[132:135], v[112:115], v[202:205], v[132:135]
	v_mfma_f32_16x16x32_bf16 v[116:119], v[100:103], v[210:213], v[116:119]
	v_mfma_f32_16x16x32_bf16 v[124:127], v[112:115], v[210:213], v[124:127]
	v_mfma_f32_16x16x32_bf16 v[84:87], v[100:103], v[218:221], v[84:87]
	v_mfma_f32_16x16x32_bf16 v[92:95], v[112:115], v[218:221], v[92:95]
	v_mfma_f32_16x16x32_bf16 v[68:71], v[100:103], v[226:229], v[68:71]
	v_mfma_f32_16x16x32_bf16 v[76:79], v[112:115], v[226:229], v[76:79]
	v_mfma_f32_16x16x32_bf16 v[128:131], v[178:181], v[198:201], v[128:131]
	v_mfma_f32_16x16x32_bf16 v[136:139], v[186:189], v[198:201], v[136:139]
	v_mfma_f32_16x16x32_bf16 v[120:123], v[178:181], v[206:209], v[120:123]
	v_mfma_f32_16x16x32_bf16 v[108:111], v[186:189], v[206:209], v[108:111]
	v_mfma_f32_16x16x32_bf16 v[88:91], v[178:181], v[214:217], v[88:91]
	v_mfma_f32_16x16x32_bf16 v[80:83], v[186:189], v[214:217], v[80:83]
	v_mfma_f32_16x16x32_bf16 v[72:75], v[178:181], v[222:225], v[72:75]
	v_mfma_f32_16x16x32_bf16 v[64:67], v[186:189], v[222:225], v[64:67]
	v_mfma_f32_16x16x32_bf16 v[128:131], v[182:185], v[202:205], v[128:131]
	v_mfma_f32_16x16x32_bf16 v[136:139], v[190:193], v[202:205], v[136:139]
	v_mfma_f32_16x16x32_bf16 v[120:123], v[182:185], v[210:213], v[120:123]
	v_mfma_f32_16x16x32_bf16 v[108:111], v[190:193], v[210:213], v[108:111]
	v_mfma_f32_16x16x32_bf16 v[88:91], v[182:185], v[218:221], v[88:91]
	v_mfma_f32_16x16x32_bf16 v[80:83], v[190:193], v[218:221], v[80:83]
	v_mfma_f32_16x16x32_bf16 v[72:75], v[182:185], v[226:229], v[72:75]
	v_mfma_f32_16x16x32_bf16 v[64:67], v[190:193], v[226:229], v[64:67]
	s_barrier
; #define PG8_STAGE(bufoff, gbase, voff) do { _Pragma("unroll") for (int _i = 0; _i < 2; ++_i) \
;         __builtin_amdgcn_global_load_lds((const unsigned*)((const char*)(gbase) + (voff)[_i]), (PG8_LAS unsigned*)(lds + (bufoff) + ldsw + _i * 8192), 16, 0, 0); } while (0)
; #define PG8_LDA(dst, b, h) do { _Pragma("unroll") for (int m = 0; m < 4; ++m) _Pragma("unroll") for (int k = 0; k < 2; ++k) dst[m][k] = *(const PG8_LAS bf16x8*)(lds + PG8_SA(b, h) + aoff + m * 2048 + k * 1024); } while (0)
; #define PG8_LDB(dst, b, h) do { _Pragma("unroll") for (int n = 0; n < 2; ++n) _Pragma("unroll") for (int k = 0; k < 2; ++k) dst[n][k] = *(const PG8_LAS bf16x8*)(lds + PG8_SB(b, h) + boff + n * 2048 + k * 1024); } while (0)
; #define PG8_MMA(ai, bj, At, Bt) do { __builtin_amdgcn_s_setprio(1); _Pragma("unroll") for (int m = 0; m < 4; ++m) _Pragma("unroll") for (int n = 0; n < 2; ++n) _Pragma("unroll") for (int k = 0; k < 2; ++k) \
;         acc[ai][bj][m][n] = __builtin_amdgcn_mfma_f32_16x16x32_bf16(Bt[n][k], At[m][k], acc[ai][bj][m][n], 0, 0, 0); __builtin_amdgcn_s_setprio(0); } while (0)
; #define PG8_WAIT_V(n) asm volatile("s_waitcnt vmcnt(" #n ")" ::: "memory")
; #define PG8_WAIT_L(n) asm volatile("s_waitcnt lgkmcnt(" #n ")" ::: "memory")
; #define PG8_BAR __builtin_amdgcn_s_barrier()
; #define PG8_SCHED __builtin_amdgcn_sched_barrier(0)
; template <class Epi, class Sched, bool ALIGN_EPI = false, bool SP2 = false>
; __device__ __forceinline__ void gemm_phase(PG8_LAS unsigned char* lds, const Gemm g, const Sched& S, const Epi& E) {
;     ...
;             PG8_LDA(At, 0, 1); PG8_STAGE(PG8_SB(0, 0), b2, voffB); PG8_STAGE(PG8_SB(0, 1), b2 + hstep, voffB); PG8_STAGE(PG8_SA(0, 0), a2, voffA);
;             PG8_WAIT_V(8); PG8_WAIT_L(0); PG8_BAR; PG8_MMA(1, 0, At, B0); PG8_MMA(1, 1, At, B1); PG8_BAR; PG8_SCHED;
;             PG8_LDB(B0, 1, 0); PG8_LDB(B1, 1, 1); PG8_SCHED; PG8_LDA(At, 1, 0); PG8_STAGE(PG8_SA(0, 1), a2 + hstep, voffA);
	s_setprio 0
	v_lshl_add_u64 v[160:161], s[44:45], 0, v[144:145]
	s_mov_b32 m0, s98
	ds_read_b128 v[198:201], v177 offset:16384
	ds_read_b128 v[202:205], v177 offset:17408
	ds_read_b128 v[206:209], v177 offset:18432
	ds_read_b128 v[210:213], v177 offset:19456
	ds_read_b128 v[214:217], v177 offset:20480
	ds_read_b128 v[218:221], v177 offset:21504
	ds_read_b128 v[222:225], v177 offset:22528
	ds_read_b128 v[226:229], v177 offset:23552
	global_load_lds_dwordx4 v[160:161], off
	s_add_i32 m0, s98, 0x2000
	s_add_u32 s56, s44, 0x80000
	v_lshl_add_u64 v[164:165], s[44:45], 0, v[146:147]
	s_addc_u32 s57, s45, 0
	global_load_lds_dwordx4 v[164:165], off
	s_mov_b32 m0, s99
	v_lshl_add_u64 v[194:195], s[46:47], 0, v[146:147]
	global_load_lds_dwordx4 v144, s[56:57]
	s_add_i32 m0, s99, 0x2000
	s_nop 0
	global_load_lds_dwordx4 v146, s[56:57]
	s_mov_b32 m0, s63
	v_lshl_add_u64 v[170:171], s[46:47], 0, v[144:145]
	global_load_lds_dwordx4 v[170:171], off
	s_mov_b32 m0, s64
	s_nop 0
	global_load_lds_dwordx4 v[194:195], off
	s_waitcnt vmcnt(8) lgkmcnt(0)
	s_setprio 1
	s_barrier
	v_mfma_f32_16x16x32_bf16 v[60:63], v[96:99], v[198:201], v[60:63]
	v_mfma_f32_16x16x32_bf16 v[52:55], v[104:107], v[198:201], v[52:55]
	v_mfma_f32_16x16x32_bf16 v[36:39], v[96:99], v[206:209], v[36:39]
	v_mfma_f32_16x16x32_bf16 v[44:47], v[104:107], v[206:209], v[44:47]
	v_mfma_f32_16x16x32_bf16 v[20:23], v[96:99], v[214:217], v[20:23]
	v_mfma_f32_16x16x32_bf16 v[28:31], v[104:107], v[214:217], v[28:31]
	v_mfma_f32_16x16x32_bf16 v[4:7], v[96:99], v[222:225], v[4:7]
	v_mfma_f32_16x16x32_bf16 v[12:15], v[104:107], v[222:225], v[12:15]
	v_mfma_f32_16x16x32_bf16 v[60:63], v[100:103], v[202:205], v[60:63]
	v_mfma_f32_16x16x32_bf16 v[52:55], v[112:115], v[202:205], v[52:55]
	v_mfma_f32_16x16x32_bf16 v[36:39], v[100:103], v[210:213], v[36:39]
	v_mfma_f32_16x16x32_bf16 v[44:47], v[112:115], v[210:213], v[44:47]
	v_mfma_f32_16x16x32_bf16 v[20:23], v[100:103], v[218:221], v[20:23]
	v_mfma_f32_16x16x32_bf16 v[28:31], v[112:115], v[218:221], v[28:31]
	v_mfma_f32_16x16x32_bf16 v[4:7], v[100:103], v[226:229], v[4:7]
	v_mfma_f32_16x16x32_bf16 v[12:15], v[112:115], v[226:229], v[12:15]
	v_mfma_f32_16x16x32_bf16 v[48:51], v[178:181], v[198:201], v[48:51]
	v_mfma_f32_16x16x32_bf16 v[56:59], v[186:189], v[198:201], v[56:59]
	v_mfma_f32_16x16x32_bf16 v[40:43], v[178:181], v[206:209], v[40:43]
	v_mfma_f32_16x16x32_bf16 v[32:35], v[186:189], v[206:209], v[32:35]
	v_mfma_f32_16x16x32_bf16 v[24:27], v[178:181], v[214:217], v[24:27]
	v_mfma_f32_16x16x32_bf16 v[16:19], v[186:189], v[214:217], v[16:19]
	v_mfma_f32_16x16x32_bf16 v[8:11], v[178:181], v[222:225], v[8:11]
	v_mfma_f32_16x16x32_bf16 v[0:3], v[186:189], v[222:225], v[0:3]
	v_mfma_f32_16x16x32_bf16 v[48:51], v[182:185], v[202:205], v[48:51]
	v_mfma_f32_16x16x32_bf16 v[56:59], v[190:193], v[202:205], v[56:59]
	v_mfma_f32_16x16x32_bf16 v[40:43], v[182:185], v[210:213], v[40:43]
	v_mfma_f32_16x16x32_bf16 v[32:35], v[190:193], v[210:213], v[32:35]
	v_mfma_f32_16x16x32_bf16 v[24:27], v[182:185], v[218:221], v[24:27]
	v_mfma_f32_16x16x32_bf16 v[16:19], v[190:193], v[218:221], v[16:19]
	v_mfma_f32_16x16x32_bf16 v[8:11], v[182:185], v[226:229], v[8:11]
	v_mfma_f32_16x16x32_bf16 v[0:3], v[190:193], v[226:229], v[0:3]
	s_barrier
	s_setprio 0
	s_add_i32 s55, 0, 0x18000
	s_add_i32 s56, 0, 0x1c000
	v_add_u32_e32 v112, s55, v167
	v_add_u32_e32 v162, s56, v167
	ds_read_b128 v[96:99], v112
	ds_read_b128 v[100:103], v112 offset:1024
	ds_read_b128 v[104:107], v112 offset:2048
	ds_read_b128 v[112:115], v112 offset:3072
	ds_read_b128 v[178:181], v162
	ds_read_b128 v[182:185], v162 offset:1024
	ds_read_b128 v[186:189], v162 offset:2048
	ds_read_b128 v[190:193], v162 offset:3072
	s_add_u32 s46, s46, 0x80000
	s_addc_u32 s47, s47, 0
	s_mov_b32 m0, s65
	ds_read_b128 v[198:201], v177 offset:32768
	ds_read_b128 v[202:205], v177 offset:33792
	ds_read_b128 v[206:209], v177 offset:34816
	ds_read_b128 v[210:213], v177 offset:35840
	ds_read_b128 v[214:217], v177 offset:36864
	ds_read_b128 v[218:221], v177 offset:37888
	ds_read_b128 v[222:225], v177 offset:38912
	ds_read_b128 v[226:229], v177 offset:39936
	global_load_lds_dwordx4 v144, s[46:47]
	s_mov_b32 m0, s66
	s_nop 0
	global_load_lds_dwordx4 v146, s[46:47]
	s_waitcnt vmcnt(8) lgkmcnt(0)
	s_setprio 1
	s_barrier
; #define PG8_STAGE(bufoff, gbase, voff) do { _Pragma("unroll") for (int _i = 0; _i < 2; ++_i) \
;         __builtin_amdgcn_global_load_lds((const unsigned*)((const char*)(gbase) + (voff)[_i]), (PG8_LAS unsigned*)(lds + (bufoff) + ldsw + _i * 8192), 16, 0, 0); } while (0)
; #define PG8_LDA(dst, b, h) do { _Pragma("unroll") for (int m = 0; m < 4; ++m) _Pragma("unroll") for (int k = 0; k < 2; ++k) dst[m][k] = *(const PG8_LAS bf16x8*)(lds + PG8_SA(b, h) + aoff + m * 2048 + k * 1024); } while (0)
; #define PG8_MMA(ai, bj, At, Bt) do { __builtin_amdgcn_s_setprio(1); _Pragma("unroll") for (int m = 0; m < 4; ++m) _Pragma("unroll") for (int n = 0; n < 2; ++n) _Pragma("unroll") for (int k = 0; k < 2; ++k) \
;         acc[ai][bj][m][n] = __builtin_amdgcn_mfma_f32_16x16x32_bf16(Bt[n][k], At[m][k], acc[ai][bj][m][n], 0, 0, 0); __builtin_amdgcn_s_setprio(0); } while (0)
; #define PG8_WAIT_V(n) asm volatile("s_waitcnt vmcnt(" #n ")" ::: "memory")
; #define PG8_WAIT_L(n) asm volatile("s_waitcnt lgkmcnt(" #n ")" ::: "memory")
; #define PG8_BAR __builtin_amdgcn_s_barrier()
; #define PG8_SCHED __builtin_amdgcn_sched_barrier(0)
; template <class Epi, class Sched, bool ALIGN_EPI = false, bool SP2 = false>
; __device__ __forceinline__ void gemm_phase(PG8_LAS unsigned char* lds, const Gemm g, const Sched& S, const Epi& E) {
;     ...
;             PG8_WAIT_V(8); PG8_WAIT_L(0); PG8_BAR; PG8_MMA(0, 0, At, B0); PG8_MMA(0, 1, At, B1); PG8_BAR; PG8_SCHED;
;             PG8_LDA(At, 1, 1); PG8_STAGE(PG8_SB(1, 0), b3, voffB); PG8_STAGE(PG8_SB(1, 1), b3 + hstep, voffB); PG8_STAGE(PG8_SA(1, 0), a3, voffA);
;             PG8_WAIT_V(8); PG8_WAIT_L(0); PG8_BAR; PG8_MMA(1, 0, At, B0); PG8_MMA(1, 1, At, B1); PG8_BAR; PG8_SCHED;
;     ...
;         if constexpr (ALIGN_EPI) { if (wr == 0) PG8_BAR; }
	v_mfma_f32_16x16x32_bf16 v[140:143], v[96:99], v[198:201], v[140:143]
	v_mfma_f32_16x16x32_bf16 v[132:135], v[104:107], v[198:201], v[132:135]
	v_mfma_f32_16x16x32_bf16 v[116:119], v[96:99], v[206:209], v[116:119]
	v_mfma_f32_16x16x32_bf16 v[124:127], v[104:107], v[206:209], v[124:127]
	v_mfma_f32_16x16x32_bf16 v[84:87], v[96:99], v[214:217], v[84:87]
	v_mfma_f32_16x16x32_bf16 v[92:95], v[104:107], v[214:217], v[92:95]
	v_mfma_f32_16x16x32_bf16 v[68:71], v[96:99], v[222:225], v[68:71]
	v_mfma_f32_16x16x32_bf16 v[76:79], v[104:107], v[222:225], v[76:79]
	v_mfma_f32_16x16x32_bf16 v[140:143], v[100:103], v[202:205], v[140:143]
	v_mfma_f32_16x16x32_bf16 v[132:135], v[112:115], v[202:205], v[132:135]
	v_mfma_f32_16x16x32_bf16 v[116:119], v[100:103], v[210:213], v[116:119]
	v_mfma_f32_16x16x32_bf16 v[124:127], v[112:115], v[210:213], v[124:127]
	v_mfma_f32_16x16x32_bf16 v[84:87], v[100:103], v[218:221], v[84:87]
	v_mfma_f32_16x16x32_bf16 v[92:95], v[112:115], v[218:221], v[92:95]
	v_mfma_f32_16x16x32_bf16 v[68:71], v[100:103], v[226:229], v[68:71]
	v_mfma_f32_16x16x32_bf16 v[76:79], v[112:115], v[226:229], v[76:79]
	v_mfma_f32_16x16x32_bf16 v[128:131], v[178:181], v[198:201], v[128:131]
	v_mfma_f32_16x16x32_bf16 v[136:139], v[186:189], v[198:201], v[136:139]
	v_mfma_f32_16x16x32_bf16 v[120:123], v[178:181], v[206:209], v[120:123]
	v_mfma_f32_16x16x32_bf16 v[108:111], v[186:189], v[206:209], v[108:111]
	v_mfma_f32_16x16x32_bf16 v[88:91], v[178:181], v[214:217], v[88:91]
	v_mfma_f32_16x16x32_bf16 v[80:83], v[186:189], v[214:217], v[80:83]
	v_mfma_f32_16x16x32_bf16 v[72:75], v[178:181], v[222:225], v[72:75]
	v_mfma_f32_16x16x32_bf16 v[64:67], v[186:189], v[222:225], v[64:67]
	v_mfma_f32_16x16x32_bf16 v[128:131], v[182:185], v[202:205], v[128:131]
	v_mfma_f32_16x16x32_bf16 v[136:139], v[190:193], v[202:205], v[136:139]
	v_mfma_f32_16x16x32_bf16 v[120:123], v[182:185], v[210:213], v[120:123]
	v_mfma_f32_16x16x32_bf16 v[108:111], v[190:193], v[210:213], v[108:111]
	v_mfma_f32_16x16x32_bf16 v[88:91], v[182:185], v[218:221], v[88:91]
	v_mfma_f32_16x16x32_bf16 v[80:83], v[190:193], v[218:221], v[80:83]
	v_mfma_f32_16x16x32_bf16 v[72:75], v[182:185], v[226:229], v[72:75]
	v_mfma_f32_16x16x32_bf16 v[64:67], v[190:193], v[226:229], v[64:67]
	s_barrier
	s_setprio 0
	v_lshl_add_u64 v[160:161], v[160:161], 0, s[12:13]
	s_mov_b32 m0, s100
	ds_read_b128 v[198:201], v177 offset:49152
	ds_read_b128 v[202:205], v177 offset:50176
	ds_read_b128 v[206:209], v177 offset:51200
	ds_read_b128 v[210:213], v177 offset:52224
	ds_read_b128 v[214:217], v177 offset:53248
	ds_read_b128 v[218:221], v177 offset:54272
	ds_read_b128 v[222:225], v177 offset:55296
	ds_read_b128 v[226:229], v177 offset:56320
	global_load_lds_dwordx4 v[160:161], off
	s_add_i32 m0, s100, 0x2000
	s_add_u32 s44, s44, 0x80080
	v_lshl_add_u64 v[160:161], v[164:165], 0, s[12:13]
	s_addc_u32 s45, s45, 0
	global_load_lds_dwordx4 v[160:161], off
	s_mov_b32 m0, s101
	s_nop 0
	global_load_lds_dwordx4 v144, s[44:45]
	s_add_i32 m0, s101, 0x2000
	v_lshl_add_u64 v[160:161], s[44:45], 0, v[146:147]
	global_load_lds_dwordx4 v[160:161], off
	s_mov_b32 m0, s68
	v_lshl_add_u64 v[160:161], v[170:171], 0, s[12:13]
	global_load_lds_dwordx4 v[160:161], off
	s_mov_b32 m0, s69
	v_lshl_add_u64 v[160:161], v[194:195], 0, s[12:13]
	global_load_lds_dwordx4 v[160:161], off
	s_waitcnt vmcnt(8) lgkmcnt(0)
	s_setprio 1
	s_barrier
	v_mfma_f32_16x16x32_bf16 v[60:63], v[96:99], v[198:201], v[60:63]
	v_mfma_f32_16x16x32_bf16 v[52:55], v[104:107], v[198:201], v[52:55]
	v_mfma_f32_16x16x32_bf16 v[36:39], v[96:99], v[206:209], v[36:39]
	v_mfma_f32_16x16x32_bf16 v[44:47], v[104:107], v[206:209], v[44:47]
	v_mfma_f32_16x16x32_bf16 v[20:23], v[96:99], v[214:217], v[20:23]
	v_mfma_f32_16x16x32_bf16 v[28:31], v[104:107], v[214:217], v[28:31]
	v_mfma_f32_16x16x32_bf16 v[4:7], v[96:99], v[222:225], v[4:7]
	v_mfma_f32_16x16x32_bf16 v[12:15], v[104:107], v[222:225], v[12:15]
	v_mfma_f32_16x16x32_bf16 v[60:63], v[100:103], v[202:205], v[60:63]
	v_mfma_f32_16x16x32_bf16 v[52:55], v[112:115], v[202:205], v[52:55]
	v_mfma_f32_16x16x32_bf16 v[36:39], v[100:103], v[210:213], v[36:39]
	v_mfma_f32_16x16x32_bf16 v[44:47], v[112:115], v[210:213], v[44:47]
	v_mfma_f32_16x16x32_bf16 v[20:23], v[100:103], v[218:221], v[20:23]
	v_mfma_f32_16x16x32_bf16 v[28:31], v[112:115], v[218:221], v[28:31]
	v_mfma_f32_16x16x32_bf16 v[4:7], v[100:103], v[226:229], v[4:7]
	v_mfma_f32_16x16x32_bf16 v[12:15], v[112:115], v[226:229], v[12:15]
	v_mfma_f32_16x16x32_bf16 v[48:51], v[178:181], v[198:201], v[48:51]
	v_mfma_f32_16x16x32_bf16 v[56:59], v[186:189], v[198:201], v[56:59]
	v_mfma_f32_16x16x32_bf16 v[40:43], v[178:181], v[206:209], v[40:43]
	v_mfma_f32_16x16x32_bf16 v[32:35], v[186:189], v[206:209], v[32:35]
	v_mfma_f32_16x16x32_bf16 v[24:27], v[178:181], v[214:217], v[24:27]
	v_mfma_f32_16x16x32_bf16 v[16:19], v[186:189], v[214:217], v[16:19]
	v_mfma_f32_16x16x32_bf16 v[8:11], v[178:181], v[222:225], v[8:11]
	v_mfma_f32_16x16x32_bf16 v[0:3], v[186:189], v[222:225], v[0:3]
	v_mfma_f32_16x16x32_bf16 v[48:51], v[182:185], v[202:205], v[48:51]
	v_mfma_f32_16x16x32_bf16 v[56:59], v[190:193], v[202:205], v[56:59]
	v_mfma_f32_16x16x32_bf16 v[40:43], v[182:185], v[210:213], v[40:43]
	v_mfma_f32_16x16x32_bf16 v[32:35], v[190:193], v[210:213], v[32:35]
	v_mfma_f32_16x16x32_bf16 v[24:27], v[182:185], v[218:221], v[24:27]
	v_mfma_f32_16x16x32_bf16 v[16:19], v[190:193], v[218:221], v[16:19]
	v_mfma_f32_16x16x32_bf16 v[8:11], v[182:185], v[226:229], v[8:11]
	v_mfma_f32_16x16x32_bf16 v[0:3], v[190:193], v[226:229], v[0:3]
	s_barrier
	s_setprio 0
	s_add_i32 s54, s54, 2
	s_add_u32 s8, s8, 0x100
	s_addc_u32 s9, s9, 0
	s_add_u32 s48, s48, 0x100
	s_addc_u32 s49, s49, 0
	s_cmp_gt_u32 s54, 29
	s_cbranch_scc0 .LBB0_129
	s_and_b64 vcc, exec, s[14:15]
	s_cbranch_vccz .LBB0_132
	s_barrier

; #define PG8_STAGE(bufoff, gbase, voff) do { _Pragma("unroll") for (int _i = 0; _i < 2; ++_i) \
;         __builtin_amdgcn_global_load_lds((const unsigned*)((const char*)(gbase) + (voff)[_i]), (PG8_LAS unsigned*)(lds + (bufoff) + ldsw + _i * 8192), 16, 0, 0); } while (0)
; #define PG8_LDA(dst, b, h) do { _Pragma("unroll") for (int m = 0; m < 4; ++m) _Pragma("unroll") for (int k = 0; k < 2; ++k) dst[m][k] = *(const PG8_LAS bf16x8*)(lds + PG8_SA(b, h) + aoff + m * 2048 + k * 1024); } while (0)
; #define PG8_LDB(dst, b, h) do { _Pragma("unroll") for (int n = 0; n < 2; ++n) _Pragma("unroll") for (int k = 0; k < 2; ++k) dst[n][k] = *(const PG8_LAS bf16x8*)(lds + PG8_SB(b, h) + boff + n * 2048 + k * 1024); } while (0)
; #define PG8_MMA(ai, bj, At, Bt) do { __builtin_amdgcn_s_setprio(1); _Pragma("unroll") for (int m = 0; m < 4; ++m) _Pragma("unroll") for (int n = 0; n < 2; ++n) _Pragma("unroll") for (int k = 0; k < 2; ++k) \
;         acc[ai][bj][m][n] = __builtin_amdgcn_mfma_f32_16x16x32_bf16(Bt[n][k], At[m][k], acc[ai][bj][m][n], 0, 0, 0); __builtin_amdgcn_s_setprio(0); } while (0)
; #define PG8_WAIT_V(n) asm volatile("s_waitcnt vmcnt(" #n ")" ::: "memory")
; template <class Epi, class Sched, bool ALIGN_EPI = false, bool SP2 = false>
; __device__ __forceinline__ void gemm_phase(PG8_LAS unsigned char* lds, const Gemm g, const Sched& S, const Epi& E) {
;     ...
;         const char* nA = has_next ? (const char*)g.A + (size_t)nxt.pm * tstep : cA; const char* nB = has_next ? (const char*)g.Bt + (size_t)nxt.pn * tstep : cB;
;         for (int t = 0; t < nt; t += 2) {
;             const bool last = (t == nt - 2);
;             const char* a1 = cA + (size_t)(t + 1) * kstep;
;             const char* a2 = last ? nA : cA + (size_t)(t + 2) * kstep; const char* b2 = last ? nB : cB + (size_t)(t + 2) * kstep;
;             const char* a3 = a2 + kstep; const char* b3 = b2 + kstep;
;             if (last && has_next) S.a_ready(nxt);
;             if constexpr (SP2) {
;             PG8_LDB(B0, 0, 0); PG8_LDB(B1, 0, 1); PG8_SCHED; PG8_LDA(At, 0, 0); PG8_STAGE(PG8_SA(1, 1), a1 + hstep, voffA);
;             PG8_WAIT_V(8); PG8_WAIT_L(0); PG8_BAR; PG8_MMA(0, 0, At, B0); PG8_MMA(0, 1, At, B1); PG8_BAR; PG8_SCHED;
;             PG8_LDA(At, 0, 1); PG8_STAGE(PG8_SB(0, 0), b2, voffB); PG8_STAGE(PG8_SB(0, 1), b2 + hstep, voffB); PG8_STAGE(PG8_SA(0, 0), a2, voffA);
.LBB0_306:
	s_ashr_i32 s21, s20, 31
	s_lshl_b64 s[22:23], s[20:21], 20
	s_add_u32 s22, s60, s22
	s_addc_u32 s23, s61, s23
	s_and_b64 s[24:25], s[4:5], exec
	s_cselect_b32 s7, s23, s27
	s_cselect_b32 s21, s22, s26
	s_ashr_i32 s19, s18, 31
	s_lshl_b64 s[24:25], s[18:19], 20
	s_add_u32 s24, s68, s24
	s_addc_u32 s25, s69, s25
	s_and_b64 s[30:31], s[4:5], exec
	s_cselect_b32 s19, s25, s29
	s_cselect_b32 s33, s24, s28
	s_add_u32 s26, s26, 0x80080
	s_addc_u32 s27, s27, 0
	s_add_u32 s48, s28, 0x100
	s_addc_u32 s49, s29, 0
	s_mov_b32 s50, -2
	s_waitcnt lgkmcnt(0)
	s_waitcnt lgkmcnt(0)
	s_add_i32 s98, s34, 0x10000
	s_add_i32 s99, s34, 0x14000
	s_add_i32 s100, s34, 0x18000
	s_add_i32 s101, s34, 0x1c000
	ds_read_b128 v[128:131], v181
	ds_read_b128 v[132:135], v181 offset:1024
	ds_read_b128 v[136:139], v181 offset:2048
	ds_read_b128 v[140:143], v181 offset:3072
	ds_read_b128 v[144:147], v182
	ds_read_b128 v[148:151], v182 offset:1024
	ds_read_b128 v[168:171], v182 offset:2048
	ds_read_b128 v[172:175], v182 offset:3072
	s_add_u32 s28, s26, 0xfff80080
	s_addc_u32 s29, s27, -1
	s_cmp_eq_u32 s50, 28
	s_cselect_b32 s31, s7, s29
	s_cselect_b32 s30, s21, s28
	s_cselect_b32 s29, s19, s49
	s_cselect_b32 s28, s33, s48
	s_add_i32 m0, s35, 0xc000
	ds_read_b128 v[186:189], v183
	ds_read_b128 v[190:193], v183 offset:1024
	ds_read_b128 v[198:201], v183 offset:2048
	ds_read_b128 v[202:205], v183 offset:3072
	ds_read_b128 v[206:209], v183 offset:4096
	ds_read_b128 v[210:213], v183 offset:5120
	ds_read_b128 v[214:217], v183 offset:6144
	ds_read_b128 v[218:221], v183 offset:7168
	global_load_lds_dwordx4 v160, s[26:27]
	s_add_i32 m0, s35, 0xe000
	s_nop 0
	global_load_lds_dwordx4 v162, s[26:27]
	s_waitcnt lgkmcnt(0)
	s_setprio 1
	s_barrier
	v_mfma_f32_16x16x32_bf16 v[124:127], v[128:131], v[186:189], 0
	v_mfma_f32_16x16x32_bf16 v[120:123], v[136:139], v[186:189], 0
	v_mfma_f32_16x16x32_bf16 v[104:107], v[128:131], v[198:201], 0
	v_mfma_f32_16x16x32_bf16 v[108:111], v[136:139], v[198:201], 0
	v_mfma_f32_16x16x32_bf16 v[88:91], v[128:131], v[206:209], 0
	v_mfma_f32_16x16x32_bf16 v[92:95], v[136:139], v[206:209], 0
	v_mfma_f32_16x16x32_bf16 v[72:75], v[128:131], v[214:217], 0
	v_mfma_f32_16x16x32_bf16 v[76:79], v[136:139], v[214:217], 0
	v_mfma_f32_16x16x32_bf16 v[124:127], v[132:135], v[190:193], v[124:127]
	v_mfma_f32_16x16x32_bf16 v[120:123], v[140:143], v[190:193], v[120:123]
	v_mfma_f32_16x16x32_bf16 v[104:107], v[132:135], v[202:205], v[104:107]
	v_mfma_f32_16x16x32_bf16 v[108:111], v[140:143], v[202:205], v[108:111]
	v_mfma_f32_16x16x32_bf16 v[88:91], v[132:135], v[210:213], v[88:91]
	v_mfma_f32_16x16x32_bf16 v[92:95], v[140:143], v[210:213], v[92:95]
	v_mfma_f32_16x16x32_bf16 v[72:75], v[132:135], v[218:221], v[72:75]
	v_mfma_f32_16x16x32_bf16 v[76:79], v[140:143], v[218:221], v[76:79]
	v_mfma_f32_16x16x32_bf16 v[116:119], v[144:147], v[186:189], 0
	v_mfma_f32_16x16x32_bf16 v[112:115], v[168:171], v[186:189], 0
	v_mfma_f32_16x16x32_bf16 v[100:103], v[144:147], v[198:201], 0
	v_mfma_f32_16x16x32_bf16 v[96:99], v[168:171], v[198:201], 0
	v_mfma_f32_16x16x32_bf16 v[84:87], v[144:147], v[206:209], 0
	v_mfma_f32_16x16x32_bf16 v[80:83], v[168:171], v[206:209], 0
	v_mfma_f32_16x16x32_bf16 v[68:71], v[144:147], v[214:217], 0
	v_mfma_f32_16x16x32_bf16 v[64:67], v[168:171], v[214:217], 0
	v_mfma_f32_16x16x32_bf16 v[116:119], v[148:151], v[190:193], v[116:119]
	v_mfma_f32_16x16x32_bf16 v[112:115], v[172:175], v[190:193], v[112:115]
	v_mfma_f32_16x16x32_bf16 v[100:103], v[148:151], v[202:205], v[100:103]
	v_mfma_f32_16x16x32_bf16 v[96:99], v[172:175], v[202:205], v[96:99]
	v_mfma_f32_16x16x32_bf16 v[84:87], v[148:151], v[210:213], v[84:87]
	v_mfma_f32_16x16x32_bf16 v[80:83], v[172:175], v[210:213], v[80:83]
	v_mfma_f32_16x16x32_bf16 v[68:71], v[148:151], v[218:221], v[68:71]
	v_mfma_f32_16x16x32_bf16 v[64:67], v[172:175], v[218:221], v[64:67]
	s_barrier
	s_setprio 0
	v_lshl_add_u64 v[176:177], s[28:29], 0, v[154:155]
	s_mov_b32 m0, s98
	ds_read_b128 v[186:189], v183 offset:16384
	ds_read_b128 v[190:193], v183 offset:17408
	ds_read_b128 v[198:201], v183 offset:18432
	ds_read_b128 v[202:205], v183 offset:19456
	ds_read_b128 v[206:209], v183 offset:20480
	ds_read_b128 v[210:213], v183 offset:21504
	ds_read_b128 v[214:217], v183 offset:22528
	ds_read_b128 v[218:221], v183 offset:23552
	global_load_lds_dwordx4 v[176:177], off
	s_add_i32 m0, s98, 0x2000
	s_add_u32 s52, s28, 0x80000
	v_lshl_add_u64 v[194:195], s[28:29], 0, v[158:159]
	s_addc_u32 s53, s29, 0
	global_load_lds_dwordx4 v[194:195], off
	s_mov_b32 m0, s99
	v_lshl_add_u64 v[224:225], s[30:31], 0, v[156:157]
	global_load_lds_dwordx4 v154, s[52:53]
	s_add_i32 m0, s99, 0x2000
	s_nop 0
	global_load_lds_dwordx4 v158, s[52:53]
	s_mov_b32 m0, s35
	v_lshl_add_u64 v[222:223], s[30:31], 0, v[152:153]
	global_load_lds_dwordx4 v[222:223], off
	s_mov_b32 m0, s37
	s_nop 0
	global_load_lds_dwordx4 v[224:225], off
	s_waitcnt lgkmcnt(0)
	s_setprio 1
	s_barrier
; #define PG8_STAGE(bufoff, gbase, voff) do { _Pragma("unroll") for (int _i = 0; _i < 2; ++_i) \
;         __builtin_amdgcn_global_load_lds((const unsigned*)((const char*)(gbase) + (voff)[_i]), (PG8_LAS unsigned*)(lds + (bufoff) + ldsw + _i * 8192), 16, 0, 0); } while (0)
; #define PG8_LDA(dst, b, h) do { _Pragma("unroll") for (int m = 0; m < 4; ++m) _Pragma("unroll") for (int k = 0; k < 2; ++k) dst[m][k] = *(const PG8_LAS bf16x8*)(lds + PG8_SA(b, h) + aoff + m * 2048 + k * 1024); } while (0)
; #define PG8_LDB(dst, b, h) do { _Pragma("unroll") for (int n = 0; n < 2; ++n) _Pragma("unroll") for (int k = 0; k < 2; ++k) dst[n][k] = *(const PG8_LAS bf16x8*)(lds + PG8_SB(b, h) + boff + n * 2048 + k * 1024); } while (0)
; #define PG8_MMA(ai, bj, At, Bt) do { __builtin_amdgcn_s_setprio(1); _Pragma("unroll") for (int m = 0; m < 4; ++m) _Pragma("unroll") for (int n = 0; n < 2; ++n) _Pragma("unroll") for (int k = 0; k < 2; ++k) \
;         acc[ai][bj][m][n] = __builtin_amdgcn_mfma_f32_16x16x32_bf16(Bt[n][k], At[m][k], acc[ai][bj][m][n], 0, 0, 0); __builtin_amdgcn_s_setprio(0); } while (0)
; #define PG8_WAIT_V(n) asm volatile("s_waitcnt vmcnt(" #n ")" ::: "memory")
; #define PG8_WAIT_L(n) asm volatile("s_waitcnt lgkmcnt(" #n ")" ::: "memory")
; #define PG8_BAR __builtin_amdgcn_s_barrier()
; #define PG8_SCHED __builtin_amdgcn_sched_barrier(0)
; template <class Epi, class Sched, bool ALIGN_EPI = false, bool SP2 = false>
; __device__ __forceinline__ void gemm_phase(PG8_LAS unsigned char* lds, const Gemm g, const Sched& S, const Epi& E) {
;     ...
;             PG8_WAIT_V(8); PG8_WAIT_L(0); PG8_BAR; PG8_MMA(1, 0, At, B0); PG8_MMA(1, 1, At, B1); PG8_BAR; PG8_SCHED;
;             PG8_LDB(B0, 1, 0); PG8_LDB(B1, 1, 1); PG8_SCHED; PG8_LDA(At, 1, 0); PG8_STAGE(PG8_SA(0, 1), a2 + hstep, voffA);
;             PG8_WAIT_V(8); PG8_WAIT_L(0); PG8_BAR; PG8_MMA(0, 0, At, B0); PG8_MMA(0, 1, At, B1); PG8_BAR; PG8_SCHED;
	v_mfma_f32_16x16x32_bf16 v[56:59], v[128:131], v[186:189], 0
	v_mfma_f32_16x16x32_bf16 v[60:63], v[136:139], v[186:189], 0
	v_mfma_f32_16x16x32_bf16 v[40:43], v[128:131], v[198:201], 0
	v_mfma_f32_16x16x32_bf16 v[44:47], v[136:139], v[198:201], 0
	v_mfma_f32_16x16x32_bf16 v[24:27], v[128:131], v[206:209], 0
	v_mfma_f32_16x16x32_bf16 v[28:31], v[136:139], v[206:209], 0
	v_mfma_f32_16x16x32_bf16 v[8:11], v[128:131], v[214:217], 0
	v_mfma_f32_16x16x32_bf16 v[12:15], v[136:139], v[214:217], 0
	v_mfma_f32_16x16x32_bf16 v[56:59], v[132:135], v[190:193], v[56:59]
	v_mfma_f32_16x16x32_bf16 v[60:63], v[140:143], v[190:193], v[60:63]
	v_mfma_f32_16x16x32_bf16 v[40:43], v[132:135], v[202:205], v[40:43]
	v_mfma_f32_16x16x32_bf16 v[44:47], v[140:143], v[202:205], v[44:47]
	v_mfma_f32_16x16x32_bf16 v[24:27], v[132:135], v[210:213], v[24:27]
	v_mfma_f32_16x16x32_bf16 v[28:31], v[140:143], v[210:213], v[28:31]
	v_mfma_f32_16x16x32_bf16 v[8:11], v[132:135], v[218:221], v[8:11]
	v_mfma_f32_16x16x32_bf16 v[12:15], v[140:143], v[218:221], v[12:15]
	v_mfma_f32_16x16x32_bf16 v[52:55], v[144:147], v[186:189], 0
	v_mfma_f32_16x16x32_bf16 v[48:51], v[168:171], v[186:189], 0
	v_mfma_f32_16x16x32_bf16 v[36:39], v[144:147], v[198:201], 0
	v_mfma_f32_16x16x32_bf16 v[32:35], v[168:171], v[198:201], 0
	v_mfma_f32_16x16x32_bf16 v[20:23], v[144:147], v[206:209], 0
	v_mfma_f32_16x16x32_bf16 v[16:19], v[168:171], v[206:209], 0
	v_mfma_f32_16x16x32_bf16 v[4:7], v[144:147], v[214:217], 0
	v_mfma_f32_16x16x32_bf16 v[0:3], v[168:171], v[214:217], 0
	v_mfma_f32_16x16x32_bf16 v[52:55], v[148:151], v[190:193], v[52:55]
	v_mfma_f32_16x16x32_bf16 v[48:51], v[172:175], v[190:193], v[48:51]
	v_mfma_f32_16x16x32_bf16 v[36:39], v[148:151], v[202:205], v[36:39]
	v_mfma_f32_16x16x32_bf16 v[32:35], v[172:175], v[202:205], v[32:35]
	v_mfma_f32_16x16x32_bf16 v[20:23], v[148:151], v[210:213], v[20:23]
	v_mfma_f32_16x16x32_bf16 v[16:19], v[172:175], v[210:213], v[16:19]
	v_mfma_f32_16x16x32_bf16 v[4:7], v[148:151], v[218:221], v[4:7]
	v_mfma_f32_16x16x32_bf16 v[0:3], v[172:175], v[218:221], v[0:3]
	s_barrier
	s_setprio 0
	s_add_i32 s51, 0, 0x18000
	s_add_i32 s52, 0, 0x1c000
	v_add_u32_e32 v140, s51, v179
	v_add_u32_e32 v172, s52, v179
	ds_read_b128 v[128:131], v140
	ds_read_b128 v[132:135], v140 offset:1024
	ds_read_b128 v[136:139], v140 offset:2048
	ds_read_b128 v[140:143], v140 offset:3072
	ds_read_b128 v[144:147], v172
	ds_read_b128 v[148:151], v172 offset:1024
	ds_read_b128 v[168:171], v172 offset:2048
	ds_read_b128 v[172:175], v172 offset:3072
	s_add_u32 s30, s30, 0x80000
	s_addc_u32 s31, s31, 0
	s_mov_b32 m0, s39
	ds_read_b128 v[186:189], v183 offset:32768
	ds_read_b128 v[190:193], v183 offset:33792
	ds_read_b128 v[198:201], v183 offset:34816
	ds_read_b128 v[202:205], v183 offset:35840
	ds_read_b128 v[206:209], v183 offset:36864
	ds_read_b128 v[210:213], v183 offset:37888
	ds_read_b128 v[214:217], v183 offset:38912
	ds_read_b128 v[218:221], v183 offset:39936
	global_load_lds_dwordx4 v152, s[30:31]
	s_mov_b32 m0, s42
	v_lshl_add_u64 v[226:227], s[30:31], 0, v[156:157]
	global_load_lds_dwordx4 v[226:227], off
	s_waitcnt vmcnt(8) lgkmcnt(0)
	s_setprio 1
	s_barrier
	v_mfma_f32_16x16x32_bf16 v[124:127], v[128:131], v[186:189], v[124:127]
	v_mfma_f32_16x16x32_bf16 v[120:123], v[136:139], v[186:189], v[120:123]
	v_mfma_f32_16x16x32_bf16 v[104:107], v[128:131], v[198:201], v[104:107]
	v_mfma_f32_16x16x32_bf16 v[108:111], v[136:139], v[198:201], v[108:111]
	v_mfma_f32_16x16x32_bf16 v[88:91], v[128:131], v[206:209], v[88:91]
	v_mfma_f32_16x16x32_bf16 v[92:95], v[136:139], v[206:209], v[92:95]
	v_mfma_f32_16x16x32_bf16 v[72:75], v[128:131], v[214:217], v[72:75]
	v_mfma_f32_16x16x32_bf16 v[76:79], v[136:139], v[214:217], v[76:79]
	v_mfma_f32_16x16x32_bf16 v[124:127], v[132:135], v[190:193], v[124:127]
	v_mfma_f32_16x16x32_bf16 v[120:123], v[140:143], v[190:193], v[120:123]
	v_mfma_f32_16x16x32_bf16 v[104:107], v[132:135], v[202:205], v[104:107]
	v_mfma_f32_16x16x32_bf16 v[108:111], v[140:143], v[202:205], v[108:111]
	v_mfma_f32_16x16x32_bf16 v[88:91], v[132:135], v[210:213], v[88:91]
	v_mfma_f32_16x16x32_bf16 v[92:95], v[140:143], v[210:213], v[92:95]
	v_mfma_f32_16x16x32_bf16 v[72:75], v[132:135], v[218:221], v[72:75]
	v_mfma_f32_16x16x32_bf16 v[76:79], v[140:143], v[218:221], v[76:79]
	v_mfma_f32_16x16x32_bf16 v[116:119], v[144:147], v[186:189], v[116:119]
	v_mfma_f32_16x16x32_bf16 v[112:115], v[168:171], v[186:189], v[112:115]
	v_mfma_f32_16x16x32_bf16 v[100:103], v[144:147], v[198:201], v[100:103]
	v_mfma_f32_16x16x32_bf16 v[96:99], v[168:171], v[198:201], v[96:99]
	v_mfma_f32_16x16x32_bf16 v[84:87], v[144:147], v[206:209], v[84:87]
	v_mfma_f32_16x16x32_bf16 v[80:83], v[168:171], v[206:209], v[80:83]
	v_mfma_f32_16x16x32_bf16 v[68:71], v[144:147], v[214:217], v[68:71]
	v_mfma_f32_16x16x32_bf16 v[64:67], v[168:171], v[214:217], v[64:67]
	v_mfma_f32_16x16x32_bf16 v[116:119], v[148:151], v[190:193], v[116:119]
	v_mfma_f32_16x16x32_bf16 v[112:115], v[172:175], v[190:193], v[112:115]
	v_mfma_f32_16x16x32_bf16 v[100:103], v[148:151], v[202:205], v[100:103]
	v_mfma_f32_16x16x32_bf16 v[96:99], v[172:175], v[202:205], v[96:99]
	v_mfma_f32_16x16x32_bf16 v[84:87], v[148:151], v[210:213], v[84:87]
	v_mfma_f32_16x16x32_bf16 v[80:83], v[172:175], v[210:213], v[80:83]
	v_mfma_f32_16x16x32_bf16 v[68:71], v[148:151], v[218:221], v[68:71]
	v_mfma_f32_16x16x32_bf16 v[64:67], v[172:175], v[218:221], v[64:67]
	s_barrier
; #define PG8_STAGE(bufoff, gbase, voff) do { _Pragma("unroll") for (int _i = 0; _i < 2; ++_i) \
;         __builtin_amdgcn_global_load_lds((const unsigned*)((const char*)(gbase) + (voff)[_i]), (PG8_LAS unsigned*)(lds + (bufoff) + ldsw + _i * 8192), 16, 0, 0); } while (0)
; #define PG8_LDA(dst, b, h) do { _Pragma("unroll") for (int m = 0; m < 4; ++m) _Pragma("unroll") for (int k = 0; k < 2; ++k) dst[m][k] = *(const PG8_LAS bf16x8*)(lds + PG8_SA(b, h) + aoff + m * 2048 + k * 1024); } while (0)
; #define PG8_LDB(dst, b, h) do { _Pragma("unroll") for (int n = 0; n < 2; ++n) _Pragma("unroll") for (int k = 0; k < 2; ++k) dst[n][k] = *(const PG8_LAS bf16x8*)(lds + PG8_SB(b, h) + boff + n * 2048 + k * 1024); } while (0)
; #define PG8_MMA(ai, bj, At, Bt) do { __builtin_amdgcn_s_setprio(1); _Pragma("unroll") for (int m = 0; m < 4; ++m) _Pragma("unroll") for (int n = 0; n < 2; ++n) _Pragma("unroll") for (int k = 0; k < 2; ++k) \
;         acc[ai][bj][m][n] = __builtin_amdgcn_mfma_f32_16x16x32_bf16(Bt[n][k], At[m][k], acc[ai][bj][m][n], 0, 0, 0); __builtin_amdgcn_s_setprio(0); } while (0)
; #define PG8_WAIT_V(n) asm volatile("s_waitcnt vmcnt(" #n ")" ::: "memory")
; #define PG8_WAIT_L(n) asm volatile("s_waitcnt lgkmcnt(" #n ")" ::: "memory")
; #define PG8_BAR __builtin_amdgcn_s_barrier()
; #define PG8_SCHED __builtin_amdgcn_sched_barrier(0)
; template <class Epi, class Sched, bool ALIGN_EPI = false, bool SP2 = false>
; __device__ __forceinline__ void gemm_phase(PG8_LAS unsigned char* lds, const Gemm g, const Sched& S, const Epi& E) {
;     ...
;             const bool last = (t == nt - 2);
;             const char* a1 = cA + (size_t)(t + 1) * kstep;
;             const char* a2 = last ? nA : cA + (size_t)(t + 2) * kstep; const char* b2 = last ? nB : cB + (size_t)(t + 2) * kstep;
;             const char* a3 = a2 + kstep; const char* b3 = b2 + kstep;
;             if (last && has_next) S.a_ready(nxt);
;             if constexpr (SP2) {
;             PG8_LDB(B0, 0, 0); PG8_LDB(B1, 0, 1); PG8_SCHED; PG8_LDA(At, 0, 0); PG8_STAGE(PG8_SA(1, 1), a1 + hstep, voffA);
;     ...
;             PG8_LDA(At, 1, 1); PG8_STAGE(PG8_SB(1, 0), b3, voffB); PG8_STAGE(PG8_SB(1, 1), b3 + hstep, voffB); PG8_STAGE(PG8_SA(1, 0), a3, voffA);
;             PG8_WAIT_V(8); PG8_WAIT_L(0); PG8_BAR; PG8_MMA(1, 0, At, B0); PG8_MMA(1, 1, At, B1); PG8_BAR; PG8_SCHED;
	s_setprio 0
	v_lshl_add_u64 v[176:177], v[176:177], 0, s[12:13]
	s_mov_b32 m0, s100
	ds_read_b128 v[186:189], v183 offset:49152
	ds_read_b128 v[190:193], v183 offset:50176
	ds_read_b128 v[198:201], v183 offset:51200
	ds_read_b128 v[202:205], v183 offset:52224
	ds_read_b128 v[206:209], v183 offset:53248
	ds_read_b128 v[210:213], v183 offset:54272
	ds_read_b128 v[214:217], v183 offset:55296
	ds_read_b128 v[218:221], v183 offset:56320
	global_load_lds_dwordx4 v[176:177], off
	s_add_i32 m0, s100, 0x2000
	s_add_u32 s28, s28, 0x80080
	v_lshl_add_u64 v[176:177], v[194:195], 0, s[12:13]
	s_addc_u32 s29, s29, 0
	global_load_lds_dwordx4 v[176:177], off
	s_mov_b32 m0, s101
	s_nop 0
	global_load_lds_dwordx4 v154, s[28:29]
	s_add_i32 m0, s101, 0x2000
	v_lshl_add_u64 v[176:177], s[28:29], 0, v[158:159]
	global_load_lds_dwordx4 v[176:177], off
	s_mov_b32 m0, s44
	v_lshl_add_u64 v[176:177], v[222:223], 0, s[12:13]
	global_load_lds_dwordx4 v[176:177], off
	s_mov_b32 m0, s45
	v_lshl_add_u64 v[176:177], v[224:225], 0, s[12:13]
	global_load_lds_dwordx4 v[176:177], off
	s_waitcnt vmcnt(8) lgkmcnt(0)
	s_setprio 1
	s_barrier
	v_mfma_f32_16x16x32_bf16 v[56:59], v[128:131], v[186:189], v[56:59]
	v_mfma_f32_16x16x32_bf16 v[60:63], v[136:139], v[186:189], v[60:63]
	v_mfma_f32_16x16x32_bf16 v[40:43], v[128:131], v[198:201], v[40:43]
	v_mfma_f32_16x16x32_bf16 v[44:47], v[136:139], v[198:201], v[44:47]
	v_mfma_f32_16x16x32_bf16 v[24:27], v[128:131], v[206:209], v[24:27]
	v_mfma_f32_16x16x32_bf16 v[28:31], v[136:139], v[206:209], v[28:31]
	v_mfma_f32_16x16x32_bf16 v[8:11], v[128:131], v[214:217], v[8:11]
	v_mfma_f32_16x16x32_bf16 v[12:15], v[136:139], v[214:217], v[12:15]
	v_mfma_f32_16x16x32_bf16 v[56:59], v[132:135], v[190:193], v[56:59]
	v_mfma_f32_16x16x32_bf16 v[60:63], v[140:143], v[190:193], v[60:63]
	v_mfma_f32_16x16x32_bf16 v[40:43], v[132:135], v[202:205], v[40:43]
	v_mfma_f32_16x16x32_bf16 v[44:47], v[140:143], v[202:205], v[44:47]
	v_mfma_f32_16x16x32_bf16 v[24:27], v[132:135], v[210:213], v[24:27]
	v_mfma_f32_16x16x32_bf16 v[28:31], v[140:143], v[210:213], v[28:31]
	v_mfma_f32_16x16x32_bf16 v[8:11], v[132:135], v[218:221], v[8:11]
	v_mfma_f32_16x16x32_bf16 v[12:15], v[140:143], v[218:221], v[12:15]
	v_mfma_f32_16x16x32_bf16 v[52:55], v[144:147], v[186:189], v[52:55]
	v_mfma_f32_16x16x32_bf16 v[48:51], v[168:171], v[186:189], v[48:51]
	v_mfma_f32_16x16x32_bf16 v[36:39], v[144:147], v[198:201], v[36:39]
	v_mfma_f32_16x16x32_bf16 v[32:35], v[168:171], v[198:201], v[32:35]
	v_mfma_f32_16x16x32_bf16 v[20:23], v[144:147], v[206:209], v[20:23]
	v_mfma_f32_16x16x32_bf16 v[16:19], v[168:171], v[206:209], v[16:19]
	v_mfma_f32_16x16x32_bf16 v[4:7], v[144:147], v[214:217], v[4:7]
	v_mfma_f32_16x16x32_bf16 v[0:3], v[168:171], v[214:217], v[0:3]
	v_mfma_f32_16x16x32_bf16 v[52:55], v[148:151], v[190:193], v[52:55]
	v_mfma_f32_16x16x32_bf16 v[48:51], v[172:175], v[190:193], v[48:51]
	v_mfma_f32_16x16x32_bf16 v[36:39], v[148:151], v[202:205], v[36:39]
	v_mfma_f32_16x16x32_bf16 v[32:35], v[172:175], v[202:205], v[32:35]
	v_mfma_f32_16x16x32_bf16 v[20:23], v[148:151], v[210:213], v[20:23]
	v_mfma_f32_16x16x32_bf16 v[16:19], v[172:175], v[210:213], v[16:19]
	v_mfma_f32_16x16x32_bf16 v[4:7], v[148:151], v[218:221], v[4:7]
	v_mfma_f32_16x16x32_bf16 v[0:3], v[172:175], v[218:221], v[0:3]
	s_barrier
	s_setprio 0
	s_add_i32 s50, s50, 2
	s_add_u32 s26, s26, 0x100
	s_addc_u32 s27, s27, 0
	s_add_u32 s48, s48, 0x100
	s_addc_u32 s49, s49, 0
.LBB0_307:
	ds_read_b128 v[128:131], v181
	ds_read_b128 v[132:135], v181 offset:1024
	ds_read_b128 v[136:139], v181 offset:2048
	ds_read_b128 v[140:143], v181 offset:3072
	ds_read_b128 v[144:147], v182
	ds_read_b128 v[148:151], v182 offset:1024
	ds_read_b128 v[168:171], v182 offset:2048
	ds_read_b128 v[172:175], v182 offset:3072
	s_add_u32 s28, s26, 0xfff80080
	s_addc_u32 s29, s27, -1
	s_cmp_eq_u32 s50, 28
	s_cselect_b32 s31, s7, s29
	s_cselect_b32 s30, s21, s28
	s_cselect_b32 s29, s19, s49
	s_cselect_b32 s28, s33, s48
	s_add_i32 m0, s35, 0xc000
	ds_read_b128 v[186:189], v183
	ds_read_b128 v[190:193], v183 offset:1024
	ds_read_b128 v[198:201], v183 offset:2048
	ds_read_b128 v[202:205], v183 offset:3072
	ds_read_b128 v[206:209], v183 offset:4096
	ds_read_b128 v[210:213], v183 offset:5120
	ds_read_b128 v[214:217], v183 offset:6144
	ds_read_b128 v[218:221], v183 offset:7168
	global_load_lds_dwordx4 v160, s[26:27]
	s_add_i32 m0, s35, 0xe000
	s_nop 0
	global_load_lds_dwordx4 v162, s[26:27]
	s_waitcnt vmcnt(8) lgkmcnt(0)
	s_setprio 1
	s_barrier
; #define PG8_STAGE(bufoff, gbase, voff) do { _Pragma("unroll") for (int _i = 0; _i < 2; ++_i) \
;         __builtin_amdgcn_global_load_lds((const unsigned*)((const char*)(gbase) + (voff)[_i]), (PG8_LAS unsigned*)(lds + (bufoff) + ldsw + _i * 8192), 16, 0, 0); } while (0)
; #define PG8_LDA(dst, b, h) do { _Pragma("unroll") for (int m = 0; m < 4; ++m) _Pragma("unroll") for (int k = 0; k < 2; ++k) dst[m][k] = *(const PG8_LAS bf16x8*)(lds + PG8_SA(b, h) + aoff + m * 2048 + k * 1024); } while (0)
; #define PG8_LDB(dst, b, h) do { _Pragma("unroll") for (int n = 0; n < 2; ++n) _Pragma("unroll") for (int k = 0; k < 2; ++k) dst[n][k] = *(const PG8_LAS bf16x8*)(lds + PG8_SB(b, h) + boff + n * 2048 + k * 1024); } while (0)
; #define PG8_MMA(ai, bj, At, Bt) do { __builtin_amdgcn_s_setprio(1); _Pragma("unroll") for (int m = 0; m < 4; ++m) _Pragma("unroll") for (int n = 0; n < 2; ++n) _Pragma("unroll") for (int k = 0; k < 2; ++k) \
;         acc[ai][bj][m][n] = __builtin_amdgcn_mfma_f32_16x16x32_bf16(Bt[n][k], At[m][k], acc[ai][bj][m][n], 0, 0, 0); __builtin_amdgcn_s_setprio(0); } while (0)
; #define PG8_WAIT_V(n) asm volatile("s_waitcnt vmcnt(" #n ")" ::: "memory")
; #define PG8_WAIT_L(n) asm volatile("s_waitcnt lgkmcnt(" #n ")" ::: "memory")
; #define PG8_BAR __builtin_amdgcn_s_barrier()
; #define PG8_SCHED __builtin_amdgcn_sched_barrier(0)
; template <class Epi, class Sched, bool ALIGN_EPI = false, bool SP2 = false>
; __device__ __forceinline__ void gemm_phase(PG8_LAS unsigned char* lds, const Gemm g, const Sched& S, const Epi& E) {
;     ...
;             PG8_WAIT_V(8); PG8_WAIT_L(0); PG8_BAR; PG8_MMA(0, 0, At, B0); PG8_MMA(0, 1, At, B1); PG8_BAR; PG8_SCHED;
;             PG8_LDA(At, 0, 1); PG8_STAGE(PG8_SB(0, 0), b2, voffB); PG8_STAGE(PG8_SB(0, 1), b2 + hstep, voffB); PG8_STAGE(PG8_SA(0, 0), a2, voffA);
;             PG8_WAIT_V(8); PG8_WAIT_L(0); PG8_BAR; PG8_MMA(1, 0, At, B0); PG8_MMA(1, 1, At, B1); PG8_BAR; PG8_SCHED;
;             PG8_LDB(B0, 1, 0); PG8_LDB(B1, 1, 1); PG8_SCHED; PG8_LDA(At, 1, 0); PG8_STAGE(PG8_SA(0, 1), a2 + hstep, voffA);
	v_mfma_f32_16x16x32_bf16 v[124:127], v[128:131], v[186:189], v[124:127]
	v_mfma_f32_16x16x32_bf16 v[120:123], v[136:139], v[186:189], v[120:123]
	v_mfma_f32_16x16x32_bf16 v[104:107], v[128:131], v[198:201], v[104:107]
	v_mfma_f32_16x16x32_bf16 v[108:111], v[136:139], v[198:201], v[108:111]
	v_mfma_f32_16x16x32_bf16 v[88:91], v[128:131], v[206:209], v[88:91]
	v_mfma_f32_16x16x32_bf16 v[92:95], v[136:139], v[206:209], v[92:95]
	v_mfma_f32_16x16x32_bf16 v[72:75], v[128:131], v[214:217], v[72:75]
	v_mfma_f32_16x16x32_bf16 v[76:79], v[136:139], v[214:217], v[76:79]
	v_mfma_f32_16x16x32_bf16 v[124:127], v[132:135], v[190:193], v[124:127]
	v_mfma_f32_16x16x32_bf16 v[120:123], v[140:143], v[190:193], v[120:123]
	v_mfma_f32_16x16x32_bf16 v[104:107], v[132:135], v[202:205], v[104:107]
	v_mfma_f32_16x16x32_bf16 v[108:111], v[140:143], v[202:205], v[108:111]
	v_mfma_f32_16x16x32_bf16 v[88:91], v[132:135], v[210:213], v[88:91]
	v_mfma_f32_16x16x32_bf16 v[92:95], v[140:143], v[210:213], v[92:95]
	v_mfma_f32_16x16x32_bf16 v[72:75], v[132:135], v[218:221], v[72:75]
	v_mfma_f32_16x16x32_bf16 v[76:79], v[140:143], v[218:221], v[76:79]
	v_mfma_f32_16x16x32_bf16 v[116:119], v[144:147], v[186:189], v[116:119]
	v_mfma_f32_16x16x32_bf16 v[112:115], v[168:171], v[186:189], v[112:115]
	v_mfma_f32_16x16x32_bf16 v[100:103], v[144:147], v[198:201], v[100:103]
	v_mfma_f32_16x16x32_bf16 v[96:99], v[168:171], v[198:201], v[96:99]
	v_mfma_f32_16x16x32_bf16 v[84:87], v[144:147], v[206:209], v[84:87]
	v_mfma_f32_16x16x32_bf16 v[80:83], v[168:171], v[206:209], v[80:83]
	v_mfma_f32_16x16x32_bf16 v[68:71], v[144:147], v[214:217], v[68:71]
	v_mfma_f32_16x16x32_bf16 v[64:67], v[168:171], v[214:217], v[64:67]
	v_mfma_f32_16x16x32_bf16 v[116:119], v[148:151], v[190:193], v[116:119]
	v_mfma_f32_16x16x32_bf16 v[112:115], v[172:175], v[190:193], v[112:115]
	v_mfma_f32_16x16x32_bf16 v[100:103], v[148:151], v[202:205], v[100:103]
	v_mfma_f32_16x16x32_bf16 v[96:99], v[172:175], v[202:205], v[96:99]
	v_mfma_f32_16x16x32_bf16 v[84:87], v[148:151], v[210:213], v[84:87]
	v_mfma_f32_16x16x32_bf16 v[80:83], v[172:175], v[210:213], v[80:83]
	v_mfma_f32_16x16x32_bf16 v[68:71], v[148:151], v[218:221], v[68:71]
	v_mfma_f32_16x16x32_bf16 v[64:67], v[172:175], v[218:221], v[64:67]
	s_barrier
	s_setprio 0
	v_lshl_add_u64 v[176:177], s[28:29], 0, v[154:155]
	s_mov_b32 m0, s98
	ds_read_b128 v[186:189], v183 offset:16384
	ds_read_b128 v[190:193], v183 offset:17408
	ds_read_b128 v[198:201], v183 offset:18432
	ds_read_b128 v[202:205], v183 offset:19456
	ds_read_b128 v[206:209], v183 offset:20480
	ds_read_b128 v[210:213], v183 offset:21504
	ds_read_b128 v[214:217], v183 offset:22528
	ds_read_b128 v[218:221], v183 offset:23552
	global_load_lds_dwordx4 v[176:177], off
	s_add_i32 m0, s98, 0x2000
	s_add_u32 s52, s28, 0x80000
	v_lshl_add_u64 v[194:195], s[28:29], 0, v[158:159]
	s_addc_u32 s53, s29, 0
	global_load_lds_dwordx4 v[194:195], off
	s_mov_b32 m0, s99
	v_lshl_add_u64 v[224:225], s[30:31], 0, v[156:157]
	global_load_lds_dwordx4 v154, s[52:53]
	s_add_i32 m0, s99, 0x2000
	s_nop 0
	global_load_lds_dwordx4 v158, s[52:53]
	s_mov_b32 m0, s35
	v_lshl_add_u64 v[222:223], s[30:31], 0, v[152:153]
	global_load_lds_dwordx4 v[222:223], off
	s_mov_b32 m0, s37
	s_nop 0
	global_load_lds_dwordx4 v[224:225], off
	s_waitcnt vmcnt(8) lgkmcnt(0)
	s_setprio 1
	s_barrier
	v_mfma_f32_16x16x32_bf16 v[56:59], v[128:131], v[186:189], v[56:59]
	v_mfma_f32_16x16x32_bf16 v[60:63], v[136:139], v[186:189], v[60:63]
	v_mfma_f32_16x16x32_bf16 v[40:43], v[128:131], v[198:201], v[40:43]
	v_mfma_f32_16x16x32_bf16 v[44:47], v[136:139], v[198:201], v[44:47]
	v_mfma_f32_16x16x32_bf16 v[24:27], v[128:131], v[206:209], v[24:27]
	v_mfma_f32_16x16x32_bf16 v[28:31], v[136:139], v[206:209], v[28:31]
	v_mfma_f32_16x16x32_bf16 v[8:11], v[128:131], v[214:217], v[8:11]
	v_mfma_f32_16x16x32_bf16 v[12:15], v[136:139], v[214:217], v[12:15]
	v_mfma_f32_16x16x32_bf16 v[56:59], v[132:135], v[190:193], v[56:59]
	v_mfma_f32_16x16x32_bf16 v[60:63], v[140:143], v[190:193], v[60:63]
	v_mfma_f32_16x16x32_bf16 v[40:43], v[132:135], v[202:205], v[40:43]
	v_mfma_f32_16x16x32_bf16 v[44:47], v[140:143], v[202:205], v[44:47]
	v_mfma_f32_16x16x32_bf16 v[24:27], v[132:135], v[210:213], v[24:27]
	v_mfma_f32_16x16x32_bf16 v[28:31], v[140:143], v[210:213], v[28:31]
	v_mfma_f32_16x16x32_bf16 v[8:11], v[132:135], v[218:221], v[8:11]
	v_mfma_f32_16x16x32_bf16 v[12:15], v[140:143], v[218:221], v[12:15]
	v_mfma_f32_16x16x32_bf16 v[52:55], v[144:147], v[186:189], v[52:55]
	v_mfma_f32_16x16x32_bf16 v[48:51], v[168:171], v[186:189], v[48:51]
	v_mfma_f32_16x16x32_bf16 v[36:39], v[144:147], v[198:201], v[36:39]
	v_mfma_f32_16x16x32_bf16 v[32:35], v[168:171], v[198:201], v[32:35]
	v_mfma_f32_16x16x32_bf16 v[20:23], v[144:147], v[206:209], v[20:23]
	v_mfma_f32_16x16x32_bf16 v[16:19], v[168:171], v[206:209], v[16:19]
	v_mfma_f32_16x16x32_bf16 v[4:7], v[144:147], v[214:217], v[4:7]
	v_mfma_f32_16x16x32_bf16 v[0:3], v[168:171], v[214:217], v[0:3]
	v_mfma_f32_16x16x32_bf16 v[52:55], v[148:151], v[190:193], v[52:55]
	v_mfma_f32_16x16x32_bf16 v[48:51], v[172:175], v[190:193], v[48:51]
	v_mfma_f32_16x16x32_bf16 v[36:39], v[148:151], v[202:205], v[36:39]
	v_mfma_f32_16x16x32_bf16 v[32:35], v[172:175], v[202:205], v[32:35]
	v_mfma_f32_16x16x32_bf16 v[20:23], v[148:151], v[210:213], v[20:23]
	v_mfma_f32_16x16x32_bf16 v[16:19], v[172:175], v[210:213], v[16:19]
	v_mfma_f32_16x16x32_bf16 v[4:7], v[148:151], v[218:221], v[4:7]
	v_mfma_f32_16x16x32_bf16 v[0:3], v[172:175], v[218:221], v[0:3]
	s_barrier
; #define PG8_STAGE(bufoff, gbase, voff) do { _Pragma("unroll") for (int _i = 0; _i < 2; ++_i) \
;         __builtin_amdgcn_global_load_lds((const unsigned*)((const char*)(gbase) + (voff)[_i]), (PG8_LAS unsigned*)(lds + (bufoff) + ldsw + _i * 8192), 16, 0, 0); } while (0)
; #define PG8_LDA(dst, b, h) do { _Pragma("unroll") for (int m = 0; m < 4; ++m) _Pragma("unroll") for (int k = 0; k < 2; ++k) dst[m][k] = *(const PG8_LAS bf16x8*)(lds + PG8_SA(b, h) + aoff + m * 2048 + k * 1024); } while (0)
; #define PG8_LDB(dst, b, h) do { _Pragma("unroll") for (int n = 0; n < 2; ++n) _Pragma("unroll") for (int k = 0; k < 2; ++k) dst[n][k] = *(const PG8_LAS bf16x8*)(lds + PG8_SB(b, h) + boff + n * 2048 + k * 1024); } while (0)
; #define PG8_MMA(ai, bj, At, Bt) do { __builtin_amdgcn_s_setprio(1); _Pragma("unroll") for (int m = 0; m < 4; ++m) _Pragma("unroll") for (int n = 0; n < 2; ++n) _Pragma("unroll") for (int k = 0; k < 2; ++k) \
;         acc[ai][bj][m][n] = __builtin_amdgcn_mfma_f32_16x16x32_bf16(Bt[n][k], At[m][k], acc[ai][bj][m][n], 0, 0, 0); __builtin_amdgcn_s_setprio(0); } while (0)
; #define PG8_WAIT_V(n) asm volatile("s_waitcnt vmcnt(" #n ")" ::: "memory")
; #define PG8_WAIT_L(n) asm volatile("s_waitcnt lgkmcnt(" #n ")" ::: "memory")
; #define PG8_BAR __builtin_amdgcn_s_barrier()
; #define PG8_SCHED __builtin_amdgcn_sched_barrier(0)
; template <class Epi, class Sched, bool ALIGN_EPI = false, bool SP2 = false>
; __device__ __forceinline__ void gemm_phase(PG8_LAS unsigned char* lds, const Gemm g, const Sched& S, const Epi& E) {
;     ...
;             PG8_LDB(B0, 1, 0); PG8_LDB(B1, 1, 1); PG8_SCHED; PG8_LDA(At, 1, 0); PG8_STAGE(PG8_SA(0, 1), a2 + hstep, voffA);
;             PG8_WAIT_V(8); PG8_WAIT_L(0); PG8_BAR; PG8_MMA(0, 0, At, B0); PG8_MMA(0, 1, At, B1); PG8_BAR; PG8_SCHED;
;             PG8_LDA(At, 1, 1); PG8_STAGE(PG8_SB(1, 0), b3, voffB); PG8_STAGE(PG8_SB(1, 1), b3 + hstep, voffB); PG8_STAGE(PG8_SA(1, 0), a3, voffA);
;             PG8_WAIT_V(8); PG8_WAIT_L(0); PG8_BAR; PG8_MMA(1, 0, At, B0); PG8_MMA(1, 1, At, B1); PG8_BAR; PG8_SCHED;
;     ...
;         if constexpr (ALIGN_EPI) { if (wr == 0) PG8_BAR; }
	s_setprio 0
	s_add_i32 s51, 0, 0x18000
	s_add_i32 s52, 0, 0x1c000
	v_add_u32_e32 v140, s51, v179
	v_add_u32_e32 v172, s52, v179
	ds_read_b128 v[128:131], v140
	ds_read_b128 v[132:135], v140 offset:1024
	ds_read_b128 v[136:139], v140 offset:2048
	ds_read_b128 v[140:143], v140 offset:3072
	ds_read_b128 v[144:147], v172
	ds_read_b128 v[148:151], v172 offset:1024
	ds_read_b128 v[168:171], v172 offset:2048
	ds_read_b128 v[172:175], v172 offset:3072
	s_add_u32 s30, s30, 0x80000
	s_addc_u32 s31, s31, 0
	s_mov_b32 m0, s39
	ds_read_b128 v[186:189], v183 offset:32768
	ds_read_b128 v[190:193], v183 offset:33792
	ds_read_b128 v[198:201], v183 offset:34816
	ds_read_b128 v[202:205], v183 offset:35840
	ds_read_b128 v[206:209], v183 offset:36864
	ds_read_b128 v[210:213], v183 offset:37888
	ds_read_b128 v[214:217], v183 offset:38912
	ds_read_b128 v[218:221], v183 offset:39936
	global_load_lds_dwordx4 v152, s[30:31]
	s_mov_b32 m0, s42
	s_nop 0
	global_load_lds_dwordx4 v156, s[30:31]
	s_waitcnt vmcnt(8) lgkmcnt(0)
	s_setprio 1
	s_barrier
	v_mfma_f32_16x16x32_bf16 v[124:127], v[128:131], v[186:189], v[124:127]
	v_mfma_f32_16x16x32_bf16 v[120:123], v[136:139], v[186:189], v[120:123]
	v_mfma_f32_16x16x32_bf16 v[104:107], v[128:131], v[198:201], v[104:107]
	v_mfma_f32_16x16x32_bf16 v[108:111], v[136:139], v[198:201], v[108:111]
	v_mfma_f32_16x16x32_bf16 v[88:91], v[128:131], v[206:209], v[88:91]
	v_mfma_f32_16x16x32_bf16 v[92:95], v[136:139], v[206:209], v[92:95]
	v_mfma_f32_16x16x32_bf16 v[72:75], v[128:131], v[214:217], v[72:75]
	v_mfma_f32_16x16x32_bf16 v[76:79], v[136:139], v[214:217], v[76:79]
	v_mfma_f32_16x16x32_bf16 v[124:127], v[132:135], v[190:193], v[124:127]
	v_mfma_f32_16x16x32_bf16 v[120:123], v[140:143], v[190:193], v[120:123]
	v_mfma_f32_16x16x32_bf16 v[104:107], v[132:135], v[202:205], v[104:107]
	v_mfma_f32_16x16x32_bf16 v[108:111], v[140:143], v[202:205], v[108:111]
	v_mfma_f32_16x16x32_bf16 v[88:91], v[132:135], v[210:213], v[88:91]
	v_mfma_f32_16x16x32_bf16 v[92:95], v[140:143], v[210:213], v[92:95]
	v_mfma_f32_16x16x32_bf16 v[72:75], v[132:135], v[218:221], v[72:75]
	v_mfma_f32_16x16x32_bf16 v[76:79], v[140:143], v[218:221], v[76:79]
	v_mfma_f32_16x16x32_bf16 v[116:119], v[144:147], v[186:189], v[116:119]
	v_mfma_f32_16x16x32_bf16 v[112:115], v[168:171], v[186:189], v[112:115]
	v_mfma_f32_16x16x32_bf16 v[100:103], v[144:147], v[198:201], v[100:103]
	v_mfma_f32_16x16x32_bf16 v[96:99], v[168:171], v[198:201], v[96:99]
	v_mfma_f32_16x16x32_bf16 v[84:87], v[144:147], v[206:209], v[84:87]
	v_mfma_f32_16x16x32_bf16 v[80:83], v[168:171], v[206:209], v[80:83]
	v_mfma_f32_16x16x32_bf16 v[68:71], v[144:147], v[214:217], v[68:71]
	v_mfma_f32_16x16x32_bf16 v[64:67], v[168:171], v[214:217], v[64:67]
	v_mfma_f32_16x16x32_bf16 v[116:119], v[148:151], v[190:193], v[116:119]
	v_mfma_f32_16x16x32_bf16 v[112:115], v[172:175], v[190:193], v[112:115]
	v_mfma_f32_16x16x32_bf16 v[100:103], v[148:151], v[202:205], v[100:103]
	v_mfma_f32_16x16x32_bf16 v[96:99], v[172:175], v[202:205], v[96:99]
	v_mfma_f32_16x16x32_bf16 v[84:87], v[148:151], v[210:213], v[84:87]
	v_mfma_f32_16x16x32_bf16 v[80:83], v[172:175], v[210:213], v[80:83]
	v_mfma_f32_16x16x32_bf16 v[68:71], v[148:151], v[218:221], v[68:71]
	v_mfma_f32_16x16x32_bf16 v[64:67], v[172:175], v[218:221], v[64:67]
	s_barrier
	s_setprio 0
	v_lshl_add_u64 v[176:177], v[176:177], 0, s[12:13]
	s_mov_b32 m0, s100
	ds_read_b128 v[186:189], v183 offset:49152
	ds_read_b128 v[190:193], v183 offset:50176
	ds_read_b128 v[198:201], v183 offset:51200
	ds_read_b128 v[202:205], v183 offset:52224
	ds_read_b128 v[206:209], v183 offset:53248
	ds_read_b128 v[210:213], v183 offset:54272
	ds_read_b128 v[214:217], v183 offset:55296
	ds_read_b128 v[218:221], v183 offset:56320
	global_load_lds_dwordx4 v[176:177], off
	s_add_i32 m0, s100, 0x2000
	s_add_u32 s28, s28, 0x80080
	v_lshl_add_u64 v[176:177], v[194:195], 0, s[12:13]
	s_addc_u32 s29, s29, 0
	global_load_lds_dwordx4 v[176:177], off
	s_mov_b32 m0, s101
	s_nop 0
	global_load_lds_dwordx4 v154, s[28:29]
	s_add_i32 m0, s101, 0x2000
	v_lshl_add_u64 v[176:177], s[28:29], 0, v[158:159]
	global_load_lds_dwordx4 v[176:177], off
	s_mov_b32 m0, s44
	v_lshl_add_u64 v[176:177], v[222:223], 0, s[12:13]
	global_load_lds_dwordx4 v[176:177], off
	s_mov_b32 m0, s45
	v_lshl_add_u64 v[176:177], v[224:225], 0, s[12:13]
	global_load_lds_dwordx4 v[176:177], off
	s_waitcnt vmcnt(8) lgkmcnt(0)
	s_setprio 1
	s_barrier
	v_mfma_f32_16x16x32_bf16 v[56:59], v[128:131], v[186:189], v[56:59]
	v_mfma_f32_16x16x32_bf16 v[60:63], v[136:139], v[186:189], v[60:63]
	v_mfma_f32_16x16x32_bf16 v[40:43], v[128:131], v[198:201], v[40:43]
	v_mfma_f32_16x16x32_bf16 v[44:47], v[136:139], v[198:201], v[44:47]
	v_mfma_f32_16x16x32_bf16 v[24:27], v[128:131], v[206:209], v[24:27]
	v_mfma_f32_16x16x32_bf16 v[28:31], v[136:139], v[206:209], v[28:31]
	v_mfma_f32_16x16x32_bf16 v[8:11], v[128:131], v[214:217], v[8:11]
	v_mfma_f32_16x16x32_bf16 v[12:15], v[136:139], v[214:217], v[12:15]
	v_mfma_f32_16x16x32_bf16 v[56:59], v[132:135], v[190:193], v[56:59]
	v_mfma_f32_16x16x32_bf16 v[60:63], v[140:143], v[190:193], v[60:63]
	v_mfma_f32_16x16x32_bf16 v[40:43], v[132:135], v[202:205], v[40:43]
	v_mfma_f32_16x16x32_bf16 v[44:47], v[140:143], v[202:205], v[44:47]
	v_mfma_f32_16x16x32_bf16 v[24:27], v[132:135], v[210:213], v[24:27]
	v_mfma_f32_16x16x32_bf16 v[28:31], v[140:143], v[210:213], v[28:31]
	v_mfma_f32_16x16x32_bf16 v[8:11], v[132:135], v[218:221], v[8:11]
	v_mfma_f32_16x16x32_bf16 v[12:15], v[140:143], v[218:221], v[12:15]
	v_mfma_f32_16x16x32_bf16 v[52:55], v[144:147], v[186:189], v[52:55]
	v_mfma_f32_16x16x32_bf16 v[48:51], v[168:171], v[186:189], v[48:51]
	v_mfma_f32_16x16x32_bf16 v[36:39], v[144:147], v[198:201], v[36:39]
	v_mfma_f32_16x16x32_bf16 v[32:35], v[168:171], v[198:201], v[32:35]
	v_mfma_f32_16x16x32_bf16 v[20:23], v[144:147], v[206:209], v[20:23]
	v_mfma_f32_16x16x32_bf16 v[16:19], v[168:171], v[206:209], v[16:19]
	v_mfma_f32_16x16x32_bf16 v[4:7], v[144:147], v[214:217], v[4:7]
	v_mfma_f32_16x16x32_bf16 v[0:3], v[168:171], v[214:217], v[0:3]
	v_mfma_f32_16x16x32_bf16 v[52:55], v[148:151], v[190:193], v[52:55]
	v_mfma_f32_16x16x32_bf16 v[48:51], v[172:175], v[190:193], v[48:51]
	v_mfma_f32_16x16x32_bf16 v[36:39], v[148:151], v[202:205], v[36:39]
	v_mfma_f32_16x16x32_bf16 v[32:35], v[172:175], v[202:205], v[32:35]
	v_mfma_f32_16x16x32_bf16 v[20:23], v[148:151], v[210:213], v[20:23]
	v_mfma_f32_16x16x32_bf16 v[16:19], v[172:175], v[210:213], v[16:19]
	v_mfma_f32_16x16x32_bf16 v[4:7], v[148:151], v[218:221], v[4:7]
	v_mfma_f32_16x16x32_bf16 v[0:3], v[172:175], v[218:221], v[0:3]
	s_barrier
	s_setprio 0
	s_add_i32 s50, s50, 2
	s_add_u32 s26, s26, 0x100
	s_addc_u32 s27, s27, 0
	s_add_u32 s48, s48, 0x100
	s_addc_u32 s49, s49, 0
	s_cmp_gt_u32 s50, 29
	s_cbranch_scc0 .LBB0_307
	s_and_b64 vcc, exec, s[14:15]
	s_cbranch_vccz .LBB0_310
	s_barrier

; #define PG8_STAGE(bufoff, gbase, voff) do { _Pragma("unroll") for (int _i = 0; _i < 2; ++_i) \
;         __builtin_amdgcn_global_load_lds((const unsigned*)((const char*)(gbase) + (voff)[_i]), (PG8_LAS unsigned*)(lds + (bufoff) + ldsw + _i * 8192), 16, 0, 0); } while (0)
; #define PG8_LDA(dst, b, h) do { _Pragma("unroll") for (int m = 0; m < 4; ++m) _Pragma("unroll") for (int k = 0; k < 2; ++k) dst[m][k] = *(const PG8_LAS bf16x8*)(lds + PG8_SA(b, h) + aoff + m * 2048 + k * 1024); } while (0)
; #define PG8_LDB(dst, b, h) do { _Pragma("unroll") for (int n = 0; n < 2; ++n) _Pragma("unroll") for (int k = 0; k < 2; ++k) dst[n][k] = *(const PG8_LAS bf16x8*)(lds + PG8_SB(b, h) + boff + n * 2048 + k * 1024); } while (0)
; #define PG8_MMA(ai, bj, At, Bt) do { __builtin_amdgcn_s_setprio(1); _Pragma("unroll") for (int m = 0; m < 4; ++m) _Pragma("unroll") for (int n = 0; n < 2; ++n) _Pragma("unroll") for (int k = 0; k < 2; ++k) \
;         acc[ai][bj][m][n] = __builtin_amdgcn_mfma_f32_16x16x32_bf16(Bt[n][k], At[m][k], acc[ai][bj][m][n], 0, 0, 0); __builtin_amdgcn_s_setprio(0); } while (0)
; #define PG8_WAIT_V(n) asm volatile("s_waitcnt vmcnt(" #n ")" ::: "memory")
; template <class Epi, class Sched, bool ALIGN_EPI = false, bool SP2 = false>
; __device__ __forceinline__ void gemm_phase(PG8_LAS unsigned char* lds, const Gemm g, const Sched& S, const Epi& E) {
;     ...
;         const char* nA = has_next ? (const char*)g.A + (size_t)nxt.pm * tstep : cA; const char* nB = has_next ? (const char*)g.Bt + (size_t)nxt.pn * tstep : cB;
;         for (int t = 0; t < nt; t += 2) {
;             const bool last = (t == nt - 2);
;             const char* a1 = cA + (size_t)(t + 1) * kstep;
;             const char* a2 = last ? nA : cA + (size_t)(t + 2) * kstep; const char* b2 = last ? nB : cB + (size_t)(t + 2) * kstep;
;             const char* a3 = a2 + kstep; const char* b3 = b2 + kstep;
;             if (last && has_next) S.a_ready(nxt);
;             if constexpr (SP2) {
;             PG8_LDB(B0, 0, 0); PG8_LDB(B1, 0, 1); PG8_SCHED; PG8_LDA(At, 0, 0); PG8_STAGE(PG8_SA(1, 1), a1 + hstep, voffA);
;             PG8_WAIT_V(8); PG8_WAIT_L(0); PG8_BAR; PG8_MMA(0, 0, At, B0); PG8_MMA(0, 1, At, B1); PG8_BAR; PG8_SCHED;
;             PG8_LDA(At, 0, 1); PG8_STAGE(PG8_SB(0, 0), b2, voffB); PG8_STAGE(PG8_SB(0, 1), b2 + hstep, voffB); PG8_STAGE(PG8_SA(0, 0), a2, voffA);
.LBB0_490:
	s_ashr_i32 s21, s20, 31
	s_lshl_b64 s[0:1], s[20:21], 20
	v_readlane_b32 s24, v254, 51
	v_readlane_b32 s25, v254, 52
	s_add_u32 s24, s24, s0
	s_addc_u32 s25, s25, s1
	s_and_b64 s[0:1], s[22:23], exec
	s_cselect_b32 s5, s25, s31
	s_cselect_b32 s21, s24, s30
	s_ashr_i32 s19, s18, 31
	s_lshl_b64 s[0:1], s[18:19], 20
	v_readlane_b32 s26, v254, 22
	v_readlane_b32 s27, v254, 23
	s_add_u32 s26, s26, s0
	s_addc_u32 s27, s27, s1
	s_and_b64 s[0:1], s[22:23], exec
	s_cselect_b32 s19, s27, s29
	s_cselect_b32 s33, s26, s28
	s_add_u32 s0, s30, 0x80080
	s_addc_u32 s1, s31, 0
	s_add_u32 s44, s28, 0x100
	s_addc_u32 s45, s29, 0
	s_mov_b32 s48, -2
	s_add_i32 s98, s34, 0x10000
	s_add_i32 s99, s34, 0x14000
	s_add_i32 s100, s34, 0x18000
	s_add_i32 s101, s34, 0x1c000
	v_add_u32_e32 v140, s68, v163
	v_add_u32_e32 v152, s69, v163
	ds_read_b128 v[128:131], v140
	ds_read_b128 v[132:135], v140 offset:1024
	ds_read_b128 v[136:139], v140 offset:2048
	ds_read_b128 v[140:143], v140 offset:3072
	ds_read_b128 v[184:187], v152
	ds_read_b128 v[218:221], v152 offset:1024
	ds_read_b128 v[222:225], v152 offset:2048
	ds_read_b128 v[226:229], v152 offset:3072
	s_add_u32 s28, s0, 0xfff80080
	s_addc_u32 s29, s1, -1
	s_cmp_eq_u32 s48, 28
	s_cselect_b32 s31, s5, s29
	s_cselect_b32 s30, s21, s28
	s_cselect_b32 s29, s19, s45
	s_cselect_b32 s28, s33, s44
	s_add_i32 m0, s17, 0xc000
	ds_read_b128 v[230:233], v214
	ds_read_b128 v[234:237], v214 offset:1024
	ds_read_b128 v[238:241], v214 offset:2048
	ds_read_b128 v[242:245], v214 offset:3072
	ds_read_b128 v[246:249], v214 offset:4096
	ds_read_b128 v[250:253], v214 offset:5120
	ds_read_b128 v[206:209], v214 offset:6144
	ds_read_b128 v[210:213], v214 offset:7168
	global_load_lds_dwordx4 v156, s[0:1]
	s_add_i32 m0, s17, 0xe000
	s_nop 0
	global_load_lds_dwordx4 v158, s[0:1]
	s_waitcnt lgkmcnt(0)
	s_setprio 1
	s_barrier
	v_mfma_f32_16x16x32_bf16 v[124:127], v[128:131], v[230:233], 0
	v_mfma_f32_16x16x32_bf16 v[120:123], v[136:139], v[230:233], 0
	v_mfma_f32_16x16x32_bf16 v[116:119], v[128:131], v[238:241], 0
	v_mfma_f32_16x16x32_bf16 v[108:111], v[136:139], v[238:241], 0
	v_mfma_f32_16x16x32_bf16 v[100:103], v[128:131], v[246:249], 0
	v_mfma_f32_16x16x32_bf16 v[92:95], v[136:139], v[246:249], 0
	v_mfma_f32_16x16x32_bf16 v[84:87], v[128:131], v[206:209], 0
	v_mfma_f32_16x16x32_bf16 v[76:79], v[136:139], v[206:209], 0
	v_mfma_f32_16x16x32_bf16 v[124:127], v[132:135], v[234:237], v[124:127]
	v_mfma_f32_16x16x32_bf16 v[120:123], v[140:143], v[234:237], v[120:123]
	v_mfma_f32_16x16x32_bf16 v[116:119], v[132:135], v[242:245], v[116:119]
	v_mfma_f32_16x16x32_bf16 v[108:111], v[140:143], v[242:245], v[108:111]
	v_mfma_f32_16x16x32_bf16 v[100:103], v[132:135], v[250:253], v[100:103]
	v_mfma_f32_16x16x32_bf16 v[92:95], v[140:143], v[250:253], v[92:95]
	v_mfma_f32_16x16x32_bf16 v[84:87], v[132:135], v[210:213], v[84:87]
	v_mfma_f32_16x16x32_bf16 v[76:79], v[140:143], v[210:213], v[76:79]
	v_mfma_f32_16x16x32_bf16 v[112:115], v[184:187], v[230:233], 0
	v_mfma_f32_16x16x32_bf16 v[104:107], v[222:225], v[230:233], 0
	v_mfma_f32_16x16x32_bf16 v[96:99], v[184:187], v[238:241], 0
	v_mfma_f32_16x16x32_bf16 v[88:91], v[222:225], v[238:241], 0
	v_mfma_f32_16x16x32_bf16 v[80:83], v[184:187], v[246:249], 0
	v_mfma_f32_16x16x32_bf16 v[72:75], v[222:225], v[246:249], 0
	v_mfma_f32_16x16x32_bf16 v[68:71], v[184:187], v[206:209], 0
	v_mfma_f32_16x16x32_bf16 v[64:67], v[222:225], v[206:209], 0
	v_mfma_f32_16x16x32_bf16 v[112:115], v[218:221], v[234:237], v[112:115]
	v_mfma_f32_16x16x32_bf16 v[104:107], v[226:229], v[234:237], v[104:107]
	v_mfma_f32_16x16x32_bf16 v[96:99], v[218:221], v[242:245], v[96:99]
	v_mfma_f32_16x16x32_bf16 v[88:91], v[226:229], v[242:245], v[88:91]
	v_mfma_f32_16x16x32_bf16 v[80:83], v[218:221], v[250:253], v[80:83]
	v_mfma_f32_16x16x32_bf16 v[72:75], v[226:229], v[250:253], v[72:75]
	v_mfma_f32_16x16x32_bf16 v[68:71], v[218:221], v[210:213], v[68:71]
	v_mfma_f32_16x16x32_bf16 v[64:67], v[226:229], v[210:213], v[64:67]
	s_barrier
	s_setprio 0
	v_lshl_add_u64 v[172:173], s[28:29], 0, v[146:147]
	s_mov_b32 m0, s98
	ds_read_b128 v[206:209], v214 offset:16384
	ds_read_b128 v[210:213], v214 offset:17408
	ds_read_b128 v[230:233], v214 offset:18432
	ds_read_b128 v[234:237], v214 offset:19456
	ds_read_b128 v[238:241], v214 offset:20480
	ds_read_b128 v[242:245], v214 offset:21504
	ds_read_b128 v[246:249], v214 offset:22528
	ds_read_b128 v[250:253], v214 offset:23552
	global_load_lds_dwordx4 v[172:173], off
	s_add_i32 m0, s98, 0x2000
	s_add_u32 s50, s28, 0x80000
	v_lshl_add_u64 v[176:177], s[28:29], 0, v[150:151]
	s_addc_u32 s51, s29, 0
	global_load_lds_dwordx4 v[176:177], off
	s_mov_b32 m0, s99
	v_lshl_add_u64 v[188:189], s[30:31], 0, v[148:149]
	global_load_lds_dwordx4 v146, s[50:51]
	s_add_i32 m0, s99, 0x2000
	s_nop 0
	global_load_lds_dwordx4 v150, s[50:51]
	s_mov_b32 m0, s17
	v_lshl_add_u64 v[180:181], s[30:31], 0, v[144:145]
	global_load_lds_dwordx4 v[180:181], off
	s_mov_b32 m0, s35
	s_nop 0
	global_load_lds_dwordx4 v[188:189], off
	s_waitcnt lgkmcnt(0)
	s_setprio 1
	s_barrier
; #define PG8_STAGE(bufoff, gbase, voff) do { _Pragma("unroll") for (int _i = 0; _i < 2; ++_i) \
;         __builtin_amdgcn_global_load_lds((const unsigned*)((const char*)(gbase) + (voff)[_i]), (PG8_LAS unsigned*)(lds + (bufoff) + ldsw + _i * 8192), 16, 0, 0); } while (0)
; #define PG8_LDA(dst, b, h) do { _Pragma("unroll") for (int m = 0; m < 4; ++m) _Pragma("unroll") for (int k = 0; k < 2; ++k) dst[m][k] = *(const PG8_LAS bf16x8*)(lds + PG8_SA(b, h) + aoff + m * 2048 + k * 1024); } while (0)
; #define PG8_LDB(dst, b, h) do { _Pragma("unroll") for (int n = 0; n < 2; ++n) _Pragma("unroll") for (int k = 0; k < 2; ++k) dst[n][k] = *(const PG8_LAS bf16x8*)(lds + PG8_SB(b, h) + boff + n * 2048 + k * 1024); } while (0)
; #define PG8_MMA(ai, bj, At, Bt) do { __builtin_amdgcn_s_setprio(1); _Pragma("unroll") for (int m = 0; m < 4; ++m) _Pragma("unroll") for (int n = 0; n < 2; ++n) _Pragma("unroll") for (int k = 0; k < 2; ++k) \
;         acc[ai][bj][m][n] = __builtin_amdgcn_mfma_f32_16x16x32_bf16(Bt[n][k], At[m][k], acc[ai][bj][m][n], 0, 0, 0); __builtin_amdgcn_s_setprio(0); } while (0)
; #define PG8_WAIT_V(n) asm volatile("s_waitcnt vmcnt(" #n ")" ::: "memory")
; #define PG8_WAIT_L(n) asm volatile("s_waitcnt lgkmcnt(" #n ")" ::: "memory")
; #define PG8_BAR __builtin_amdgcn_s_barrier()
; #define PG8_SCHED __builtin_amdgcn_sched_barrier(0)
; template <class Epi, class Sched, bool ALIGN_EPI = false, bool SP2 = false>
; __device__ __forceinline__ void gemm_phase(PG8_LAS unsigned char* lds, const Gemm g, const Sched& S, const Epi& E) {
;     ...
;             PG8_WAIT_V(8); PG8_WAIT_L(0); PG8_BAR; PG8_MMA(1, 0, At, B0); PG8_MMA(1, 1, At, B1); PG8_BAR; PG8_SCHED;
;             PG8_LDB(B0, 1, 0); PG8_LDB(B1, 1, 1); PG8_SCHED; PG8_LDA(At, 1, 0); PG8_STAGE(PG8_SA(0, 1), a2 + hstep, voffA);
;             PG8_WAIT_V(8); PG8_WAIT_L(0); PG8_BAR; PG8_MMA(0, 0, At, B0); PG8_MMA(0, 1, At, B1); PG8_BAR; PG8_SCHED;
	v_mfma_f32_16x16x32_bf16 v[60:63], v[128:131], v[206:209], 0
	v_mfma_f32_16x16x32_bf16 v[56:59], v[136:139], v[206:209], 0
	v_mfma_f32_16x16x32_bf16 v[52:55], v[128:131], v[230:233], 0
	v_mfma_f32_16x16x32_bf16 v[44:47], v[136:139], v[230:233], 0
	v_mfma_f32_16x16x32_bf16 v[36:39], v[128:131], v[238:241], 0
	v_mfma_f32_16x16x32_bf16 v[28:31], v[136:139], v[238:241], 0
	v_mfma_f32_16x16x32_bf16 v[20:23], v[128:131], v[246:249], 0
	v_mfma_f32_16x16x32_bf16 v[12:15], v[136:139], v[246:249], 0
	v_mfma_f32_16x16x32_bf16 v[60:63], v[132:135], v[210:213], v[60:63]
	v_mfma_f32_16x16x32_bf16 v[56:59], v[140:143], v[210:213], v[56:59]
	v_mfma_f32_16x16x32_bf16 v[52:55], v[132:135], v[234:237], v[52:55]
	v_mfma_f32_16x16x32_bf16 v[44:47], v[140:143], v[234:237], v[44:47]
	v_mfma_f32_16x16x32_bf16 v[36:39], v[132:135], v[242:245], v[36:39]
	v_mfma_f32_16x16x32_bf16 v[28:31], v[140:143], v[242:245], v[28:31]
	v_mfma_f32_16x16x32_bf16 v[20:23], v[132:135], v[250:253], v[20:23]
	v_mfma_f32_16x16x32_bf16 v[12:15], v[140:143], v[250:253], v[12:15]
	v_mfma_f32_16x16x32_bf16 v[48:51], v[184:187], v[206:209], 0
	v_mfma_f32_16x16x32_bf16 v[40:43], v[222:225], v[206:209], 0
	v_mfma_f32_16x16x32_bf16 v[32:35], v[184:187], v[230:233], 0
	v_mfma_f32_16x16x32_bf16 v[24:27], v[222:225], v[230:233], 0
	v_mfma_f32_16x16x32_bf16 v[16:19], v[184:187], v[238:241], 0
	v_mfma_f32_16x16x32_bf16 v[8:11], v[222:225], v[238:241], 0
	v_mfma_f32_16x16x32_bf16 v[4:7], v[184:187], v[246:249], 0
	v_mfma_f32_16x16x32_bf16 v[0:3], v[222:225], v[246:249], 0
	v_mfma_f32_16x16x32_bf16 v[48:51], v[218:221], v[210:213], v[48:51]
	v_mfma_f32_16x16x32_bf16 v[40:43], v[226:229], v[210:213], v[40:43]
	v_mfma_f32_16x16x32_bf16 v[32:35], v[218:221], v[234:237], v[32:35]
	v_mfma_f32_16x16x32_bf16 v[24:27], v[226:229], v[234:237], v[24:27]
	v_mfma_f32_16x16x32_bf16 v[16:19], v[218:221], v[242:245], v[16:19]
	v_mfma_f32_16x16x32_bf16 v[8:11], v[226:229], v[242:245], v[8:11]
	v_mfma_f32_16x16x32_bf16 v[4:7], v[218:221], v[250:253], v[4:7]
	v_mfma_f32_16x16x32_bf16 v[0:3], v[226:229], v[250:253], v[0:3]
	s_barrier
	s_setprio 0
	s_add_i32 s49, 0, 0x18000
	s_add_i32 s50, 0, 0x1c000
	v_add_u32_e32 v140, s49, v163
	v_add_u32_e32 v152, s50, v163
	ds_read_b128 v[128:131], v140
	ds_read_b128 v[132:135], v140 offset:1024
	ds_read_b128 v[136:139], v140 offset:2048
	ds_read_b128 v[140:143], v140 offset:3072
	ds_read_b128 v[184:187], v152
	ds_read_b128 v[206:209], v152 offset:1024
	ds_read_b128 v[210:213], v152 offset:2048
	ds_read_b128 v[218:221], v152 offset:3072
	s_add_u32 s30, s30, 0x80000
	s_addc_u32 s31, s31, 0
	s_mov_b32 m0, s37
	ds_read_b128 v[222:225], v214 offset:32768
	ds_read_b128 v[226:229], v214 offset:33792
	ds_read_b128 v[230:233], v214 offset:34816
	ds_read_b128 v[234:237], v214 offset:35840
	ds_read_b128 v[238:241], v214 offset:36864
	ds_read_b128 v[242:245], v214 offset:37888
	ds_read_b128 v[246:249], v214 offset:38912
	ds_read_b128 v[250:253], v214 offset:39936
	global_load_lds_dwordx4 v144, s[30:31]
	s_mov_b32 m0, s39
	v_lshl_add_u64 v[216:217], s[30:31], 0, v[148:149]
	global_load_lds_dwordx4 v[216:217], off
	s_waitcnt vmcnt(8) lgkmcnt(0)
	s_setprio 1
	s_barrier
	v_mfma_f32_16x16x32_bf16 v[124:127], v[128:131], v[222:225], v[124:127]
	v_mfma_f32_16x16x32_bf16 v[120:123], v[136:139], v[222:225], v[120:123]
	v_mfma_f32_16x16x32_bf16 v[116:119], v[128:131], v[230:233], v[116:119]
	v_mfma_f32_16x16x32_bf16 v[108:111], v[136:139], v[230:233], v[108:111]
	v_mfma_f32_16x16x32_bf16 v[100:103], v[128:131], v[238:241], v[100:103]
	v_mfma_f32_16x16x32_bf16 v[92:95], v[136:139], v[238:241], v[92:95]
	v_mfma_f32_16x16x32_bf16 v[84:87], v[128:131], v[246:249], v[84:87]
	v_mfma_f32_16x16x32_bf16 v[76:79], v[136:139], v[246:249], v[76:79]
	v_mfma_f32_16x16x32_bf16 v[124:127], v[132:135], v[226:229], v[124:127]
	v_mfma_f32_16x16x32_bf16 v[120:123], v[140:143], v[226:229], v[120:123]
	v_mfma_f32_16x16x32_bf16 v[116:119], v[132:135], v[234:237], v[116:119]
	v_mfma_f32_16x16x32_bf16 v[108:111], v[140:143], v[234:237], v[108:111]
	v_mfma_f32_16x16x32_bf16 v[100:103], v[132:135], v[242:245], v[100:103]
	v_mfma_f32_16x16x32_bf16 v[92:95], v[140:143], v[242:245], v[92:95]
	v_mfma_f32_16x16x32_bf16 v[84:87], v[132:135], v[250:253], v[84:87]
	v_mfma_f32_16x16x32_bf16 v[76:79], v[140:143], v[250:253], v[76:79]
	v_mfma_f32_16x16x32_bf16 v[112:115], v[184:187], v[222:225], v[112:115]
	v_mfma_f32_16x16x32_bf16 v[104:107], v[210:213], v[222:225], v[104:107]
	v_mfma_f32_16x16x32_bf16 v[96:99], v[184:187], v[230:233], v[96:99]
	v_mfma_f32_16x16x32_bf16 v[88:91], v[210:213], v[230:233], v[88:91]
	v_mfma_f32_16x16x32_bf16 v[80:83], v[184:187], v[238:241], v[80:83]
	v_mfma_f32_16x16x32_bf16 v[72:75], v[210:213], v[238:241], v[72:75]
	v_mfma_f32_16x16x32_bf16 v[68:71], v[184:187], v[246:249], v[68:71]
	v_mfma_f32_16x16x32_bf16 v[64:67], v[210:213], v[246:249], v[64:67]
	v_mfma_f32_16x16x32_bf16 v[112:115], v[206:209], v[226:229], v[112:115]
	v_mfma_f32_16x16x32_bf16 v[104:107], v[218:221], v[226:229], v[104:107]
	v_mfma_f32_16x16x32_bf16 v[96:99], v[206:209], v[234:237], v[96:99]
	v_mfma_f32_16x16x32_bf16 v[88:91], v[218:221], v[234:237], v[88:91]
	v_mfma_f32_16x16x32_bf16 v[80:83], v[206:209], v[242:245], v[80:83]
	v_mfma_f32_16x16x32_bf16 v[72:75], v[218:221], v[242:245], v[72:75]
	v_mfma_f32_16x16x32_bf16 v[68:71], v[206:209], v[250:253], v[68:71]
	v_mfma_f32_16x16x32_bf16 v[64:67], v[218:221], v[250:253], v[64:67]
	s_barrier
; #define PG8_STAGE(bufoff, gbase, voff) do { _Pragma("unroll") for (int _i = 0; _i < 2; ++_i) \
;         __builtin_amdgcn_global_load_lds((const unsigned*)((const char*)(gbase) + (voff)[_i]), (PG8_LAS unsigned*)(lds + (bufoff) + ldsw + _i * 8192), 16, 0, 0); } while (0)
; #define PG8_LDA(dst, b, h) do { _Pragma("unroll") for (int m = 0; m < 4; ++m) _Pragma("unroll") for (int k = 0; k < 2; ++k) dst[m][k] = *(const PG8_LAS bf16x8*)(lds + PG8_SA(b, h) + aoff + m * 2048 + k * 1024); } while (0)
; #define PG8_LDB(dst, b, h) do { _Pragma("unroll") for (int n = 0; n < 2; ++n) _Pragma("unroll") for (int k = 0; k < 2; ++k) dst[n][k] = *(const PG8_LAS bf16x8*)(lds + PG8_SB(b, h) + boff + n * 2048 + k * 1024); } while (0)
; #define PG8_MMA(ai, bj, At, Bt) do { __builtin_amdgcn_s_setprio(1); _Pragma("unroll") for (int m = 0; m < 4; ++m) _Pragma("unroll") for (int n = 0; n < 2; ++n) _Pragma("unroll") for (int k = 0; k < 2; ++k) \
;         acc[ai][bj][m][n] = __builtin_amdgcn_mfma_f32_16x16x32_bf16(Bt[n][k], At[m][k], acc[ai][bj][m][n], 0, 0, 0); __builtin_amdgcn_s_setprio(0); } while (0)
; #define PG8_WAIT_V(n) asm volatile("s_waitcnt vmcnt(" #n ")" ::: "memory")
; #define PG8_WAIT_L(n) asm volatile("s_waitcnt lgkmcnt(" #n ")" ::: "memory")
; #define PG8_BAR __builtin_amdgcn_s_barrier()
; #define PG8_SCHED __builtin_amdgcn_sched_barrier(0)
; template <class Epi, class Sched, bool ALIGN_EPI = false, bool SP2 = false>
; __device__ __forceinline__ void gemm_phase(PG8_LAS unsigned char* lds, const Gemm g, const Sched& S, const Epi& E) {
;     ...
;             const bool last = (t == nt - 2);
;             const char* a1 = cA + (size_t)(t + 1) * kstep;
;             const char* a2 = last ? nA : cA + (size_t)(t + 2) * kstep; const char* b2 = last ? nB : cB + (size_t)(t + 2) * kstep;
;             const char* a3 = a2 + kstep; const char* b3 = b2 + kstep;
;             if (last && has_next) S.a_ready(nxt);
;             if constexpr (SP2) {
;             PG8_LDB(B0, 0, 0); PG8_LDB(B1, 0, 1); PG8_SCHED; PG8_LDA(At, 0, 0); PG8_STAGE(PG8_SA(1, 1), a1 + hstep, voffA);
;     ...
;             PG8_LDA(At, 1, 1); PG8_STAGE(PG8_SB(1, 0), b3, voffB); PG8_STAGE(PG8_SB(1, 1), b3 + hstep, voffB); PG8_STAGE(PG8_SA(1, 0), a3, voffA);
;             PG8_WAIT_V(8); PG8_WAIT_L(0); PG8_BAR; PG8_MMA(1, 0, At, B0); PG8_MMA(1, 1, At, B1); PG8_BAR; PG8_SCHED;
	s_setprio 0
	v_lshl_add_u64 v[172:173], v[172:173], 0, s[10:11]
	s_mov_b32 m0, s100
	ds_read_b128 v[222:225], v214 offset:49152
	ds_read_b128 v[226:229], v214 offset:50176
	ds_read_b128 v[230:233], v214 offset:51200
	ds_read_b128 v[234:237], v214 offset:52224
	ds_read_b128 v[238:241], v214 offset:53248
	ds_read_b128 v[242:245], v214 offset:54272
	ds_read_b128 v[246:249], v214 offset:55296
	ds_read_b128 v[250:253], v214 offset:56320
	global_load_lds_dwordx4 v[172:173], off
	s_add_i32 m0, s100, 0x2000
	s_add_u32 s28, s28, 0x80080
	v_lshl_add_u64 v[172:173], v[176:177], 0, s[10:11]
	s_addc_u32 s29, s29, 0
	global_load_lds_dwordx4 v[172:173], off
	s_mov_b32 m0, s101
	s_nop 0
	global_load_lds_dwordx4 v146, s[28:29]
	s_add_i32 m0, s101, 0x2000
	v_lshl_add_u64 v[172:173], s[28:29], 0, v[150:151]
	global_load_lds_dwordx4 v[172:173], off
	s_mov_b32 m0, s43
	v_lshl_add_u64 v[172:173], v[180:181], 0, s[10:11]
	global_load_lds_dwordx4 v[172:173], off
	s_mov_b32 m0, s46
	v_lshl_add_u64 v[172:173], v[188:189], 0, s[10:11]
	global_load_lds_dwordx4 v[172:173], off
	s_waitcnt vmcnt(8) lgkmcnt(0)
	s_setprio 1
	s_barrier
	v_mfma_f32_16x16x32_bf16 v[60:63], v[128:131], v[222:225], v[60:63]
	v_mfma_f32_16x16x32_bf16 v[56:59], v[136:139], v[222:225], v[56:59]
	v_mfma_f32_16x16x32_bf16 v[52:55], v[128:131], v[230:233], v[52:55]
	v_mfma_f32_16x16x32_bf16 v[44:47], v[136:139], v[230:233], v[44:47]
	v_mfma_f32_16x16x32_bf16 v[36:39], v[128:131], v[238:241], v[36:39]
	v_mfma_f32_16x16x32_bf16 v[28:31], v[136:139], v[238:241], v[28:31]
	v_mfma_f32_16x16x32_bf16 v[20:23], v[128:131], v[246:249], v[20:23]
	v_mfma_f32_16x16x32_bf16 v[12:15], v[136:139], v[246:249], v[12:15]
	v_mfma_f32_16x16x32_bf16 v[60:63], v[132:135], v[226:229], v[60:63]
	v_mfma_f32_16x16x32_bf16 v[56:59], v[140:143], v[226:229], v[56:59]
	v_mfma_f32_16x16x32_bf16 v[52:55], v[132:135], v[234:237], v[52:55]
	v_mfma_f32_16x16x32_bf16 v[44:47], v[140:143], v[234:237], v[44:47]
	v_mfma_f32_16x16x32_bf16 v[36:39], v[132:135], v[242:245], v[36:39]
	v_mfma_f32_16x16x32_bf16 v[28:31], v[140:143], v[242:245], v[28:31]
	v_mfma_f32_16x16x32_bf16 v[20:23], v[132:135], v[250:253], v[20:23]
	v_mfma_f32_16x16x32_bf16 v[12:15], v[140:143], v[250:253], v[12:15]
	v_mfma_f32_16x16x32_bf16 v[48:51], v[184:187], v[222:225], v[48:51]
	v_mfma_f32_16x16x32_bf16 v[40:43], v[210:213], v[222:225], v[40:43]
	v_mfma_f32_16x16x32_bf16 v[32:35], v[184:187], v[230:233], v[32:35]
	v_mfma_f32_16x16x32_bf16 v[24:27], v[210:213], v[230:233], v[24:27]
	v_mfma_f32_16x16x32_bf16 v[16:19], v[184:187], v[238:241], v[16:19]
	v_mfma_f32_16x16x32_bf16 v[8:11], v[210:213], v[238:241], v[8:11]
	v_mfma_f32_16x16x32_bf16 v[4:7], v[184:187], v[246:249], v[4:7]
	v_mfma_f32_16x16x32_bf16 v[0:3], v[210:213], v[246:249], v[0:3]
	v_mfma_f32_16x16x32_bf16 v[48:51], v[206:209], v[226:229], v[48:51]
	v_mfma_f32_16x16x32_bf16 v[40:43], v[218:221], v[226:229], v[40:43]
	v_mfma_f32_16x16x32_bf16 v[32:35], v[206:209], v[234:237], v[32:35]
	v_mfma_f32_16x16x32_bf16 v[24:27], v[218:221], v[234:237], v[24:27]
	v_mfma_f32_16x16x32_bf16 v[16:19], v[206:209], v[242:245], v[16:19]
	v_mfma_f32_16x16x32_bf16 v[8:11], v[218:221], v[242:245], v[8:11]
	v_mfma_f32_16x16x32_bf16 v[4:7], v[206:209], v[250:253], v[4:7]
	v_mfma_f32_16x16x32_bf16 v[0:3], v[218:221], v[250:253], v[0:3]
	s_barrier
	s_setprio 0
	s_add_i32 s48, s48, 2
	s_add_u32 s0, s0, 0x100
	s_addc_u32 s1, s1, 0
	s_add_u32 s44, s44, 0x100
	s_addc_u32 s45, s45, 0
.LBB0_491:
	v_add_u32_e32 v140, s68, v163
	v_add_u32_e32 v152, s69, v163
	ds_read_b128 v[128:131], v140
	ds_read_b128 v[132:135], v140 offset:1024
	ds_read_b128 v[136:139], v140 offset:2048
	ds_read_b128 v[140:143], v140 offset:3072
	ds_read_b128 v[184:187], v152
	ds_read_b128 v[218:221], v152 offset:1024
	ds_read_b128 v[222:225], v152 offset:2048
	ds_read_b128 v[226:229], v152 offset:3072
	s_add_u32 s28, s0, 0xfff80080
	s_addc_u32 s29, s1, -1
	s_cmp_eq_u32 s48, 28
	s_cselect_b32 s31, s5, s29
	s_cselect_b32 s30, s21, s28
	s_cselect_b32 s29, s19, s45
	s_cselect_b32 s28, s33, s44
	s_add_i32 m0, s17, 0xc000
	ds_read_b128 v[230:233], v214
	ds_read_b128 v[234:237], v214 offset:1024
	ds_read_b128 v[238:241], v214 offset:2048
	ds_read_b128 v[242:245], v214 offset:3072
	ds_read_b128 v[246:249], v214 offset:4096
	ds_read_b128 v[250:253], v214 offset:5120
	ds_read_b128 v[206:209], v214 offset:6144
	ds_read_b128 v[210:213], v214 offset:7168
	global_load_lds_dwordx4 v156, s[0:1]
	s_add_i32 m0, s17, 0xe000
	s_nop 0
	global_load_lds_dwordx4 v158, s[0:1]
	s_waitcnt vmcnt(8) lgkmcnt(0)
	s_setprio 1
	s_barrier
; #define PG8_STAGE(bufoff, gbase, voff) do { _Pragma("unroll") for (int _i = 0; _i < 2; ++_i) \
;         __builtin_amdgcn_global_load_lds((const unsigned*)((const char*)(gbase) + (voff)[_i]), (PG8_LAS unsigned*)(lds + (bufoff) + ldsw + _i * 8192), 16, 0, 0); } while (0)
; #define PG8_LDA(dst, b, h) do { _Pragma("unroll") for (int m = 0; m < 4; ++m) _Pragma("unroll") for (int k = 0; k < 2; ++k) dst[m][k] = *(const PG8_LAS bf16x8*)(lds + PG8_SA(b, h) + aoff + m * 2048 + k * 1024); } while (0)
; #define PG8_LDB(dst, b, h) do { _Pragma("unroll") for (int n = 0; n < 2; ++n) _Pragma("unroll") for (int k = 0; k < 2; ++k) dst[n][k] = *(const PG8_LAS bf16x8*)(lds + PG8_SB(b, h) + boff + n * 2048 + k * 1024); } while (0)
; #define PG8_MMA(ai, bj, At, Bt) do { __builtin_amdgcn_s_setprio(1); _Pragma("unroll") for (int m = 0; m < 4; ++m) _Pragma("unroll") for (int n = 0; n < 2; ++n) _Pragma("unroll") for (int k = 0; k < 2; ++k) \
;         acc[ai][bj][m][n] = __builtin_amdgcn_mfma_f32_16x16x32_bf16(Bt[n][k], At[m][k], acc[ai][bj][m][n], 0, 0, 0); __builtin_amdgcn_s_setprio(0); } while (0)
; #define PG8_WAIT_V(n) asm volatile("s_waitcnt vmcnt(" #n ")" ::: "memory")
; #define PG8_WAIT_L(n) asm volatile("s_waitcnt lgkmcnt(" #n ")" ::: "memory")
; #define PG8_BAR __builtin_amdgcn_s_barrier()
; #define PG8_SCHED __builtin_amdgcn_sched_barrier(0)
; template <class Epi, class Sched, bool ALIGN_EPI = false, bool SP2 = false>
; __device__ __forceinline__ void gemm_phase(PG8_LAS unsigned char* lds, const Gemm g, const Sched& S, const Epi& E) {
;     ...
;             PG8_WAIT_V(8); PG8_WAIT_L(0); PG8_BAR; PG8_MMA(0, 0, At, B0); PG8_MMA(0, 1, At, B1); PG8_BAR; PG8_SCHED;
;             PG8_LDA(At, 0, 1); PG8_STAGE(PG8_SB(0, 0), b2, voffB); PG8_STAGE(PG8_SB(0, 1), b2 + hstep, voffB); PG8_STAGE(PG8_SA(0, 0), a2, voffA);
;             PG8_WAIT_V(8); PG8_WAIT_L(0); PG8_BAR; PG8_MMA(1, 0, At, B0); PG8_MMA(1, 1, At, B1); PG8_BAR; PG8_SCHED;
;             PG8_LDB(B0, 1, 0); PG8_LDB(B1, 1, 1); PG8_SCHED; PG8_LDA(At, 1, 0); PG8_STAGE(PG8_SA(0, 1), a2 + hstep, voffA);
	v_mfma_f32_16x16x32_bf16 v[124:127], v[128:131], v[230:233], v[124:127]
	v_mfma_f32_16x16x32_bf16 v[120:123], v[136:139], v[230:233], v[120:123]
	v_mfma_f32_16x16x32_bf16 v[116:119], v[128:131], v[238:241], v[116:119]
	v_mfma_f32_16x16x32_bf16 v[108:111], v[136:139], v[238:241], v[108:111]
	v_mfma_f32_16x16x32_bf16 v[100:103], v[128:131], v[246:249], v[100:103]
	v_mfma_f32_16x16x32_bf16 v[92:95], v[136:139], v[246:249], v[92:95]
	v_mfma_f32_16x16x32_bf16 v[84:87], v[128:131], v[206:209], v[84:87]
	v_mfma_f32_16x16x32_bf16 v[76:79], v[136:139], v[206:209], v[76:79]
	v_mfma_f32_16x16x32_bf16 v[124:127], v[132:135], v[234:237], v[124:127]
	v_mfma_f32_16x16x32_bf16 v[120:123], v[140:143], v[234:237], v[120:123]
	v_mfma_f32_16x16x32_bf16 v[116:119], v[132:135], v[242:245], v[116:119]
	v_mfma_f32_16x16x32_bf16 v[108:111], v[140:143], v[242:245], v[108:111]
	v_mfma_f32_16x16x32_bf16 v[100:103], v[132:135], v[250:253], v[100:103]
	v_mfma_f32_16x16x32_bf16 v[92:95], v[140:143], v[250:253], v[92:95]
	v_mfma_f32_16x16x32_bf16 v[84:87], v[132:135], v[210:213], v[84:87]
	v_mfma_f32_16x16x32_bf16 v[76:79], v[140:143], v[210:213], v[76:79]
	v_mfma_f32_16x16x32_bf16 v[112:115], v[184:187], v[230:233], v[112:115]
	v_mfma_f32_16x16x32_bf16 v[104:107], v[222:225], v[230:233], v[104:107]
	v_mfma_f32_16x16x32_bf16 v[96:99], v[184:187], v[238:241], v[96:99]
	v_mfma_f32_16x16x32_bf16 v[88:91], v[222:225], v[238:241], v[88:91]
	v_mfma_f32_16x16x32_bf16 v[80:83], v[184:187], v[246:249], v[80:83]
	v_mfma_f32_16x16x32_bf16 v[72:75], v[222:225], v[246:249], v[72:75]
	v_mfma_f32_16x16x32_bf16 v[68:71], v[184:187], v[206:209], v[68:71]
	v_mfma_f32_16x16x32_bf16 v[64:67], v[222:225], v[206:209], v[64:67]
	v_mfma_f32_16x16x32_bf16 v[112:115], v[218:221], v[234:237], v[112:115]
	v_mfma_f32_16x16x32_bf16 v[104:107], v[226:229], v[234:237], v[104:107]
	v_mfma_f32_16x16x32_bf16 v[96:99], v[218:221], v[242:245], v[96:99]
	v_mfma_f32_16x16x32_bf16 v[88:91], v[226:229], v[242:245], v[88:91]
	v_mfma_f32_16x16x32_bf16 v[80:83], v[218:221], v[250:253], v[80:83]
	v_mfma_f32_16x16x32_bf16 v[72:75], v[226:229], v[250:253], v[72:75]
	v_mfma_f32_16x16x32_bf16 v[68:71], v[218:221], v[210:213], v[68:71]
	v_mfma_f32_16x16x32_bf16 v[64:67], v[226:229], v[210:213], v[64:67]
	s_barrier
	s_setprio 0
	v_lshl_add_u64 v[172:173], s[28:29], 0, v[146:147]
	s_mov_b32 m0, s98
	ds_read_b128 v[206:209], v214 offset:16384
	ds_read_b128 v[210:213], v214 offset:17408
	ds_read_b128 v[230:233], v214 offset:18432
	ds_read_b128 v[234:237], v214 offset:19456
	ds_read_b128 v[238:241], v214 offset:20480
	ds_read_b128 v[242:245], v214 offset:21504
	ds_read_b128 v[246:249], v214 offset:22528
	ds_read_b128 v[250:253], v214 offset:23552
	global_load_lds_dwordx4 v[172:173], off
	s_add_i32 m0, s98, 0x2000
	s_add_u32 s50, s28, 0x80000
	v_lshl_add_u64 v[176:177], s[28:29], 0, v[150:151]
	s_addc_u32 s51, s29, 0
	global_load_lds_dwordx4 v[176:177], off
	s_mov_b32 m0, s99
	v_lshl_add_u64 v[188:189], s[30:31], 0, v[148:149]
	global_load_lds_dwordx4 v146, s[50:51]
	s_add_i32 m0, s99, 0x2000
	s_nop 0
	global_load_lds_dwordx4 v150, s[50:51]
	s_mov_b32 m0, s17
	v_lshl_add_u64 v[180:181], s[30:31], 0, v[144:145]
	global_load_lds_dwordx4 v[180:181], off
	s_mov_b32 m0, s35
	s_nop 0
	global_load_lds_dwordx4 v[188:189], off
	s_waitcnt vmcnt(8) lgkmcnt(0)
	s_setprio 1
	s_barrier
	v_mfma_f32_16x16x32_bf16 v[60:63], v[128:131], v[206:209], v[60:63]
	v_mfma_f32_16x16x32_bf16 v[56:59], v[136:139], v[206:209], v[56:59]
	v_mfma_f32_16x16x32_bf16 v[52:55], v[128:131], v[230:233], v[52:55]
	v_mfma_f32_16x16x32_bf16 v[44:47], v[136:139], v[230:233], v[44:47]
	v_mfma_f32_16x16x32_bf16 v[36:39], v[128:131], v[238:241], v[36:39]
	v_mfma_f32_16x16x32_bf16 v[28:31], v[136:139], v[238:241], v[28:31]
	v_mfma_f32_16x16x32_bf16 v[20:23], v[128:131], v[246:249], v[20:23]
	v_mfma_f32_16x16x32_bf16 v[12:15], v[136:139], v[246:249], v[12:15]
	v_mfma_f32_16x16x32_bf16 v[60:63], v[132:135], v[210:213], v[60:63]
	v_mfma_f32_16x16x32_bf16 v[56:59], v[140:143], v[210:213], v[56:59]
	v_mfma_f32_16x16x32_bf16 v[52:55], v[132:135], v[234:237], v[52:55]
	v_mfma_f32_16x16x32_bf16 v[44:47], v[140:143], v[234:237], v[44:47]
	v_mfma_f32_16x16x32_bf16 v[36:39], v[132:135], v[242:245], v[36:39]
	v_mfma_f32_16x16x32_bf16 v[28:31], v[140:143], v[242:245], v[28:31]
	v_mfma_f32_16x16x32_bf16 v[20:23], v[132:135], v[250:253], v[20:23]
	v_mfma_f32_16x16x32_bf16 v[12:15], v[140:143], v[250:253], v[12:15]
	v_mfma_f32_16x16x32_bf16 v[48:51], v[184:187], v[206:209], v[48:51]
	v_mfma_f32_16x16x32_bf16 v[40:43], v[222:225], v[206:209], v[40:43]
	v_mfma_f32_16x16x32_bf16 v[32:35], v[184:187], v[230:233], v[32:35]
	v_mfma_f32_16x16x32_bf16 v[24:27], v[222:225], v[230:233], v[24:27]
	v_mfma_f32_16x16x32_bf16 v[16:19], v[184:187], v[238:241], v[16:19]
	v_mfma_f32_16x16x32_bf16 v[8:11], v[222:225], v[238:241], v[8:11]
	v_mfma_f32_16x16x32_bf16 v[4:7], v[184:187], v[246:249], v[4:7]
	v_mfma_f32_16x16x32_bf16 v[0:3], v[222:225], v[246:249], v[0:3]
	v_mfma_f32_16x16x32_bf16 v[48:51], v[218:221], v[210:213], v[48:51]
	v_mfma_f32_16x16x32_bf16 v[40:43], v[226:229], v[210:213], v[40:43]
	v_mfma_f32_16x16x32_bf16 v[32:35], v[218:221], v[234:237], v[32:35]
	v_mfma_f32_16x16x32_bf16 v[24:27], v[226:229], v[234:237], v[24:27]
	v_mfma_f32_16x16x32_bf16 v[16:19], v[218:221], v[242:245], v[16:19]
	v_mfma_f32_16x16x32_bf16 v[8:11], v[226:229], v[242:245], v[8:11]
	v_mfma_f32_16x16x32_bf16 v[4:7], v[218:221], v[250:253], v[4:7]
	v_mfma_f32_16x16x32_bf16 v[0:3], v[226:229], v[250:253], v[0:3]
	s_barrier
; #define PG8_STAGE(bufoff, gbase, voff) do { _Pragma("unroll") for (int _i = 0; _i < 2; ++_i) \
;         __builtin_amdgcn_global_load_lds((const unsigned*)((const char*)(gbase) + (voff)[_i]), (PG8_LAS unsigned*)(lds + (bufoff) + ldsw + _i * 8192), 16, 0, 0); } while (0)
; #define PG8_LDA(dst, b, h) do { _Pragma("unroll") for (int m = 0; m < 4; ++m) _Pragma("unroll") for (int k = 0; k < 2; ++k) dst[m][k] = *(const PG8_LAS bf16x8*)(lds + PG8_SA(b, h) + aoff + m * 2048 + k * 1024); } while (0)
; #define PG8_LDB(dst, b, h) do { _Pragma("unroll") for (int n = 0; n < 2; ++n) _Pragma("unroll") for (int k = 0; k < 2; ++k) dst[n][k] = *(const PG8_LAS bf16x8*)(lds + PG8_SB(b, h) + boff + n * 2048 + k * 1024); } while (0)
; #define PG8_MMA(ai, bj, At, Bt) do { __builtin_amdgcn_s_setprio(1); _Pragma("unroll") for (int m = 0; m < 4; ++m) _Pragma("unroll") for (int n = 0; n < 2; ++n) _Pragma("unroll") for (int k = 0; k < 2; ++k) \
;         acc[ai][bj][m][n] = __builtin_amdgcn_mfma_f32_16x16x32_bf16(Bt[n][k], At[m][k], acc[ai][bj][m][n], 0, 0, 0); __builtin_amdgcn_s_setprio(0); } while (0)
; #define PG8_WAIT_V(n) asm volatile("s_waitcnt vmcnt(" #n ")" ::: "memory")
; #define PG8_WAIT_L(n) asm volatile("s_waitcnt lgkmcnt(" #n ")" ::: "memory")
; #define PG8_BAR __builtin_amdgcn_s_barrier()
; #define PG8_SCHED __builtin_amdgcn_sched_barrier(0)
; template <class Epi, class Sched, bool ALIGN_EPI = false, bool SP2 = false>
; __device__ __forceinline__ void gemm_phase(PG8_LAS unsigned char* lds, const Gemm g, const Sched& S, const Epi& E) {
;     ...
;             PG8_LDB(B0, 1, 0); PG8_LDB(B1, 1, 1); PG8_SCHED; PG8_LDA(At, 1, 0); PG8_STAGE(PG8_SA(0, 1), a2 + hstep, voffA);
;             PG8_WAIT_V(8); PG8_WAIT_L(0); PG8_BAR; PG8_MMA(0, 0, At, B0); PG8_MMA(0, 1, At, B1); PG8_BAR; PG8_SCHED;
;             PG8_LDA(At, 1, 1); PG8_STAGE(PG8_SB(1, 0), b3, voffB); PG8_STAGE(PG8_SB(1, 1), b3 + hstep, voffB); PG8_STAGE(PG8_SA(1, 0), a3, voffA);
;             PG8_WAIT_V(8); PG8_WAIT_L(0); PG8_BAR; PG8_MMA(1, 0, At, B0); PG8_MMA(1, 1, At, B1); PG8_BAR; PG8_SCHED;
;     ...
;         if constexpr (ALIGN_EPI) { if (wr == 0) PG8_BAR; }
	s_setprio 0
	s_add_i32 s49, 0, 0x18000
	s_add_i32 s50, 0, 0x1c000
	v_add_u32_e32 v140, s49, v163
	v_add_u32_e32 v152, s50, v163
	ds_read_b128 v[128:131], v140
	ds_read_b128 v[132:135], v140 offset:1024
	ds_read_b128 v[136:139], v140 offset:2048
	ds_read_b128 v[140:143], v140 offset:3072
	ds_read_b128 v[184:187], v152
	ds_read_b128 v[206:209], v152 offset:1024
	ds_read_b128 v[210:213], v152 offset:2048
	ds_read_b128 v[218:221], v152 offset:3072
	s_add_u32 s30, s30, 0x80000
	s_addc_u32 s31, s31, 0
	s_mov_b32 m0, s37
	ds_read_b128 v[222:225], v214 offset:32768
	ds_read_b128 v[226:229], v214 offset:33792
	ds_read_b128 v[230:233], v214 offset:34816
	ds_read_b128 v[234:237], v214 offset:35840
	ds_read_b128 v[238:241], v214 offset:36864
	ds_read_b128 v[242:245], v214 offset:37888
	ds_read_b128 v[246:249], v214 offset:38912
	ds_read_b128 v[250:253], v214 offset:39936
	global_load_lds_dwordx4 v144, s[30:31]
	s_mov_b32 m0, s39
	s_nop 0
	global_load_lds_dwordx4 v148, s[30:31]
	s_waitcnt vmcnt(8) lgkmcnt(0)
	s_setprio 1
	s_barrier
	v_mfma_f32_16x16x32_bf16 v[124:127], v[128:131], v[222:225], v[124:127]
	v_mfma_f32_16x16x32_bf16 v[120:123], v[136:139], v[222:225], v[120:123]
	v_mfma_f32_16x16x32_bf16 v[116:119], v[128:131], v[230:233], v[116:119]
	v_mfma_f32_16x16x32_bf16 v[108:111], v[136:139], v[230:233], v[108:111]
	v_mfma_f32_16x16x32_bf16 v[100:103], v[128:131], v[238:241], v[100:103]
	v_mfma_f32_16x16x32_bf16 v[92:95], v[136:139], v[238:241], v[92:95]
	v_mfma_f32_16x16x32_bf16 v[84:87], v[128:131], v[246:249], v[84:87]
	v_mfma_f32_16x16x32_bf16 v[76:79], v[136:139], v[246:249], v[76:79]
	v_mfma_f32_16x16x32_bf16 v[124:127], v[132:135], v[226:229], v[124:127]
	v_mfma_f32_16x16x32_bf16 v[120:123], v[140:143], v[226:229], v[120:123]
	v_mfma_f32_16x16x32_bf16 v[116:119], v[132:135], v[234:237], v[116:119]
	v_mfma_f32_16x16x32_bf16 v[108:111], v[140:143], v[234:237], v[108:111]
	v_mfma_f32_16x16x32_bf16 v[100:103], v[132:135], v[242:245], v[100:103]
	v_mfma_f32_16x16x32_bf16 v[92:95], v[140:143], v[242:245], v[92:95]
	v_mfma_f32_16x16x32_bf16 v[84:87], v[132:135], v[250:253], v[84:87]
	v_mfma_f32_16x16x32_bf16 v[76:79], v[140:143], v[250:253], v[76:79]
	v_mfma_f32_16x16x32_bf16 v[112:115], v[184:187], v[222:225], v[112:115]
	v_mfma_f32_16x16x32_bf16 v[104:107], v[210:213], v[222:225], v[104:107]
	v_mfma_f32_16x16x32_bf16 v[96:99], v[184:187], v[230:233], v[96:99]
	v_mfma_f32_16x16x32_bf16 v[88:91], v[210:213], v[230:233], v[88:91]
	v_mfma_f32_16x16x32_bf16 v[80:83], v[184:187], v[238:241], v[80:83]
	v_mfma_f32_16x16x32_bf16 v[72:75], v[210:213], v[238:241], v[72:75]
	v_mfma_f32_16x16x32_bf16 v[68:71], v[184:187], v[246:249], v[68:71]
	v_mfma_f32_16x16x32_bf16 v[64:67], v[210:213], v[246:249], v[64:67]
	v_mfma_f32_16x16x32_bf16 v[112:115], v[206:209], v[226:229], v[112:115]
	v_mfma_f32_16x16x32_bf16 v[104:107], v[218:221], v[226:229], v[104:107]
	v_mfma_f32_16x16x32_bf16 v[96:99], v[206:209], v[234:237], v[96:99]
	v_mfma_f32_16x16x32_bf16 v[88:91], v[218:221], v[234:237], v[88:91]
	v_mfma_f32_16x16x32_bf16 v[80:83], v[206:209], v[242:245], v[80:83]
	v_mfma_f32_16x16x32_bf16 v[72:75], v[218:221], v[242:245], v[72:75]
	v_mfma_f32_16x16x32_bf16 v[68:71], v[206:209], v[250:253], v[68:71]
	v_mfma_f32_16x16x32_bf16 v[64:67], v[218:221], v[250:253], v[64:67]
	s_barrier
	s_setprio 0
	v_lshl_add_u64 v[172:173], v[172:173], 0, s[10:11]
	s_mov_b32 m0, s100
	ds_read_b128 v[222:225], v214 offset:49152
	ds_read_b128 v[226:229], v214 offset:50176
	ds_read_b128 v[230:233], v214 offset:51200
	ds_read_b128 v[234:237], v214 offset:52224
	ds_read_b128 v[238:241], v214 offset:53248
	ds_read_b128 v[242:245], v214 offset:54272
	ds_read_b128 v[246:249], v214 offset:55296
	ds_read_b128 v[250:253], v214 offset:56320
	global_load_lds_dwordx4 v[172:173], off
	s_add_i32 m0, s100, 0x2000
	s_add_u32 s28, s28, 0x80080
	v_lshl_add_u64 v[172:173], v[176:177], 0, s[10:11]
	s_addc_u32 s29, s29, 0
	global_load_lds_dwordx4 v[172:173], off
	s_mov_b32 m0, s101
	s_nop 0
	global_load_lds_dwordx4 v146, s[28:29]
	s_add_i32 m0, s101, 0x2000
	v_lshl_add_u64 v[172:173], s[28:29], 0, v[150:151]
	global_load_lds_dwordx4 v[172:173], off
	s_mov_b32 m0, s43
	v_lshl_add_u64 v[172:173], v[180:181], 0, s[10:11]
	global_load_lds_dwordx4 v[172:173], off
	s_mov_b32 m0, s46
	v_lshl_add_u64 v[172:173], v[188:189], 0, s[10:11]
	global_load_lds_dwordx4 v[172:173], off
	s_waitcnt vmcnt(8) lgkmcnt(0)
	s_setprio 1
	s_barrier
	v_mfma_f32_16x16x32_bf16 v[60:63], v[128:131], v[222:225], v[60:63]
	v_mfma_f32_16x16x32_bf16 v[56:59], v[136:139], v[222:225], v[56:59]
	v_mfma_f32_16x16x32_bf16 v[52:55], v[128:131], v[230:233], v[52:55]
	v_mfma_f32_16x16x32_bf16 v[44:47], v[136:139], v[230:233], v[44:47]
	v_mfma_f32_16x16x32_bf16 v[36:39], v[128:131], v[238:241], v[36:39]
	v_mfma_f32_16x16x32_bf16 v[28:31], v[136:139], v[238:241], v[28:31]
	v_mfma_f32_16x16x32_bf16 v[20:23], v[128:131], v[246:249], v[20:23]
	v_mfma_f32_16x16x32_bf16 v[12:15], v[136:139], v[246:249], v[12:15]
	v_mfma_f32_16x16x32_bf16 v[60:63], v[132:135], v[226:229], v[60:63]
	v_mfma_f32_16x16x32_bf16 v[56:59], v[140:143], v[226:229], v[56:59]
	v_mfma_f32_16x16x32_bf16 v[52:55], v[132:135], v[234:237], v[52:55]
	v_mfma_f32_16x16x32_bf16 v[44:47], v[140:143], v[234:237], v[44:47]
	v_mfma_f32_16x16x32_bf16 v[36:39], v[132:135], v[242:245], v[36:39]
	v_mfma_f32_16x16x32_bf16 v[28:31], v[140:143], v[242:245], v[28:31]
	v_mfma_f32_16x16x32_bf16 v[20:23], v[132:135], v[250:253], v[20:23]
	v_mfma_f32_16x16x32_bf16 v[12:15], v[140:143], v[250:253], v[12:15]
	v_mfma_f32_16x16x32_bf16 v[48:51], v[184:187], v[222:225], v[48:51]
	v_mfma_f32_16x16x32_bf16 v[40:43], v[210:213], v[222:225], v[40:43]
	v_mfma_f32_16x16x32_bf16 v[32:35], v[184:187], v[230:233], v[32:35]
	v_mfma_f32_16x16x32_bf16 v[24:27], v[210:213], v[230:233], v[24:27]
	v_mfma_f32_16x16x32_bf16 v[16:19], v[184:187], v[238:241], v[16:19]
	v_mfma_f32_16x16x32_bf16 v[8:11], v[210:213], v[238:241], v[8:11]
	v_mfma_f32_16x16x32_bf16 v[4:7], v[184:187], v[246:249], v[4:7]
	v_mfma_f32_16x16x32_bf16 v[0:3], v[210:213], v[246:249], v[0:3]
	v_mfma_f32_16x16x32_bf16 v[48:51], v[206:209], v[226:229], v[48:51]
	v_mfma_f32_16x16x32_bf16 v[40:43], v[218:221], v[226:229], v[40:43]
	v_mfma_f32_16x16x32_bf16 v[32:35], v[206:209], v[234:237], v[32:35]
	v_mfma_f32_16x16x32_bf16 v[24:27], v[218:221], v[234:237], v[24:27]
	v_mfma_f32_16x16x32_bf16 v[16:19], v[206:209], v[242:245], v[16:19]
	v_mfma_f32_16x16x32_bf16 v[8:11], v[218:221], v[242:245], v[8:11]
	v_mfma_f32_16x16x32_bf16 v[4:7], v[206:209], v[250:253], v[4:7]
	v_mfma_f32_16x16x32_bf16 v[0:3], v[218:221], v[250:253], v[0:3]
	s_barrier
	s_setprio 0
	s_add_i32 s48, s48, 2
	s_add_u32 s0, s0, 0x100
	s_addc_u32 s1, s1, 0
	s_add_u32 s44, s44, 0x100
	s_addc_u32 s45, s45, 0
	s_cmp_gt_u32 s48, 29
	s_cbranch_scc0 .LBB0_491
	s_and_b64 vcc, exec, s[12:13]
	s_cbranch_vccz .LBB0_494
	s_barrier

; #define PG8_STAGE(bufoff, gbase, voff) do { _Pragma("unroll") for (int _i = 0; _i < 2; ++_i) \
;         __builtin_amdgcn_global_load_lds((const unsigned*)((const char*)(gbase) + (voff)[_i]), (PG8_LAS unsigned*)(lds + (bufoff) + ldsw + _i * 8192), 16, 0, 0); } while (0)
; #define PG8_LDA(dst, b, h) do { _Pragma("unroll") for (int m = 0; m < 4; ++m) _Pragma("unroll") for (int k = 0; k < 2; ++k) dst[m][k] = *(const PG8_LAS bf16x8*)(lds + PG8_SA(b, h) + aoff + m * 2048 + k * 1024); } while (0)
; #define PG8_LDB(dst, b, h) do { _Pragma("unroll") for (int n = 0; n < 2; ++n) _Pragma("unroll") for (int k = 0; k < 2; ++k) dst[n][k] = *(const PG8_LAS bf16x8*)(lds + PG8_SB(b, h) + boff + n * 2048 + k * 1024); } while (0)
; #define PG8_MMA(ai, bj, At, Bt) do { __builtin_amdgcn_s_setprio(1); _Pragma("unroll") for (int m = 0; m < 4; ++m) _Pragma("unroll") for (int n = 0; n < 2; ++n) _Pragma("unroll") for (int k = 0; k < 2; ++k) \
;         acc[ai][bj][m][n] = __builtin_amdgcn_mfma_f32_16x16x32_bf16(Bt[n][k], At[m][k], acc[ai][bj][m][n], 0, 0, 0); __builtin_amdgcn_s_setprio(0); } while (0)
; #define PG8_WAIT_V(n) asm volatile("s_waitcnt vmcnt(" #n ")" ::: "memory")
; template <class Epi, class Sched, bool ALIGN_EPI = false, bool SP2 = false>
; __device__ __forceinline__ void gemm_phase(PG8_LAS unsigned char* lds, const Gemm g, const Sched& S, const Epi& E) {
;     ...
;         const char* nA = has_next ? (const char*)g.A + (size_t)nxt.pm * tstep : cA; const char* nB = has_next ? (const char*)g.Bt + (size_t)nxt.pn * tstep : cB;
;         for (int t = 0; t < nt; t += 2) {
;             const bool last = (t == nt - 2);
;             const char* a1 = cA + (size_t)(t + 1) * kstep;
;             const char* a2 = last ? nA : cA + (size_t)(t + 2) * kstep; const char* b2 = last ? nB : cB + (size_t)(t + 2) * kstep;
;             const char* a3 = a2 + kstep; const char* b3 = b2 + kstep;
;             if (last && has_next) S.a_ready(nxt);
;             if constexpr (SP2) {
;             PG8_LDB(B0, 0, 0); PG8_LDB(B1, 0, 1); PG8_SCHED; PG8_LDA(At, 0, 0); PG8_STAGE(PG8_SA(1, 1), a1 + hstep, voffA);
;             PG8_WAIT_V(8); PG8_WAIT_L(0); PG8_BAR; PG8_MMA(0, 0, At, B0); PG8_MMA(0, 1, At, B1); PG8_BAR; PG8_SCHED;
;             PG8_LDA(At, 0, 1); PG8_STAGE(PG8_SB(0, 0), b2, voffB); PG8_STAGE(PG8_SB(0, 1), b2 + hstep, voffB); PG8_STAGE(PG8_SA(0, 0), a2, voffA);
.LBB0_762:
	s_ashr_i32 s21, s20, 31
	s_lshl_b64 s[22:23], s[20:21], 21
	s_add_u32 s22, s60, s22
	s_addc_u32 s23, s61, s23
	s_and_b64 s[24:25], s[4:5], exec
	s_cselect_b32 s7, s23, s27
	s_cselect_b32 s21, s22, s26
	s_ashr_i32 s19, s18, 31
	s_lshl_b64 s[24:25], s[18:19], 21
	v_readlane_b32 s30, v254, 32
	v_readlane_b32 s31, v254, 33
	s_add_u32 s24, s30, s24
	s_addc_u32 s25, s31, s25
	s_and_b64 s[30:31], s[4:5], exec
	s_cselect_b32 s19, s25, s29
	s_cselect_b32 s48, s24, s28
	s_add_u32 s26, s26, 0x100080
	s_addc_u32 s27, s27, 0
	s_add_u32 s49, s28, 0x100
	s_addc_u32 s52, s29, 0
	s_mov_b32 s53, -2
	s_waitcnt lgkmcnt(0)
	s_add_i32 s98, s34, 0x10000
	s_add_i32 s99, s34, 0x14000
	s_add_i32 s100, s34, 0x18000
	s_add_i32 s101, s34, 0x1c000
	ds_read_b128 v[128:131], v181
	ds_read_b128 v[132:135], v181 offset:1024
	ds_read_b128 v[136:139], v181 offset:2048
	ds_read_b128 v[140:143], v181 offset:3072
	ds_read_b128 v[144:147], v182
	ds_read_b128 v[148:151], v182 offset:1024
	ds_read_b128 v[168:171], v182 offset:2048
	ds_read_b128 v[172:175], v182 offset:3072
	s_add_u32 s28, s26, 0xfff00080
	s_addc_u32 s29, s27, -1
	s_cmp_eq_u32 s53, 60
	s_cselect_b32 s31, s7, s29
	s_cselect_b32 s30, s21, s28
	s_cselect_b32 s29, s19, s52
	s_cselect_b32 s28, s48, s49
	s_add_i32 m0, s35, 0xc000
	ds_read_b128 v[186:189], v183
	ds_read_b128 v[190:193], v183 offset:1024
	ds_read_b128 v[198:201], v183 offset:2048
	ds_read_b128 v[202:205], v183 offset:3072
	ds_read_b128 v[206:209], v183 offset:4096
	ds_read_b128 v[210:213], v183 offset:5120
	ds_read_b128 v[214:217], v183 offset:6144
	ds_read_b128 v[218:221], v183 offset:7168
	global_load_lds_dwordx4 v160, s[26:27]
	s_add_i32 m0, s35, 0xe000
	s_nop 0
	global_load_lds_dwordx4 v162, s[26:27]
	s_waitcnt lgkmcnt(0)
	s_setprio 1
	s_barrier
	v_mfma_f32_16x16x32_bf16 v[124:127], v[128:131], v[186:189], 0
	v_mfma_f32_16x16x32_bf16 v[120:123], v[136:139], v[186:189], 0
	v_mfma_f32_16x16x32_bf16 v[104:107], v[128:131], v[198:201], 0
	v_mfma_f32_16x16x32_bf16 v[108:111], v[136:139], v[198:201], 0
	v_mfma_f32_16x16x32_bf16 v[88:91], v[128:131], v[206:209], 0
	v_mfma_f32_16x16x32_bf16 v[92:95], v[136:139], v[206:209], 0
	v_mfma_f32_16x16x32_bf16 v[72:75], v[128:131], v[214:217], 0
	v_mfma_f32_16x16x32_bf16 v[76:79], v[136:139], v[214:217], 0
	v_mfma_f32_16x16x32_bf16 v[124:127], v[132:135], v[190:193], v[124:127]
	v_mfma_f32_16x16x32_bf16 v[120:123], v[140:143], v[190:193], v[120:123]
	v_mfma_f32_16x16x32_bf16 v[104:107], v[132:135], v[202:205], v[104:107]
	v_mfma_f32_16x16x32_bf16 v[108:111], v[140:143], v[202:205], v[108:111]
	v_mfma_f32_16x16x32_bf16 v[88:91], v[132:135], v[210:213], v[88:91]
	v_mfma_f32_16x16x32_bf16 v[92:95], v[140:143], v[210:213], v[92:95]
	v_mfma_f32_16x16x32_bf16 v[72:75], v[132:135], v[218:221], v[72:75]
	v_mfma_f32_16x16x32_bf16 v[76:79], v[140:143], v[218:221], v[76:79]
	v_mfma_f32_16x16x32_bf16 v[116:119], v[144:147], v[186:189], 0
	v_mfma_f32_16x16x32_bf16 v[112:115], v[168:171], v[186:189], 0
	v_mfma_f32_16x16x32_bf16 v[100:103], v[144:147], v[198:201], 0
	v_mfma_f32_16x16x32_bf16 v[96:99], v[168:171], v[198:201], 0
	v_mfma_f32_16x16x32_bf16 v[84:87], v[144:147], v[206:209], 0
	v_mfma_f32_16x16x32_bf16 v[80:83], v[168:171], v[206:209], 0
	v_mfma_f32_16x16x32_bf16 v[68:71], v[144:147], v[214:217], 0
	v_mfma_f32_16x16x32_bf16 v[64:67], v[168:171], v[214:217], 0
	v_mfma_f32_16x16x32_bf16 v[116:119], v[148:151], v[190:193], v[116:119]
	v_mfma_f32_16x16x32_bf16 v[112:115], v[172:175], v[190:193], v[112:115]
	v_mfma_f32_16x16x32_bf16 v[100:103], v[148:151], v[202:205], v[100:103]
	v_mfma_f32_16x16x32_bf16 v[96:99], v[172:175], v[202:205], v[96:99]
	v_mfma_f32_16x16x32_bf16 v[84:87], v[148:151], v[210:213], v[84:87]
	v_mfma_f32_16x16x32_bf16 v[80:83], v[172:175], v[210:213], v[80:83]
	v_mfma_f32_16x16x32_bf16 v[68:71], v[148:151], v[218:221], v[68:71]
	v_mfma_f32_16x16x32_bf16 v[64:67], v[172:175], v[218:221], v[64:67]
	s_barrier
	s_setprio 0
	v_lshl_add_u64 v[176:177], s[28:29], 0, v[154:155]
	s_mov_b32 m0, s98
	ds_read_b128 v[186:189], v183 offset:16384
	ds_read_b128 v[190:193], v183 offset:17408
	ds_read_b128 v[198:201], v183 offset:18432
	ds_read_b128 v[202:205], v183 offset:19456
	ds_read_b128 v[206:209], v183 offset:20480
	ds_read_b128 v[210:213], v183 offset:21504
	ds_read_b128 v[214:217], v183 offset:22528
	ds_read_b128 v[218:221], v183 offset:23552
	global_load_lds_dwordx4 v[176:177], off
	s_add_i32 m0, s98, 0x2000
	s_add_u32 s54, s28, 0x100000
	v_lshl_add_u64 v[194:195], s[28:29], 0, v[158:159]
	s_addc_u32 s55, s29, 0
	global_load_lds_dwordx4 v[194:195], off
	s_mov_b32 m0, s99
	v_lshl_add_u64 v[224:225], s[30:31], 0, v[156:157]
	global_load_lds_dwordx4 v154, s[54:55]
	s_add_i32 m0, s99, 0x2000
	s_nop 0
	global_load_lds_dwordx4 v158, s[54:55]
	s_mov_b32 m0, s35
	v_lshl_add_u64 v[222:223], s[30:31], 0, v[152:153]
	global_load_lds_dwordx4 v[222:223], off
	s_mov_b32 m0, s33
	s_nop 0
	global_load_lds_dwordx4 v[224:225], off
	s_waitcnt lgkmcnt(0)
	s_setprio 1
	s_barrier
; #define PG8_STAGE(bufoff, gbase, voff) do { _Pragma("unroll") for (int _i = 0; _i < 2; ++_i) \
;         __builtin_amdgcn_global_load_lds((const unsigned*)((const char*)(gbase) + (voff)[_i]), (PG8_LAS unsigned*)(lds + (bufoff) + ldsw + _i * 8192), 16, 0, 0); } while (0)
; #define PG8_LDA(dst, b, h) do { _Pragma("unroll") for (int m = 0; m < 4; ++m) _Pragma("unroll") for (int k = 0; k < 2; ++k) dst[m][k] = *(const PG8_LAS bf16x8*)(lds + PG8_SA(b, h) + aoff + m * 2048 + k * 1024); } while (0)
; #define PG8_LDB(dst, b, h) do { _Pragma("unroll") for (int n = 0; n < 2; ++n) _Pragma("unroll") for (int k = 0; k < 2; ++k) dst[n][k] = *(const PG8_LAS bf16x8*)(lds + PG8_SB(b, h) + boff + n * 2048 + k * 1024); } while (0)
; #define PG8_MMA(ai, bj, At, Bt) do { __builtin_amdgcn_s_setprio(1); _Pragma("unroll") for (int m = 0; m < 4; ++m) _Pragma("unroll") for (int n = 0; n < 2; ++n) _Pragma("unroll") for (int k = 0; k < 2; ++k) \
;         acc[ai][bj][m][n] = __builtin_amdgcn_mfma_f32_16x16x32_bf16(Bt[n][k], At[m][k], acc[ai][bj][m][n], 0, 0, 0); __builtin_amdgcn_s_setprio(0); } while (0)
; #define PG8_WAIT_V(n) asm volatile("s_waitcnt vmcnt(" #n ")" ::: "memory")
; #define PG8_WAIT_L(n) asm volatile("s_waitcnt lgkmcnt(" #n ")" ::: "memory")
; #define PG8_BAR __builtin_amdgcn_s_barrier()
; #define PG8_SCHED __builtin_amdgcn_sched_barrier(0)
; template <class Epi, class Sched, bool ALIGN_EPI = false, bool SP2 = false>
; __device__ __forceinline__ void gemm_phase(PG8_LAS unsigned char* lds, const Gemm g, const Sched& S, const Epi& E) {
;     ...
;             PG8_WAIT_V(8); PG8_WAIT_L(0); PG8_BAR; PG8_MMA(1, 0, At, B0); PG8_MMA(1, 1, At, B1); PG8_BAR; PG8_SCHED;
;             PG8_LDB(B0, 1, 0); PG8_LDB(B1, 1, 1); PG8_SCHED; PG8_LDA(At, 1, 0); PG8_STAGE(PG8_SA(0, 1), a2 + hstep, voffA);
;             PG8_WAIT_V(8); PG8_WAIT_L(0); PG8_BAR; PG8_MMA(0, 0, At, B0); PG8_MMA(0, 1, At, B1); PG8_BAR; PG8_SCHED;
	v_mfma_f32_16x16x32_bf16 v[56:59], v[128:131], v[186:189], 0
	v_mfma_f32_16x16x32_bf16 v[60:63], v[136:139], v[186:189], 0
	v_mfma_f32_16x16x32_bf16 v[40:43], v[128:131], v[198:201], 0
	v_mfma_f32_16x16x32_bf16 v[44:47], v[136:139], v[198:201], 0
	v_mfma_f32_16x16x32_bf16 v[24:27], v[128:131], v[206:209], 0
	v_mfma_f32_16x16x32_bf16 v[28:31], v[136:139], v[206:209], 0
	v_mfma_f32_16x16x32_bf16 v[8:11], v[128:131], v[214:217], 0
	v_mfma_f32_16x16x32_bf16 v[12:15], v[136:139], v[214:217], 0
	v_mfma_f32_16x16x32_bf16 v[56:59], v[132:135], v[190:193], v[56:59]
	v_mfma_f32_16x16x32_bf16 v[60:63], v[140:143], v[190:193], v[60:63]
	v_mfma_f32_16x16x32_bf16 v[40:43], v[132:135], v[202:205], v[40:43]
	v_mfma_f32_16x16x32_bf16 v[44:47], v[140:143], v[202:205], v[44:47]
	v_mfma_f32_16x16x32_bf16 v[24:27], v[132:135], v[210:213], v[24:27]
	v_mfma_f32_16x16x32_bf16 v[28:31], v[140:143], v[210:213], v[28:31]
	v_mfma_f32_16x16x32_bf16 v[8:11], v[132:135], v[218:221], v[8:11]
	v_mfma_f32_16x16x32_bf16 v[12:15], v[140:143], v[218:221], v[12:15]
	v_mfma_f32_16x16x32_bf16 v[52:55], v[144:147], v[186:189], 0
	v_mfma_f32_16x16x32_bf16 v[48:51], v[168:171], v[186:189], 0
	v_mfma_f32_16x16x32_bf16 v[36:39], v[144:147], v[198:201], 0
	v_mfma_f32_16x16x32_bf16 v[32:35], v[168:171], v[198:201], 0
	v_mfma_f32_16x16x32_bf16 v[20:23], v[144:147], v[206:209], 0
	v_mfma_f32_16x16x32_bf16 v[16:19], v[168:171], v[206:209], 0
	v_mfma_f32_16x16x32_bf16 v[4:7], v[144:147], v[214:217], 0
	v_mfma_f32_16x16x32_bf16 v[0:3], v[168:171], v[214:217], 0
	v_mfma_f32_16x16x32_bf16 v[52:55], v[148:151], v[190:193], v[52:55]
	v_mfma_f32_16x16x32_bf16 v[48:51], v[172:175], v[190:193], v[48:51]
	v_mfma_f32_16x16x32_bf16 v[36:39], v[148:151], v[202:205], v[36:39]
	v_mfma_f32_16x16x32_bf16 v[32:35], v[172:175], v[202:205], v[32:35]
	v_mfma_f32_16x16x32_bf16 v[20:23], v[148:151], v[210:213], v[20:23]
	v_mfma_f32_16x16x32_bf16 v[16:19], v[172:175], v[210:213], v[16:19]
	v_mfma_f32_16x16x32_bf16 v[4:7], v[148:151], v[218:221], v[4:7]
	v_mfma_f32_16x16x32_bf16 v[0:3], v[172:175], v[218:221], v[0:3]
	s_barrier
	s_setprio 0
	s_add_i32 s54, 0, 0x18000
	s_add_i32 s55, 0, 0x1c000
	v_add_u32_e32 v140, s54, v179
	v_add_u32_e32 v172, s55, v179
	ds_read_b128 v[128:131], v140
	ds_read_b128 v[132:135], v140 offset:1024
	ds_read_b128 v[136:139], v140 offset:2048
	ds_read_b128 v[140:143], v140 offset:3072
	ds_read_b128 v[144:147], v172
	ds_read_b128 v[148:151], v172 offset:1024
	ds_read_b128 v[168:171], v172 offset:2048
	ds_read_b128 v[172:175], v172 offset:3072
	s_add_u32 s30, s30, 0x100000
	s_addc_u32 s31, s31, 0
	s_mov_b32 m0, s37
	ds_read_b128 v[186:189], v183 offset:32768
	ds_read_b128 v[190:193], v183 offset:33792
	ds_read_b128 v[198:201], v183 offset:34816
	ds_read_b128 v[202:205], v183 offset:35840
	ds_read_b128 v[206:209], v183 offset:36864
	ds_read_b128 v[210:213], v183 offset:37888
	ds_read_b128 v[214:217], v183 offset:38912
	ds_read_b128 v[218:221], v183 offset:39936
	global_load_lds_dwordx4 v152, s[30:31]
	s_mov_b32 m0, s39
	v_lshl_add_u64 v[226:227], s[30:31], 0, v[156:157]
	global_load_lds_dwordx4 v[226:227], off
	s_waitcnt vmcnt(8) lgkmcnt(0)
	s_setprio 1
	s_barrier
	v_mfma_f32_16x16x32_bf16 v[124:127], v[128:131], v[186:189], v[124:127]
	v_mfma_f32_16x16x32_bf16 v[120:123], v[136:139], v[186:189], v[120:123]
	v_mfma_f32_16x16x32_bf16 v[104:107], v[128:131], v[198:201], v[104:107]
	v_mfma_f32_16x16x32_bf16 v[108:111], v[136:139], v[198:201], v[108:111]
	v_mfma_f32_16x16x32_bf16 v[88:91], v[128:131], v[206:209], v[88:91]
	v_mfma_f32_16x16x32_bf16 v[92:95], v[136:139], v[206:209], v[92:95]
	v_mfma_f32_16x16x32_bf16 v[72:75], v[128:131], v[214:217], v[72:75]
	v_mfma_f32_16x16x32_bf16 v[76:79], v[136:139], v[214:217], v[76:79]
	v_mfma_f32_16x16x32_bf16 v[124:127], v[132:135], v[190:193], v[124:127]
	v_mfma_f32_16x16x32_bf16 v[120:123], v[140:143], v[190:193], v[120:123]
	v_mfma_f32_16x16x32_bf16 v[104:107], v[132:135], v[202:205], v[104:107]
	v_mfma_f32_16x16x32_bf16 v[108:111], v[140:143], v[202:205], v[108:111]
	v_mfma_f32_16x16x32_bf16 v[88:91], v[132:135], v[210:213], v[88:91]
	v_mfma_f32_16x16x32_bf16 v[92:95], v[140:143], v[210:213], v[92:95]
	v_mfma_f32_16x16x32_bf16 v[72:75], v[132:135], v[218:221], v[72:75]
	v_mfma_f32_16x16x32_bf16 v[76:79], v[140:143], v[218:221], v[76:79]
	v_mfma_f32_16x16x32_bf16 v[116:119], v[144:147], v[186:189], v[116:119]
	v_mfma_f32_16x16x32_bf16 v[112:115], v[168:171], v[186:189], v[112:115]
	v_mfma_f32_16x16x32_bf16 v[100:103], v[144:147], v[198:201], v[100:103]
	v_mfma_f32_16x16x32_bf16 v[96:99], v[168:171], v[198:201], v[96:99]
	v_mfma_f32_16x16x32_bf16 v[84:87], v[144:147], v[206:209], v[84:87]
	v_mfma_f32_16x16x32_bf16 v[80:83], v[168:171], v[206:209], v[80:83]
	v_mfma_f32_16x16x32_bf16 v[68:71], v[144:147], v[214:217], v[68:71]
	v_mfma_f32_16x16x32_bf16 v[64:67], v[168:171], v[214:217], v[64:67]
	v_mfma_f32_16x16x32_bf16 v[116:119], v[148:151], v[190:193], v[116:119]
	v_mfma_f32_16x16x32_bf16 v[112:115], v[172:175], v[190:193], v[112:115]
	v_mfma_f32_16x16x32_bf16 v[100:103], v[148:151], v[202:205], v[100:103]
	v_mfma_f32_16x16x32_bf16 v[96:99], v[172:175], v[202:205], v[96:99]
	v_mfma_f32_16x16x32_bf16 v[84:87], v[148:151], v[210:213], v[84:87]
	v_mfma_f32_16x16x32_bf16 v[80:83], v[172:175], v[210:213], v[80:83]
	v_mfma_f32_16x16x32_bf16 v[68:71], v[148:151], v[218:221], v[68:71]
	v_mfma_f32_16x16x32_bf16 v[64:67], v[172:175], v[218:221], v[64:67]
	s_barrier
; #define PG8_STAGE(bufoff, gbase, voff) do { _Pragma("unroll") for (int _i = 0; _i < 2; ++_i) \
;         __builtin_amdgcn_global_load_lds((const unsigned*)((const char*)(gbase) + (voff)[_i]), (PG8_LAS unsigned*)(lds + (bufoff) + ldsw + _i * 8192), 16, 0, 0); } while (0)
; #define PG8_LDA(dst, b, h) do { _Pragma("unroll") for (int m = 0; m < 4; ++m) _Pragma("unroll") for (int k = 0; k < 2; ++k) dst[m][k] = *(const PG8_LAS bf16x8*)(lds + PG8_SA(b, h) + aoff + m * 2048 + k * 1024); } while (0)
; #define PG8_LDB(dst, b, h) do { _Pragma("unroll") for (int n = 0; n < 2; ++n) _Pragma("unroll") for (int k = 0; k < 2; ++k) dst[n][k] = *(const PG8_LAS bf16x8*)(lds + PG8_SB(b, h) + boff + n * 2048 + k * 1024); } while (0)
; #define PG8_MMA(ai, bj, At, Bt) do { __builtin_amdgcn_s_setprio(1); _Pragma("unroll") for (int m = 0; m < 4; ++m) _Pragma("unroll") for (int n = 0; n < 2; ++n) _Pragma("unroll") for (int k = 0; k < 2; ++k) \
;         acc[ai][bj][m][n] = __builtin_amdgcn_mfma_f32_16x16x32_bf16(Bt[n][k], At[m][k], acc[ai][bj][m][n], 0, 0, 0); __builtin_amdgcn_s_setprio(0); } while (0)
; #define PG8_WAIT_V(n) asm volatile("s_waitcnt vmcnt(" #n ")" ::: "memory")
; #define PG8_WAIT_L(n) asm volatile("s_waitcnt lgkmcnt(" #n ")" ::: "memory")
; #define PG8_BAR __builtin_amdgcn_s_barrier()
; #define PG8_SCHED __builtin_amdgcn_sched_barrier(0)
; template <class Epi, class Sched, bool ALIGN_EPI = false, bool SP2 = false>
; __device__ __forceinline__ void gemm_phase(PG8_LAS unsigned char* lds, const Gemm g, const Sched& S, const Epi& E) {
;     ...
;             const bool last = (t == nt - 2);
;             const char* a1 = cA + (size_t)(t + 1) * kstep;
;             const char* a2 = last ? nA : cA + (size_t)(t + 2) * kstep; const char* b2 = last ? nB : cB + (size_t)(t + 2) * kstep;
;             const char* a3 = a2 + kstep; const char* b3 = b2 + kstep;
;             if (last && has_next) S.a_ready(nxt);
;             if constexpr (SP2) {
;             PG8_LDB(B0, 0, 0); PG8_LDB(B1, 0, 1); PG8_SCHED; PG8_LDA(At, 0, 0); PG8_STAGE(PG8_SA(1, 1), a1 + hstep, voffA);
;     ...
;             PG8_LDA(At, 1, 1); PG8_STAGE(PG8_SB(1, 0), b3, voffB); PG8_STAGE(PG8_SB(1, 1), b3 + hstep, voffB); PG8_STAGE(PG8_SA(1, 0), a3, voffA);
;             PG8_WAIT_V(8); PG8_WAIT_L(0); PG8_BAR; PG8_MMA(1, 0, At, B0); PG8_MMA(1, 1, At, B1); PG8_BAR; PG8_SCHED;
	s_setprio 0
	v_lshl_add_u64 v[176:177], v[176:177], 0, s[12:13]
	s_mov_b32 m0, s100
	ds_read_b128 v[186:189], v183 offset:49152
	ds_read_b128 v[190:193], v183 offset:50176
	ds_read_b128 v[198:201], v183 offset:51200
	ds_read_b128 v[202:205], v183 offset:52224
	ds_read_b128 v[206:209], v183 offset:53248
	ds_read_b128 v[210:213], v183 offset:54272
	ds_read_b128 v[214:217], v183 offset:55296
	ds_read_b128 v[218:221], v183 offset:56320
	global_load_lds_dwordx4 v[176:177], off
	s_add_i32 m0, s100, 0x2000
	s_add_u32 s28, s28, 0x100080
	v_lshl_add_u64 v[176:177], v[194:195], 0, s[12:13]
	s_addc_u32 s29, s29, 0
	global_load_lds_dwordx4 v[176:177], off
	s_mov_b32 m0, s101
	s_nop 0
	global_load_lds_dwordx4 v154, s[28:29]
	s_add_i32 m0, s101, 0x2000
	v_lshl_add_u64 v[176:177], s[28:29], 0, v[158:159]
	global_load_lds_dwordx4 v[176:177], off
	s_mov_b32 m0, s43
	v_lshl_add_u64 v[176:177], v[222:223], 0, s[12:13]
	global_load_lds_dwordx4 v[176:177], off
	s_mov_b32 m0, s44
	v_lshl_add_u64 v[176:177], v[224:225], 0, s[12:13]
	global_load_lds_dwordx4 v[176:177], off
	s_waitcnt vmcnt(8) lgkmcnt(0)
	s_setprio 1
	s_barrier
	v_mfma_f32_16x16x32_bf16 v[56:59], v[128:131], v[186:189], v[56:59]
	v_mfma_f32_16x16x32_bf16 v[60:63], v[136:139], v[186:189], v[60:63]
	v_mfma_f32_16x16x32_bf16 v[40:43], v[128:131], v[198:201], v[40:43]
	v_mfma_f32_16x16x32_bf16 v[44:47], v[136:139], v[198:201], v[44:47]
	v_mfma_f32_16x16x32_bf16 v[24:27], v[128:131], v[206:209], v[24:27]
	v_mfma_f32_16x16x32_bf16 v[28:31], v[136:139], v[206:209], v[28:31]
	v_mfma_f32_16x16x32_bf16 v[8:11], v[128:131], v[214:217], v[8:11]
	v_mfma_f32_16x16x32_bf16 v[12:15], v[136:139], v[214:217], v[12:15]
	v_mfma_f32_16x16x32_bf16 v[56:59], v[132:135], v[190:193], v[56:59]
	v_mfma_f32_16x16x32_bf16 v[60:63], v[140:143], v[190:193], v[60:63]
	v_mfma_f32_16x16x32_bf16 v[40:43], v[132:135], v[202:205], v[40:43]
	v_mfma_f32_16x16x32_bf16 v[44:47], v[140:143], v[202:205], v[44:47]
	v_mfma_f32_16x16x32_bf16 v[24:27], v[132:135], v[210:213], v[24:27]
	v_mfma_f32_16x16x32_bf16 v[28:31], v[140:143], v[210:213], v[28:31]
	v_mfma_f32_16x16x32_bf16 v[8:11], v[132:135], v[218:221], v[8:11]
	v_mfma_f32_16x16x32_bf16 v[12:15], v[140:143], v[218:221], v[12:15]
	v_mfma_f32_16x16x32_bf16 v[52:55], v[144:147], v[186:189], v[52:55]
	v_mfma_f32_16x16x32_bf16 v[48:51], v[168:171], v[186:189], v[48:51]
	v_mfma_f32_16x16x32_bf16 v[36:39], v[144:147], v[198:201], v[36:39]
	v_mfma_f32_16x16x32_bf16 v[32:35], v[168:171], v[198:201], v[32:35]
	v_mfma_f32_16x16x32_bf16 v[20:23], v[144:147], v[206:209], v[20:23]
	v_mfma_f32_16x16x32_bf16 v[16:19], v[168:171], v[206:209], v[16:19]
	v_mfma_f32_16x16x32_bf16 v[4:7], v[144:147], v[214:217], v[4:7]
	v_mfma_f32_16x16x32_bf16 v[0:3], v[168:171], v[214:217], v[0:3]
	v_mfma_f32_16x16x32_bf16 v[52:55], v[148:151], v[190:193], v[52:55]
	v_mfma_f32_16x16x32_bf16 v[48:51], v[172:175], v[190:193], v[48:51]
	v_mfma_f32_16x16x32_bf16 v[36:39], v[148:151], v[202:205], v[36:39]
	v_mfma_f32_16x16x32_bf16 v[32:35], v[172:175], v[202:205], v[32:35]
	v_mfma_f32_16x16x32_bf16 v[20:23], v[148:151], v[210:213], v[20:23]
	v_mfma_f32_16x16x32_bf16 v[16:19], v[172:175], v[210:213], v[16:19]
	v_mfma_f32_16x16x32_bf16 v[4:7], v[148:151], v[218:221], v[4:7]
	v_mfma_f32_16x16x32_bf16 v[0:3], v[172:175], v[218:221], v[0:3]
	s_barrier
	s_setprio 0
	s_add_i32 s53, s53, 2
	s_add_u32 s26, s26, 0x100
	s_addc_u32 s27, s27, 0
	s_add_u32 s49, s49, 0x100
	s_addc_u32 s52, s52, 0
.LBB0_763:
	ds_read_b128 v[128:131], v181
	ds_read_b128 v[132:135], v181 offset:1024
	ds_read_b128 v[136:139], v181 offset:2048
	ds_read_b128 v[140:143], v181 offset:3072
	ds_read_b128 v[144:147], v182
	ds_read_b128 v[148:151], v182 offset:1024
	ds_read_b128 v[168:171], v182 offset:2048
	ds_read_b128 v[172:175], v182 offset:3072
	s_add_u32 s28, s26, 0xfff00080
	s_addc_u32 s29, s27, -1
	s_cmp_eq_u32 s53, 60
	s_cselect_b32 s31, s7, s29
	s_cselect_b32 s30, s21, s28
	s_cselect_b32 s29, s19, s52
	s_cselect_b32 s28, s48, s49
	s_add_i32 m0, s35, 0xc000
	ds_read_b128 v[186:189], v183
	ds_read_b128 v[190:193], v183 offset:1024
	ds_read_b128 v[198:201], v183 offset:2048
	ds_read_b128 v[202:205], v183 offset:3072
	ds_read_b128 v[206:209], v183 offset:4096
	ds_read_b128 v[210:213], v183 offset:5120
	ds_read_b128 v[214:217], v183 offset:6144
	ds_read_b128 v[218:221], v183 offset:7168
	global_load_lds_dwordx4 v160, s[26:27]
	s_add_i32 m0, s35, 0xe000
	s_nop 0
	global_load_lds_dwordx4 v162, s[26:27]
	s_waitcnt vmcnt(8) lgkmcnt(0)
	s_setprio 1
	s_barrier
; #define PG8_STAGE(bufoff, gbase, voff) do { _Pragma("unroll") for (int _i = 0; _i < 2; ++_i) \
;         __builtin_amdgcn_global_load_lds((const unsigned*)((const char*)(gbase) + (voff)[_i]), (PG8_LAS unsigned*)(lds + (bufoff) + ldsw + _i * 8192), 16, 0, 0); } while (0)
; #define PG8_LDA(dst, b, h) do { _Pragma("unroll") for (int m = 0; m < 4; ++m) _Pragma("unroll") for (int k = 0; k < 2; ++k) dst[m][k] = *(const PG8_LAS bf16x8*)(lds + PG8_SA(b, h) + aoff + m * 2048 + k * 1024); } while (0)
; #define PG8_MMA(ai, bj, At, Bt) do { __builtin_amdgcn_s_setprio(1); _Pragma("unroll") for (int m = 0; m < 4; ++m) _Pragma("unroll") for (int n = 0; n < 2; ++n) _Pragma("unroll") for (int k = 0; k < 2; ++k) \
;         acc[ai][bj][m][n] = __builtin_amdgcn_mfma_f32_16x16x32_bf16(Bt[n][k], At[m][k], acc[ai][bj][m][n], 0, 0, 0); __builtin_amdgcn_s_setprio(0); } while (0)
; #define PG8_WAIT_V(n) asm volatile("s_waitcnt vmcnt(" #n ")" ::: "memory")
; #define PG8_WAIT_L(n) asm volatile("s_waitcnt lgkmcnt(" #n ")" ::: "memory")
; #define PG8_BAR __builtin_amdgcn_s_barrier()
; #define PG8_SCHED __builtin_amdgcn_sched_barrier(0)
; template <class Epi, class Sched, bool ALIGN_EPI = false, bool SP2 = false>
; __device__ __forceinline__ void gemm_phase(PG8_LAS unsigned char* lds, const Gemm g, const Sched& S, const Epi& E) {
;     ...
;             PG8_WAIT_V(8); PG8_WAIT_L(0); PG8_BAR; PG8_MMA(0, 0, At, B0); PG8_MMA(0, 1, At, B1); PG8_BAR; PG8_SCHED;
;             PG8_LDA(At, 0, 1); PG8_STAGE(PG8_SB(0, 0), b2, voffB); PG8_STAGE(PG8_SB(0, 1), b2 + hstep, voffB); PG8_STAGE(PG8_SA(0, 0), a2, voffA);
;             PG8_WAIT_V(8); PG8_WAIT_L(0); PG8_BAR; PG8_MMA(1, 0, At, B0); PG8_MMA(1, 1, At, B1); PG8_BAR; PG8_SCHED;
	v_mfma_f32_16x16x32_bf16 v[124:127], v[128:131], v[186:189], v[124:127]
	v_mfma_f32_16x16x32_bf16 v[120:123], v[136:139], v[186:189], v[120:123]
	v_mfma_f32_16x16x32_bf16 v[104:107], v[128:131], v[198:201], v[104:107]
	v_mfma_f32_16x16x32_bf16 v[108:111], v[136:139], v[198:201], v[108:111]
	v_mfma_f32_16x16x32_bf16 v[88:91], v[128:131], v[206:209], v[88:91]
	v_mfma_f32_16x16x32_bf16 v[92:95], v[136:139], v[206:209], v[92:95]
	v_mfma_f32_16x16x32_bf16 v[72:75], v[128:131], v[214:217], v[72:75]
	v_mfma_f32_16x16x32_bf16 v[76:79], v[136:139], v[214:217], v[76:79]
	v_mfma_f32_16x16x32_bf16 v[124:127], v[132:135], v[190:193], v[124:127]
	v_mfma_f32_16x16x32_bf16 v[120:123], v[140:143], v[190:193], v[120:123]
	v_mfma_f32_16x16x32_bf16 v[104:107], v[132:135], v[202:205], v[104:107]
	v_mfma_f32_16x16x32_bf16 v[108:111], v[140:143], v[202:205], v[108:111]
	v_mfma_f32_16x16x32_bf16 v[88:91], v[132:135], v[210:213], v[88:91]
	v_mfma_f32_16x16x32_bf16 v[92:95], v[140:143], v[210:213], v[92:95]
	v_mfma_f32_16x16x32_bf16 v[72:75], v[132:135], v[218:221], v[72:75]
	v_mfma_f32_16x16x32_bf16 v[76:79], v[140:143], v[218:221], v[76:79]
	v_mfma_f32_16x16x32_bf16 v[116:119], v[144:147], v[186:189], v[116:119]
	v_mfma_f32_16x16x32_bf16 v[112:115], v[168:171], v[186:189], v[112:115]
	v_mfma_f32_16x16x32_bf16 v[100:103], v[144:147], v[198:201], v[100:103]
	v_mfma_f32_16x16x32_bf16 v[96:99], v[168:171], v[198:201], v[96:99]
	v_mfma_f32_16x16x32_bf16 v[84:87], v[144:147], v[206:209], v[84:87]
	v_mfma_f32_16x16x32_bf16 v[80:83], v[168:171], v[206:209], v[80:83]
	v_mfma_f32_16x16x32_bf16 v[68:71], v[144:147], v[214:217], v[68:71]
	v_mfma_f32_16x16x32_bf16 v[64:67], v[168:171], v[214:217], v[64:67]
	v_mfma_f32_16x16x32_bf16 v[116:119], v[148:151], v[190:193], v[116:119]
	v_mfma_f32_16x16x32_bf16 v[112:115], v[172:175], v[190:193], v[112:115]
	v_mfma_f32_16x16x32_bf16 v[100:103], v[148:151], v[202:205], v[100:103]
	v_mfma_f32_16x16x32_bf16 v[96:99], v[172:175], v[202:205], v[96:99]
	v_mfma_f32_16x16x32_bf16 v[84:87], v[148:151], v[210:213], v[84:87]
	v_mfma_f32_16x16x32_bf16 v[80:83], v[172:175], v[210:213], v[80:83]
	v_mfma_f32_16x16x32_bf16 v[68:71], v[148:151], v[218:221], v[68:71]
	v_mfma_f32_16x16x32_bf16 v[64:67], v[172:175], v[218:221], v[64:67]
	s_barrier
	s_setprio 0
	v_lshl_add_u64 v[176:177], s[28:29], 0, v[154:155]
	s_mov_b32 m0, s98
	ds_read_b128 v[186:189], v183 offset:16384
	ds_read_b128 v[190:193], v183 offset:17408
	ds_read_b128 v[198:201], v183 offset:18432
	ds_read_b128 v[202:205], v183 offset:19456
	ds_read_b128 v[206:209], v183 offset:20480
	ds_read_b128 v[210:213], v183 offset:21504
	ds_read_b128 v[214:217], v183 offset:22528
	ds_read_b128 v[218:221], v183 offset:23552
	global_load_lds_dwordx4 v[176:177], off
	s_add_i32 m0, s98, 0x2000
	s_add_u32 s54, s28, 0x100000
	v_lshl_add_u64 v[194:195], s[28:29], 0, v[158:159]
	s_addc_u32 s55, s29, 0
	global_load_lds_dwordx4 v[194:195], off
	s_mov_b32 m0, s99
	v_lshl_add_u64 v[224:225], s[30:31], 0, v[156:157]
	global_load_lds_dwordx4 v154, s[54:55]
	s_add_i32 m0, s99, 0x2000
	s_nop 0
	global_load_lds_dwordx4 v158, s[54:55]
	s_mov_b32 m0, s35
	v_lshl_add_u64 v[222:223], s[30:31], 0, v[152:153]
	global_load_lds_dwordx4 v[222:223], off
	s_mov_b32 m0, s33
	s_nop 0
	global_load_lds_dwordx4 v[224:225], off
	s_waitcnt vmcnt(8) lgkmcnt(0)
	s_setprio 1
	s_barrier
	v_mfma_f32_16x16x32_bf16 v[56:59], v[128:131], v[186:189], v[56:59]
	v_mfma_f32_16x16x32_bf16 v[60:63], v[136:139], v[186:189], v[60:63]
	v_mfma_f32_16x16x32_bf16 v[40:43], v[128:131], v[198:201], v[40:43]
	v_mfma_f32_16x16x32_bf16 v[44:47], v[136:139], v[198:201], v[44:47]
	v_mfma_f32_16x16x32_bf16 v[24:27], v[128:131], v[206:209], v[24:27]
	v_mfma_f32_16x16x32_bf16 v[28:31], v[136:139], v[206:209], v[28:31]
	v_mfma_f32_16x16x32_bf16 v[8:11], v[128:131], v[214:217], v[8:11]
	v_mfma_f32_16x16x32_bf16 v[12:15], v[136:139], v[214:217], v[12:15]
	v_mfma_f32_16x16x32_bf16 v[56:59], v[132:135], v[190:193], v[56:59]
	v_mfma_f32_16x16x32_bf16 v[60:63], v[140:143], v[190:193], v[60:63]
	v_mfma_f32_16x16x32_bf16 v[40:43], v[132:135], v[202:205], v[40:43]
	v_mfma_f32_16x16x32_bf16 v[44:47], v[140:143], v[202:205], v[44:47]
	v_mfma_f32_16x16x32_bf16 v[24:27], v[132:135], v[210:213], v[24:27]
	v_mfma_f32_16x16x32_bf16 v[28:31], v[140:143], v[210:213], v[28:31]
	v_mfma_f32_16x16x32_bf16 v[8:11], v[132:135], v[218:221], v[8:11]
	v_mfma_f32_16x16x32_bf16 v[12:15], v[140:143], v[218:221], v[12:15]
	v_mfma_f32_16x16x32_bf16 v[52:55], v[144:147], v[186:189], v[52:55]
	v_mfma_f32_16x16x32_bf16 v[48:51], v[168:171], v[186:189], v[48:51]
	v_mfma_f32_16x16x32_bf16 v[36:39], v[144:147], v[198:201], v[36:39]
	v_mfma_f32_16x16x32_bf16 v[32:35], v[168:171], v[198:201], v[32:35]
	v_mfma_f32_16x16x32_bf16 v[20:23], v[144:147], v[206:209], v[20:23]
	v_mfma_f32_16x16x32_bf16 v[16:19], v[168:171], v[206:209], v[16:19]
	v_mfma_f32_16x16x32_bf16 v[4:7], v[144:147], v[214:217], v[4:7]
	v_mfma_f32_16x16x32_bf16 v[0:3], v[168:171], v[214:217], v[0:3]
	v_mfma_f32_16x16x32_bf16 v[52:55], v[148:151], v[190:193], v[52:55]
	v_mfma_f32_16x16x32_bf16 v[48:51], v[172:175], v[190:193], v[48:51]
	v_mfma_f32_16x16x32_bf16 v[36:39], v[148:151], v[202:205], v[36:39]
	v_mfma_f32_16x16x32_bf16 v[32:35], v[172:175], v[202:205], v[32:35]
	v_mfma_f32_16x16x32_bf16 v[20:23], v[148:151], v[210:213], v[20:23]
	v_mfma_f32_16x16x32_bf16 v[16:19], v[172:175], v[210:213], v[16:19]
	v_mfma_f32_16x16x32_bf16 v[4:7], v[148:151], v[218:221], v[4:7]
	v_mfma_f32_16x16x32_bf16 v[0:3], v[172:175], v[218:221], v[0:3]
	s_barrier
; #define PG8_STAGE(bufoff, gbase, voff) do { _Pragma("unroll") for (int _i = 0; _i < 2; ++_i) \
;         __builtin_amdgcn_global_load_lds((const unsigned*)((const char*)(gbase) + (voff)[_i]), (PG8_LAS unsigned*)(lds + (bufoff) + ldsw + _i * 8192), 16, 0, 0); } while (0)
; #define PG8_LDA(dst, b, h) do { _Pragma("unroll") for (int m = 0; m < 4; ++m) _Pragma("unroll") for (int k = 0; k < 2; ++k) dst[m][k] = *(const PG8_LAS bf16x8*)(lds + PG8_SA(b, h) + aoff + m * 2048 + k * 1024); } while (0)
; #define PG8_LDB(dst, b, h) do { _Pragma("unroll") for (int n = 0; n < 2; ++n) _Pragma("unroll") for (int k = 0; k < 2; ++k) dst[n][k] = *(const PG8_LAS bf16x8*)(lds + PG8_SB(b, h) + boff + n * 2048 + k * 1024); } while (0)
; #define PG8_MMA(ai, bj, At, Bt) do { __builtin_amdgcn_s_setprio(1); _Pragma("unroll") for (int m = 0; m < 4; ++m) _Pragma("unroll") for (int n = 0; n < 2; ++n) _Pragma("unroll") for (int k = 0; k < 2; ++k) \
;         acc[ai][bj][m][n] = __builtin_amdgcn_mfma_f32_16x16x32_bf16(Bt[n][k], At[m][k], acc[ai][bj][m][n], 0, 0, 0); __builtin_amdgcn_s_setprio(0); } while (0)
; #define PG8_WAIT_V(n) asm volatile("s_waitcnt vmcnt(" #n ")" ::: "memory")
; #define PG8_WAIT_L(n) asm volatile("s_waitcnt lgkmcnt(" #n ")" ::: "memory")
; #define PG8_BAR __builtin_amdgcn_s_barrier()
; #define PG8_SCHED __builtin_amdgcn_sched_barrier(0)
; template <class Epi, class Sched, bool ALIGN_EPI = false, bool SP2 = false>
; __device__ __forceinline__ void gemm_phase(PG8_LAS unsigned char* lds, const Gemm g, const Sched& S, const Epi& E) {
;     ...
;             PG8_LDB(B0, 1, 0); PG8_LDB(B1, 1, 1); PG8_SCHED; PG8_LDA(At, 1, 0); PG8_STAGE(PG8_SA(0, 1), a2 + hstep, voffA);
;             PG8_WAIT_V(8); PG8_WAIT_L(0); PG8_BAR; PG8_MMA(0, 0, At, B0); PG8_MMA(0, 1, At, B1); PG8_BAR; PG8_SCHED;
;             PG8_LDA(At, 1, 1); PG8_STAGE(PG8_SB(1, 0), b3, voffB); PG8_STAGE(PG8_SB(1, 1), b3 + hstep, voffB); PG8_STAGE(PG8_SA(1, 0), a3, voffA);
;             PG8_WAIT_V(8); PG8_WAIT_L(0); PG8_BAR; PG8_MMA(1, 0, At, B0); PG8_MMA(1, 1, At, B1); PG8_BAR; PG8_SCHED;
;     ...
;         if constexpr (ALIGN_EPI) { if (wr == 0) PG8_BAR; }
	s_setprio 0
	s_add_i32 s54, 0, 0x18000
	s_add_i32 s55, 0, 0x1c000
	v_add_u32_e32 v140, s54, v179
	v_add_u32_e32 v172, s55, v179
	ds_read_b128 v[128:131], v140
	ds_read_b128 v[132:135], v140 offset:1024
	ds_read_b128 v[136:139], v140 offset:2048
	ds_read_b128 v[140:143], v140 offset:3072
	ds_read_b128 v[144:147], v172
	ds_read_b128 v[148:151], v172 offset:1024
	ds_read_b128 v[168:171], v172 offset:2048
	ds_read_b128 v[172:175], v172 offset:3072
	s_add_u32 s30, s30, 0x100000
	s_addc_u32 s31, s31, 0
	s_mov_b32 m0, s37
	ds_read_b128 v[186:189], v183 offset:32768
	ds_read_b128 v[190:193], v183 offset:33792
	ds_read_b128 v[198:201], v183 offset:34816
	ds_read_b128 v[202:205], v183 offset:35840
	ds_read_b128 v[206:209], v183 offset:36864
	ds_read_b128 v[210:213], v183 offset:37888
	ds_read_b128 v[214:217], v183 offset:38912
	ds_read_b128 v[218:221], v183 offset:39936
	global_load_lds_dwordx4 v152, s[30:31]
	s_mov_b32 m0, s39
	s_nop 0
	global_load_lds_dwordx4 v156, s[30:31]
	s_waitcnt vmcnt(8) lgkmcnt(0)
	s_setprio 1
	s_barrier
	v_mfma_f32_16x16x32_bf16 v[124:127], v[128:131], v[186:189], v[124:127]
	v_mfma_f32_16x16x32_bf16 v[120:123], v[136:139], v[186:189], v[120:123]
	v_mfma_f32_16x16x32_bf16 v[104:107], v[128:131], v[198:201], v[104:107]
	v_mfma_f32_16x16x32_bf16 v[108:111], v[136:139], v[198:201], v[108:111]
	v_mfma_f32_16x16x32_bf16 v[88:91], v[128:131], v[206:209], v[88:91]
	v_mfma_f32_16x16x32_bf16 v[92:95], v[136:139], v[206:209], v[92:95]
	v_mfma_f32_16x16x32_bf16 v[72:75], v[128:131], v[214:217], v[72:75]
	v_mfma_f32_16x16x32_bf16 v[76:79], v[136:139], v[214:217], v[76:79]
	v_mfma_f32_16x16x32_bf16 v[124:127], v[132:135], v[190:193], v[124:127]
	v_mfma_f32_16x16x32_bf16 v[120:123], v[140:143], v[190:193], v[120:123]
	v_mfma_f32_16x16x32_bf16 v[104:107], v[132:135], v[202:205], v[104:107]
	v_mfma_f32_16x16x32_bf16 v[108:111], v[140:143], v[202:205], v[108:111]
	v_mfma_f32_16x16x32_bf16 v[88:91], v[132:135], v[210:213], v[88:91]
	v_mfma_f32_16x16x32_bf16 v[92:95], v[140:143], v[210:213], v[92:95]
	v_mfma_f32_16x16x32_bf16 v[72:75], v[132:135], v[218:221], v[72:75]
	v_mfma_f32_16x16x32_bf16 v[76:79], v[140:143], v[218:221], v[76:79]
	v_mfma_f32_16x16x32_bf16 v[116:119], v[144:147], v[186:189], v[116:119]
	v_mfma_f32_16x16x32_bf16 v[112:115], v[168:171], v[186:189], v[112:115]
	v_mfma_f32_16x16x32_bf16 v[100:103], v[144:147], v[198:201], v[100:103]
	v_mfma_f32_16x16x32_bf16 v[96:99], v[168:171], v[198:201], v[96:99]
	v_mfma_f32_16x16x32_bf16 v[84:87], v[144:147], v[206:209], v[84:87]
	v_mfma_f32_16x16x32_bf16 v[80:83], v[168:171], v[206:209], v[80:83]
	v_mfma_f32_16x16x32_bf16 v[68:71], v[144:147], v[214:217], v[68:71]
	v_mfma_f32_16x16x32_bf16 v[64:67], v[168:171], v[214:217], v[64:67]
	v_mfma_f32_16x16x32_bf16 v[116:119], v[148:151], v[190:193], v[116:119]
	v_mfma_f32_16x16x32_bf16 v[112:115], v[172:175], v[190:193], v[112:115]
	v_mfma_f32_16x16x32_bf16 v[100:103], v[148:151], v[202:205], v[100:103]
	v_mfma_f32_16x16x32_bf16 v[96:99], v[172:175], v[202:205], v[96:99]
	v_mfma_f32_16x16x32_bf16 v[84:87], v[148:151], v[210:213], v[84:87]
	v_mfma_f32_16x16x32_bf16 v[80:83], v[172:175], v[210:213], v[80:83]
	v_mfma_f32_16x16x32_bf16 v[68:71], v[148:151], v[218:221], v[68:71]
	v_mfma_f32_16x16x32_bf16 v[64:67], v[172:175], v[218:221], v[64:67]
	s_barrier
	s_setprio 0
	v_lshl_add_u64 v[176:177], v[176:177], 0, s[12:13]
	s_mov_b32 m0, s100
	ds_read_b128 v[186:189], v183 offset:49152
	ds_read_b128 v[190:193], v183 offset:50176
	ds_read_b128 v[198:201], v183 offset:51200
	ds_read_b128 v[202:205], v183 offset:52224
	ds_read_b128 v[206:209], v183 offset:53248
	ds_read_b128 v[210:213], v183 offset:54272
	ds_read_b128 v[214:217], v183 offset:55296
	ds_read_b128 v[218:221], v183 offset:56320
	global_load_lds_dwordx4 v[176:177], off
	s_add_i32 m0, s100, 0x2000
	s_add_u32 s28, s28, 0x100080
	v_lshl_add_u64 v[176:177], v[194:195], 0, s[12:13]
	s_addc_u32 s29, s29, 0
	global_load_lds_dwordx4 v[176:177], off
	s_mov_b32 m0, s101
	s_nop 0
	global_load_lds_dwordx4 v154, s[28:29]
	s_add_i32 m0, s101, 0x2000
	v_lshl_add_u64 v[176:177], s[28:29], 0, v[158:159]
	global_load_lds_dwordx4 v[176:177], off
	s_mov_b32 m0, s43
	v_lshl_add_u64 v[176:177], v[222:223], 0, s[12:13]
	global_load_lds_dwordx4 v[176:177], off
	s_mov_b32 m0, s44
	v_lshl_add_u64 v[176:177], v[224:225], 0, s[12:13]
	global_load_lds_dwordx4 v[176:177], off
	s_waitcnt vmcnt(8) lgkmcnt(0)
	s_setprio 1
	s_barrier
	v_mfma_f32_16x16x32_bf16 v[56:59], v[128:131], v[186:189], v[56:59]
	v_mfma_f32_16x16x32_bf16 v[60:63], v[136:139], v[186:189], v[60:63]
	v_mfma_f32_16x16x32_bf16 v[40:43], v[128:131], v[198:201], v[40:43]
	v_mfma_f32_16x16x32_bf16 v[44:47], v[136:139], v[198:201], v[44:47]
	v_mfma_f32_16x16x32_bf16 v[24:27], v[128:131], v[206:209], v[24:27]
	v_mfma_f32_16x16x32_bf16 v[28:31], v[136:139], v[206:209], v[28:31]
	v_mfma_f32_16x16x32_bf16 v[8:11], v[128:131], v[214:217], v[8:11]
	v_mfma_f32_16x16x32_bf16 v[12:15], v[136:139], v[214:217], v[12:15]
	v_mfma_f32_16x16x32_bf16 v[56:59], v[132:135], v[190:193], v[56:59]
	v_mfma_f32_16x16x32_bf16 v[60:63], v[140:143], v[190:193], v[60:63]
	v_mfma_f32_16x16x32_bf16 v[40:43], v[132:135], v[202:205], v[40:43]
	v_mfma_f32_16x16x32_bf16 v[44:47], v[140:143], v[202:205], v[44:47]
	v_mfma_f32_16x16x32_bf16 v[24:27], v[132:135], v[210:213], v[24:27]
	v_mfma_f32_16x16x32_bf16 v[28:31], v[140:143], v[210:213], v[28:31]
	v_mfma_f32_16x16x32_bf16 v[8:11], v[132:135], v[218:221], v[8:11]
	v_mfma_f32_16x16x32_bf16 v[12:15], v[140:143], v[218:221], v[12:15]
	v_mfma_f32_16x16x32_bf16 v[52:55], v[144:147], v[186:189], v[52:55]
	v_mfma_f32_16x16x32_bf16 v[48:51], v[168:171], v[186:189], v[48:51]
	v_mfma_f32_16x16x32_bf16 v[36:39], v[144:147], v[198:201], v[36:39]
	v_mfma_f32_16x16x32_bf16 v[32:35], v[168:171], v[198:201], v[32:35]
	v_mfma_f32_16x16x32_bf16 v[20:23], v[144:147], v[206:209], v[20:23]
	v_mfma_f32_16x16x32_bf16 v[16:19], v[168:171], v[206:209], v[16:19]
	v_mfma_f32_16x16x32_bf16 v[4:7], v[144:147], v[214:217], v[4:7]
	v_mfma_f32_16x16x32_bf16 v[0:3], v[168:171], v[214:217], v[0:3]
	v_mfma_f32_16x16x32_bf16 v[52:55], v[148:151], v[190:193], v[52:55]
	v_mfma_f32_16x16x32_bf16 v[48:51], v[172:175], v[190:193], v[48:51]
	v_mfma_f32_16x16x32_bf16 v[36:39], v[148:151], v[202:205], v[36:39]
	v_mfma_f32_16x16x32_bf16 v[32:35], v[172:175], v[202:205], v[32:35]
	v_mfma_f32_16x16x32_bf16 v[20:23], v[148:151], v[210:213], v[20:23]
	v_mfma_f32_16x16x32_bf16 v[16:19], v[172:175], v[210:213], v[16:19]
	v_mfma_f32_16x16x32_bf16 v[4:7], v[148:151], v[218:221], v[4:7]
	v_mfma_f32_16x16x32_bf16 v[0:3], v[172:175], v[218:221], v[0:3]
	s_barrier
	s_setprio 0
	s_add_i32 s53, s53, 2
	s_add_u32 s26, s26, 0x100
	s_addc_u32 s27, s27, 0
	s_add_u32 s49, s49, 0x100
	s_addc_u32 s52, s52, 0
	s_cmp_gt_u32 s53, 61
	s_cbranch_scc0 .LBB0_763
	s_and_b64 vcc, exec, s[14:15]
	s_cbranch_vccz .LBB0_766
	s_barrier

; #define PG8_STAGE(bufoff, gbase, voff) do { _Pragma("unroll") for (int _i = 0; _i < 2; ++_i) \
;         __builtin_amdgcn_global_load_lds((const unsigned*)((const char*)(gbase) + (voff)[_i]), (PG8_LAS unsigned*)(lds + (bufoff) + ldsw + _i * 8192), 16, 0, 0); } while (0)
; #define PG8_LDA(dst, b, h) do { _Pragma("unroll") for (int m = 0; m < 4; ++m) _Pragma("unroll") for (int k = 0; k < 2; ++k) dst[m][k] = *(const PG8_LAS bf16x8*)(lds + PG8_SA(b, h) + aoff + m * 2048 + k * 1024); } while (0)
; #define PG8_LDB(dst, b, h) do { _Pragma("unroll") for (int n = 0; n < 2; ++n) _Pragma("unroll") for (int k = 0; k < 2; ++k) dst[n][k] = *(const PG8_LAS bf16x8*)(lds + PG8_SB(b, h) + boff + n * 2048 + k * 1024); } while (0)
; #define PG8_MMA(ai, bj, At, Bt) do { __builtin_amdgcn_s_setprio(1); _Pragma("unroll") for (int m = 0; m < 4; ++m) _Pragma("unroll") for (int n = 0; n < 2; ++n) _Pragma("unroll") for (int k = 0; k < 2; ++k) \
;         acc[ai][bj][m][n] = __builtin_amdgcn_mfma_f32_16x16x32_bf16(Bt[n][k], At[m][k], acc[ai][bj][m][n], 0, 0, 0); __builtin_amdgcn_s_setprio(0); } while (0)
; #define PG8_BAR __builtin_amdgcn_s_barrier()
; template <class Epi, class Sched, bool ALIGN_EPI = false, bool SP2 = false>
; __device__ __forceinline__ void gemm_phase(PG8_LAS unsigned char* lds, const Gemm g, const Sched& S, const Epi& E) {
;     ...
;         const bool has_next = S.next(ui + 1, nxt);
;         const char* nA = has_next ? (const char*)g.A + (size_t)nxt.pm * tstep : cA; const char* nB = has_next ? (const char*)g.Bt + (size_t)nxt.pn * tstep : cB;
;         for (int t = 0; t < nt; t += 2) {
;             const bool last = (t == nt - 2);
;             const char* a1 = cA + (size_t)(t + 1) * kstep;
;             const char* a2 = last ? nA : cA + (size_t)(t + 2) * kstep; const char* b2 = last ? nB : cB + (size_t)(t + 2) * kstep;
;             const char* a3 = a2 + kstep; const char* b3 = b2 + kstep;
;             if (last && has_next) S.a_ready(nxt);
;             if constexpr (SP2) {
;             PG8_LDB(B0, 0, 0); PG8_LDB(B1, 0, 1); PG8_SCHED; PG8_LDA(At, 0, 0); PG8_STAGE(PG8_SA(1, 1), a1 + hstep, voffA);
;             PG8_WAIT_V(8); PG8_WAIT_L(0); PG8_BAR; PG8_MMA(0, 0, At, B0); PG8_MMA(0, 1, At, B1); PG8_BAR; PG8_SCHED;
;             PG8_LDA(At, 0, 1); PG8_STAGE(PG8_SB(0, 0), b2, voffB); PG8_STAGE(PG8_SB(0, 1), b2 + hstep, voffB); PG8_STAGE(PG8_SA(0, 0), a2, voffA);
.LBB0_954:
	s_ashr_i32 s53, s52, 31
	s_lshl_b64 s[22:23], s[52:53], 20
	s_add_u32 s54, s74, s22
	s_addc_u32 s55, s75, s23
	s_and_b64 s[24:25], s[62:63], exec
	s_cselect_b32 s1, s55, s27
	s_cselect_b32 s5, s54, s26
	s_ashr_i32 s41, s40, 31
	s_lshl_b64 s[24:25], s[40:41], 20
	s_add_u32 s56, s94, s24
	s_addc_u32 s57, s95, s25
	s_and_b64 s[30:31], s[62:63], exec
	s_cselect_b32 s17, s57, s29
	s_cselect_b32 s19, s56, s28
	s_add_u32 s26, s26, 0x80080
	s_addc_u32 s27, s27, 0
	s_add_u32 s33, s28, 0x100
	s_addc_u32 s44, s29, 0
	s_mov_b32 s45, -2
	s_waitcnt vmcnt(0)
	s_add_i32 s98, s34, 0x10000
	s_add_i32 s99, s34, 0x14000
	s_add_i32 s100, s34, 0x18000
	s_add_i32 s101, s34, 0x1c000
	ds_read_b128 v[128:131], v209
	ds_read_b128 v[132:135], v209 offset:1024
	ds_read_b128 v[136:139], v209 offset:2048
	ds_read_b128 v[178:181], v209 offset:3072
	ds_read_b128 v[182:185], v210
	ds_read_b128 v[186:189], v210 offset:1024
	ds_read_b128 v[190:193], v210 offset:2048
	ds_read_b128 v[222:225], v210 offset:3072
	s_add_u32 s28, s26, 0xfff80080
	s_addc_u32 s29, s27, -1
	s_cmp_eq_u32 s45, 28
	s_cselect_b32 s31, s1, s29
	s_cselect_b32 s30, s5, s28
	s_cselect_b32 s29, s17, s44
	s_cselect_b32 s28, s19, s33
	s_add_i32 m0, s35, 0xc000
	ds_read_b128 v[226:229], v211
	ds_read_b128 v[230:233], v211 offset:1024
	ds_read_b128 v[234:237], v211 offset:2048
	ds_read_b128 v[238:241], v211 offset:3072
	ds_read_b128 v[242:245], v211 offset:4096
	ds_read_b128 v[246:249], v211 offset:5120
	ds_read_b128 v[250:253], v211 offset:6144
	ds_read_b128 v[160:163], v211 offset:7168
	global_load_lds_dwordx4 v150, s[26:27]
	s_add_i32 m0, s35, 0xe000
	s_nop 0
	global_load_lds_dwordx4 v152, s[26:27]
	s_waitcnt lgkmcnt(0)
	s_setprio 1
	s_barrier
	v_mfma_f32_16x16x32_bf16 v[124:127], v[128:131], v[226:229], 0
	v_mfma_f32_16x16x32_bf16 v[120:123], v[136:139], v[226:229], 0
	v_mfma_f32_16x16x32_bf16 v[116:119], v[128:131], v[234:237], 0
	v_mfma_f32_16x16x32_bf16 v[108:111], v[136:139], v[234:237], 0
	v_mfma_f32_16x16x32_bf16 v[100:103], v[128:131], v[242:245], 0
	v_mfma_f32_16x16x32_bf16 v[92:95], v[136:139], v[242:245], 0
	v_mfma_f32_16x16x32_bf16 v[84:87], v[128:131], v[250:253], 0
	v_mfma_f32_16x16x32_bf16 v[76:79], v[136:139], v[250:253], 0
	v_mfma_f32_16x16x32_bf16 v[124:127], v[132:135], v[230:233], v[124:127]
	v_mfma_f32_16x16x32_bf16 v[120:123], v[178:181], v[230:233], v[120:123]
	v_mfma_f32_16x16x32_bf16 v[116:119], v[132:135], v[238:241], v[116:119]
	v_mfma_f32_16x16x32_bf16 v[108:111], v[178:181], v[238:241], v[108:111]
	v_mfma_f32_16x16x32_bf16 v[100:103], v[132:135], v[246:249], v[100:103]
	v_mfma_f32_16x16x32_bf16 v[92:95], v[178:181], v[246:249], v[92:95]
	v_mfma_f32_16x16x32_bf16 v[84:87], v[132:135], v[160:163], v[84:87]
	v_mfma_f32_16x16x32_bf16 v[76:79], v[178:181], v[160:163], v[76:79]
	v_mfma_f32_16x16x32_bf16 v[112:115], v[182:185], v[226:229], 0
	v_mfma_f32_16x16x32_bf16 v[104:107], v[190:193], v[226:229], 0
	v_mfma_f32_16x16x32_bf16 v[96:99], v[182:185], v[234:237], 0
	v_mfma_f32_16x16x32_bf16 v[88:91], v[190:193], v[234:237], 0
	v_mfma_f32_16x16x32_bf16 v[80:83], v[182:185], v[242:245], 0
	v_mfma_f32_16x16x32_bf16 v[72:75], v[190:193], v[242:245], 0
	v_mfma_f32_16x16x32_bf16 v[68:71], v[182:185], v[250:253], 0
	v_mfma_f32_16x16x32_bf16 v[64:67], v[190:193], v[250:253], 0
	v_mfma_f32_16x16x32_bf16 v[112:115], v[186:189], v[230:233], v[112:115]
	v_mfma_f32_16x16x32_bf16 v[104:107], v[222:225], v[230:233], v[104:107]
	v_mfma_f32_16x16x32_bf16 v[96:99], v[186:189], v[238:241], v[96:99]
	v_mfma_f32_16x16x32_bf16 v[88:91], v[222:225], v[238:241], v[88:91]
	v_mfma_f32_16x16x32_bf16 v[80:83], v[186:189], v[246:249], v[80:83]
	v_mfma_f32_16x16x32_bf16 v[72:75], v[222:225], v[246:249], v[72:75]
	v_mfma_f32_16x16x32_bf16 v[68:71], v[186:189], v[160:163], v[68:71]
	v_mfma_f32_16x16x32_bf16 v[64:67], v[222:225], v[160:163], v[64:67]
	s_barrier
	s_setprio 0
	v_lshl_add_u64 v[166:167], s[28:29], 0, v[142:143]
	s_mov_b32 m0, s98
	ds_read_b128 v[160:163], v211 offset:16384
	ds_read_b128 v[226:229], v211 offset:17408
	ds_read_b128 v[230:233], v211 offset:18432
	ds_read_b128 v[234:237], v211 offset:19456
	ds_read_b128 v[238:241], v211 offset:20480
	ds_read_b128 v[242:245], v211 offset:21504
	ds_read_b128 v[246:249], v211 offset:22528
	ds_read_b128 v[250:253], v211 offset:23552
	global_load_lds_dwordx4 v[166:167], off
	s_add_i32 m0, s98, 0x2000
	s_add_u32 s48, s28, 0x80000
	v_lshl_add_u64 v[170:171], s[28:29], 0, v[146:147]
	s_addc_u32 s49, s29, 0
	global_load_lds_dwordx4 v[170:171], off
	s_mov_b32 m0, s99
	v_lshl_add_u64 v[194:195], s[30:31], 0, v[144:145]
	global_load_lds_dwordx4 v142, s[48:49]
	s_add_i32 m0, s99, 0x2000
	s_nop 0
	global_load_lds_dwordx4 v146, s[48:49]
	s_mov_b32 m0, s35
	v_lshl_add_u64 v[174:175], s[30:31], 0, v[140:141]
	global_load_lds_dwordx4 v[174:175], off
	s_mov_b32 m0, s37
	s_nop 0
	global_load_lds_dwordx4 v[194:195], off
	s_waitcnt lgkmcnt(0)
	s_setprio 1
	s_barrier
; #define PG8_STAGE(bufoff, gbase, voff) do { _Pragma("unroll") for (int _i = 0; _i < 2; ++_i) \
;         __builtin_amdgcn_global_load_lds((const unsigned*)((const char*)(gbase) + (voff)[_i]), (PG8_LAS unsigned*)(lds + (bufoff) + ldsw + _i * 8192), 16, 0, 0); } while (0)
; #define PG8_LDA(dst, b, h) do { _Pragma("unroll") for (int m = 0; m < 4; ++m) _Pragma("unroll") for (int k = 0; k < 2; ++k) dst[m][k] = *(const PG8_LAS bf16x8*)(lds + PG8_SA(b, h) + aoff + m * 2048 + k * 1024); } while (0)
; #define PG8_LDB(dst, b, h) do { _Pragma("unroll") for (int n = 0; n < 2; ++n) _Pragma("unroll") for (int k = 0; k < 2; ++k) dst[n][k] = *(const PG8_LAS bf16x8*)(lds + PG8_SB(b, h) + boff + n * 2048 + k * 1024); } while (0)
; #define PG8_MMA(ai, bj, At, Bt) do { __builtin_amdgcn_s_setprio(1); _Pragma("unroll") for (int m = 0; m < 4; ++m) _Pragma("unroll") for (int n = 0; n < 2; ++n) _Pragma("unroll") for (int k = 0; k < 2; ++k) \
;         acc[ai][bj][m][n] = __builtin_amdgcn_mfma_f32_16x16x32_bf16(Bt[n][k], At[m][k], acc[ai][bj][m][n], 0, 0, 0); __builtin_amdgcn_s_setprio(0); } while (0)
; #define PG8_WAIT_V(n) asm volatile("s_waitcnt vmcnt(" #n ")" ::: "memory")
; #define PG8_WAIT_L(n) asm volatile("s_waitcnt lgkmcnt(" #n ")" ::: "memory")
; #define PG8_BAR __builtin_amdgcn_s_barrier()
; #define PG8_SCHED __builtin_amdgcn_sched_barrier(0)
; template <class Epi, class Sched, bool ALIGN_EPI = false, bool SP2 = false>
; __device__ __forceinline__ void gemm_phase(PG8_LAS unsigned char* lds, const Gemm g, const Sched& S, const Epi& E) {
;     ...
;             PG8_WAIT_V(8); PG8_WAIT_L(0); PG8_BAR; PG8_MMA(1, 0, At, B0); PG8_MMA(1, 1, At, B1); PG8_BAR; PG8_SCHED;
;             PG8_LDB(B0, 1, 0); PG8_LDB(B1, 1, 1); PG8_SCHED; PG8_LDA(At, 1, 0); PG8_STAGE(PG8_SA(0, 1), a2 + hstep, voffA);
;             PG8_WAIT_V(8); PG8_WAIT_L(0); PG8_BAR; PG8_MMA(0, 0, At, B0); PG8_MMA(0, 1, At, B1); PG8_BAR; PG8_SCHED;
	v_mfma_f32_16x16x32_bf16 v[60:63], v[128:131], v[160:163], 0
	v_mfma_f32_16x16x32_bf16 v[56:59], v[136:139], v[160:163], 0
	v_mfma_f32_16x16x32_bf16 v[52:55], v[128:131], v[230:233], 0
	v_mfma_f32_16x16x32_bf16 v[44:47], v[136:139], v[230:233], 0
	v_mfma_f32_16x16x32_bf16 v[36:39], v[128:131], v[238:241], 0
	v_mfma_f32_16x16x32_bf16 v[28:31], v[136:139], v[238:241], 0
	v_mfma_f32_16x16x32_bf16 v[20:23], v[128:131], v[246:249], 0
	v_mfma_f32_16x16x32_bf16 v[12:15], v[136:139], v[246:249], 0
	v_mfma_f32_16x16x32_bf16 v[60:63], v[132:135], v[226:229], v[60:63]
	v_mfma_f32_16x16x32_bf16 v[56:59], v[178:181], v[226:229], v[56:59]
	v_mfma_f32_16x16x32_bf16 v[52:55], v[132:135], v[234:237], v[52:55]
	v_mfma_f32_16x16x32_bf16 v[44:47], v[178:181], v[234:237], v[44:47]
	v_mfma_f32_16x16x32_bf16 v[36:39], v[132:135], v[242:245], v[36:39]
	v_mfma_f32_16x16x32_bf16 v[28:31], v[178:181], v[242:245], v[28:31]
	v_mfma_f32_16x16x32_bf16 v[20:23], v[132:135], v[250:253], v[20:23]
	v_mfma_f32_16x16x32_bf16 v[12:15], v[178:181], v[250:253], v[12:15]
	v_mfma_f32_16x16x32_bf16 v[48:51], v[182:185], v[160:163], 0
	v_mfma_f32_16x16x32_bf16 v[40:43], v[190:193], v[160:163], 0
	v_mfma_f32_16x16x32_bf16 v[32:35], v[182:185], v[230:233], 0
	v_mfma_f32_16x16x32_bf16 v[24:27], v[190:193], v[230:233], 0
	v_mfma_f32_16x16x32_bf16 v[16:19], v[182:185], v[238:241], 0
	v_mfma_f32_16x16x32_bf16 v[8:11], v[190:193], v[238:241], 0
	v_mfma_f32_16x16x32_bf16 v[4:7], v[182:185], v[246:249], 0
	v_mfma_f32_16x16x32_bf16 v[0:3], v[190:193], v[246:249], 0
	v_mfma_f32_16x16x32_bf16 v[48:51], v[186:189], v[226:229], v[48:51]
	v_mfma_f32_16x16x32_bf16 v[40:43], v[222:225], v[226:229], v[40:43]
	v_mfma_f32_16x16x32_bf16 v[32:35], v[186:189], v[234:237], v[32:35]
	v_mfma_f32_16x16x32_bf16 v[24:27], v[222:225], v[234:237], v[24:27]
	v_mfma_f32_16x16x32_bf16 v[16:19], v[186:189], v[242:245], v[16:19]
	v_mfma_f32_16x16x32_bf16 v[8:11], v[222:225], v[242:245], v[8:11]
	v_mfma_f32_16x16x32_bf16 v[4:7], v[186:189], v[250:253], v[4:7]
	v_mfma_f32_16x16x32_bf16 v[0:3], v[222:225], v[250:253], v[0:3]
	s_barrier
	s_setprio 0
	s_add_i32 s48, 0, 0x18000
	v_add_u32_e32 v148, s48, v159
	s_add_i32 s49, 0, 0x1c000
	ds_read_b128 v[128:131], v148
	ds_read_b128 v[132:135], v148 offset:1024
	ds_read_b128 v[136:139], v148 offset:2048
	ds_read_b128 v[160:163], v148 offset:3072
	v_add_u32_e32 v148, s49, v159
	ds_read_b128 v[178:181], v148
	ds_read_b128 v[182:185], v148 offset:1024
	ds_read_b128 v[186:189], v148 offset:2048
	ds_read_b128 v[190:193], v148 offset:3072
	s_add_u32 s30, s30, 0x80000
	s_addc_u32 s31, s31, 0
	s_mov_b32 m0, s39
	ds_read_b128 v[222:225], v211 offset:32768
	ds_read_b128 v[226:229], v211 offset:33792
	ds_read_b128 v[230:233], v211 offset:34816
	ds_read_b128 v[234:237], v211 offset:35840
	ds_read_b128 v[238:241], v211 offset:36864
	ds_read_b128 v[242:245], v211 offset:37888
	ds_read_b128 v[246:249], v211 offset:38912
	ds_read_b128 v[250:253], v211 offset:39936
	global_load_lds_dwordx4 v140, s[30:31]
	s_mov_b32 m0, s42
	v_lshl_add_u64 v[154:155], s[30:31], 0, v[144:145]
	global_load_lds_dwordx4 v[154:155], off
	s_waitcnt vmcnt(8) lgkmcnt(0)
	s_setprio 1
	s_barrier
	v_mfma_f32_16x16x32_bf16 v[124:127], v[128:131], v[222:225], v[124:127]
	v_mfma_f32_16x16x32_bf16 v[120:123], v[136:139], v[222:225], v[120:123]
	v_mfma_f32_16x16x32_bf16 v[116:119], v[128:131], v[230:233], v[116:119]
	v_mfma_f32_16x16x32_bf16 v[108:111], v[136:139], v[230:233], v[108:111]
	v_mfma_f32_16x16x32_bf16 v[100:103], v[128:131], v[238:241], v[100:103]
	v_mfma_f32_16x16x32_bf16 v[92:95], v[136:139], v[238:241], v[92:95]
	v_mfma_f32_16x16x32_bf16 v[84:87], v[128:131], v[246:249], v[84:87]
	v_mfma_f32_16x16x32_bf16 v[76:79], v[136:139], v[246:249], v[76:79]
	v_mfma_f32_16x16x32_bf16 v[124:127], v[132:135], v[226:229], v[124:127]
	v_mfma_f32_16x16x32_bf16 v[120:123], v[160:163], v[226:229], v[120:123]
	v_mfma_f32_16x16x32_bf16 v[116:119], v[132:135], v[234:237], v[116:119]
	v_mfma_f32_16x16x32_bf16 v[108:111], v[160:163], v[234:237], v[108:111]
	v_mfma_f32_16x16x32_bf16 v[100:103], v[132:135], v[242:245], v[100:103]
	v_mfma_f32_16x16x32_bf16 v[92:95], v[160:163], v[242:245], v[92:95]
	v_mfma_f32_16x16x32_bf16 v[84:87], v[132:135], v[250:253], v[84:87]
	v_mfma_f32_16x16x32_bf16 v[76:79], v[160:163], v[250:253], v[76:79]
	v_mfma_f32_16x16x32_bf16 v[112:115], v[178:181], v[222:225], v[112:115]
	v_mfma_f32_16x16x32_bf16 v[104:107], v[186:189], v[222:225], v[104:107]
	v_mfma_f32_16x16x32_bf16 v[96:99], v[178:181], v[230:233], v[96:99]
	v_mfma_f32_16x16x32_bf16 v[88:91], v[186:189], v[230:233], v[88:91]
	v_mfma_f32_16x16x32_bf16 v[80:83], v[178:181], v[238:241], v[80:83]
	v_mfma_f32_16x16x32_bf16 v[72:75], v[186:189], v[238:241], v[72:75]
	v_mfma_f32_16x16x32_bf16 v[68:71], v[178:181], v[246:249], v[68:71]
	v_mfma_f32_16x16x32_bf16 v[64:67], v[186:189], v[246:249], v[64:67]
	v_mfma_f32_16x16x32_bf16 v[112:115], v[182:185], v[226:229], v[112:115]
	v_mfma_f32_16x16x32_bf16 v[104:107], v[190:193], v[226:229], v[104:107]
	v_mfma_f32_16x16x32_bf16 v[96:99], v[182:185], v[234:237], v[96:99]
	v_mfma_f32_16x16x32_bf16 v[88:91], v[190:193], v[234:237], v[88:91]
	v_mfma_f32_16x16x32_bf16 v[80:83], v[182:185], v[242:245], v[80:83]
	v_mfma_f32_16x16x32_bf16 v[72:75], v[190:193], v[242:245], v[72:75]
	v_mfma_f32_16x16x32_bf16 v[68:71], v[182:185], v[250:253], v[68:71]
	v_mfma_f32_16x16x32_bf16 v[64:67], v[190:193], v[250:253], v[64:67]
	s_barrier
; #define PG8_STAGE(bufoff, gbase, voff) do { _Pragma("unroll") for (int _i = 0; _i < 2; ++_i) \
;         __builtin_amdgcn_global_load_lds((const unsigned*)((const char*)(gbase) + (voff)[_i]), (PG8_LAS unsigned*)(lds + (bufoff) + ldsw + _i * 8192), 16, 0, 0); } while (0)
; #define PG8_LDA(dst, b, h) do { _Pragma("unroll") for (int m = 0; m < 4; ++m) _Pragma("unroll") for (int k = 0; k < 2; ++k) dst[m][k] = *(const PG8_LAS bf16x8*)(lds + PG8_SA(b, h) + aoff + m * 2048 + k * 1024); } while (0)
; #define PG8_LDB(dst, b, h) do { _Pragma("unroll") for (int n = 0; n < 2; ++n) _Pragma("unroll") for (int k = 0; k < 2; ++k) dst[n][k] = *(const PG8_LAS bf16x8*)(lds + PG8_SB(b, h) + boff + n * 2048 + k * 1024); } while (0)
; #define PG8_MMA(ai, bj, At, Bt) do { __builtin_amdgcn_s_setprio(1); _Pragma("unroll") for (int m = 0; m < 4; ++m) _Pragma("unroll") for (int n = 0; n < 2; ++n) _Pragma("unroll") for (int k = 0; k < 2; ++k) \
;         acc[ai][bj][m][n] = __builtin_amdgcn_mfma_f32_16x16x32_bf16(Bt[n][k], At[m][k], acc[ai][bj][m][n], 0, 0, 0); __builtin_amdgcn_s_setprio(0); } while (0)
; #define PG8_WAIT_V(n) asm volatile("s_waitcnt vmcnt(" #n ")" ::: "memory")
; #define PG8_BAR __builtin_amdgcn_s_barrier()
; template <class Epi, class Sched, bool ALIGN_EPI = false, bool SP2 = false>
; __device__ __forceinline__ void gemm_phase(PG8_LAS unsigned char* lds, const Gemm g, const Sched& S, const Epi& E) {
;     ...
;         for (int t = 0; t < nt; t += 2) {
;             const bool last = (t == nt - 2);
;             const char* a1 = cA + (size_t)(t + 1) * kstep;
;             const char* a2 = last ? nA : cA + (size_t)(t + 2) * kstep; const char* b2 = last ? nB : cB + (size_t)(t + 2) * kstep;
;             const char* a3 = a2 + kstep; const char* b3 = b2 + kstep;
;             if (last && has_next) S.a_ready(nxt);
;             if constexpr (SP2) {
;             PG8_LDB(B0, 0, 0); PG8_LDB(B1, 0, 1); PG8_SCHED; PG8_LDA(At, 0, 0); PG8_STAGE(PG8_SA(1, 1), a1 + hstep, voffA);
;             PG8_WAIT_V(8); PG8_WAIT_L(0); PG8_BAR; PG8_MMA(0, 0, At, B0); PG8_MMA(0, 1, At, B1); PG8_BAR; PG8_SCHED;
;     ...
;             PG8_LDA(At, 1, 1); PG8_STAGE(PG8_SB(1, 0), b3, voffB); PG8_STAGE(PG8_SB(1, 1), b3 + hstep, voffB); PG8_STAGE(PG8_SA(1, 0), a3, voffA);
;             PG8_WAIT_V(8); PG8_WAIT_L(0); PG8_BAR; PG8_MMA(1, 0, At, B0); PG8_MMA(1, 1, At, B1); PG8_BAR; PG8_SCHED;
	s_setprio 0
	v_lshl_add_u64 v[154:155], v[166:167], 0, s[10:11]
	s_mov_b32 m0, s100
	ds_read_b128 v[222:225], v211 offset:49152
	ds_read_b128 v[226:229], v211 offset:50176
	ds_read_b128 v[230:233], v211 offset:51200
	ds_read_b128 v[234:237], v211 offset:52224
	ds_read_b128 v[238:241], v211 offset:53248
	ds_read_b128 v[242:245], v211 offset:54272
	ds_read_b128 v[246:249], v211 offset:55296
	ds_read_b128 v[250:253], v211 offset:56320
	global_load_lds_dwordx4 v[154:155], off
	s_add_i32 m0, s100, 0x2000
	s_add_u32 s28, s28, 0x80080
	v_lshl_add_u64 v[154:155], v[170:171], 0, s[10:11]
	s_addc_u32 s29, s29, 0
	global_load_lds_dwordx4 v[154:155], off
	s_mov_b32 m0, s101
	s_nop 0
	global_load_lds_dwordx4 v142, s[28:29]
	s_add_i32 m0, s101, 0x2000
	v_lshl_add_u64 v[154:155], s[28:29], 0, v[146:147]
	global_load_lds_dwordx4 v[154:155], off
	s_mov_b32 m0, s46
	v_lshl_add_u64 v[154:155], v[174:175], 0, s[10:11]
	global_load_lds_dwordx4 v[154:155], off
	s_mov_b32 m0, s47
	v_lshl_add_u64 v[154:155], v[194:195], 0, s[10:11]
	global_load_lds_dwordx4 v[154:155], off
	s_waitcnt vmcnt(8) lgkmcnt(0)
	s_setprio 1
	s_barrier
	v_mfma_f32_16x16x32_bf16 v[60:63], v[128:131], v[222:225], v[60:63]
	v_mfma_f32_16x16x32_bf16 v[56:59], v[136:139], v[222:225], v[56:59]
	v_mfma_f32_16x16x32_bf16 v[52:55], v[128:131], v[230:233], v[52:55]
	v_mfma_f32_16x16x32_bf16 v[44:47], v[136:139], v[230:233], v[44:47]
	v_mfma_f32_16x16x32_bf16 v[36:39], v[128:131], v[238:241], v[36:39]
	v_mfma_f32_16x16x32_bf16 v[28:31], v[136:139], v[238:241], v[28:31]
	v_mfma_f32_16x16x32_bf16 v[20:23], v[128:131], v[246:249], v[20:23]
	v_mfma_f32_16x16x32_bf16 v[12:15], v[136:139], v[246:249], v[12:15]
	v_mfma_f32_16x16x32_bf16 v[60:63], v[132:135], v[226:229], v[60:63]
	v_mfma_f32_16x16x32_bf16 v[56:59], v[160:163], v[226:229], v[56:59]
	v_mfma_f32_16x16x32_bf16 v[52:55], v[132:135], v[234:237], v[52:55]
	v_mfma_f32_16x16x32_bf16 v[44:47], v[160:163], v[234:237], v[44:47]
	v_mfma_f32_16x16x32_bf16 v[36:39], v[132:135], v[242:245], v[36:39]
	v_mfma_f32_16x16x32_bf16 v[28:31], v[160:163], v[242:245], v[28:31]
	v_mfma_f32_16x16x32_bf16 v[20:23], v[132:135], v[250:253], v[20:23]
	v_mfma_f32_16x16x32_bf16 v[12:15], v[160:163], v[250:253], v[12:15]
	v_mfma_f32_16x16x32_bf16 v[48:51], v[178:181], v[222:225], v[48:51]
	v_mfma_f32_16x16x32_bf16 v[40:43], v[186:189], v[222:225], v[40:43]
	v_mfma_f32_16x16x32_bf16 v[32:35], v[178:181], v[230:233], v[32:35]
	v_mfma_f32_16x16x32_bf16 v[24:27], v[186:189], v[230:233], v[24:27]
	v_mfma_f32_16x16x32_bf16 v[16:19], v[178:181], v[238:241], v[16:19]
	v_mfma_f32_16x16x32_bf16 v[8:11], v[186:189], v[238:241], v[8:11]
	v_mfma_f32_16x16x32_bf16 v[4:7], v[178:181], v[246:249], v[4:7]
	v_mfma_f32_16x16x32_bf16 v[0:3], v[186:189], v[246:249], v[0:3]
	v_mfma_f32_16x16x32_bf16 v[48:51], v[182:185], v[226:229], v[48:51]
	v_mfma_f32_16x16x32_bf16 v[40:43], v[190:193], v[226:229], v[40:43]
	v_mfma_f32_16x16x32_bf16 v[32:35], v[182:185], v[234:237], v[32:35]
	v_mfma_f32_16x16x32_bf16 v[24:27], v[190:193], v[234:237], v[24:27]
	v_mfma_f32_16x16x32_bf16 v[16:19], v[182:185], v[242:245], v[16:19]
	v_mfma_f32_16x16x32_bf16 v[8:11], v[190:193], v[242:245], v[8:11]
	v_mfma_f32_16x16x32_bf16 v[4:7], v[182:185], v[250:253], v[4:7]
	v_mfma_f32_16x16x32_bf16 v[0:3], v[190:193], v[250:253], v[0:3]
	s_barrier
	s_setprio 0
	s_add_i32 s45, s45, 2
	s_add_u32 s26, s26, 0x100
	s_addc_u32 s27, s27, 0
	s_add_u32 s33, s33, 0x100
	s_addc_u32 s44, s44, 0
.LBB0_955:
	ds_read_b128 v[128:131], v209
	ds_read_b128 v[132:135], v209 offset:1024
	ds_read_b128 v[136:139], v209 offset:2048
	ds_read_b128 v[178:181], v209 offset:3072
	ds_read_b128 v[182:185], v210
	ds_read_b128 v[186:189], v210 offset:1024
	ds_read_b128 v[190:193], v210 offset:2048
	ds_read_b128 v[222:225], v210 offset:3072
	s_add_u32 s28, s26, 0xfff80080
	s_addc_u32 s29, s27, -1
	s_cmp_eq_u32 s45, 28
	s_cselect_b32 s31, s1, s29
	s_cselect_b32 s30, s5, s28
	s_cselect_b32 s29, s17, s44
	s_cselect_b32 s28, s19, s33
	s_add_i32 m0, s35, 0xc000
	ds_read_b128 v[226:229], v211
	ds_read_b128 v[230:233], v211 offset:1024
	ds_read_b128 v[234:237], v211 offset:2048
	ds_read_b128 v[238:241], v211 offset:3072
	ds_read_b128 v[242:245], v211 offset:4096
	ds_read_b128 v[246:249], v211 offset:5120
	ds_read_b128 v[250:253], v211 offset:6144
	ds_read_b128 v[160:163], v211 offset:7168
	global_load_lds_dwordx4 v150, s[26:27]
	s_add_i32 m0, s35, 0xe000
	s_nop 0
	global_load_lds_dwordx4 v152, s[26:27]
	s_waitcnt vmcnt(8) lgkmcnt(0)
	s_setprio 1
	s_barrier
; #define PG8_STAGE(bufoff, gbase, voff) do { _Pragma("unroll") for (int _i = 0; _i < 2; ++_i) \
;         __builtin_amdgcn_global_load_lds((const unsigned*)((const char*)(gbase) + (voff)[_i]), (PG8_LAS unsigned*)(lds + (bufoff) + ldsw + _i * 8192), 16, 0, 0); } while (0)
; #define PG8_LDA(dst, b, h) do { _Pragma("unroll") for (int m = 0; m < 4; ++m) _Pragma("unroll") for (int k = 0; k < 2; ++k) dst[m][k] = *(const PG8_LAS bf16x8*)(lds + PG8_SA(b, h) + aoff + m * 2048 + k * 1024); } while (0)
; #define PG8_MMA(ai, bj, At, Bt) do { __builtin_amdgcn_s_setprio(1); _Pragma("unroll") for (int m = 0; m < 4; ++m) _Pragma("unroll") for (int n = 0; n < 2; ++n) _Pragma("unroll") for (int k = 0; k < 2; ++k) \
;         acc[ai][bj][m][n] = __builtin_amdgcn_mfma_f32_16x16x32_bf16(Bt[n][k], At[m][k], acc[ai][bj][m][n], 0, 0, 0); __builtin_amdgcn_s_setprio(0); } while (0)
; #define PG8_WAIT_V(n) asm volatile("s_waitcnt vmcnt(" #n ")" ::: "memory")
; #define PG8_WAIT_L(n) asm volatile("s_waitcnt lgkmcnt(" #n ")" ::: "memory")
; #define PG8_BAR __builtin_amdgcn_s_barrier()
; #define PG8_SCHED __builtin_amdgcn_sched_barrier(0)
; template <class Epi, class Sched, bool ALIGN_EPI = false, bool SP2 = false>
; __device__ __forceinline__ void gemm_phase(PG8_LAS unsigned char* lds, const Gemm g, const Sched& S, const Epi& E) {
;     ...
;             PG8_WAIT_V(8); PG8_WAIT_L(0); PG8_BAR; PG8_MMA(0, 0, At, B0); PG8_MMA(0, 1, At, B1); PG8_BAR; PG8_SCHED;
;             PG8_LDA(At, 0, 1); PG8_STAGE(PG8_SB(0, 0), b2, voffB); PG8_STAGE(PG8_SB(0, 1), b2 + hstep, voffB); PG8_STAGE(PG8_SA(0, 0), a2, voffA);
;             PG8_WAIT_V(8); PG8_WAIT_L(0); PG8_BAR; PG8_MMA(1, 0, At, B0); PG8_MMA(1, 1, At, B1); PG8_BAR; PG8_SCHED;
	v_mfma_f32_16x16x32_bf16 v[124:127], v[128:131], v[226:229], v[124:127]
	v_mfma_f32_16x16x32_bf16 v[120:123], v[136:139], v[226:229], v[120:123]
	v_mfma_f32_16x16x32_bf16 v[116:119], v[128:131], v[234:237], v[116:119]
	v_mfma_f32_16x16x32_bf16 v[108:111], v[136:139], v[234:237], v[108:111]
	v_mfma_f32_16x16x32_bf16 v[100:103], v[128:131], v[242:245], v[100:103]
	v_mfma_f32_16x16x32_bf16 v[92:95], v[136:139], v[242:245], v[92:95]
	v_mfma_f32_16x16x32_bf16 v[84:87], v[128:131], v[250:253], v[84:87]
	v_mfma_f32_16x16x32_bf16 v[76:79], v[136:139], v[250:253], v[76:79]
	v_mfma_f32_16x16x32_bf16 v[124:127], v[132:135], v[230:233], v[124:127]
	v_mfma_f32_16x16x32_bf16 v[120:123], v[178:181], v[230:233], v[120:123]
	v_mfma_f32_16x16x32_bf16 v[116:119], v[132:135], v[238:241], v[116:119]
	v_mfma_f32_16x16x32_bf16 v[108:111], v[178:181], v[238:241], v[108:111]
	v_mfma_f32_16x16x32_bf16 v[100:103], v[132:135], v[246:249], v[100:103]
	v_mfma_f32_16x16x32_bf16 v[92:95], v[178:181], v[246:249], v[92:95]
	v_mfma_f32_16x16x32_bf16 v[84:87], v[132:135], v[160:163], v[84:87]
	v_mfma_f32_16x16x32_bf16 v[76:79], v[178:181], v[160:163], v[76:79]
	v_mfma_f32_16x16x32_bf16 v[112:115], v[182:185], v[226:229], v[112:115]
	v_mfma_f32_16x16x32_bf16 v[104:107], v[190:193], v[226:229], v[104:107]
	v_mfma_f32_16x16x32_bf16 v[96:99], v[182:185], v[234:237], v[96:99]
	v_mfma_f32_16x16x32_bf16 v[88:91], v[190:193], v[234:237], v[88:91]
	v_mfma_f32_16x16x32_bf16 v[80:83], v[182:185], v[242:245], v[80:83]
	v_mfma_f32_16x16x32_bf16 v[72:75], v[190:193], v[242:245], v[72:75]
	v_mfma_f32_16x16x32_bf16 v[68:71], v[182:185], v[250:253], v[68:71]
	v_mfma_f32_16x16x32_bf16 v[64:67], v[190:193], v[250:253], v[64:67]
	v_mfma_f32_16x16x32_bf16 v[112:115], v[186:189], v[230:233], v[112:115]
	v_mfma_f32_16x16x32_bf16 v[104:107], v[222:225], v[230:233], v[104:107]
	v_mfma_f32_16x16x32_bf16 v[96:99], v[186:189], v[238:241], v[96:99]
	v_mfma_f32_16x16x32_bf16 v[88:91], v[222:225], v[238:241], v[88:91]
	v_mfma_f32_16x16x32_bf16 v[80:83], v[186:189], v[246:249], v[80:83]
	v_mfma_f32_16x16x32_bf16 v[72:75], v[222:225], v[246:249], v[72:75]
	v_mfma_f32_16x16x32_bf16 v[68:71], v[186:189], v[160:163], v[68:71]
	v_mfma_f32_16x16x32_bf16 v[64:67], v[222:225], v[160:163], v[64:67]
	s_barrier
	s_setprio 0
	v_lshl_add_u64 v[166:167], s[28:29], 0, v[142:143]
	s_mov_b32 m0, s98
	ds_read_b128 v[160:163], v211 offset:16384
	ds_read_b128 v[226:229], v211 offset:17408
	ds_read_b128 v[230:233], v211 offset:18432
	ds_read_b128 v[234:237], v211 offset:19456
	ds_read_b128 v[238:241], v211 offset:20480
	ds_read_b128 v[242:245], v211 offset:21504
	ds_read_b128 v[246:249], v211 offset:22528
	ds_read_b128 v[250:253], v211 offset:23552
	global_load_lds_dwordx4 v[166:167], off
	s_add_i32 m0, s98, 0x2000
	s_add_u32 s48, s28, 0x80000
	v_lshl_add_u64 v[170:171], s[28:29], 0, v[146:147]
	s_addc_u32 s49, s29, 0
	global_load_lds_dwordx4 v[170:171], off
	s_mov_b32 m0, s99
	v_lshl_add_u64 v[194:195], s[30:31], 0, v[144:145]
	global_load_lds_dwordx4 v142, s[48:49]
	s_add_i32 m0, s99, 0x2000
	s_nop 0
	global_load_lds_dwordx4 v146, s[48:49]
	s_mov_b32 m0, s35
	v_lshl_add_u64 v[174:175], s[30:31], 0, v[140:141]
	global_load_lds_dwordx4 v[174:175], off
	s_mov_b32 m0, s37
	s_nop 0
	global_load_lds_dwordx4 v[194:195], off
	s_waitcnt vmcnt(8) lgkmcnt(0)
	s_setprio 1
	s_barrier
	v_mfma_f32_16x16x32_bf16 v[60:63], v[128:131], v[160:163], v[60:63]
	v_mfma_f32_16x16x32_bf16 v[56:59], v[136:139], v[160:163], v[56:59]
	v_mfma_f32_16x16x32_bf16 v[52:55], v[128:131], v[230:233], v[52:55]
	v_mfma_f32_16x16x32_bf16 v[44:47], v[136:139], v[230:233], v[44:47]
	v_mfma_f32_16x16x32_bf16 v[36:39], v[128:131], v[238:241], v[36:39]
	v_mfma_f32_16x16x32_bf16 v[28:31], v[136:139], v[238:241], v[28:31]
	v_mfma_f32_16x16x32_bf16 v[20:23], v[128:131], v[246:249], v[20:23]
	v_mfma_f32_16x16x32_bf16 v[12:15], v[136:139], v[246:249], v[12:15]
	v_mfma_f32_16x16x32_bf16 v[60:63], v[132:135], v[226:229], v[60:63]
	v_mfma_f32_16x16x32_bf16 v[56:59], v[178:181], v[226:229], v[56:59]
	v_mfma_f32_16x16x32_bf16 v[52:55], v[132:135], v[234:237], v[52:55]
	v_mfma_f32_16x16x32_bf16 v[44:47], v[178:181], v[234:237], v[44:47]
	v_mfma_f32_16x16x32_bf16 v[36:39], v[132:135], v[242:245], v[36:39]
	v_mfma_f32_16x16x32_bf16 v[28:31], v[178:181], v[242:245], v[28:31]
	v_mfma_f32_16x16x32_bf16 v[20:23], v[132:135], v[250:253], v[20:23]
	v_mfma_f32_16x16x32_bf16 v[12:15], v[178:181], v[250:253], v[12:15]
	v_mfma_f32_16x16x32_bf16 v[48:51], v[182:185], v[160:163], v[48:51]
	v_mfma_f32_16x16x32_bf16 v[40:43], v[190:193], v[160:163], v[40:43]
	v_mfma_f32_16x16x32_bf16 v[32:35], v[182:185], v[230:233], v[32:35]
	v_mfma_f32_16x16x32_bf16 v[24:27], v[190:193], v[230:233], v[24:27]
	v_mfma_f32_16x16x32_bf16 v[16:19], v[182:185], v[238:241], v[16:19]
	v_mfma_f32_16x16x32_bf16 v[8:11], v[190:193], v[238:241], v[8:11]
	v_mfma_f32_16x16x32_bf16 v[4:7], v[182:185], v[246:249], v[4:7]
	v_mfma_f32_16x16x32_bf16 v[0:3], v[190:193], v[246:249], v[0:3]
	v_mfma_f32_16x16x32_bf16 v[48:51], v[186:189], v[226:229], v[48:51]
	v_mfma_f32_16x16x32_bf16 v[40:43], v[222:225], v[226:229], v[40:43]
	v_mfma_f32_16x16x32_bf16 v[32:35], v[186:189], v[234:237], v[32:35]
	v_mfma_f32_16x16x32_bf16 v[24:27], v[222:225], v[234:237], v[24:27]
	v_mfma_f32_16x16x32_bf16 v[16:19], v[186:189], v[242:245], v[16:19]
	v_mfma_f32_16x16x32_bf16 v[8:11], v[222:225], v[242:245], v[8:11]
	v_mfma_f32_16x16x32_bf16 v[4:7], v[186:189], v[250:253], v[4:7]
	v_mfma_f32_16x16x32_bf16 v[0:3], v[222:225], v[250:253], v[0:3]
	s_barrier
; #define PG8_STAGE(bufoff, gbase, voff) do { _Pragma("unroll") for (int _i = 0; _i < 2; ++_i) \
;         __builtin_amdgcn_global_load_lds((const unsigned*)((const char*)(gbase) + (voff)[_i]), (PG8_LAS unsigned*)(lds + (bufoff) + ldsw + _i * 8192), 16, 0, 0); } while (0)
; #define PG8_LDA(dst, b, h) do { _Pragma("unroll") for (int m = 0; m < 4; ++m) _Pragma("unroll") for (int k = 0; k < 2; ++k) dst[m][k] = *(const PG8_LAS bf16x8*)(lds + PG8_SA(b, h) + aoff + m * 2048 + k * 1024); } while (0)
; #define PG8_LDB(dst, b, h) do { _Pragma("unroll") for (int n = 0; n < 2; ++n) _Pragma("unroll") for (int k = 0; k < 2; ++k) dst[n][k] = *(const PG8_LAS bf16x8*)(lds + PG8_SB(b, h) + boff + n * 2048 + k * 1024); } while (0)
; #define PG8_MMA(ai, bj, At, Bt) do { __builtin_amdgcn_s_setprio(1); _Pragma("unroll") for (int m = 0; m < 4; ++m) _Pragma("unroll") for (int n = 0; n < 2; ++n) _Pragma("unroll") for (int k = 0; k < 2; ++k) \
;         acc[ai][bj][m][n] = __builtin_amdgcn_mfma_f32_16x16x32_bf16(Bt[n][k], At[m][k], acc[ai][bj][m][n], 0, 0, 0); __builtin_amdgcn_s_setprio(0); } while (0)
; #define PG8_WAIT_V(n) asm volatile("s_waitcnt vmcnt(" #n ")" ::: "memory")
; #define PG8_WAIT_L(n) asm volatile("s_waitcnt lgkmcnt(" #n ")" ::: "memory")
; #define PG8_BAR __builtin_amdgcn_s_barrier()
; #define PG8_SCHED __builtin_amdgcn_sched_barrier(0)
; template <class Epi, class Sched, bool ALIGN_EPI = false, bool SP2 = false>
; __device__ __forceinline__ void gemm_phase(PG8_LAS unsigned char* lds, const Gemm g, const Sched& S, const Epi& E) {
;     ...
;             PG8_LDB(B0, 1, 0); PG8_LDB(B1, 1, 1); PG8_SCHED; PG8_LDA(At, 1, 0); PG8_STAGE(PG8_SA(0, 1), a2 + hstep, voffA);
;             PG8_WAIT_V(8); PG8_WAIT_L(0); PG8_BAR; PG8_MMA(0, 0, At, B0); PG8_MMA(0, 1, At, B1); PG8_BAR; PG8_SCHED;
;             PG8_LDA(At, 1, 1); PG8_STAGE(PG8_SB(1, 0), b3, voffB); PG8_STAGE(PG8_SB(1, 1), b3 + hstep, voffB); PG8_STAGE(PG8_SA(1, 0), a3, voffA);
;             PG8_WAIT_V(8); PG8_WAIT_L(0); PG8_BAR; PG8_MMA(1, 0, At, B0); PG8_MMA(1, 1, At, B1); PG8_BAR; PG8_SCHED;
;     ...
;         if constexpr (ALIGN_EPI) { if (wr == 0) PG8_BAR; }
	s_setprio 0
	s_add_i32 s48, 0, 0x18000
	v_add_u32_e32 v148, s48, v159
	s_add_i32 s49, 0, 0x1c000
	ds_read_b128 v[128:131], v148
	ds_read_b128 v[132:135], v148 offset:1024
	ds_read_b128 v[136:139], v148 offset:2048
	ds_read_b128 v[160:163], v148 offset:3072
	v_add_u32_e32 v148, s49, v159
	ds_read_b128 v[178:181], v148
	ds_read_b128 v[182:185], v148 offset:1024
	ds_read_b128 v[186:189], v148 offset:2048
	ds_read_b128 v[190:193], v148 offset:3072
	s_add_u32 s30, s30, 0x80000
	s_addc_u32 s31, s31, 0
	s_mov_b32 m0, s39
	ds_read_b128 v[222:225], v211 offset:32768
	ds_read_b128 v[226:229], v211 offset:33792
	ds_read_b128 v[230:233], v211 offset:34816
	ds_read_b128 v[234:237], v211 offset:35840
	ds_read_b128 v[238:241], v211 offset:36864
	ds_read_b128 v[242:245], v211 offset:37888
	ds_read_b128 v[246:249], v211 offset:38912
	ds_read_b128 v[250:253], v211 offset:39936
	global_load_lds_dwordx4 v140, s[30:31]
	s_mov_b32 m0, s42
	v_lshl_add_u64 v[154:155], s[30:31], 0, v[144:145]
	global_load_lds_dwordx4 v[154:155], off
	s_waitcnt vmcnt(8) lgkmcnt(0)
	s_setprio 1
	s_barrier
	v_mfma_f32_16x16x32_bf16 v[124:127], v[128:131], v[222:225], v[124:127]
	v_mfma_f32_16x16x32_bf16 v[120:123], v[136:139], v[222:225], v[120:123]
	v_mfma_f32_16x16x32_bf16 v[116:119], v[128:131], v[230:233], v[116:119]
	v_mfma_f32_16x16x32_bf16 v[108:111], v[136:139], v[230:233], v[108:111]
	v_mfma_f32_16x16x32_bf16 v[100:103], v[128:131], v[238:241], v[100:103]
	v_mfma_f32_16x16x32_bf16 v[92:95], v[136:139], v[238:241], v[92:95]
	v_mfma_f32_16x16x32_bf16 v[84:87], v[128:131], v[246:249], v[84:87]
	v_mfma_f32_16x16x32_bf16 v[76:79], v[136:139], v[246:249], v[76:79]
	v_mfma_f32_16x16x32_bf16 v[124:127], v[132:135], v[226:229], v[124:127]
	v_mfma_f32_16x16x32_bf16 v[120:123], v[160:163], v[226:229], v[120:123]
	v_mfma_f32_16x16x32_bf16 v[116:119], v[132:135], v[234:237], v[116:119]
	v_mfma_f32_16x16x32_bf16 v[108:111], v[160:163], v[234:237], v[108:111]
	v_mfma_f32_16x16x32_bf16 v[100:103], v[132:135], v[242:245], v[100:103]
	v_mfma_f32_16x16x32_bf16 v[92:95], v[160:163], v[242:245], v[92:95]
	v_mfma_f32_16x16x32_bf16 v[84:87], v[132:135], v[250:253], v[84:87]
	v_mfma_f32_16x16x32_bf16 v[76:79], v[160:163], v[250:253], v[76:79]
	v_mfma_f32_16x16x32_bf16 v[112:115], v[178:181], v[222:225], v[112:115]
	v_mfma_f32_16x16x32_bf16 v[104:107], v[186:189], v[222:225], v[104:107]
	v_mfma_f32_16x16x32_bf16 v[96:99], v[178:181], v[230:233], v[96:99]
	v_mfma_f32_16x16x32_bf16 v[88:91], v[186:189], v[230:233], v[88:91]
	v_mfma_f32_16x16x32_bf16 v[80:83], v[178:181], v[238:241], v[80:83]
	v_mfma_f32_16x16x32_bf16 v[72:75], v[186:189], v[238:241], v[72:75]
	v_mfma_f32_16x16x32_bf16 v[68:71], v[178:181], v[246:249], v[68:71]
	v_mfma_f32_16x16x32_bf16 v[64:67], v[186:189], v[246:249], v[64:67]
	v_mfma_f32_16x16x32_bf16 v[112:115], v[182:185], v[226:229], v[112:115]
	v_mfma_f32_16x16x32_bf16 v[104:107], v[190:193], v[226:229], v[104:107]
	v_mfma_f32_16x16x32_bf16 v[96:99], v[182:185], v[234:237], v[96:99]
	v_mfma_f32_16x16x32_bf16 v[88:91], v[190:193], v[234:237], v[88:91]
	v_mfma_f32_16x16x32_bf16 v[80:83], v[182:185], v[242:245], v[80:83]
	v_mfma_f32_16x16x32_bf16 v[72:75], v[190:193], v[242:245], v[72:75]
	v_mfma_f32_16x16x32_bf16 v[68:71], v[182:185], v[250:253], v[68:71]
	v_mfma_f32_16x16x32_bf16 v[64:67], v[190:193], v[250:253], v[64:67]
	s_barrier
	s_setprio 0
	v_lshl_add_u64 v[154:155], v[166:167], 0, s[10:11]
	s_mov_b32 m0, s100
	ds_read_b128 v[222:225], v211 offset:49152
	ds_read_b128 v[226:229], v211 offset:50176
	ds_read_b128 v[230:233], v211 offset:51200
	ds_read_b128 v[234:237], v211 offset:52224
	ds_read_b128 v[238:241], v211 offset:53248
	ds_read_b128 v[242:245], v211 offset:54272
	ds_read_b128 v[246:249], v211 offset:55296
	ds_read_b128 v[250:253], v211 offset:56320
	global_load_lds_dwordx4 v[154:155], off
	s_add_i32 m0, s100, 0x2000
	s_add_u32 s28, s28, 0x80080
	v_lshl_add_u64 v[154:155], v[170:171], 0, s[10:11]
	s_addc_u32 s29, s29, 0
	global_load_lds_dwordx4 v[154:155], off
	s_mov_b32 m0, s101
	s_nop 0
	global_load_lds_dwordx4 v142, s[28:29]
	s_add_i32 m0, s101, 0x2000
	v_lshl_add_u64 v[154:155], s[28:29], 0, v[146:147]
	global_load_lds_dwordx4 v[154:155], off
	s_mov_b32 m0, s46
	v_lshl_add_u64 v[154:155], v[174:175], 0, s[10:11]
	global_load_lds_dwordx4 v[154:155], off
	s_mov_b32 m0, s47
	v_lshl_add_u64 v[154:155], v[194:195], 0, s[10:11]
	global_load_lds_dwordx4 v[154:155], off
	s_waitcnt vmcnt(8) lgkmcnt(0)
	s_setprio 1
	s_barrier
	v_mfma_f32_16x16x32_bf16 v[60:63], v[128:131], v[222:225], v[60:63]
	v_mfma_f32_16x16x32_bf16 v[56:59], v[136:139], v[222:225], v[56:59]
	v_mfma_f32_16x16x32_bf16 v[52:55], v[128:131], v[230:233], v[52:55]
	v_mfma_f32_16x16x32_bf16 v[44:47], v[136:139], v[230:233], v[44:47]
	v_mfma_f32_16x16x32_bf16 v[36:39], v[128:131], v[238:241], v[36:39]
	v_mfma_f32_16x16x32_bf16 v[28:31], v[136:139], v[238:241], v[28:31]
	v_mfma_f32_16x16x32_bf16 v[20:23], v[128:131], v[246:249], v[20:23]
	v_mfma_f32_16x16x32_bf16 v[12:15], v[136:139], v[246:249], v[12:15]
	v_mfma_f32_16x16x32_bf16 v[60:63], v[132:135], v[226:229], v[60:63]
	v_mfma_f32_16x16x32_bf16 v[56:59], v[160:163], v[226:229], v[56:59]
	v_mfma_f32_16x16x32_bf16 v[52:55], v[132:135], v[234:237], v[52:55]
	v_mfma_f32_16x16x32_bf16 v[44:47], v[160:163], v[234:237], v[44:47]
	v_mfma_f32_16x16x32_bf16 v[36:39], v[132:135], v[242:245], v[36:39]
	v_mfma_f32_16x16x32_bf16 v[28:31], v[160:163], v[242:245], v[28:31]
	v_mfma_f32_16x16x32_bf16 v[20:23], v[132:135], v[250:253], v[20:23]
	v_mfma_f32_16x16x32_bf16 v[12:15], v[160:163], v[250:253], v[12:15]
	v_mfma_f32_16x16x32_bf16 v[48:51], v[178:181], v[222:225], v[48:51]
	v_mfma_f32_16x16x32_bf16 v[40:43], v[186:189], v[222:225], v[40:43]
	v_mfma_f32_16x16x32_bf16 v[32:35], v[178:181], v[230:233], v[32:35]
	v_mfma_f32_16x16x32_bf16 v[24:27], v[186:189], v[230:233], v[24:27]
	v_mfma_f32_16x16x32_bf16 v[16:19], v[178:181], v[238:241], v[16:19]
	v_mfma_f32_16x16x32_bf16 v[8:11], v[186:189], v[238:241], v[8:11]
	v_mfma_f32_16x16x32_bf16 v[4:7], v[178:181], v[246:249], v[4:7]
	v_mfma_f32_16x16x32_bf16 v[0:3], v[186:189], v[246:249], v[0:3]
	v_mfma_f32_16x16x32_bf16 v[48:51], v[182:185], v[226:229], v[48:51]
	v_mfma_f32_16x16x32_bf16 v[40:43], v[190:193], v[226:229], v[40:43]
	v_mfma_f32_16x16x32_bf16 v[32:35], v[182:185], v[234:237], v[32:35]
	v_mfma_f32_16x16x32_bf16 v[24:27], v[190:193], v[234:237], v[24:27]
	v_mfma_f32_16x16x32_bf16 v[16:19], v[182:185], v[242:245], v[16:19]
	v_mfma_f32_16x16x32_bf16 v[8:11], v[190:193], v[242:245], v[8:11]
	v_mfma_f32_16x16x32_bf16 v[4:7], v[182:185], v[250:253], v[4:7]
	v_mfma_f32_16x16x32_bf16 v[0:3], v[190:193], v[250:253], v[0:3]
	s_barrier
	s_setprio 0
	s_add_i32 s45, s45, 2
	s_add_u32 s26, s26, 0x100
	s_addc_u32 s27, s27, 0
	s_add_u32 s33, s33, 0x100
	s_addc_u32 s44, s44, 0
	s_cmp_gt_u32 s45, 29
	s_cbranch_scc0 .LBB0_955
	s_and_b64 vcc, exec, s[12:13]
	s_cbranch_vccz .LBB0_958
	s_barrier

; #define PG8_STAGE(bufoff, gbase, voff) do { _Pragma("unroll") for (int _i = 0; _i < 2; ++_i) \
;         __builtin_amdgcn_global_load_lds((const unsigned*)((const char*)(gbase) + (voff)[_i]), (PG8_LAS unsigned*)(lds + (bufoff) + ldsw + _i * 8192), 16, 0, 0); } while (0)
; #define PG8_LDA(dst, b, h) do { _Pragma("unroll") for (int m = 0; m < 4; ++m) _Pragma("unroll") for (int k = 0; k < 2; ++k) dst[m][k] = *(const PG8_LAS bf16x8*)(lds + PG8_SA(b, h) + aoff + m * 2048 + k * 1024); } while (0)
; #define PG8_LDB(dst, b, h) do { _Pragma("unroll") for (int n = 0; n < 2; ++n) _Pragma("unroll") for (int k = 0; k < 2; ++k) dst[n][k] = *(const PG8_LAS bf16x8*)(lds + PG8_SB(b, h) + boff + n * 2048 + k * 1024); } while (0)
; #define PG8_MMA(ai, bj, At, Bt) do { __builtin_amdgcn_s_setprio(1); _Pragma("unroll") for (int m = 0; m < 4; ++m) _Pragma("unroll") for (int n = 0; n < 2; ++n) _Pragma("unroll") for (int k = 0; k < 2; ++k) \
;         acc[ai][bj][m][n] = __builtin_amdgcn_mfma_f32_16x16x32_bf16(Bt[n][k], At[m][k], acc[ai][bj][m][n], 0, 0, 0); __builtin_amdgcn_s_setprio(0); } while (0)
; #define PG8_BAR __builtin_amdgcn_s_barrier()
; template <class Epi, class Sched, bool ALIGN_EPI = false, bool SP2 = false>
; __device__ __forceinline__ void gemm_phase(PG8_LAS unsigned char* lds, const Gemm g, const Sched& S, const Epi& E) {
;     ...
;         const bool has_next = S.next(ui + 1, nxt);
;         const char* nA = has_next ? (const char*)g.A + (size_t)nxt.pm * tstep : cA; const char* nB = has_next ? (const char*)g.Bt + (size_t)nxt.pn * tstep : cB;
;         for (int t = 0; t < nt; t += 2) {
;             const bool last = (t == nt - 2);
;             const char* a1 = cA + (size_t)(t + 1) * kstep;
;             const char* a2 = last ? nA : cA + (size_t)(t + 2) * kstep; const char* b2 = last ? nB : cB + (size_t)(t + 2) * kstep;
;             const char* a3 = a2 + kstep; const char* b3 = b2 + kstep;
;             if (last && has_next) S.a_ready(nxt);
;             if constexpr (SP2) {
;             PG8_LDB(B0, 0, 0); PG8_LDB(B1, 0, 1); PG8_SCHED; PG8_LDA(At, 0, 0); PG8_STAGE(PG8_SA(1, 1), a1 + hstep, voffA);
;             PG8_WAIT_V(8); PG8_WAIT_L(0); PG8_BAR; PG8_MMA(0, 0, At, B0); PG8_MMA(0, 1, At, B1); PG8_BAR; PG8_SCHED;
;             PG8_LDA(At, 0, 1); PG8_STAGE(PG8_SB(0, 0), b2, voffB); PG8_STAGE(PG8_SB(0, 1), b2 + hstep, voffB); PG8_STAGE(PG8_SA(0, 0), a2, voffA);
.LBB0_1179:
	s_ashr_i32 s21, s20, 31
	s_lshl_b64 s[22:23], s[20:21], 20
	s_add_u32 s22, s56, s22
	s_addc_u32 s23, s57, s23
	s_and_b64 s[24:25], s[4:5], exec
	s_cselect_b32 s7, s23, s27
	s_cselect_b32 s21, s22, s26
	s_ashr_i32 s19, s18, 31
	s_lshl_b64 s[24:25], s[18:19], 20
	s_add_u32 s24, s68, s24
	s_addc_u32 s25, s69, s25
	s_and_b64 s[30:31], s[4:5], exec
	s_cselect_b32 s19, s25, s29
	s_cselect_b32 s46, s24, s28
	s_add_u32 s26, s26, 0x80080
	s_addc_u32 s27, s27, 0
	s_add_u32 s47, s28, 0x100
	s_addc_u32 s48, s29, 0
	s_mov_b32 s49, -2
	s_waitcnt lgkmcnt(0)
	s_add_i32 s98, s34, 0x10000
	s_add_i32 s99, s34, 0x14000
	s_add_i32 s100, s34, 0x18000
	s_add_i32 s101, s34, 0x1c000
	ds_read_b128 v[128:131], v181
	ds_read_b128 v[132:135], v181 offset:1024
	ds_read_b128 v[136:139], v181 offset:2048
	ds_read_b128 v[140:143], v181 offset:3072
	ds_read_b128 v[144:147], v182
	ds_read_b128 v[148:151], v182 offset:1024
	ds_read_b128 v[168:171], v182 offset:2048
	ds_read_b128 v[172:175], v182 offset:3072
	s_add_u32 s28, s26, 0xfff80080
	s_addc_u32 s29, s27, -1
	s_cmp_eq_u32 s49, 28
	s_cselect_b32 s31, s7, s29
	s_cselect_b32 s30, s21, s28
	s_cselect_b32 s29, s19, s48
	s_cselect_b32 s28, s46, s47
	s_add_i32 m0, s35, 0xc000
	ds_read_b128 v[186:189], v183
	ds_read_b128 v[190:193], v183 offset:1024
	ds_read_b128 v[198:201], v183 offset:2048
	ds_read_b128 v[202:205], v183 offset:3072
	ds_read_b128 v[206:209], v183 offset:4096
	ds_read_b128 v[210:213], v183 offset:5120
	ds_read_b128 v[214:217], v183 offset:6144
	ds_read_b128 v[218:221], v183 offset:7168
	global_load_lds_dwordx4 v160, s[26:27]
	s_add_i32 m0, s35, 0xe000
	s_nop 0
	global_load_lds_dwordx4 v162, s[26:27]
	s_waitcnt lgkmcnt(0)
	s_setprio 1
	s_barrier
	v_mfma_f32_16x16x32_bf16 v[124:127], v[128:131], v[186:189], 0
	v_mfma_f32_16x16x32_bf16 v[120:123], v[136:139], v[186:189], 0
	v_mfma_f32_16x16x32_bf16 v[104:107], v[128:131], v[198:201], 0
	v_mfma_f32_16x16x32_bf16 v[108:111], v[136:139], v[198:201], 0
	v_mfma_f32_16x16x32_bf16 v[88:91], v[128:131], v[206:209], 0
	v_mfma_f32_16x16x32_bf16 v[92:95], v[136:139], v[206:209], 0
	v_mfma_f32_16x16x32_bf16 v[72:75], v[128:131], v[214:217], 0
	v_mfma_f32_16x16x32_bf16 v[76:79], v[136:139], v[214:217], 0
	v_mfma_f32_16x16x32_bf16 v[124:127], v[132:135], v[190:193], v[124:127]
	v_mfma_f32_16x16x32_bf16 v[120:123], v[140:143], v[190:193], v[120:123]
	v_mfma_f32_16x16x32_bf16 v[104:107], v[132:135], v[202:205], v[104:107]
	v_mfma_f32_16x16x32_bf16 v[108:111], v[140:143], v[202:205], v[108:111]
	v_mfma_f32_16x16x32_bf16 v[88:91], v[132:135], v[210:213], v[88:91]
	v_mfma_f32_16x16x32_bf16 v[92:95], v[140:143], v[210:213], v[92:95]
	v_mfma_f32_16x16x32_bf16 v[72:75], v[132:135], v[218:221], v[72:75]
	v_mfma_f32_16x16x32_bf16 v[76:79], v[140:143], v[218:221], v[76:79]
	v_mfma_f32_16x16x32_bf16 v[116:119], v[144:147], v[186:189], 0
	v_mfma_f32_16x16x32_bf16 v[112:115], v[168:171], v[186:189], 0
	v_mfma_f32_16x16x32_bf16 v[100:103], v[144:147], v[198:201], 0
	v_mfma_f32_16x16x32_bf16 v[96:99], v[168:171], v[198:201], 0
	v_mfma_f32_16x16x32_bf16 v[84:87], v[144:147], v[206:209], 0
	v_mfma_f32_16x16x32_bf16 v[80:83], v[168:171], v[206:209], 0
	v_mfma_f32_16x16x32_bf16 v[68:71], v[144:147], v[214:217], 0
	v_mfma_f32_16x16x32_bf16 v[64:67], v[168:171], v[214:217], 0
	v_mfma_f32_16x16x32_bf16 v[116:119], v[148:151], v[190:193], v[116:119]
	v_mfma_f32_16x16x32_bf16 v[112:115], v[172:175], v[190:193], v[112:115]
	v_mfma_f32_16x16x32_bf16 v[100:103], v[148:151], v[202:205], v[100:103]
	v_mfma_f32_16x16x32_bf16 v[96:99], v[172:175], v[202:205], v[96:99]
	v_mfma_f32_16x16x32_bf16 v[84:87], v[148:151], v[210:213], v[84:87]
	v_mfma_f32_16x16x32_bf16 v[80:83], v[172:175], v[210:213], v[80:83]
	v_mfma_f32_16x16x32_bf16 v[68:71], v[148:151], v[218:221], v[68:71]
	v_mfma_f32_16x16x32_bf16 v[64:67], v[172:175], v[218:221], v[64:67]
	s_barrier
	s_setprio 0
	v_lshl_add_u64 v[176:177], s[28:29], 0, v[154:155]
	s_mov_b32 m0, s98
	ds_read_b128 v[186:189], v183 offset:16384
	ds_read_b128 v[190:193], v183 offset:17408
	ds_read_b128 v[198:201], v183 offset:18432
	ds_read_b128 v[202:205], v183 offset:19456
	ds_read_b128 v[206:209], v183 offset:20480
	ds_read_b128 v[210:213], v183 offset:21504
	ds_read_b128 v[214:217], v183 offset:22528
	ds_read_b128 v[218:221], v183 offset:23552
	global_load_lds_dwordx4 v[176:177], off
	s_add_i32 m0, s98, 0x2000
	s_add_u32 s50, s28, 0x80000
	v_lshl_add_u64 v[194:195], s[28:29], 0, v[158:159]
	s_addc_u32 s51, s29, 0
	global_load_lds_dwordx4 v[194:195], off
	s_mov_b32 m0, s99
	v_lshl_add_u64 v[224:225], s[30:31], 0, v[156:157]
	global_load_lds_dwordx4 v154, s[50:51]
	s_add_i32 m0, s99, 0x2000
	s_nop 0
	global_load_lds_dwordx4 v158, s[50:51]
	s_mov_b32 m0, s35
	v_lshl_add_u64 v[222:223], s[30:31], 0, v[152:153]
	global_load_lds_dwordx4 v[222:223], off
	s_mov_b32 m0, s33
	s_nop 0
	global_load_lds_dwordx4 v[224:225], off
	s_waitcnt lgkmcnt(0)
	s_setprio 1
	s_barrier
; #define PG8_STAGE(bufoff, gbase, voff) do { _Pragma("unroll") for (int _i = 0; _i < 2; ++_i) \
;         __builtin_amdgcn_global_load_lds((const unsigned*)((const char*)(gbase) + (voff)[_i]), (PG8_LAS unsigned*)(lds + (bufoff) + ldsw + _i * 8192), 16, 0, 0); } while (0)
; #define PG8_LDA(dst, b, h) do { _Pragma("unroll") for (int m = 0; m < 4; ++m) _Pragma("unroll") for (int k = 0; k < 2; ++k) dst[m][k] = *(const PG8_LAS bf16x8*)(lds + PG8_SA(b, h) + aoff + m * 2048 + k * 1024); } while (0)
; #define PG8_LDB(dst, b, h) do { _Pragma("unroll") for (int n = 0; n < 2; ++n) _Pragma("unroll") for (int k = 0; k < 2; ++k) dst[n][k] = *(const PG8_LAS bf16x8*)(lds + PG8_SB(b, h) + boff + n * 2048 + k * 1024); } while (0)
; #define PG8_MMA(ai, bj, At, Bt) do { __builtin_amdgcn_s_setprio(1); _Pragma("unroll") for (int m = 0; m < 4; ++m) _Pragma("unroll") for (int n = 0; n < 2; ++n) _Pragma("unroll") for (int k = 0; k < 2; ++k) \
;         acc[ai][bj][m][n] = __builtin_amdgcn_mfma_f32_16x16x32_bf16(Bt[n][k], At[m][k], acc[ai][bj][m][n], 0, 0, 0); __builtin_amdgcn_s_setprio(0); } while (0)
; #define PG8_WAIT_V(n) asm volatile("s_waitcnt vmcnt(" #n ")" ::: "memory")
; #define PG8_WAIT_L(n) asm volatile("s_waitcnt lgkmcnt(" #n ")" ::: "memory")
; #define PG8_BAR __builtin_amdgcn_s_barrier()
; #define PG8_SCHED __builtin_amdgcn_sched_barrier(0)
; template <class Epi, class Sched, bool ALIGN_EPI = false, bool SP2 = false>
; __device__ __forceinline__ void gemm_phase(PG8_LAS unsigned char* lds, const Gemm g, const Sched& S, const Epi& E) {
;     ...
;             PG8_WAIT_V(8); PG8_WAIT_L(0); PG8_BAR; PG8_MMA(1, 0, At, B0); PG8_MMA(1, 1, At, B1); PG8_BAR; PG8_SCHED;
;             PG8_LDB(B0, 1, 0); PG8_LDB(B1, 1, 1); PG8_SCHED; PG8_LDA(At, 1, 0); PG8_STAGE(PG8_SA(0, 1), a2 + hstep, voffA);
;             PG8_WAIT_V(8); PG8_WAIT_L(0); PG8_BAR; PG8_MMA(0, 0, At, B0); PG8_MMA(0, 1, At, B1); PG8_BAR; PG8_SCHED;
	v_mfma_f32_16x16x32_bf16 v[56:59], v[128:131], v[186:189], 0
	v_mfma_f32_16x16x32_bf16 v[60:63], v[136:139], v[186:189], 0
	v_mfma_f32_16x16x32_bf16 v[40:43], v[128:131], v[198:201], 0
	v_mfma_f32_16x16x32_bf16 v[44:47], v[136:139], v[198:201], 0
	v_mfma_f32_16x16x32_bf16 v[24:27], v[128:131], v[206:209], 0
	v_mfma_f32_16x16x32_bf16 v[28:31], v[136:139], v[206:209], 0
	v_mfma_f32_16x16x32_bf16 v[8:11], v[128:131], v[214:217], 0
	v_mfma_f32_16x16x32_bf16 v[12:15], v[136:139], v[214:217], 0
	v_mfma_f32_16x16x32_bf16 v[56:59], v[132:135], v[190:193], v[56:59]
	v_mfma_f32_16x16x32_bf16 v[60:63], v[140:143], v[190:193], v[60:63]
	v_mfma_f32_16x16x32_bf16 v[40:43], v[132:135], v[202:205], v[40:43]
	v_mfma_f32_16x16x32_bf16 v[44:47], v[140:143], v[202:205], v[44:47]
	v_mfma_f32_16x16x32_bf16 v[24:27], v[132:135], v[210:213], v[24:27]
	v_mfma_f32_16x16x32_bf16 v[28:31], v[140:143], v[210:213], v[28:31]
	v_mfma_f32_16x16x32_bf16 v[8:11], v[132:135], v[218:221], v[8:11]
	v_mfma_f32_16x16x32_bf16 v[12:15], v[140:143], v[218:221], v[12:15]
	v_mfma_f32_16x16x32_bf16 v[52:55], v[144:147], v[186:189], 0
	v_mfma_f32_16x16x32_bf16 v[48:51], v[168:171], v[186:189], 0
	v_mfma_f32_16x16x32_bf16 v[36:39], v[144:147], v[198:201], 0
	v_mfma_f32_16x16x32_bf16 v[32:35], v[168:171], v[198:201], 0
	v_mfma_f32_16x16x32_bf16 v[20:23], v[144:147], v[206:209], 0
	v_mfma_f32_16x16x32_bf16 v[16:19], v[168:171], v[206:209], 0
	v_mfma_f32_16x16x32_bf16 v[4:7], v[144:147], v[214:217], 0
	v_mfma_f32_16x16x32_bf16 v[0:3], v[168:171], v[214:217], 0
	v_mfma_f32_16x16x32_bf16 v[52:55], v[148:151], v[190:193], v[52:55]
	v_mfma_f32_16x16x32_bf16 v[48:51], v[172:175], v[190:193], v[48:51]
	v_mfma_f32_16x16x32_bf16 v[36:39], v[148:151], v[202:205], v[36:39]
	v_mfma_f32_16x16x32_bf16 v[32:35], v[172:175], v[202:205], v[32:35]
	v_mfma_f32_16x16x32_bf16 v[20:23], v[148:151], v[210:213], v[20:23]
	v_mfma_f32_16x16x32_bf16 v[16:19], v[172:175], v[210:213], v[16:19]
	v_mfma_f32_16x16x32_bf16 v[4:7], v[148:151], v[218:221], v[4:7]
	v_mfma_f32_16x16x32_bf16 v[0:3], v[172:175], v[218:221], v[0:3]
	s_barrier
	s_setprio 0
	s_add_i32 s50, 0, 0x18000
	s_add_i32 s51, 0, 0x1c000
	v_add_u32_e32 v140, s50, v179
	v_add_u32_e32 v172, s51, v179
	ds_read_b128 v[128:131], v140
	ds_read_b128 v[132:135], v140 offset:1024
	ds_read_b128 v[136:139], v140 offset:2048
	ds_read_b128 v[140:143], v140 offset:3072
	ds_read_b128 v[144:147], v172
	ds_read_b128 v[148:151], v172 offset:1024
	ds_read_b128 v[168:171], v172 offset:2048
	ds_read_b128 v[172:175], v172 offset:3072
	s_add_u32 s30, s30, 0x80000
	s_addc_u32 s31, s31, 0
	s_mov_b32 m0, s36
	ds_read_b128 v[186:189], v183 offset:32768
	ds_read_b128 v[190:193], v183 offset:33792
	ds_read_b128 v[198:201], v183 offset:34816
	ds_read_b128 v[202:205], v183 offset:35840
	ds_read_b128 v[206:209], v183 offset:36864
	ds_read_b128 v[210:213], v183 offset:37888
	ds_read_b128 v[214:217], v183 offset:38912
	ds_read_b128 v[218:221], v183 offset:39936
	global_load_lds_dwordx4 v152, s[30:31]
	s_mov_b32 m0, s37
	v_lshl_add_u64 v[226:227], s[30:31], 0, v[156:157]
	global_load_lds_dwordx4 v[226:227], off
	s_waitcnt vmcnt(8) lgkmcnt(0)
	s_setprio 1
	s_barrier
	v_mfma_f32_16x16x32_bf16 v[124:127], v[128:131], v[186:189], v[124:127]
	v_mfma_f32_16x16x32_bf16 v[120:123], v[136:139], v[186:189], v[120:123]
	v_mfma_f32_16x16x32_bf16 v[104:107], v[128:131], v[198:201], v[104:107]
	v_mfma_f32_16x16x32_bf16 v[108:111], v[136:139], v[198:201], v[108:111]
	v_mfma_f32_16x16x32_bf16 v[88:91], v[128:131], v[206:209], v[88:91]
	v_mfma_f32_16x16x32_bf16 v[92:95], v[136:139], v[206:209], v[92:95]
	v_mfma_f32_16x16x32_bf16 v[72:75], v[128:131], v[214:217], v[72:75]
	v_mfma_f32_16x16x32_bf16 v[76:79], v[136:139], v[214:217], v[76:79]
	v_mfma_f32_16x16x32_bf16 v[124:127], v[132:135], v[190:193], v[124:127]
	v_mfma_f32_16x16x32_bf16 v[120:123], v[140:143], v[190:193], v[120:123]
	v_mfma_f32_16x16x32_bf16 v[104:107], v[132:135], v[202:205], v[104:107]
	v_mfma_f32_16x16x32_bf16 v[108:111], v[140:143], v[202:205], v[108:111]
	v_mfma_f32_16x16x32_bf16 v[88:91], v[132:135], v[210:213], v[88:91]
	v_mfma_f32_16x16x32_bf16 v[92:95], v[140:143], v[210:213], v[92:95]
	v_mfma_f32_16x16x32_bf16 v[72:75], v[132:135], v[218:221], v[72:75]
	v_mfma_f32_16x16x32_bf16 v[76:79], v[140:143], v[218:221], v[76:79]
	v_mfma_f32_16x16x32_bf16 v[116:119], v[144:147], v[186:189], v[116:119]
	v_mfma_f32_16x16x32_bf16 v[112:115], v[168:171], v[186:189], v[112:115]
	v_mfma_f32_16x16x32_bf16 v[100:103], v[144:147], v[198:201], v[100:103]
	v_mfma_f32_16x16x32_bf16 v[96:99], v[168:171], v[198:201], v[96:99]
	v_mfma_f32_16x16x32_bf16 v[84:87], v[144:147], v[206:209], v[84:87]
	v_mfma_f32_16x16x32_bf16 v[80:83], v[168:171], v[206:209], v[80:83]
	v_mfma_f32_16x16x32_bf16 v[68:71], v[144:147], v[214:217], v[68:71]
	v_mfma_f32_16x16x32_bf16 v[64:67], v[168:171], v[214:217], v[64:67]
	v_mfma_f32_16x16x32_bf16 v[116:119], v[148:151], v[190:193], v[116:119]
	v_mfma_f32_16x16x32_bf16 v[112:115], v[172:175], v[190:193], v[112:115]
	v_mfma_f32_16x16x32_bf16 v[100:103], v[148:151], v[202:205], v[100:103]
	v_mfma_f32_16x16x32_bf16 v[96:99], v[172:175], v[202:205], v[96:99]
	v_mfma_f32_16x16x32_bf16 v[84:87], v[148:151], v[210:213], v[84:87]
	v_mfma_f32_16x16x32_bf16 v[80:83], v[172:175], v[210:213], v[80:83]
	v_mfma_f32_16x16x32_bf16 v[68:71], v[148:151], v[218:221], v[68:71]
	v_mfma_f32_16x16x32_bf16 v[64:67], v[172:175], v[218:221], v[64:67]
	s_barrier
; #define PG8_STAGE(bufoff, gbase, voff) do { _Pragma("unroll") for (int _i = 0; _i < 2; ++_i) \
;         __builtin_amdgcn_global_load_lds((const unsigned*)((const char*)(gbase) + (voff)[_i]), (PG8_LAS unsigned*)(lds + (bufoff) + ldsw + _i * 8192), 16, 0, 0); } while (0)
; #define PG8_LDA(dst, b, h) do { _Pragma("unroll") for (int m = 0; m < 4; ++m) _Pragma("unroll") for (int k = 0; k < 2; ++k) dst[m][k] = *(const PG8_LAS bf16x8*)(lds + PG8_SA(b, h) + aoff + m * 2048 + k * 1024); } while (0)
; #define PG8_LDB(dst, b, h) do { _Pragma("unroll") for (int n = 0; n < 2; ++n) _Pragma("unroll") for (int k = 0; k < 2; ++k) dst[n][k] = *(const PG8_LAS bf16x8*)(lds + PG8_SB(b, h) + boff + n * 2048 + k * 1024); } while (0)
; #define PG8_MMA(ai, bj, At, Bt) do { __builtin_amdgcn_s_setprio(1); _Pragma("unroll") for (int m = 0; m < 4; ++m) _Pragma("unroll") for (int n = 0; n < 2; ++n) _Pragma("unroll") for (int k = 0; k < 2; ++k) \
;         acc[ai][bj][m][n] = __builtin_amdgcn_mfma_f32_16x16x32_bf16(Bt[n][k], At[m][k], acc[ai][bj][m][n], 0, 0, 0); __builtin_amdgcn_s_setprio(0); } while (0)
; #define PG8_WAIT_V(n) asm volatile("s_waitcnt vmcnt(" #n ")" ::: "memory")
; #define PG8_BAR __builtin_amdgcn_s_barrier()
; template <class Epi, class Sched, bool ALIGN_EPI = false, bool SP2 = false>
; __device__ __forceinline__ void gemm_phase(PG8_LAS unsigned char* lds, const Gemm g, const Sched& S, const Epi& E) {
;     ...
;         for (int t = 0; t < nt; t += 2) {
;             const bool last = (t == nt - 2);
;             const char* a1 = cA + (size_t)(t + 1) * kstep;
;             const char* a2 = last ? nA : cA + (size_t)(t + 2) * kstep; const char* b2 = last ? nB : cB + (size_t)(t + 2) * kstep;
;             const char* a3 = a2 + kstep; const char* b3 = b2 + kstep;
;             if (last && has_next) S.a_ready(nxt);
;             if constexpr (SP2) {
;             PG8_LDB(B0, 0, 0); PG8_LDB(B1, 0, 1); PG8_SCHED; PG8_LDA(At, 0, 0); PG8_STAGE(PG8_SA(1, 1), a1 + hstep, voffA);
;             PG8_WAIT_V(8); PG8_WAIT_L(0); PG8_BAR; PG8_MMA(0, 0, At, B0); PG8_MMA(0, 1, At, B1); PG8_BAR; PG8_SCHED;
;     ...
;             PG8_LDA(At, 1, 1); PG8_STAGE(PG8_SB(1, 0), b3, voffB); PG8_STAGE(PG8_SB(1, 1), b3 + hstep, voffB); PG8_STAGE(PG8_SA(1, 0), a3, voffA);
;             PG8_WAIT_V(8); PG8_WAIT_L(0); PG8_BAR; PG8_MMA(1, 0, At, B0); PG8_MMA(1, 1, At, B1); PG8_BAR; PG8_SCHED;
	s_setprio 0
	v_lshl_add_u64 v[176:177], v[176:177], 0, s[12:13]
	s_mov_b32 m0, s100
	ds_read_b128 v[186:189], v183 offset:49152
	ds_read_b128 v[190:193], v183 offset:50176
	ds_read_b128 v[198:201], v183 offset:51200
	ds_read_b128 v[202:205], v183 offset:52224
	ds_read_b128 v[206:209], v183 offset:53248
	ds_read_b128 v[210:213], v183 offset:54272
	ds_read_b128 v[214:217], v183 offset:55296
	ds_read_b128 v[218:221], v183 offset:56320
	global_load_lds_dwordx4 v[176:177], off
	s_add_i32 m0, s100, 0x2000
	s_add_u32 s28, s28, 0x80080
	v_lshl_add_u64 v[176:177], v[194:195], 0, s[12:13]
	s_addc_u32 s29, s29, 0
	global_load_lds_dwordx4 v[176:177], off
	s_mov_b32 m0, s101
	s_nop 0
	global_load_lds_dwordx4 v154, s[28:29]
	s_add_i32 m0, s101, 0x2000
	v_lshl_add_u64 v[176:177], s[28:29], 0, v[158:159]
	global_load_lds_dwordx4 v[176:177], off
	s_mov_b32 m0, s39
	v_lshl_add_u64 v[176:177], v[222:223], 0, s[12:13]
	global_load_lds_dwordx4 v[176:177], off
	s_mov_b32 m0, s40
	v_lshl_add_u64 v[176:177], v[224:225], 0, s[12:13]
	global_load_lds_dwordx4 v[176:177], off
	s_waitcnt vmcnt(8) lgkmcnt(0)
	s_setprio 1
	s_barrier
	v_mfma_f32_16x16x32_bf16 v[56:59], v[128:131], v[186:189], v[56:59]
	v_mfma_f32_16x16x32_bf16 v[60:63], v[136:139], v[186:189], v[60:63]
	v_mfma_f32_16x16x32_bf16 v[40:43], v[128:131], v[198:201], v[40:43]
	v_mfma_f32_16x16x32_bf16 v[44:47], v[136:139], v[198:201], v[44:47]
	v_mfma_f32_16x16x32_bf16 v[24:27], v[128:131], v[206:209], v[24:27]
	v_mfma_f32_16x16x32_bf16 v[28:31], v[136:139], v[206:209], v[28:31]
	v_mfma_f32_16x16x32_bf16 v[8:11], v[128:131], v[214:217], v[8:11]
	v_mfma_f32_16x16x32_bf16 v[12:15], v[136:139], v[214:217], v[12:15]
	v_mfma_f32_16x16x32_bf16 v[56:59], v[132:135], v[190:193], v[56:59]
	v_mfma_f32_16x16x32_bf16 v[60:63], v[140:143], v[190:193], v[60:63]
	v_mfma_f32_16x16x32_bf16 v[40:43], v[132:135], v[202:205], v[40:43]
	v_mfma_f32_16x16x32_bf16 v[44:47], v[140:143], v[202:205], v[44:47]
	v_mfma_f32_16x16x32_bf16 v[24:27], v[132:135], v[210:213], v[24:27]
	v_mfma_f32_16x16x32_bf16 v[28:31], v[140:143], v[210:213], v[28:31]
	v_mfma_f32_16x16x32_bf16 v[8:11], v[132:135], v[218:221], v[8:11]
	v_mfma_f32_16x16x32_bf16 v[12:15], v[140:143], v[218:221], v[12:15]
	v_mfma_f32_16x16x32_bf16 v[52:55], v[144:147], v[186:189], v[52:55]
	v_mfma_f32_16x16x32_bf16 v[48:51], v[168:171], v[186:189], v[48:51]
	v_mfma_f32_16x16x32_bf16 v[36:39], v[144:147], v[198:201], v[36:39]
	v_mfma_f32_16x16x32_bf16 v[32:35], v[168:171], v[198:201], v[32:35]
	v_mfma_f32_16x16x32_bf16 v[20:23], v[144:147], v[206:209], v[20:23]
	v_mfma_f32_16x16x32_bf16 v[16:19], v[168:171], v[206:209], v[16:19]
	v_mfma_f32_16x16x32_bf16 v[4:7], v[144:147], v[214:217], v[4:7]
	v_mfma_f32_16x16x32_bf16 v[0:3], v[168:171], v[214:217], v[0:3]
	v_mfma_f32_16x16x32_bf16 v[52:55], v[148:151], v[190:193], v[52:55]
	v_mfma_f32_16x16x32_bf16 v[48:51], v[172:175], v[190:193], v[48:51]
	v_mfma_f32_16x16x32_bf16 v[36:39], v[148:151], v[202:205], v[36:39]
	v_mfma_f32_16x16x32_bf16 v[32:35], v[172:175], v[202:205], v[32:35]
	v_mfma_f32_16x16x32_bf16 v[20:23], v[148:151], v[210:213], v[20:23]
	v_mfma_f32_16x16x32_bf16 v[16:19], v[172:175], v[210:213], v[16:19]
	v_mfma_f32_16x16x32_bf16 v[4:7], v[148:151], v[218:221], v[4:7]
	v_mfma_f32_16x16x32_bf16 v[0:3], v[172:175], v[218:221], v[0:3]
	s_barrier
	s_setprio 0
	s_add_i32 s49, s49, 2
	s_add_u32 s26, s26, 0x100
	s_addc_u32 s27, s27, 0
	s_add_u32 s47, s47, 0x100
	s_addc_u32 s48, s48, 0
.LBB0_1180:
	ds_read_b128 v[128:131], v181
	ds_read_b128 v[132:135], v181 offset:1024
	ds_read_b128 v[136:139], v181 offset:2048
	ds_read_b128 v[140:143], v181 offset:3072
	ds_read_b128 v[144:147], v182
	ds_read_b128 v[148:151], v182 offset:1024
	ds_read_b128 v[168:171], v182 offset:2048
	ds_read_b128 v[172:175], v182 offset:3072
	s_add_u32 s28, s26, 0xfff80080
	s_addc_u32 s29, s27, -1
	s_cmp_eq_u32 s49, 28
	s_cselect_b32 s31, s7, s29
	s_cselect_b32 s30, s21, s28
	s_cselect_b32 s29, s19, s48
	s_cselect_b32 s28, s46, s47
	s_add_i32 m0, s35, 0xc000
	ds_read_b128 v[186:189], v183
	ds_read_b128 v[190:193], v183 offset:1024
	ds_read_b128 v[198:201], v183 offset:2048
	ds_read_b128 v[202:205], v183 offset:3072
	ds_read_b128 v[206:209], v183 offset:4096
	ds_read_b128 v[210:213], v183 offset:5120
	ds_read_b128 v[214:217], v183 offset:6144
	ds_read_b128 v[218:221], v183 offset:7168
	global_load_lds_dwordx4 v160, s[26:27]
	s_add_i32 m0, s35, 0xe000
	s_nop 0
	global_load_lds_dwordx4 v162, s[26:27]
	s_waitcnt vmcnt(8) lgkmcnt(0)
	s_setprio 1
	s_barrier
; #define PG8_STAGE(bufoff, gbase, voff) do { _Pragma("unroll") for (int _i = 0; _i < 2; ++_i) \
;         __builtin_amdgcn_global_load_lds((const unsigned*)((const char*)(gbase) + (voff)[_i]), (PG8_LAS unsigned*)(lds + (bufoff) + ldsw + _i * 8192), 16, 0, 0); } while (0)
; #define PG8_LDA(dst, b, h) do { _Pragma("unroll") for (int m = 0; m < 4; ++m) _Pragma("unroll") for (int k = 0; k < 2; ++k) dst[m][k] = *(const PG8_LAS bf16x8*)(lds + PG8_SA(b, h) + aoff + m * 2048 + k * 1024); } while (0)
; #define PG8_MMA(ai, bj, At, Bt) do { __builtin_amdgcn_s_setprio(1); _Pragma("unroll") for (int m = 0; m < 4; ++m) _Pragma("unroll") for (int n = 0; n < 2; ++n) _Pragma("unroll") for (int k = 0; k < 2; ++k) \
;         acc[ai][bj][m][n] = __builtin_amdgcn_mfma_f32_16x16x32_bf16(Bt[n][k], At[m][k], acc[ai][bj][m][n], 0, 0, 0); __builtin_amdgcn_s_setprio(0); } while (0)
; #define PG8_WAIT_V(n) asm volatile("s_waitcnt vmcnt(" #n ")" ::: "memory")
; #define PG8_WAIT_L(n) asm volatile("s_waitcnt lgkmcnt(" #n ")" ::: "memory")
; #define PG8_BAR __builtin_amdgcn_s_barrier()
; #define PG8_SCHED __builtin_amdgcn_sched_barrier(0)
; template <class Epi, class Sched, bool ALIGN_EPI = false, bool SP2 = false>
; __device__ __forceinline__ void gemm_phase(PG8_LAS unsigned char* lds, const Gemm g, const Sched& S, const Epi& E) {
;     ...
;             PG8_WAIT_V(8); PG8_WAIT_L(0); PG8_BAR; PG8_MMA(0, 0, At, B0); PG8_MMA(0, 1, At, B1); PG8_BAR; PG8_SCHED;
;             PG8_LDA(At, 0, 1); PG8_STAGE(PG8_SB(0, 0), b2, voffB); PG8_STAGE(PG8_SB(0, 1), b2 + hstep, voffB); PG8_STAGE(PG8_SA(0, 0), a2, voffA);
;             PG8_WAIT_V(8); PG8_WAIT_L(0); PG8_BAR; PG8_MMA(1, 0, At, B0); PG8_MMA(1, 1, At, B1); PG8_BAR; PG8_SCHED;
	v_mfma_f32_16x16x32_bf16 v[124:127], v[128:131], v[186:189], v[124:127]
	v_mfma_f32_16x16x32_bf16 v[120:123], v[136:139], v[186:189], v[120:123]
	v_mfma_f32_16x16x32_bf16 v[104:107], v[128:131], v[198:201], v[104:107]
	v_mfma_f32_16x16x32_bf16 v[108:111], v[136:139], v[198:201], v[108:111]
	v_mfma_f32_16x16x32_bf16 v[88:91], v[128:131], v[206:209], v[88:91]
	v_mfma_f32_16x16x32_bf16 v[92:95], v[136:139], v[206:209], v[92:95]
	v_mfma_f32_16x16x32_bf16 v[72:75], v[128:131], v[214:217], v[72:75]
	v_mfma_f32_16x16x32_bf16 v[76:79], v[136:139], v[214:217], v[76:79]
	v_mfma_f32_16x16x32_bf16 v[124:127], v[132:135], v[190:193], v[124:127]
	v_mfma_f32_16x16x32_bf16 v[120:123], v[140:143], v[190:193], v[120:123]
	v_mfma_f32_16x16x32_bf16 v[104:107], v[132:135], v[202:205], v[104:107]
	v_mfma_f32_16x16x32_bf16 v[108:111], v[140:143], v[202:205], v[108:111]
	v_mfma_f32_16x16x32_bf16 v[88:91], v[132:135], v[210:213], v[88:91]
	v_mfma_f32_16x16x32_bf16 v[92:95], v[140:143], v[210:213], v[92:95]
	v_mfma_f32_16x16x32_bf16 v[72:75], v[132:135], v[218:221], v[72:75]
	v_mfma_f32_16x16x32_bf16 v[76:79], v[140:143], v[218:221], v[76:79]
	v_mfma_f32_16x16x32_bf16 v[116:119], v[144:147], v[186:189], v[116:119]
	v_mfma_f32_16x16x32_bf16 v[112:115], v[168:171], v[186:189], v[112:115]
	v_mfma_f32_16x16x32_bf16 v[100:103], v[144:147], v[198:201], v[100:103]
	v_mfma_f32_16x16x32_bf16 v[96:99], v[168:171], v[198:201], v[96:99]
	v_mfma_f32_16x16x32_bf16 v[84:87], v[144:147], v[206:209], v[84:87]
	v_mfma_f32_16x16x32_bf16 v[80:83], v[168:171], v[206:209], v[80:83]
	v_mfma_f32_16x16x32_bf16 v[68:71], v[144:147], v[214:217], v[68:71]
	v_mfma_f32_16x16x32_bf16 v[64:67], v[168:171], v[214:217], v[64:67]
	v_mfma_f32_16x16x32_bf16 v[116:119], v[148:151], v[190:193], v[116:119]
	v_mfma_f32_16x16x32_bf16 v[112:115], v[172:175], v[190:193], v[112:115]
	v_mfma_f32_16x16x32_bf16 v[100:103], v[148:151], v[202:205], v[100:103]
	v_mfma_f32_16x16x32_bf16 v[96:99], v[172:175], v[202:205], v[96:99]
	v_mfma_f32_16x16x32_bf16 v[84:87], v[148:151], v[210:213], v[84:87]
	v_mfma_f32_16x16x32_bf16 v[80:83], v[172:175], v[210:213], v[80:83]
	v_mfma_f32_16x16x32_bf16 v[68:71], v[148:151], v[218:221], v[68:71]
	v_mfma_f32_16x16x32_bf16 v[64:67], v[172:175], v[218:221], v[64:67]
	s_barrier
	s_setprio 0
	v_lshl_add_u64 v[176:177], s[28:29], 0, v[154:155]
	s_mov_b32 m0, s98
	ds_read_b128 v[186:189], v183 offset:16384
	ds_read_b128 v[190:193], v183 offset:17408
	ds_read_b128 v[198:201], v183 offset:18432
	ds_read_b128 v[202:205], v183 offset:19456
	ds_read_b128 v[206:209], v183 offset:20480
	ds_read_b128 v[210:213], v183 offset:21504
	ds_read_b128 v[214:217], v183 offset:22528
	ds_read_b128 v[218:221], v183 offset:23552
	global_load_lds_dwordx4 v[176:177], off
	s_add_i32 m0, s98, 0x2000
	s_add_u32 s50, s28, 0x80000
	v_lshl_add_u64 v[194:195], s[28:29], 0, v[158:159]
	s_addc_u32 s51, s29, 0
	global_load_lds_dwordx4 v[194:195], off
	s_mov_b32 m0, s99
	v_lshl_add_u64 v[224:225], s[30:31], 0, v[156:157]
	global_load_lds_dwordx4 v154, s[50:51]
	s_add_i32 m0, s99, 0x2000
	s_nop 0
	global_load_lds_dwordx4 v158, s[50:51]
	s_mov_b32 m0, s35
	v_lshl_add_u64 v[222:223], s[30:31], 0, v[152:153]
	global_load_lds_dwordx4 v[222:223], off
	s_mov_b32 m0, s33
	s_nop 0
	global_load_lds_dwordx4 v[224:225], off
	s_waitcnt vmcnt(8) lgkmcnt(0)
	s_setprio 1
	s_barrier
	v_mfma_f32_16x16x32_bf16 v[56:59], v[128:131], v[186:189], v[56:59]
	v_mfma_f32_16x16x32_bf16 v[60:63], v[136:139], v[186:189], v[60:63]
	v_mfma_f32_16x16x32_bf16 v[40:43], v[128:131], v[198:201], v[40:43]
	v_mfma_f32_16x16x32_bf16 v[44:47], v[136:139], v[198:201], v[44:47]
	v_mfma_f32_16x16x32_bf16 v[24:27], v[128:131], v[206:209], v[24:27]
	v_mfma_f32_16x16x32_bf16 v[28:31], v[136:139], v[206:209], v[28:31]
	v_mfma_f32_16x16x32_bf16 v[8:11], v[128:131], v[214:217], v[8:11]
	v_mfma_f32_16x16x32_bf16 v[12:15], v[136:139], v[214:217], v[12:15]
	v_mfma_f32_16x16x32_bf16 v[56:59], v[132:135], v[190:193], v[56:59]
	v_mfma_f32_16x16x32_bf16 v[60:63], v[140:143], v[190:193], v[60:63]
	v_mfma_f32_16x16x32_bf16 v[40:43], v[132:135], v[202:205], v[40:43]
	v_mfma_f32_16x16x32_bf16 v[44:47], v[140:143], v[202:205], v[44:47]
	v_mfma_f32_16x16x32_bf16 v[24:27], v[132:135], v[210:213], v[24:27]
	v_mfma_f32_16x16x32_bf16 v[28:31], v[140:143], v[210:213], v[28:31]
	v_mfma_f32_16x16x32_bf16 v[8:11], v[132:135], v[218:221], v[8:11]
	v_mfma_f32_16x16x32_bf16 v[12:15], v[140:143], v[218:221], v[12:15]
	v_mfma_f32_16x16x32_bf16 v[52:55], v[144:147], v[186:189], v[52:55]
	v_mfma_f32_16x16x32_bf16 v[48:51], v[168:171], v[186:189], v[48:51]
	v_mfma_f32_16x16x32_bf16 v[36:39], v[144:147], v[198:201], v[36:39]
	v_mfma_f32_16x16x32_bf16 v[32:35], v[168:171], v[198:201], v[32:35]
	v_mfma_f32_16x16x32_bf16 v[20:23], v[144:147], v[206:209], v[20:23]
	v_mfma_f32_16x16x32_bf16 v[16:19], v[168:171], v[206:209], v[16:19]
	v_mfma_f32_16x16x32_bf16 v[4:7], v[144:147], v[214:217], v[4:7]
	v_mfma_f32_16x16x32_bf16 v[0:3], v[168:171], v[214:217], v[0:3]
	v_mfma_f32_16x16x32_bf16 v[52:55], v[148:151], v[190:193], v[52:55]
	v_mfma_f32_16x16x32_bf16 v[48:51], v[172:175], v[190:193], v[48:51]
	v_mfma_f32_16x16x32_bf16 v[36:39], v[148:151], v[202:205], v[36:39]
	v_mfma_f32_16x16x32_bf16 v[32:35], v[172:175], v[202:205], v[32:35]
	v_mfma_f32_16x16x32_bf16 v[20:23], v[148:151], v[210:213], v[20:23]
	v_mfma_f32_16x16x32_bf16 v[16:19], v[172:175], v[210:213], v[16:19]
	v_mfma_f32_16x16x32_bf16 v[4:7], v[148:151], v[218:221], v[4:7]
	v_mfma_f32_16x16x32_bf16 v[0:3], v[172:175], v[218:221], v[0:3]
	s_barrier
; #define PG8_STAGE(bufoff, gbase, voff) do { _Pragma("unroll") for (int _i = 0; _i < 2; ++_i) \
;         __builtin_amdgcn_global_load_lds((const unsigned*)((const char*)(gbase) + (voff)[_i]), (PG8_LAS unsigned*)(lds + (bufoff) + ldsw + _i * 8192), 16, 0, 0); } while (0)
; #define PG8_LDA(dst, b, h) do { _Pragma("unroll") for (int m = 0; m < 4; ++m) _Pragma("unroll") for (int k = 0; k < 2; ++k) dst[m][k] = *(const PG8_LAS bf16x8*)(lds + PG8_SA(b, h) + aoff + m * 2048 + k * 1024); } while (0)
; #define PG8_LDB(dst, b, h) do { _Pragma("unroll") for (int n = 0; n < 2; ++n) _Pragma("unroll") for (int k = 0; k < 2; ++k) dst[n][k] = *(const PG8_LAS bf16x8*)(lds + PG8_SB(b, h) + boff + n * 2048 + k * 1024); } while (0)
; #define PG8_MMA(ai, bj, At, Bt) do { __builtin_amdgcn_s_setprio(1); _Pragma("unroll") for (int m = 0; m < 4; ++m) _Pragma("unroll") for (int n = 0; n < 2; ++n) _Pragma("unroll") for (int k = 0; k < 2; ++k) \
;         acc[ai][bj][m][n] = __builtin_amdgcn_mfma_f32_16x16x32_bf16(Bt[n][k], At[m][k], acc[ai][bj][m][n], 0, 0, 0); __builtin_amdgcn_s_setprio(0); } while (0)
; #define PG8_WAIT_V(n) asm volatile("s_waitcnt vmcnt(" #n ")" ::: "memory")
; #define PG8_WAIT_L(n) asm volatile("s_waitcnt lgkmcnt(" #n ")" ::: "memory")
; #define PG8_BAR __builtin_amdgcn_s_barrier()
; #define PG8_SCHED __builtin_amdgcn_sched_barrier(0)
; template <class Epi, class Sched, bool ALIGN_EPI = false, bool SP2 = false>
; __device__ __forceinline__ void gemm_phase(PG8_LAS unsigned char* lds, const Gemm g, const Sched& S, const Epi& E) {
;     ...
;             PG8_LDB(B0, 1, 0); PG8_LDB(B1, 1, 1); PG8_SCHED; PG8_LDA(At, 1, 0); PG8_STAGE(PG8_SA(0, 1), a2 + hstep, voffA);
;             PG8_WAIT_V(8); PG8_WAIT_L(0); PG8_BAR; PG8_MMA(0, 0, At, B0); PG8_MMA(0, 1, At, B1); PG8_BAR; PG8_SCHED;
;             PG8_LDA(At, 1, 1); PG8_STAGE(PG8_SB(1, 0), b3, voffB); PG8_STAGE(PG8_SB(1, 1), b3 + hstep, voffB); PG8_STAGE(PG8_SA(1, 0), a3, voffA);
;             PG8_WAIT_V(8); PG8_WAIT_L(0); PG8_BAR; PG8_MMA(1, 0, At, B0); PG8_MMA(1, 1, At, B1); PG8_BAR; PG8_SCHED;
;     ...
;         if constexpr (ALIGN_EPI) { if (wr == 0) PG8_BAR; }
	s_setprio 0
	s_add_i32 s50, 0, 0x18000
	s_add_i32 s51, 0, 0x1c000
	v_add_u32_e32 v140, s50, v179
	v_add_u32_e32 v172, s51, v179
	ds_read_b128 v[128:131], v140
	ds_read_b128 v[132:135], v140 offset:1024
	ds_read_b128 v[136:139], v140 offset:2048
	ds_read_b128 v[140:143], v140 offset:3072
	ds_read_b128 v[144:147], v172
	ds_read_b128 v[148:151], v172 offset:1024
	ds_read_b128 v[168:171], v172 offset:2048
	ds_read_b128 v[172:175], v172 offset:3072
	s_add_u32 s30, s30, 0x80000
	s_addc_u32 s31, s31, 0
	s_mov_b32 m0, s36
	ds_read_b128 v[186:189], v183 offset:32768
	ds_read_b128 v[190:193], v183 offset:33792
	ds_read_b128 v[198:201], v183 offset:34816
	ds_read_b128 v[202:205], v183 offset:35840
	ds_read_b128 v[206:209], v183 offset:36864
	ds_read_b128 v[210:213], v183 offset:37888
	ds_read_b128 v[214:217], v183 offset:38912
	ds_read_b128 v[218:221], v183 offset:39936
	global_load_lds_dwordx4 v152, s[30:31]
	s_mov_b32 m0, s37
	s_nop 0
	global_load_lds_dwordx4 v156, s[30:31]
	s_waitcnt vmcnt(8) lgkmcnt(0)
	s_setprio 1
	s_barrier
	v_mfma_f32_16x16x32_bf16 v[124:127], v[128:131], v[186:189], v[124:127]
	v_mfma_f32_16x16x32_bf16 v[120:123], v[136:139], v[186:189], v[120:123]
	v_mfma_f32_16x16x32_bf16 v[104:107], v[128:131], v[198:201], v[104:107]
	v_mfma_f32_16x16x32_bf16 v[108:111], v[136:139], v[198:201], v[108:111]
	v_mfma_f32_16x16x32_bf16 v[88:91], v[128:131], v[206:209], v[88:91]
	v_mfma_f32_16x16x32_bf16 v[92:95], v[136:139], v[206:209], v[92:95]
	v_mfma_f32_16x16x32_bf16 v[72:75], v[128:131], v[214:217], v[72:75]
	v_mfma_f32_16x16x32_bf16 v[76:79], v[136:139], v[214:217], v[76:79]
	v_mfma_f32_16x16x32_bf16 v[124:127], v[132:135], v[190:193], v[124:127]
	v_mfma_f32_16x16x32_bf16 v[120:123], v[140:143], v[190:193], v[120:123]
	v_mfma_f32_16x16x32_bf16 v[104:107], v[132:135], v[202:205], v[104:107]
	v_mfma_f32_16x16x32_bf16 v[108:111], v[140:143], v[202:205], v[108:111]
	v_mfma_f32_16x16x32_bf16 v[88:91], v[132:135], v[210:213], v[88:91]
	v_mfma_f32_16x16x32_bf16 v[92:95], v[140:143], v[210:213], v[92:95]
	v_mfma_f32_16x16x32_bf16 v[72:75], v[132:135], v[218:221], v[72:75]
	v_mfma_f32_16x16x32_bf16 v[76:79], v[140:143], v[218:221], v[76:79]
	v_mfma_f32_16x16x32_bf16 v[116:119], v[144:147], v[186:189], v[116:119]
	v_mfma_f32_16x16x32_bf16 v[112:115], v[168:171], v[186:189], v[112:115]
	v_mfma_f32_16x16x32_bf16 v[100:103], v[144:147], v[198:201], v[100:103]
	v_mfma_f32_16x16x32_bf16 v[96:99], v[168:171], v[198:201], v[96:99]
	v_mfma_f32_16x16x32_bf16 v[84:87], v[144:147], v[206:209], v[84:87]
	v_mfma_f32_16x16x32_bf16 v[80:83], v[168:171], v[206:209], v[80:83]
	v_mfma_f32_16x16x32_bf16 v[68:71], v[144:147], v[214:217], v[68:71]
	v_mfma_f32_16x16x32_bf16 v[64:67], v[168:171], v[214:217], v[64:67]
	v_mfma_f32_16x16x32_bf16 v[116:119], v[148:151], v[190:193], v[116:119]
	v_mfma_f32_16x16x32_bf16 v[112:115], v[172:175], v[190:193], v[112:115]
	v_mfma_f32_16x16x32_bf16 v[100:103], v[148:151], v[202:205], v[100:103]
	v_mfma_f32_16x16x32_bf16 v[96:99], v[172:175], v[202:205], v[96:99]
	v_mfma_f32_16x16x32_bf16 v[84:87], v[148:151], v[210:213], v[84:87]
	v_mfma_f32_16x16x32_bf16 v[80:83], v[172:175], v[210:213], v[80:83]
	v_mfma_f32_16x16x32_bf16 v[68:71], v[148:151], v[218:221], v[68:71]
	v_mfma_f32_16x16x32_bf16 v[64:67], v[172:175], v[218:221], v[64:67]
	s_barrier
	s_setprio 0
	v_lshl_add_u64 v[176:177], v[176:177], 0, s[12:13]
	s_mov_b32 m0, s100
	ds_read_b128 v[186:189], v183 offset:49152
	ds_read_b128 v[190:193], v183 offset:50176
	ds_read_b128 v[198:201], v183 offset:51200
	ds_read_b128 v[202:205], v183 offset:52224
	ds_read_b128 v[206:209], v183 offset:53248
	ds_read_b128 v[210:213], v183 offset:54272
	ds_read_b128 v[214:217], v183 offset:55296
	ds_read_b128 v[218:221], v183 offset:56320
	global_load_lds_dwordx4 v[176:177], off
	s_add_i32 m0, s100, 0x2000
	s_add_u32 s28, s28, 0x80080
	v_lshl_add_u64 v[176:177], v[194:195], 0, s[12:13]
	s_addc_u32 s29, s29, 0
	global_load_lds_dwordx4 v[176:177], off
	s_mov_b32 m0, s101
	s_nop 0
	global_load_lds_dwordx4 v154, s[28:29]
	s_add_i32 m0, s101, 0x2000
	v_lshl_add_u64 v[176:177], s[28:29], 0, v[158:159]
	global_load_lds_dwordx4 v[176:177], off
	s_mov_b32 m0, s39
	v_lshl_add_u64 v[176:177], v[222:223], 0, s[12:13]
	global_load_lds_dwordx4 v[176:177], off
	s_mov_b32 m0, s40
	v_lshl_add_u64 v[176:177], v[224:225], 0, s[12:13]
	global_load_lds_dwordx4 v[176:177], off
	s_waitcnt vmcnt(8) lgkmcnt(0)
	s_setprio 1
	s_barrier
	v_mfma_f32_16x16x32_bf16 v[56:59], v[128:131], v[186:189], v[56:59]
	v_mfma_f32_16x16x32_bf16 v[60:63], v[136:139], v[186:189], v[60:63]
	v_mfma_f32_16x16x32_bf16 v[40:43], v[128:131], v[198:201], v[40:43]
	v_mfma_f32_16x16x32_bf16 v[44:47], v[136:139], v[198:201], v[44:47]
	v_mfma_f32_16x16x32_bf16 v[24:27], v[128:131], v[206:209], v[24:27]
	v_mfma_f32_16x16x32_bf16 v[28:31], v[136:139], v[206:209], v[28:31]
	v_mfma_f32_16x16x32_bf16 v[8:11], v[128:131], v[214:217], v[8:11]
	v_mfma_f32_16x16x32_bf16 v[12:15], v[136:139], v[214:217], v[12:15]
	v_mfma_f32_16x16x32_bf16 v[56:59], v[132:135], v[190:193], v[56:59]
	v_mfma_f32_16x16x32_bf16 v[60:63], v[140:143], v[190:193], v[60:63]
	v_mfma_f32_16x16x32_bf16 v[40:43], v[132:135], v[202:205], v[40:43]
	v_mfma_f32_16x16x32_bf16 v[44:47], v[140:143], v[202:205], v[44:47]
	v_mfma_f32_16x16x32_bf16 v[24:27], v[132:135], v[210:213], v[24:27]
	v_mfma_f32_16x16x32_bf16 v[28:31], v[140:143], v[210:213], v[28:31]
	v_mfma_f32_16x16x32_bf16 v[8:11], v[132:135], v[218:221], v[8:11]
	v_mfma_f32_16x16x32_bf16 v[12:15], v[140:143], v[218:221], v[12:15]
	v_mfma_f32_16x16x32_bf16 v[52:55], v[144:147], v[186:189], v[52:55]
	v_mfma_f32_16x16x32_bf16 v[48:51], v[168:171], v[186:189], v[48:51]
	v_mfma_f32_16x16x32_bf16 v[36:39], v[144:147], v[198:201], v[36:39]
	v_mfma_f32_16x16x32_bf16 v[32:35], v[168:171], v[198:201], v[32:35]
	v_mfma_f32_16x16x32_bf16 v[20:23], v[144:147], v[206:209], v[20:23]
	v_mfma_f32_16x16x32_bf16 v[16:19], v[168:171], v[206:209], v[16:19]
	v_mfma_f32_16x16x32_bf16 v[4:7], v[144:147], v[214:217], v[4:7]
	v_mfma_f32_16x16x32_bf16 v[0:3], v[168:171], v[214:217], v[0:3]
	v_mfma_f32_16x16x32_bf16 v[52:55], v[148:151], v[190:193], v[52:55]
	v_mfma_f32_16x16x32_bf16 v[48:51], v[172:175], v[190:193], v[48:51]
	v_mfma_f32_16x16x32_bf16 v[36:39], v[148:151], v[202:205], v[36:39]
	v_mfma_f32_16x16x32_bf16 v[32:35], v[172:175], v[202:205], v[32:35]
	v_mfma_f32_16x16x32_bf16 v[20:23], v[148:151], v[210:213], v[20:23]
	v_mfma_f32_16x16x32_bf16 v[16:19], v[172:175], v[210:213], v[16:19]
	v_mfma_f32_16x16x32_bf16 v[4:7], v[148:151], v[218:221], v[4:7]
	v_mfma_f32_16x16x32_bf16 v[0:3], v[172:175], v[218:221], v[0:3]
	s_barrier
	s_setprio 0
	s_add_i32 s49, s49, 2
	s_add_u32 s26, s26, 0x100
	s_addc_u32 s27, s27, 0
	s_add_u32 s47, s47, 0x100
	s_addc_u32 s48, s48, 0
	s_cmp_gt_u32 s49, 29
	s_cbranch_scc0 .LBB0_1180
	s_and_b64 vcc, exec, s[14:15]
	s_cbranch_vccz .LBB0_1183
	s_barrier

; #define PG8_STAGE(bufoff, gbase, voff) do { _Pragma("unroll") for (int _i = 0; _i < 2; ++_i) \
;         __builtin_amdgcn_global_load_lds((const unsigned*)((const char*)(gbase) + (voff)[_i]), (PG8_LAS unsigned*)(lds + (bufoff) + ldsw + _i * 8192), 16, 0, 0); } while (0)
; #define PG8_LDA(dst, b, h) do { _Pragma("unroll") for (int m = 0; m < 4; ++m) _Pragma("unroll") for (int k = 0; k < 2; ++k) dst[m][k] = *(const PG8_LAS bf16x8*)(lds + PG8_SA(b, h) + aoff + m * 2048 + k * 1024); } while (0)
; #define PG8_LDB(dst, b, h) do { _Pragma("unroll") for (int n = 0; n < 2; ++n) _Pragma("unroll") for (int k = 0; k < 2; ++k) dst[n][k] = *(const PG8_LAS bf16x8*)(lds + PG8_SB(b, h) + boff + n * 2048 + k * 1024); } while (0)
; #define PG8_MMA(ai, bj, At, Bt) do { __builtin_amdgcn_s_setprio(1); _Pragma("unroll") for (int m = 0; m < 4; ++m) _Pragma("unroll") for (int n = 0; n < 2; ++n) _Pragma("unroll") for (int k = 0; k < 2; ++k) \
;         acc[ai][bj][m][n] = __builtin_amdgcn_mfma_f32_16x16x32_bf16(Bt[n][k], At[m][k], acc[ai][bj][m][n], 0, 0, 0); __builtin_amdgcn_s_setprio(0); } while (0)
; #define PG8_BAR __builtin_amdgcn_s_barrier()
; template <class Epi, class Sched, bool ALIGN_EPI = false, bool SP2 = false>
; __device__ __forceinline__ void gemm_phase(PG8_LAS unsigned char* lds, const Gemm g, const Sched& S, const Epi& E) {
;     ...
;         const bool has_next = S.next(ui + 1, nxt);
;         const char* nA = has_next ? (const char*)g.A + (size_t)nxt.pm * tstep : cA; const char* nB = has_next ? (const char*)g.Bt + (size_t)nxt.pn * tstep : cB;
;         for (int t = 0; t < nt; t += 2) {
;             const bool last = (t == nt - 2);
;             const char* a1 = cA + (size_t)(t + 1) * kstep;
;             const char* a2 = last ? nA : cA + (size_t)(t + 2) * kstep; const char* b2 = last ? nB : cB + (size_t)(t + 2) * kstep;
;             const char* a3 = a2 + kstep; const char* b3 = b2 + kstep;
;             if (last && has_next) S.a_ready(nxt);
;             if constexpr (SP2) {
;             PG8_LDB(B0, 0, 0); PG8_LDB(B1, 0, 1); PG8_SCHED; PG8_LDA(At, 0, 0); PG8_STAGE(PG8_SA(1, 1), a1 + hstep, voffA);
;             PG8_WAIT_V(8); PG8_WAIT_L(0); PG8_BAR; PG8_MMA(0, 0, At, B0); PG8_MMA(0, 1, At, B1); PG8_BAR; PG8_SCHED;
;             PG8_LDA(At, 0, 1); PG8_STAGE(PG8_SB(0, 0), b2, voffB); PG8_STAGE(PG8_SB(0, 1), b2 + hstep, voffB); PG8_STAGE(PG8_SA(0, 0), a2, voffA);
.LBB0_1372:
	s_ashr_i32 s29, s28, 31
	s_lshl_b64 s[34:35], s[28:29], 20
	s_add_u32 s34, s74, s34
	s_addc_u32 s35, s75, s35
	s_and_b64 s[36:37], s[30:31], exec
	s_cselect_b32 s29, s35, s9
	s_cselect_b32 s39, s34, s8
	s_ashr_i32 s27, s26, 31
	s_lshl_b64 s[36:37], s[26:27], 20
	v_readlane_b32 s44, v254, 22
	v_readlane_b32 s45, v254, 23
	s_add_u32 s36, s44, s36
	s_addc_u32 s37, s45, s37
	s_and_b64 s[44:45], s[30:31], exec
	s_cselect_b32 s27, s37, s43
	s_cselect_b32 s41, s36, s42
	s_add_u32 s8, s8, 0x80080
	s_addc_u32 s9, s9, 0
	s_add_u32 s48, s42, 0x100
	s_addc_u32 s49, s43, 0
	s_mov_b32 s66, -2
	s_add_i32 s98, s47, 0x10000
	s_add_i32 s99, s47, 0x14000
	s_add_i32 s100, s47, 0x18000
	s_add_i32 s101, s47, 0x1c000
	ds_read_b128 v[108:111], v173
	ds_read_b128 v[112:115], v173 offset:1024
	ds_read_b128 v[116:119], v173 offset:2048
	ds_read_b128 v[120:123], v173 offset:3072
	ds_read_b128 v[178:181], v175
	ds_read_b128 v[182:185], v175 offset:1024
	ds_read_b128 v[186:189], v175 offset:2048
	ds_read_b128 v[190:193], v175 offset:3072
	s_add_u32 s42, s8, 0xfff80080
	s_addc_u32 s43, s9, -1
	s_cmp_eq_u32 s66, 28
	s_cselect_b32 s45, s29, s43
	s_cselect_b32 s44, s39, s42
	s_cselect_b32 s43, s27, s49
	s_cselect_b32 s42, s41, s48
	s_add_i32 m0, s50, 0xc000
	ds_read_b128 v[198:201], v177
	ds_read_b128 v[202:205], v177 offset:1024
	ds_read_b128 v[206:209], v177 offset:2048
	ds_read_b128 v[210:213], v177 offset:3072
	ds_read_b128 v[214:217], v177 offset:4096
	ds_read_b128 v[218:221], v177 offset:5120
	ds_read_b128 v[222:225], v177 offset:6144
	ds_read_b128 v[226:229], v177 offset:7168
	global_load_lds_dwordx4 v154, s[8:9]
	s_add_i32 m0, s50, 0xe000
	s_nop 0
	global_load_lds_dwordx4 v156, s[8:9]
	s_waitcnt lgkmcnt(0)
	s_setprio 1
	s_barrier
	v_mfma_f32_16x16x32_bf16 v[140:143], v[108:111], v[198:201], 0
	v_mfma_f32_16x16x32_bf16 v[136:139], v[116:119], v[198:201], 0
	v_mfma_f32_16x16x32_bf16 v[100:103], v[108:111], v[206:209], 0
	v_mfma_f32_16x16x32_bf16 v[124:127], v[116:119], v[206:209], 0
	v_mfma_f32_16x16x32_bf16 v[84:87], v[108:111], v[214:217], 0
	v_mfma_f32_16x16x32_bf16 v[92:95], v[116:119], v[214:217], 0
	v_mfma_f32_16x16x32_bf16 v[68:71], v[108:111], v[222:225], 0
	v_mfma_f32_16x16x32_bf16 v[76:79], v[116:119], v[222:225], 0
	v_mfma_f32_16x16x32_bf16 v[140:143], v[112:115], v[202:205], v[140:143]
	v_mfma_f32_16x16x32_bf16 v[136:139], v[120:123], v[202:205], v[136:139]
	v_mfma_f32_16x16x32_bf16 v[100:103], v[112:115], v[210:213], v[100:103]
	v_mfma_f32_16x16x32_bf16 v[124:127], v[120:123], v[210:213], v[124:127]
	v_mfma_f32_16x16x32_bf16 v[84:87], v[112:115], v[218:221], v[84:87]
	v_mfma_f32_16x16x32_bf16 v[92:95], v[120:123], v[218:221], v[92:95]
	v_mfma_f32_16x16x32_bf16 v[68:71], v[112:115], v[226:229], v[68:71]
	v_mfma_f32_16x16x32_bf16 v[76:79], v[120:123], v[226:229], v[76:79]
	v_mfma_f32_16x16x32_bf16 v[128:131], v[178:181], v[198:201], 0
	v_mfma_f32_16x16x32_bf16 v[132:135], v[186:189], v[198:201], 0
	v_mfma_f32_16x16x32_bf16 v[104:107], v[178:181], v[206:209], 0
	v_mfma_f32_16x16x32_bf16 v[96:99], v[186:189], v[206:209], 0
	v_mfma_f32_16x16x32_bf16 v[88:91], v[178:181], v[214:217], 0
	v_mfma_f32_16x16x32_bf16 v[80:83], v[186:189], v[214:217], 0
	v_mfma_f32_16x16x32_bf16 v[72:75], v[178:181], v[222:225], 0
	v_mfma_f32_16x16x32_bf16 v[64:67], v[186:189], v[222:225], 0
	v_mfma_f32_16x16x32_bf16 v[128:131], v[182:185], v[202:205], v[128:131]
	v_mfma_f32_16x16x32_bf16 v[132:135], v[190:193], v[202:205], v[132:135]
	v_mfma_f32_16x16x32_bf16 v[104:107], v[182:185], v[210:213], v[104:107]
	v_mfma_f32_16x16x32_bf16 v[96:99], v[190:193], v[210:213], v[96:99]
	v_mfma_f32_16x16x32_bf16 v[88:91], v[182:185], v[218:221], v[88:91]
	v_mfma_f32_16x16x32_bf16 v[80:83], v[190:193], v[218:221], v[80:83]
	v_mfma_f32_16x16x32_bf16 v[72:75], v[182:185], v[226:229], v[72:75]
	v_mfma_f32_16x16x32_bf16 v[64:67], v[190:193], v[226:229], v[64:67]
	s_barrier
	s_setprio 0
	v_lshl_add_u64 v[160:161], s[42:43], 0, v[144:145]
	s_mov_b32 m0, s98
	ds_read_b128 v[198:201], v177 offset:16384
	ds_read_b128 v[202:205], v177 offset:17408
	ds_read_b128 v[206:209], v177 offset:18432
	ds_read_b128 v[210:213], v177 offset:19456
	ds_read_b128 v[214:217], v177 offset:20480
	ds_read_b128 v[218:221], v177 offset:21504
	ds_read_b128 v[222:225], v177 offset:22528
	ds_read_b128 v[226:229], v177 offset:23552
	global_load_lds_dwordx4 v[160:161], off
	s_add_i32 m0, s98, 0x2000
	s_add_u32 s68, s42, 0x80000
	v_lshl_add_u64 v[164:165], s[42:43], 0, v[146:147]
	s_addc_u32 s69, s43, 0
	global_load_lds_dwordx4 v[164:165], off
	s_mov_b32 m0, s99
	v_lshl_add_u64 v[194:195], s[44:45], 0, v[146:147]
	global_load_lds_dwordx4 v144, s[68:69]
	s_add_i32 m0, s99, 0x2000
	s_nop 0
	global_load_lds_dwordx4 v146, s[68:69]
	s_mov_b32 m0, s50
	v_lshl_add_u64 v[170:171], s[44:45], 0, v[144:145]
	global_load_lds_dwordx4 v[170:171], off
	s_mov_b32 m0, s51
	s_nop 0
	global_load_lds_dwordx4 v[194:195], off
	s_waitcnt lgkmcnt(0)
	s_setprio 1
	s_barrier
; #define PG8_STAGE(bufoff, gbase, voff) do { _Pragma("unroll") for (int _i = 0; _i < 2; ++_i) \
;         __builtin_amdgcn_global_load_lds((const unsigned*)((const char*)(gbase) + (voff)[_i]), (PG8_LAS unsigned*)(lds + (bufoff) + ldsw + _i * 8192), 16, 0, 0); } while (0)
; #define PG8_LDA(dst, b, h) do { _Pragma("unroll") for (int m = 0; m < 4; ++m) _Pragma("unroll") for (int k = 0; k < 2; ++k) dst[m][k] = *(const PG8_LAS bf16x8*)(lds + PG8_SA(b, h) + aoff + m * 2048 + k * 1024); } while (0)
; #define PG8_LDB(dst, b, h) do { _Pragma("unroll") for (int n = 0; n < 2; ++n) _Pragma("unroll") for (int k = 0; k < 2; ++k) dst[n][k] = *(const PG8_LAS bf16x8*)(lds + PG8_SB(b, h) + boff + n * 2048 + k * 1024); } while (0)
; #define PG8_MMA(ai, bj, At, Bt) do { __builtin_amdgcn_s_setprio(1); _Pragma("unroll") for (int m = 0; m < 4; ++m) _Pragma("unroll") for (int n = 0; n < 2; ++n) _Pragma("unroll") for (int k = 0; k < 2; ++k) \
;         acc[ai][bj][m][n] = __builtin_amdgcn_mfma_f32_16x16x32_bf16(Bt[n][k], At[m][k], acc[ai][bj][m][n], 0, 0, 0); __builtin_amdgcn_s_setprio(0); } while (0)
; #define PG8_WAIT_V(n) asm volatile("s_waitcnt vmcnt(" #n ")" ::: "memory")
; #define PG8_WAIT_L(n) asm volatile("s_waitcnt lgkmcnt(" #n ")" ::: "memory")
; #define PG8_BAR __builtin_amdgcn_s_barrier()
; #define PG8_SCHED __builtin_amdgcn_sched_barrier(0)
; template <class Epi, class Sched, bool ALIGN_EPI = false, bool SP2 = false>
; __device__ __forceinline__ void gemm_phase(PG8_LAS unsigned char* lds, const Gemm g, const Sched& S, const Epi& E) {
;     ...
;             PG8_WAIT_V(8); PG8_WAIT_L(0); PG8_BAR; PG8_MMA(1, 0, At, B0); PG8_MMA(1, 1, At, B1); PG8_BAR; PG8_SCHED;
;             PG8_LDB(B0, 1, 0); PG8_LDB(B1, 1, 1); PG8_SCHED; PG8_LDA(At, 1, 0); PG8_STAGE(PG8_SA(0, 1), a2 + hstep, voffA);
;             PG8_WAIT_V(8); PG8_WAIT_L(0); PG8_BAR; PG8_MMA(0, 0, At, B0); PG8_MMA(0, 1, At, B1); PG8_BAR; PG8_SCHED;
	v_mfma_f32_16x16x32_bf16 v[60:63], v[108:111], v[198:201], 0
	v_mfma_f32_16x16x32_bf16 v[56:59], v[116:119], v[198:201], 0
	v_mfma_f32_16x16x32_bf16 v[36:39], v[108:111], v[206:209], 0
	v_mfma_f32_16x16x32_bf16 v[44:47], v[116:119], v[206:209], 0
	v_mfma_f32_16x16x32_bf16 v[20:23], v[108:111], v[214:217], 0
	v_mfma_f32_16x16x32_bf16 v[28:31], v[116:119], v[214:217], 0
	v_mfma_f32_16x16x32_bf16 v[4:7], v[108:111], v[222:225], 0
	v_mfma_f32_16x16x32_bf16 v[12:15], v[116:119], v[222:225], 0
	v_mfma_f32_16x16x32_bf16 v[60:63], v[112:115], v[202:205], v[60:63]
	v_mfma_f32_16x16x32_bf16 v[56:59], v[120:123], v[202:205], v[56:59]
	v_mfma_f32_16x16x32_bf16 v[36:39], v[112:115], v[210:213], v[36:39]
	v_mfma_f32_16x16x32_bf16 v[44:47], v[120:123], v[210:213], v[44:47]
	v_mfma_f32_16x16x32_bf16 v[20:23], v[112:115], v[218:221], v[20:23]
	v_mfma_f32_16x16x32_bf16 v[28:31], v[120:123], v[218:221], v[28:31]
	v_mfma_f32_16x16x32_bf16 v[4:7], v[112:115], v[226:229], v[4:7]
	v_mfma_f32_16x16x32_bf16 v[12:15], v[120:123], v[226:229], v[12:15]
	v_mfma_f32_16x16x32_bf16 v[48:51], v[178:181], v[198:201], 0
	v_mfma_f32_16x16x32_bf16 v[52:55], v[186:189], v[198:201], 0
	v_mfma_f32_16x16x32_bf16 v[40:43], v[178:181], v[206:209], 0
	v_mfma_f32_16x16x32_bf16 v[32:35], v[186:189], v[206:209], 0
	v_mfma_f32_16x16x32_bf16 v[24:27], v[178:181], v[214:217], 0
	v_mfma_f32_16x16x32_bf16 v[16:19], v[186:189], v[214:217], 0
	v_mfma_f32_16x16x32_bf16 v[8:11], v[178:181], v[222:225], 0
	v_mfma_f32_16x16x32_bf16 v[0:3], v[186:189], v[222:225], 0
	v_mfma_f32_16x16x32_bf16 v[48:51], v[182:185], v[202:205], v[48:51]
	v_mfma_f32_16x16x32_bf16 v[52:55], v[190:193], v[202:205], v[52:55]
	v_mfma_f32_16x16x32_bf16 v[40:43], v[182:185], v[210:213], v[40:43]
	v_mfma_f32_16x16x32_bf16 v[32:35], v[190:193], v[210:213], v[32:35]
	v_mfma_f32_16x16x32_bf16 v[24:27], v[182:185], v[218:221], v[24:27]
	v_mfma_f32_16x16x32_bf16 v[16:19], v[190:193], v[218:221], v[16:19]
	v_mfma_f32_16x16x32_bf16 v[8:11], v[182:185], v[226:229], v[8:11]
	v_mfma_f32_16x16x32_bf16 v[0:3], v[190:193], v[226:229], v[0:3]
	s_barrier
	s_setprio 0
	s_add_i32 s67, 0, 0x18000
	s_add_i32 s68, 0, 0x1c000
	v_add_u32_e32 v120, s67, v167
	v_add_u32_e32 v162, s68, v167
	ds_read_b128 v[108:111], v120
	ds_read_b128 v[112:115], v120 offset:1024
	ds_read_b128 v[116:119], v120 offset:2048
	ds_read_b128 v[120:123], v120 offset:3072
	ds_read_b128 v[178:181], v162
	ds_read_b128 v[182:185], v162 offset:1024
	ds_read_b128 v[186:189], v162 offset:2048
	ds_read_b128 v[190:193], v162 offset:3072
	s_add_u32 s44, s44, 0x80000
	s_addc_u32 s45, s45, 0
	s_mov_b32 m0, s52
	ds_read_b128 v[198:201], v177 offset:32768
	ds_read_b128 v[202:205], v177 offset:33792
	ds_read_b128 v[206:209], v177 offset:34816
	ds_read_b128 v[210:213], v177 offset:35840
	ds_read_b128 v[214:217], v177 offset:36864
	ds_read_b128 v[218:221], v177 offset:37888
	ds_read_b128 v[222:225], v177 offset:38912
	ds_read_b128 v[226:229], v177 offset:39936
	global_load_lds_dwordx4 v144, s[44:45]
	s_mov_b32 m0, s53
	v_lshl_add_u64 v[230:231], s[44:45], 0, v[146:147]
	global_load_lds_dwordx4 v[230:231], off
	s_waitcnt vmcnt(8) lgkmcnt(0)
	s_setprio 1
	s_barrier
	v_mfma_f32_16x16x32_bf16 v[140:143], v[108:111], v[198:201], v[140:143]
	v_mfma_f32_16x16x32_bf16 v[136:139], v[116:119], v[198:201], v[136:139]
	v_mfma_f32_16x16x32_bf16 v[100:103], v[108:111], v[206:209], v[100:103]
	v_mfma_f32_16x16x32_bf16 v[124:127], v[116:119], v[206:209], v[124:127]
	v_mfma_f32_16x16x32_bf16 v[84:87], v[108:111], v[214:217], v[84:87]
	v_mfma_f32_16x16x32_bf16 v[92:95], v[116:119], v[214:217], v[92:95]
	v_mfma_f32_16x16x32_bf16 v[68:71], v[108:111], v[222:225], v[68:71]
	v_mfma_f32_16x16x32_bf16 v[76:79], v[116:119], v[222:225], v[76:79]
	v_mfma_f32_16x16x32_bf16 v[140:143], v[112:115], v[202:205], v[140:143]
	v_mfma_f32_16x16x32_bf16 v[136:139], v[120:123], v[202:205], v[136:139]
	v_mfma_f32_16x16x32_bf16 v[100:103], v[112:115], v[210:213], v[100:103]
	v_mfma_f32_16x16x32_bf16 v[124:127], v[120:123], v[210:213], v[124:127]
	v_mfma_f32_16x16x32_bf16 v[84:87], v[112:115], v[218:221], v[84:87]
	v_mfma_f32_16x16x32_bf16 v[92:95], v[120:123], v[218:221], v[92:95]
	v_mfma_f32_16x16x32_bf16 v[68:71], v[112:115], v[226:229], v[68:71]
	v_mfma_f32_16x16x32_bf16 v[76:79], v[120:123], v[226:229], v[76:79]
	v_mfma_f32_16x16x32_bf16 v[128:131], v[178:181], v[198:201], v[128:131]
	v_mfma_f32_16x16x32_bf16 v[132:135], v[186:189], v[198:201], v[132:135]
	v_mfma_f32_16x16x32_bf16 v[104:107], v[178:181], v[206:209], v[104:107]
	v_mfma_f32_16x16x32_bf16 v[96:99], v[186:189], v[206:209], v[96:99]
	v_mfma_f32_16x16x32_bf16 v[88:91], v[178:181], v[214:217], v[88:91]
	v_mfma_f32_16x16x32_bf16 v[80:83], v[186:189], v[214:217], v[80:83]
	v_mfma_f32_16x16x32_bf16 v[72:75], v[178:181], v[222:225], v[72:75]
	v_mfma_f32_16x16x32_bf16 v[64:67], v[186:189], v[222:225], v[64:67]
	v_mfma_f32_16x16x32_bf16 v[128:131], v[182:185], v[202:205], v[128:131]
	v_mfma_f32_16x16x32_bf16 v[132:135], v[190:193], v[202:205], v[132:135]
	v_mfma_f32_16x16x32_bf16 v[104:107], v[182:185], v[210:213], v[104:107]
	v_mfma_f32_16x16x32_bf16 v[96:99], v[190:193], v[210:213], v[96:99]
	v_mfma_f32_16x16x32_bf16 v[88:91], v[182:185], v[218:221], v[88:91]
	v_mfma_f32_16x16x32_bf16 v[80:83], v[190:193], v[218:221], v[80:83]
	v_mfma_f32_16x16x32_bf16 v[72:75], v[182:185], v[226:229], v[72:75]
	v_mfma_f32_16x16x32_bf16 v[64:67], v[190:193], v[226:229], v[64:67]
	s_barrier
; #define PG8_STAGE(bufoff, gbase, voff) do { _Pragma("unroll") for (int _i = 0; _i < 2; ++_i) \
;         __builtin_amdgcn_global_load_lds((const unsigned*)((const char*)(gbase) + (voff)[_i]), (PG8_LAS unsigned*)(lds + (bufoff) + ldsw + _i * 8192), 16, 0, 0); } while (0)
; #define PG8_LDA(dst, b, h) do { _Pragma("unroll") for (int m = 0; m < 4; ++m) _Pragma("unroll") for (int k = 0; k < 2; ++k) dst[m][k] = *(const PG8_LAS bf16x8*)(lds + PG8_SA(b, h) + aoff + m * 2048 + k * 1024); } while (0)
; #define PG8_LDB(dst, b, h) do { _Pragma("unroll") for (int n = 0; n < 2; ++n) _Pragma("unroll") for (int k = 0; k < 2; ++k) dst[n][k] = *(const PG8_LAS bf16x8*)(lds + PG8_SB(b, h) + boff + n * 2048 + k * 1024); } while (0)
; #define PG8_MMA(ai, bj, At, Bt) do { __builtin_amdgcn_s_setprio(1); _Pragma("unroll") for (int m = 0; m < 4; ++m) _Pragma("unroll") for (int n = 0; n < 2; ++n) _Pragma("unroll") for (int k = 0; k < 2; ++k) \
;         acc[ai][bj][m][n] = __builtin_amdgcn_mfma_f32_16x16x32_bf16(Bt[n][k], At[m][k], acc[ai][bj][m][n], 0, 0, 0); __builtin_amdgcn_s_setprio(0); } while (0)
; #define PG8_WAIT_V(n) asm volatile("s_waitcnt vmcnt(" #n ")" ::: "memory")
; #define PG8_BAR __builtin_amdgcn_s_barrier()
; template <class Epi, class Sched, bool ALIGN_EPI = false, bool SP2 = false>
; __device__ __forceinline__ void gemm_phase(PG8_LAS unsigned char* lds, const Gemm g, const Sched& S, const Epi& E) {
;     ...
;         for (int t = 0; t < nt; t += 2) {
;             const bool last = (t == nt - 2);
;             const char* a1 = cA + (size_t)(t + 1) * kstep;
;             const char* a2 = last ? nA : cA + (size_t)(t + 2) * kstep; const char* b2 = last ? nB : cB + (size_t)(t + 2) * kstep;
;             const char* a3 = a2 + kstep; const char* b3 = b2 + kstep;
;             if (last && has_next) S.a_ready(nxt);
;             if constexpr (SP2) {
;             PG8_LDB(B0, 0, 0); PG8_LDB(B1, 0, 1); PG8_SCHED; PG8_LDA(At, 0, 0); PG8_STAGE(PG8_SA(1, 1), a1 + hstep, voffA);
;             PG8_WAIT_V(8); PG8_WAIT_L(0); PG8_BAR; PG8_MMA(0, 0, At, B0); PG8_MMA(0, 1, At, B1); PG8_BAR; PG8_SCHED;
;     ...
;             PG8_LDA(At, 1, 1); PG8_STAGE(PG8_SB(1, 0), b3, voffB); PG8_STAGE(PG8_SB(1, 1), b3 + hstep, voffB); PG8_STAGE(PG8_SA(1, 0), a3, voffA);
;             PG8_WAIT_V(8); PG8_WAIT_L(0); PG8_BAR; PG8_MMA(1, 0, At, B0); PG8_MMA(1, 1, At, B1); PG8_BAR; PG8_SCHED;
	s_setprio 0
	v_lshl_add_u64 v[160:161], v[160:161], 0, s[16:17]
	s_mov_b32 m0, s100
	ds_read_b128 v[198:201], v177 offset:49152
	ds_read_b128 v[202:205], v177 offset:50176
	ds_read_b128 v[206:209], v177 offset:51200
	ds_read_b128 v[210:213], v177 offset:52224
	ds_read_b128 v[214:217], v177 offset:53248
	ds_read_b128 v[218:221], v177 offset:54272
	ds_read_b128 v[222:225], v177 offset:55296
	ds_read_b128 v[226:229], v177 offset:56320
	global_load_lds_dwordx4 v[160:161], off
	s_add_i32 m0, s100, 0x2000
	s_add_u32 s42, s42, 0x80080
	v_lshl_add_u64 v[160:161], v[164:165], 0, s[16:17]
	s_addc_u32 s43, s43, 0
	global_load_lds_dwordx4 v[160:161], off
	s_mov_b32 m0, s101
	s_nop 0
	global_load_lds_dwordx4 v144, s[42:43]
	s_add_i32 m0, s101, 0x2000
	v_lshl_add_u64 v[160:161], s[42:43], 0, v[146:147]
	global_load_lds_dwordx4 v[160:161], off
	s_mov_b32 m0, s55
	v_lshl_add_u64 v[160:161], v[170:171], 0, s[16:17]
	global_load_lds_dwordx4 v[160:161], off
	s_mov_b32 m0, s56
	v_lshl_add_u64 v[160:161], v[194:195], 0, s[16:17]
	global_load_lds_dwordx4 v[160:161], off
	s_waitcnt vmcnt(8) lgkmcnt(0)
	s_setprio 1
	s_barrier
	v_mfma_f32_16x16x32_bf16 v[60:63], v[108:111], v[198:201], v[60:63]
	v_mfma_f32_16x16x32_bf16 v[56:59], v[116:119], v[198:201], v[56:59]
	v_mfma_f32_16x16x32_bf16 v[36:39], v[108:111], v[206:209], v[36:39]
	v_mfma_f32_16x16x32_bf16 v[44:47], v[116:119], v[206:209], v[44:47]
	v_mfma_f32_16x16x32_bf16 v[20:23], v[108:111], v[214:217], v[20:23]
	v_mfma_f32_16x16x32_bf16 v[28:31], v[116:119], v[214:217], v[28:31]
	v_mfma_f32_16x16x32_bf16 v[4:7], v[108:111], v[222:225], v[4:7]
	v_mfma_f32_16x16x32_bf16 v[12:15], v[116:119], v[222:225], v[12:15]
	v_mfma_f32_16x16x32_bf16 v[60:63], v[112:115], v[202:205], v[60:63]
	v_mfma_f32_16x16x32_bf16 v[56:59], v[120:123], v[202:205], v[56:59]
	v_mfma_f32_16x16x32_bf16 v[36:39], v[112:115], v[210:213], v[36:39]
	v_mfma_f32_16x16x32_bf16 v[44:47], v[120:123], v[210:213], v[44:47]
	v_mfma_f32_16x16x32_bf16 v[20:23], v[112:115], v[218:221], v[20:23]
	v_mfma_f32_16x16x32_bf16 v[28:31], v[120:123], v[218:221], v[28:31]
	v_mfma_f32_16x16x32_bf16 v[4:7], v[112:115], v[226:229], v[4:7]
	v_mfma_f32_16x16x32_bf16 v[12:15], v[120:123], v[226:229], v[12:15]
	v_mfma_f32_16x16x32_bf16 v[48:51], v[178:181], v[198:201], v[48:51]
	v_mfma_f32_16x16x32_bf16 v[52:55], v[186:189], v[198:201], v[52:55]
	v_mfma_f32_16x16x32_bf16 v[40:43], v[178:181], v[206:209], v[40:43]
	v_mfma_f32_16x16x32_bf16 v[32:35], v[186:189], v[206:209], v[32:35]
	v_mfma_f32_16x16x32_bf16 v[24:27], v[178:181], v[214:217], v[24:27]
	v_mfma_f32_16x16x32_bf16 v[16:19], v[186:189], v[214:217], v[16:19]
	v_mfma_f32_16x16x32_bf16 v[8:11], v[178:181], v[222:225], v[8:11]
	v_mfma_f32_16x16x32_bf16 v[0:3], v[186:189], v[222:225], v[0:3]
	v_mfma_f32_16x16x32_bf16 v[48:51], v[182:185], v[202:205], v[48:51]
	v_mfma_f32_16x16x32_bf16 v[52:55], v[190:193], v[202:205], v[52:55]
	v_mfma_f32_16x16x32_bf16 v[40:43], v[182:185], v[210:213], v[40:43]
	v_mfma_f32_16x16x32_bf16 v[32:35], v[190:193], v[210:213], v[32:35]
	v_mfma_f32_16x16x32_bf16 v[24:27], v[182:185], v[218:221], v[24:27]
	v_mfma_f32_16x16x32_bf16 v[16:19], v[190:193], v[218:221], v[16:19]
	v_mfma_f32_16x16x32_bf16 v[8:11], v[182:185], v[226:229], v[8:11]
	v_mfma_f32_16x16x32_bf16 v[0:3], v[190:193], v[226:229], v[0:3]
	s_barrier
	s_setprio 0
	s_add_i32 s66, s66, 2
	s_add_u32 s8, s8, 0x100
	s_addc_u32 s9, s9, 0
	s_add_u32 s48, s48, 0x100
	s_addc_u32 s49, s49, 0
.LBB0_1373:
	ds_read_b128 v[108:111], v173
	ds_read_b128 v[112:115], v173 offset:1024
	ds_read_b128 v[116:119], v173 offset:2048
	ds_read_b128 v[120:123], v173 offset:3072
	ds_read_b128 v[178:181], v175
	ds_read_b128 v[182:185], v175 offset:1024
	ds_read_b128 v[186:189], v175 offset:2048
	ds_read_b128 v[190:193], v175 offset:3072
	s_add_u32 s42, s8, 0xfff80080
	s_addc_u32 s43, s9, -1
	s_cmp_eq_u32 s66, 28
	s_cselect_b32 s45, s29, s43
	s_cselect_b32 s44, s39, s42
	s_cselect_b32 s43, s27, s49
	s_cselect_b32 s42, s41, s48
	s_add_i32 m0, s50, 0xc000
	ds_read_b128 v[198:201], v177
	ds_read_b128 v[202:205], v177 offset:1024
	ds_read_b128 v[206:209], v177 offset:2048
	ds_read_b128 v[210:213], v177 offset:3072
	ds_read_b128 v[214:217], v177 offset:4096
	ds_read_b128 v[218:221], v177 offset:5120
	ds_read_b128 v[222:225], v177 offset:6144
	ds_read_b128 v[226:229], v177 offset:7168
	global_load_lds_dwordx4 v154, s[8:9]
	s_add_i32 m0, s50, 0xe000
	s_nop 0
	global_load_lds_dwordx4 v156, s[8:9]
	s_waitcnt vmcnt(8) lgkmcnt(0)
	s_setprio 1
	s_barrier
; #define PG8_STAGE(bufoff, gbase, voff) do { _Pragma("unroll") for (int _i = 0; _i < 2; ++_i) \
;         __builtin_amdgcn_global_load_lds((const unsigned*)((const char*)(gbase) + (voff)[_i]), (PG8_LAS unsigned*)(lds + (bufoff) + ldsw + _i * 8192), 16, 0, 0); } while (0)
; #define PG8_LDA(dst, b, h) do { _Pragma("unroll") for (int m = 0; m < 4; ++m) _Pragma("unroll") for (int k = 0; k < 2; ++k) dst[m][k] = *(const PG8_LAS bf16x8*)(lds + PG8_SA(b, h) + aoff + m * 2048 + k * 1024); } while (0)
; #define PG8_MMA(ai, bj, At, Bt) do { __builtin_amdgcn_s_setprio(1); _Pragma("unroll") for (int m = 0; m < 4; ++m) _Pragma("unroll") for (int n = 0; n < 2; ++n) _Pragma("unroll") for (int k = 0; k < 2; ++k) \
;         acc[ai][bj][m][n] = __builtin_amdgcn_mfma_f32_16x16x32_bf16(Bt[n][k], At[m][k], acc[ai][bj][m][n], 0, 0, 0); __builtin_amdgcn_s_setprio(0); } while (0)
; #define PG8_WAIT_V(n) asm volatile("s_waitcnt vmcnt(" #n ")" ::: "memory")
; #define PG8_WAIT_L(n) asm volatile("s_waitcnt lgkmcnt(" #n ")" ::: "memory")
; #define PG8_BAR __builtin_amdgcn_s_barrier()
; #define PG8_SCHED __builtin_amdgcn_sched_barrier(0)
; template <class Epi, class Sched, bool ALIGN_EPI = false, bool SP2 = false>
; __device__ __forceinline__ void gemm_phase(PG8_LAS unsigned char* lds, const Gemm g, const Sched& S, const Epi& E) {
;     ...
;             PG8_WAIT_V(8); PG8_WAIT_L(0); PG8_BAR; PG8_MMA(0, 0, At, B0); PG8_MMA(0, 1, At, B1); PG8_BAR; PG8_SCHED;
;             PG8_LDA(At, 0, 1); PG8_STAGE(PG8_SB(0, 0), b2, voffB); PG8_STAGE(PG8_SB(0, 1), b2 + hstep, voffB); PG8_STAGE(PG8_SA(0, 0), a2, voffA);
;             PG8_WAIT_V(8); PG8_WAIT_L(0); PG8_BAR; PG8_MMA(1, 0, At, B0); PG8_MMA(1, 1, At, B1); PG8_BAR; PG8_SCHED;
	v_mfma_f32_16x16x32_bf16 v[140:143], v[108:111], v[198:201], v[140:143]
	v_mfma_f32_16x16x32_bf16 v[136:139], v[116:119], v[198:201], v[136:139]
	v_mfma_f32_16x16x32_bf16 v[100:103], v[108:111], v[206:209], v[100:103]
	v_mfma_f32_16x16x32_bf16 v[124:127], v[116:119], v[206:209], v[124:127]
	v_mfma_f32_16x16x32_bf16 v[84:87], v[108:111], v[214:217], v[84:87]
	v_mfma_f32_16x16x32_bf16 v[92:95], v[116:119], v[214:217], v[92:95]
	v_mfma_f32_16x16x32_bf16 v[68:71], v[108:111], v[222:225], v[68:71]
	v_mfma_f32_16x16x32_bf16 v[76:79], v[116:119], v[222:225], v[76:79]
	v_mfma_f32_16x16x32_bf16 v[140:143], v[112:115], v[202:205], v[140:143]
	v_mfma_f32_16x16x32_bf16 v[136:139], v[120:123], v[202:205], v[136:139]
	v_mfma_f32_16x16x32_bf16 v[100:103], v[112:115], v[210:213], v[100:103]
	v_mfma_f32_16x16x32_bf16 v[124:127], v[120:123], v[210:213], v[124:127]
	v_mfma_f32_16x16x32_bf16 v[84:87], v[112:115], v[218:221], v[84:87]
	v_mfma_f32_16x16x32_bf16 v[92:95], v[120:123], v[218:221], v[92:95]
	v_mfma_f32_16x16x32_bf16 v[68:71], v[112:115], v[226:229], v[68:71]
	v_mfma_f32_16x16x32_bf16 v[76:79], v[120:123], v[226:229], v[76:79]
	v_mfma_f32_16x16x32_bf16 v[128:131], v[178:181], v[198:201], v[128:131]
	v_mfma_f32_16x16x32_bf16 v[132:135], v[186:189], v[198:201], v[132:135]
	v_mfma_f32_16x16x32_bf16 v[104:107], v[178:181], v[206:209], v[104:107]
	v_mfma_f32_16x16x32_bf16 v[96:99], v[186:189], v[206:209], v[96:99]
	v_mfma_f32_16x16x32_bf16 v[88:91], v[178:181], v[214:217], v[88:91]
	v_mfma_f32_16x16x32_bf16 v[80:83], v[186:189], v[214:217], v[80:83]
	v_mfma_f32_16x16x32_bf16 v[72:75], v[178:181], v[222:225], v[72:75]
	v_mfma_f32_16x16x32_bf16 v[64:67], v[186:189], v[222:225], v[64:67]
	v_mfma_f32_16x16x32_bf16 v[128:131], v[182:185], v[202:205], v[128:131]
	v_mfma_f32_16x16x32_bf16 v[132:135], v[190:193], v[202:205], v[132:135]
	v_mfma_f32_16x16x32_bf16 v[104:107], v[182:185], v[210:213], v[104:107]
	v_mfma_f32_16x16x32_bf16 v[96:99], v[190:193], v[210:213], v[96:99]
	v_mfma_f32_16x16x32_bf16 v[88:91], v[182:185], v[218:221], v[88:91]
	v_mfma_f32_16x16x32_bf16 v[80:83], v[190:193], v[218:221], v[80:83]
	v_mfma_f32_16x16x32_bf16 v[72:75], v[182:185], v[226:229], v[72:75]
	v_mfma_f32_16x16x32_bf16 v[64:67], v[190:193], v[226:229], v[64:67]
	s_barrier
	s_setprio 0
	v_lshl_add_u64 v[160:161], s[42:43], 0, v[144:145]
	s_mov_b32 m0, s98
	ds_read_b128 v[198:201], v177 offset:16384
	ds_read_b128 v[202:205], v177 offset:17408
	ds_read_b128 v[206:209], v177 offset:18432
	ds_read_b128 v[210:213], v177 offset:19456
	ds_read_b128 v[214:217], v177 offset:20480
	ds_read_b128 v[218:221], v177 offset:21504
	ds_read_b128 v[222:225], v177 offset:22528
	ds_read_b128 v[226:229], v177 offset:23552
	global_load_lds_dwordx4 v[160:161], off
	s_add_i32 m0, s98, 0x2000
	s_add_u32 s68, s42, 0x80000
	v_lshl_add_u64 v[164:165], s[42:43], 0, v[146:147]
	s_addc_u32 s69, s43, 0
	global_load_lds_dwordx4 v[164:165], off
	s_mov_b32 m0, s99
	v_lshl_add_u64 v[194:195], s[44:45], 0, v[146:147]
	global_load_lds_dwordx4 v144, s[68:69]
	s_add_i32 m0, s99, 0x2000
	s_nop 0
	global_load_lds_dwordx4 v146, s[68:69]
	s_mov_b32 m0, s50
	v_lshl_add_u64 v[170:171], s[44:45], 0, v[144:145]
	global_load_lds_dwordx4 v[170:171], off
	s_mov_b32 m0, s51
	s_nop 0
	global_load_lds_dwordx4 v[194:195], off
	s_waitcnt vmcnt(8) lgkmcnt(0)
	s_setprio 1
	s_barrier
	v_mfma_f32_16x16x32_bf16 v[60:63], v[108:111], v[198:201], v[60:63]
	v_mfma_f32_16x16x32_bf16 v[56:59], v[116:119], v[198:201], v[56:59]
	v_mfma_f32_16x16x32_bf16 v[36:39], v[108:111], v[206:209], v[36:39]
	v_mfma_f32_16x16x32_bf16 v[44:47], v[116:119], v[206:209], v[44:47]
	v_mfma_f32_16x16x32_bf16 v[20:23], v[108:111], v[214:217], v[20:23]
	v_mfma_f32_16x16x32_bf16 v[28:31], v[116:119], v[214:217], v[28:31]
	v_mfma_f32_16x16x32_bf16 v[4:7], v[108:111], v[222:225], v[4:7]
	v_mfma_f32_16x16x32_bf16 v[12:15], v[116:119], v[222:225], v[12:15]
	v_mfma_f32_16x16x32_bf16 v[60:63], v[112:115], v[202:205], v[60:63]
	v_mfma_f32_16x16x32_bf16 v[56:59], v[120:123], v[202:205], v[56:59]
	v_mfma_f32_16x16x32_bf16 v[36:39], v[112:115], v[210:213], v[36:39]
	v_mfma_f32_16x16x32_bf16 v[44:47], v[120:123], v[210:213], v[44:47]
	v_mfma_f32_16x16x32_bf16 v[20:23], v[112:115], v[218:221], v[20:23]
	v_mfma_f32_16x16x32_bf16 v[28:31], v[120:123], v[218:221], v[28:31]
	v_mfma_f32_16x16x32_bf16 v[4:7], v[112:115], v[226:229], v[4:7]
	v_mfma_f32_16x16x32_bf16 v[12:15], v[120:123], v[226:229], v[12:15]
	v_mfma_f32_16x16x32_bf16 v[48:51], v[178:181], v[198:201], v[48:51]
	v_mfma_f32_16x16x32_bf16 v[52:55], v[186:189], v[198:201], v[52:55]
	v_mfma_f32_16x16x32_bf16 v[40:43], v[178:181], v[206:209], v[40:43]
	v_mfma_f32_16x16x32_bf16 v[32:35], v[186:189], v[206:209], v[32:35]
	v_mfma_f32_16x16x32_bf16 v[24:27], v[178:181], v[214:217], v[24:27]
	v_mfma_f32_16x16x32_bf16 v[16:19], v[186:189], v[214:217], v[16:19]
	v_mfma_f32_16x16x32_bf16 v[8:11], v[178:181], v[222:225], v[8:11]
	v_mfma_f32_16x16x32_bf16 v[0:3], v[186:189], v[222:225], v[0:3]
	v_mfma_f32_16x16x32_bf16 v[48:51], v[182:185], v[202:205], v[48:51]
	v_mfma_f32_16x16x32_bf16 v[52:55], v[190:193], v[202:205], v[52:55]
	v_mfma_f32_16x16x32_bf16 v[40:43], v[182:185], v[210:213], v[40:43]
	v_mfma_f32_16x16x32_bf16 v[32:35], v[190:193], v[210:213], v[32:35]
	v_mfma_f32_16x16x32_bf16 v[24:27], v[182:185], v[218:221], v[24:27]
	v_mfma_f32_16x16x32_bf16 v[16:19], v[190:193], v[218:221], v[16:19]
	v_mfma_f32_16x16x32_bf16 v[8:11], v[182:185], v[226:229], v[8:11]
	v_mfma_f32_16x16x32_bf16 v[0:3], v[190:193], v[226:229], v[0:3]
	s_barrier
; #define PG8_STAGE(bufoff, gbase, voff) do { _Pragma("unroll") for (int _i = 0; _i < 2; ++_i) \
;         __builtin_amdgcn_global_load_lds((const unsigned*)((const char*)(gbase) + (voff)[_i]), (PG8_LAS unsigned*)(lds + (bufoff) + ldsw + _i * 8192), 16, 0, 0); } while (0)
; #define PG8_LDA(dst, b, h) do { _Pragma("unroll") for (int m = 0; m < 4; ++m) _Pragma("unroll") for (int k = 0; k < 2; ++k) dst[m][k] = *(const PG8_LAS bf16x8*)(lds + PG8_SA(b, h) + aoff + m * 2048 + k * 1024); } while (0)
; #define PG8_LDB(dst, b, h) do { _Pragma("unroll") for (int n = 0; n < 2; ++n) _Pragma("unroll") for (int k = 0; k < 2; ++k) dst[n][k] = *(const PG8_LAS bf16x8*)(lds + PG8_SB(b, h) + boff + n * 2048 + k * 1024); } while (0)
; #define PG8_MMA(ai, bj, At, Bt) do { __builtin_amdgcn_s_setprio(1); _Pragma("unroll") for (int m = 0; m < 4; ++m) _Pragma("unroll") for (int n = 0; n < 2; ++n) _Pragma("unroll") for (int k = 0; k < 2; ++k) \
;         acc[ai][bj][m][n] = __builtin_amdgcn_mfma_f32_16x16x32_bf16(Bt[n][k], At[m][k], acc[ai][bj][m][n], 0, 0, 0); __builtin_amdgcn_s_setprio(0); } while (0)
; #define PG8_WAIT_V(n) asm volatile("s_waitcnt vmcnt(" #n ")" ::: "memory")
; #define PG8_WAIT_L(n) asm volatile("s_waitcnt lgkmcnt(" #n ")" ::: "memory")
; #define PG8_BAR __builtin_amdgcn_s_barrier()
; #define PG8_SCHED __builtin_amdgcn_sched_barrier(0)
; template <class Epi, class Sched, bool ALIGN_EPI = false, bool SP2 = false>
; __device__ __forceinline__ void gemm_phase(PG8_LAS unsigned char* lds, const Gemm g, const Sched& S, const Epi& E) {
;     ...
;             PG8_LDB(B0, 1, 0); PG8_LDB(B1, 1, 1); PG8_SCHED; PG8_LDA(At, 1, 0); PG8_STAGE(PG8_SA(0, 1), a2 + hstep, voffA);
;             PG8_WAIT_V(8); PG8_WAIT_L(0); PG8_BAR; PG8_MMA(0, 0, At, B0); PG8_MMA(0, 1, At, B1); PG8_BAR; PG8_SCHED;
;             PG8_LDA(At, 1, 1); PG8_STAGE(PG8_SB(1, 0), b3, voffB); PG8_STAGE(PG8_SB(1, 1), b3 + hstep, voffB); PG8_STAGE(PG8_SA(1, 0), a3, voffA);
;             PG8_WAIT_V(8); PG8_WAIT_L(0); PG8_BAR; PG8_MMA(1, 0, At, B0); PG8_MMA(1, 1, At, B1); PG8_BAR; PG8_SCHED;
;     ...
;         if constexpr (ALIGN_EPI) { if (wr == 0) PG8_BAR; }
	s_setprio 0
	s_add_i32 s67, 0, 0x18000
	s_add_i32 s68, 0, 0x1c000
	v_add_u32_e32 v120, s67, v167
	v_add_u32_e32 v162, s68, v167
	ds_read_b128 v[108:111], v120
	ds_read_b128 v[112:115], v120 offset:1024
	ds_read_b128 v[116:119], v120 offset:2048
	ds_read_b128 v[120:123], v120 offset:3072
	ds_read_b128 v[178:181], v162
	ds_read_b128 v[182:185], v162 offset:1024
	ds_read_b128 v[186:189], v162 offset:2048
	ds_read_b128 v[190:193], v162 offset:3072
	s_add_u32 s44, s44, 0x80000
	s_addc_u32 s45, s45, 0
	s_mov_b32 m0, s52
	ds_read_b128 v[198:201], v177 offset:32768
	ds_read_b128 v[202:205], v177 offset:33792
	ds_read_b128 v[206:209], v177 offset:34816
	ds_read_b128 v[210:213], v177 offset:35840
	ds_read_b128 v[214:217], v177 offset:36864
	ds_read_b128 v[218:221], v177 offset:37888
	ds_read_b128 v[222:225], v177 offset:38912
	ds_read_b128 v[226:229], v177 offset:39936
	global_load_lds_dwordx4 v144, s[44:45]
	s_mov_b32 m0, s53
	s_nop 0
	global_load_lds_dwordx4 v146, s[44:45]
	s_waitcnt vmcnt(8) lgkmcnt(0)
	s_setprio 1
	s_barrier
	v_mfma_f32_16x16x32_bf16 v[140:143], v[108:111], v[198:201], v[140:143]
	v_mfma_f32_16x16x32_bf16 v[136:139], v[116:119], v[198:201], v[136:139]
	v_mfma_f32_16x16x32_bf16 v[100:103], v[108:111], v[206:209], v[100:103]
	v_mfma_f32_16x16x32_bf16 v[124:127], v[116:119], v[206:209], v[124:127]
	v_mfma_f32_16x16x32_bf16 v[84:87], v[108:111], v[214:217], v[84:87]
	v_mfma_f32_16x16x32_bf16 v[92:95], v[116:119], v[214:217], v[92:95]
	v_mfma_f32_16x16x32_bf16 v[68:71], v[108:111], v[222:225], v[68:71]
	v_mfma_f32_16x16x32_bf16 v[76:79], v[116:119], v[222:225], v[76:79]
	v_mfma_f32_16x16x32_bf16 v[140:143], v[112:115], v[202:205], v[140:143]
	v_mfma_f32_16x16x32_bf16 v[136:139], v[120:123], v[202:205], v[136:139]
	v_mfma_f32_16x16x32_bf16 v[100:103], v[112:115], v[210:213], v[100:103]
	v_mfma_f32_16x16x32_bf16 v[124:127], v[120:123], v[210:213], v[124:127]
	v_mfma_f32_16x16x32_bf16 v[84:87], v[112:115], v[218:221], v[84:87]
	v_mfma_f32_16x16x32_bf16 v[92:95], v[120:123], v[218:221], v[92:95]
	v_mfma_f32_16x16x32_bf16 v[68:71], v[112:115], v[226:229], v[68:71]
	v_mfma_f32_16x16x32_bf16 v[76:79], v[120:123], v[226:229], v[76:79]
	v_mfma_f32_16x16x32_bf16 v[128:131], v[178:181], v[198:201], v[128:131]
	v_mfma_f32_16x16x32_bf16 v[132:135], v[186:189], v[198:201], v[132:135]
	v_mfma_f32_16x16x32_bf16 v[104:107], v[178:181], v[206:209], v[104:107]
	v_mfma_f32_16x16x32_bf16 v[96:99], v[186:189], v[206:209], v[96:99]
	v_mfma_f32_16x16x32_bf16 v[88:91], v[178:181], v[214:217], v[88:91]
	v_mfma_f32_16x16x32_bf16 v[80:83], v[186:189], v[214:217], v[80:83]
	v_mfma_f32_16x16x32_bf16 v[72:75], v[178:181], v[222:225], v[72:75]
	v_mfma_f32_16x16x32_bf16 v[64:67], v[186:189], v[222:225], v[64:67]
	v_mfma_f32_16x16x32_bf16 v[128:131], v[182:185], v[202:205], v[128:131]
	v_mfma_f32_16x16x32_bf16 v[132:135], v[190:193], v[202:205], v[132:135]
	v_mfma_f32_16x16x32_bf16 v[104:107], v[182:185], v[210:213], v[104:107]
	v_mfma_f32_16x16x32_bf16 v[96:99], v[190:193], v[210:213], v[96:99]
	v_mfma_f32_16x16x32_bf16 v[88:91], v[182:185], v[218:221], v[88:91]
	v_mfma_f32_16x16x32_bf16 v[80:83], v[190:193], v[218:221], v[80:83]
	v_mfma_f32_16x16x32_bf16 v[72:75], v[182:185], v[226:229], v[72:75]
	v_mfma_f32_16x16x32_bf16 v[64:67], v[190:193], v[226:229], v[64:67]
	s_barrier
	s_setprio 0
	v_lshl_add_u64 v[160:161], v[160:161], 0, s[16:17]
	s_mov_b32 m0, s100
	ds_read_b128 v[198:201], v177 offset:49152
	ds_read_b128 v[202:205], v177 offset:50176
	ds_read_b128 v[206:209], v177 offset:51200
	ds_read_b128 v[210:213], v177 offset:52224
	ds_read_b128 v[214:217], v177 offset:53248
	ds_read_b128 v[218:221], v177 offset:54272
	ds_read_b128 v[222:225], v177 offset:55296
	ds_read_b128 v[226:229], v177 offset:56320
	global_load_lds_dwordx4 v[160:161], off
	s_add_i32 m0, s100, 0x2000
	s_add_u32 s42, s42, 0x80080
	v_lshl_add_u64 v[160:161], v[164:165], 0, s[16:17]
	s_addc_u32 s43, s43, 0
	global_load_lds_dwordx4 v[160:161], off
	s_mov_b32 m0, s101
	s_nop 0
	global_load_lds_dwordx4 v144, s[42:43]
	s_add_i32 m0, s101, 0x2000
	v_lshl_add_u64 v[160:161], s[42:43], 0, v[146:147]
	global_load_lds_dwordx4 v[160:161], off
	s_mov_b32 m0, s55
	v_lshl_add_u64 v[160:161], v[170:171], 0, s[16:17]
	global_load_lds_dwordx4 v[160:161], off
	s_mov_b32 m0, s56
	v_lshl_add_u64 v[160:161], v[194:195], 0, s[16:17]
	global_load_lds_dwordx4 v[160:161], off
	s_waitcnt vmcnt(8) lgkmcnt(0)
	s_setprio 1
	s_barrier
	v_mfma_f32_16x16x32_bf16 v[60:63], v[108:111], v[198:201], v[60:63]
	v_mfma_f32_16x16x32_bf16 v[56:59], v[116:119], v[198:201], v[56:59]
	v_mfma_f32_16x16x32_bf16 v[36:39], v[108:111], v[206:209], v[36:39]
	v_mfma_f32_16x16x32_bf16 v[44:47], v[116:119], v[206:209], v[44:47]
	v_mfma_f32_16x16x32_bf16 v[20:23], v[108:111], v[214:217], v[20:23]
	v_mfma_f32_16x16x32_bf16 v[28:31], v[116:119], v[214:217], v[28:31]
	v_mfma_f32_16x16x32_bf16 v[4:7], v[108:111], v[222:225], v[4:7]
	v_mfma_f32_16x16x32_bf16 v[12:15], v[116:119], v[222:225], v[12:15]
	v_mfma_f32_16x16x32_bf16 v[60:63], v[112:115], v[202:205], v[60:63]
	v_mfma_f32_16x16x32_bf16 v[56:59], v[120:123], v[202:205], v[56:59]
	v_mfma_f32_16x16x32_bf16 v[36:39], v[112:115], v[210:213], v[36:39]
	v_mfma_f32_16x16x32_bf16 v[44:47], v[120:123], v[210:213], v[44:47]
	v_mfma_f32_16x16x32_bf16 v[20:23], v[112:115], v[218:221], v[20:23]
	v_mfma_f32_16x16x32_bf16 v[28:31], v[120:123], v[218:221], v[28:31]
	v_mfma_f32_16x16x32_bf16 v[4:7], v[112:115], v[226:229], v[4:7]
	v_mfma_f32_16x16x32_bf16 v[12:15], v[120:123], v[226:229], v[12:15]
	v_mfma_f32_16x16x32_bf16 v[48:51], v[178:181], v[198:201], v[48:51]
	v_mfma_f32_16x16x32_bf16 v[52:55], v[186:189], v[198:201], v[52:55]
	v_mfma_f32_16x16x32_bf16 v[40:43], v[178:181], v[206:209], v[40:43]
	v_mfma_f32_16x16x32_bf16 v[32:35], v[186:189], v[206:209], v[32:35]
	v_mfma_f32_16x16x32_bf16 v[24:27], v[178:181], v[214:217], v[24:27]
	v_mfma_f32_16x16x32_bf16 v[16:19], v[186:189], v[214:217], v[16:19]
	v_mfma_f32_16x16x32_bf16 v[8:11], v[178:181], v[222:225], v[8:11]
	v_mfma_f32_16x16x32_bf16 v[0:3], v[186:189], v[222:225], v[0:3]
	v_mfma_f32_16x16x32_bf16 v[48:51], v[182:185], v[202:205], v[48:51]
	v_mfma_f32_16x16x32_bf16 v[52:55], v[190:193], v[202:205], v[52:55]
	v_mfma_f32_16x16x32_bf16 v[40:43], v[182:185], v[210:213], v[40:43]
	v_mfma_f32_16x16x32_bf16 v[32:35], v[190:193], v[210:213], v[32:35]
	v_mfma_f32_16x16x32_bf16 v[24:27], v[182:185], v[218:221], v[24:27]
	v_mfma_f32_16x16x32_bf16 v[16:19], v[190:193], v[218:221], v[16:19]
	v_mfma_f32_16x16x32_bf16 v[8:11], v[182:185], v[226:229], v[8:11]
	v_mfma_f32_16x16x32_bf16 v[0:3], v[190:193], v[226:229], v[0:3]
	s_barrier
	s_setprio 0
	s_add_i32 s66, s66, 2
	s_add_u32 s8, s8, 0x100
	s_addc_u32 s9, s9, 0
	s_add_u32 s48, s48, 0x100
	s_addc_u32 s49, s49, 0
	s_cmp_gt_u32 s66, 29
	s_cbranch_scc0 .LBB0_1373
	s_and_b64 vcc, exec, s[18:19]
	s_cbranch_vccz .LBB0_1376
	s_barrier

; #define PG8_STAGE(bufoff, gbase, voff) do { _Pragma("unroll") for (int _i = 0; _i < 2; ++_i) \
;         __builtin_amdgcn_global_load_lds((const unsigned*)((const char*)(gbase) + (voff)[_i]), (PG8_LAS unsigned*)(lds + (bufoff) + ldsw + _i * 8192), 16, 0, 0); } while (0)
; #define PG8_LDA(dst, b, h) do { _Pragma("unroll") for (int m = 0; m < 4; ++m) _Pragma("unroll") for (int k = 0; k < 2; ++k) dst[m][k] = *(const PG8_LAS bf16x8*)(lds + PG8_SA(b, h) + aoff + m * 2048 + k * 1024); } while (0)
; #define PG8_LDB(dst, b, h) do { _Pragma("unroll") for (int n = 0; n < 2; ++n) _Pragma("unroll") for (int k = 0; k < 2; ++k) dst[n][k] = *(const PG8_LAS bf16x8*)(lds + PG8_SB(b, h) + boff + n * 2048 + k * 1024); } while (0)
; #define PG8_MMA(ai, bj, At, Bt) do { __builtin_amdgcn_s_setprio(1); _Pragma("unroll") for (int m = 0; m < 4; ++m) _Pragma("unroll") for (int n = 0; n < 2; ++n) _Pragma("unroll") for (int k = 0; k < 2; ++k) \
;         acc[ai][bj][m][n] = __builtin_amdgcn_mfma_f32_16x16x32_bf16(Bt[n][k], At[m][k], acc[ai][bj][m][n], 0, 0, 0); __builtin_amdgcn_s_setprio(0); } while (0)
; #define PG8_BAR __builtin_amdgcn_s_barrier()
; template <class Epi, class Sched, bool ALIGN_EPI = false, bool SP2 = false>
; __device__ __forceinline__ void gemm_phase(PG8_LAS unsigned char* lds, const Gemm g, const Sched& S, const Epi& E) {
;     ...
;         const bool has_next = S.next(ui + 1, nxt);
;         const char* nA = has_next ? (const char*)g.A + (size_t)nxt.pm * tstep : cA; const char* nB = has_next ? (const char*)g.Bt + (size_t)nxt.pn * tstep : cB;
;         for (int t = 0; t < nt; t += 2) {
;             const bool last = (t == nt - 2);
;             const char* a1 = cA + (size_t)(t + 1) * kstep;
;             const char* a2 = last ? nA : cA + (size_t)(t + 2) * kstep; const char* b2 = last ? nB : cB + (size_t)(t + 2) * kstep;
;             const char* a3 = a2 + kstep; const char* b3 = b2 + kstep;
;             if (last && has_next) S.a_ready(nxt);
;             if constexpr (SP2) {
;             PG8_LDB(B0, 0, 0); PG8_LDB(B1, 0, 1); PG8_SCHED; PG8_LDA(At, 0, 0); PG8_STAGE(PG8_SA(1, 1), a1 + hstep, voffA);
;             PG8_WAIT_V(8); PG8_WAIT_L(0); PG8_BAR; PG8_MMA(0, 0, At, B0); PG8_MMA(0, 1, At, B1); PG8_BAR; PG8_SCHED;
;             PG8_LDA(At, 0, 1); PG8_STAGE(PG8_SB(0, 0), b2, voffB); PG8_STAGE(PG8_SB(0, 1), b2 + hstep, voffB); PG8_STAGE(PG8_SA(0, 0), a2, voffA);
.LBB0_1548:
	s_ashr_i32 s13, s12, 31
	s_lshl_b64 s[14:15], s[12:13], 20
	s_add_u32 s14, s60, s14
	s_addc_u32 s15, s61, s15
	s_and_b64 s[16:17], s[0:1], exec
	s_cselect_b32 s13, s15, s21
	s_cselect_b32 s39, s14, s20
	s_ashr_i32 s11, s10, 31
	s_lshl_b64 s[16:17], s[10:11], 20
	s_add_u32 s16, s72, s16
	s_addc_u32 s17, s73, s17
	s_and_b64 s[24:25], s[0:1], exec
	s_cselect_b32 s11, s17, s23
	s_cselect_b32 s40, s16, s22
	s_add_u32 s20, s20, 0x80080
	s_addc_u32 s21, s21, 0
	s_add_u32 s41, s22, 0x100
	s_addc_u32 s42, s23, 0
	s_mov_b32 s43, -2
	s_add_i32 s98, s27, 0x10000
	s_add_i32 s99, s27, 0x14000
	s_add_i32 s100, s27, 0x18000
	s_add_i32 s101, s27, 0x1c000
	ds_read_b128 v[144:147], v155
	ds_read_b128 v[148:151], v155 offset:1024
	ds_read_b128 v[158:161], v155 offset:2048
	ds_read_b128 v[162:165], v155 offset:3072
	ds_read_b128 v[166:169], v156
	ds_read_b128 v[170:173], v156 offset:1024
	ds_read_b128 v[174:177], v156 offset:2048
	ds_read_b128 v[178:181], v156 offset:3072
	s_add_u32 s22, s20, 0xfff80080
	s_addc_u32 s23, s21, -1
	s_cmp_eq_u32 s43, 28
	s_cselect_b32 s25, s13, s23
	s_cselect_b32 s24, s39, s22
	s_cselect_b32 s23, s11, s42
	s_cselect_b32 s22, s40, s41
	s_add_i32 m0, s19, 0xc000
	ds_read_b128 v[182:185], v157
	ds_read_b128 v[186:189], v157 offset:1024
	ds_read_b128 v[190:193], v157 offset:2048
	ds_read_b128 v[194:197], v157 offset:3072
	ds_read_b128 v[198:201], v157 offset:4096
	ds_read_b128 v[202:205], v157 offset:5120
	ds_read_b128 v[206:209], v157 offset:6144
	ds_read_b128 v[210:213], v157 offset:7168
	global_load_lds_dwordx4 v136, s[20:21]
	s_add_i32 m0, s19, 0xe000
	s_nop 0
	global_load_lds_dwordx4 v138, s[20:21]
	s_waitcnt lgkmcnt(0)
	s_setprio 1
	s_barrier
	v_mfma_f32_16x16x32_bf16 v[124:127], v[144:147], v[182:185], 0
	v_mfma_f32_16x16x32_bf16 v[120:123], v[158:161], v[182:185], 0
	v_mfma_f32_16x16x32_bf16 v[108:111], v[144:147], v[190:193], 0
	v_mfma_f32_16x16x32_bf16 v[104:107], v[158:161], v[190:193], 0
	v_mfma_f32_16x16x32_bf16 v[88:91], v[144:147], v[198:201], 0
	v_mfma_f32_16x16x32_bf16 v[92:95], v[158:161], v[198:201], 0
	v_mfma_f32_16x16x32_bf16 v[72:75], v[144:147], v[206:209], 0
	v_mfma_f32_16x16x32_bf16 v[76:79], v[158:161], v[206:209], 0
	v_mfma_f32_16x16x32_bf16 v[124:127], v[148:151], v[186:189], v[124:127]
	v_mfma_f32_16x16x32_bf16 v[120:123], v[162:165], v[186:189], v[120:123]
	v_mfma_f32_16x16x32_bf16 v[108:111], v[148:151], v[194:197], v[108:111]
	v_mfma_f32_16x16x32_bf16 v[104:107], v[162:165], v[194:197], v[104:107]
	v_mfma_f32_16x16x32_bf16 v[88:91], v[148:151], v[202:205], v[88:91]
	v_mfma_f32_16x16x32_bf16 v[92:95], v[162:165], v[202:205], v[92:95]
	v_mfma_f32_16x16x32_bf16 v[72:75], v[148:151], v[210:213], v[72:75]
	v_mfma_f32_16x16x32_bf16 v[76:79], v[162:165], v[210:213], v[76:79]
	v_mfma_f32_16x16x32_bf16 v[116:119], v[166:169], v[182:185], 0
	v_mfma_f32_16x16x32_bf16 v[112:115], v[174:177], v[182:185], 0
	v_mfma_f32_16x16x32_bf16 v[96:99], v[166:169], v[190:193], 0
	v_mfma_f32_16x16x32_bf16 v[100:103], v[174:177], v[190:193], 0
	v_mfma_f32_16x16x32_bf16 v[80:83], v[166:169], v[198:201], 0
	v_mfma_f32_16x16x32_bf16 v[84:87], v[174:177], v[198:201], 0
	v_mfma_f32_16x16x32_bf16 v[64:67], v[166:169], v[206:209], 0
	v_mfma_f32_16x16x32_bf16 v[68:71], v[174:177], v[206:209], 0
	v_mfma_f32_16x16x32_bf16 v[116:119], v[170:173], v[186:189], v[116:119]
	v_mfma_f32_16x16x32_bf16 v[112:115], v[178:181], v[186:189], v[112:115]
	v_mfma_f32_16x16x32_bf16 v[96:99], v[170:173], v[194:197], v[96:99]
	v_mfma_f32_16x16x32_bf16 v[100:103], v[178:181], v[194:197], v[100:103]
	v_mfma_f32_16x16x32_bf16 v[80:83], v[170:173], v[202:205], v[80:83]
	v_mfma_f32_16x16x32_bf16 v[84:87], v[178:181], v[202:205], v[84:87]
	v_mfma_f32_16x16x32_bf16 v[64:67], v[170:173], v[210:213], v[64:67]
	v_mfma_f32_16x16x32_bf16 v[68:71], v[178:181], v[210:213], v[68:71]
	s_barrier
	s_setprio 0
	v_lshl_add_u64 v[214:215], s[22:23], 0, v[130:131]
	s_mov_b32 m0, s98
	ds_read_b128 v[182:185], v157 offset:16384
	ds_read_b128 v[186:189], v157 offset:17408
	ds_read_b128 v[190:193], v157 offset:18432
	ds_read_b128 v[194:197], v157 offset:19456
	ds_read_b128 v[198:201], v157 offset:20480
	ds_read_b128 v[202:205], v157 offset:21504
	ds_read_b128 v[206:209], v157 offset:22528
	ds_read_b128 v[210:213], v157 offset:23552
	global_load_lds_dwordx4 v[214:215], off
	s_add_i32 m0, s98, 0x2000
	s_add_u32 s44, s22, 0x80000
	v_lshl_add_u64 v[216:217], s[22:23], 0, v[134:135]
	s_addc_u32 s45, s23, 0
	global_load_lds_dwordx4 v[216:217], off
	s_mov_b32 m0, s99
	v_lshl_add_u64 v[220:221], s[24:25], 0, v[132:133]
	global_load_lds_dwordx4 v130, s[44:45]
	s_add_i32 m0, s99, 0x2000
	s_nop 0
	global_load_lds_dwordx4 v134, s[44:45]
	s_mov_b32 m0, s19
	v_lshl_add_u64 v[218:219], s[24:25], 0, v[128:129]
	global_load_lds_dwordx4 v[218:219], off
	s_mov_b32 m0, s28
	s_nop 0
	global_load_lds_dwordx4 v[220:221], off
	s_waitcnt lgkmcnt(0)
	s_setprio 1
	s_barrier
; #define PG8_STAGE(bufoff, gbase, voff) do { _Pragma("unroll") for (int _i = 0; _i < 2; ++_i) \
;         __builtin_amdgcn_global_load_lds((const unsigned*)((const char*)(gbase) + (voff)[_i]), (PG8_LAS unsigned*)(lds + (bufoff) + ldsw + _i * 8192), 16, 0, 0); } while (0)
; #define PG8_LDA(dst, b, h) do { _Pragma("unroll") for (int m = 0; m < 4; ++m) _Pragma("unroll") for (int k = 0; k < 2; ++k) dst[m][k] = *(const PG8_LAS bf16x8*)(lds + PG8_SA(b, h) + aoff + m * 2048 + k * 1024); } while (0)
; #define PG8_LDB(dst, b, h) do { _Pragma("unroll") for (int n = 0; n < 2; ++n) _Pragma("unroll") for (int k = 0; k < 2; ++k) dst[n][k] = *(const PG8_LAS bf16x8*)(lds + PG8_SB(b, h) + boff + n * 2048 + k * 1024); } while (0)
; #define PG8_MMA(ai, bj, At, Bt) do { __builtin_amdgcn_s_setprio(1); _Pragma("unroll") for (int m = 0; m < 4; ++m) _Pragma("unroll") for (int n = 0; n < 2; ++n) _Pragma("unroll") for (int k = 0; k < 2; ++k) \
;         acc[ai][bj][m][n] = __builtin_amdgcn_mfma_f32_16x16x32_bf16(Bt[n][k], At[m][k], acc[ai][bj][m][n], 0, 0, 0); __builtin_amdgcn_s_setprio(0); } while (0)
; #define PG8_WAIT_V(n) asm volatile("s_waitcnt vmcnt(" #n ")" ::: "memory")
; #define PG8_WAIT_L(n) asm volatile("s_waitcnt lgkmcnt(" #n ")" ::: "memory")
; #define PG8_BAR __builtin_amdgcn_s_barrier()
; #define PG8_SCHED __builtin_amdgcn_sched_barrier(0)
; template <class Epi, class Sched, bool ALIGN_EPI = false, bool SP2 = false>
; __device__ __forceinline__ void gemm_phase(PG8_LAS unsigned char* lds, const Gemm g, const Sched& S, const Epi& E) {
;     ...
;             PG8_WAIT_V(8); PG8_WAIT_L(0); PG8_BAR; PG8_MMA(1, 0, At, B0); PG8_MMA(1, 1, At, B1); PG8_BAR; PG8_SCHED;
;             PG8_LDB(B0, 1, 0); PG8_LDB(B1, 1, 1); PG8_SCHED; PG8_LDA(At, 1, 0); PG8_STAGE(PG8_SA(0, 1), a2 + hstep, voffA);
;             PG8_WAIT_V(8); PG8_WAIT_L(0); PG8_BAR; PG8_MMA(0, 0, At, B0); PG8_MMA(0, 1, At, B1); PG8_BAR; PG8_SCHED;
	v_mfma_f32_16x16x32_bf16 v[56:59], v[144:147], v[182:185], 0
	v_mfma_f32_16x16x32_bf16 v[60:63], v[158:161], v[182:185], 0
	v_mfma_f32_16x16x32_bf16 v[40:43], v[144:147], v[190:193], 0
	v_mfma_f32_16x16x32_bf16 v[44:47], v[158:161], v[190:193], 0
	v_mfma_f32_16x16x32_bf16 v[24:27], v[144:147], v[198:201], 0
	v_mfma_f32_16x16x32_bf16 v[28:31], v[158:161], v[198:201], 0
	v_mfma_f32_16x16x32_bf16 v[8:11], v[144:147], v[206:209], 0
	v_mfma_f32_16x16x32_bf16 v[12:15], v[158:161], v[206:209], 0
	v_mfma_f32_16x16x32_bf16 v[56:59], v[148:151], v[186:189], v[56:59]
	v_mfma_f32_16x16x32_bf16 v[60:63], v[162:165], v[186:189], v[60:63]
	v_mfma_f32_16x16x32_bf16 v[40:43], v[148:151], v[194:197], v[40:43]
	v_mfma_f32_16x16x32_bf16 v[44:47], v[162:165], v[194:197], v[44:47]
	v_mfma_f32_16x16x32_bf16 v[24:27], v[148:151], v[202:205], v[24:27]
	v_mfma_f32_16x16x32_bf16 v[28:31], v[162:165], v[202:205], v[28:31]
	v_mfma_f32_16x16x32_bf16 v[8:11], v[148:151], v[210:213], v[8:11]
	v_mfma_f32_16x16x32_bf16 v[12:15], v[162:165], v[210:213], v[12:15]
	v_mfma_f32_16x16x32_bf16 v[48:51], v[166:169], v[182:185], 0
	v_mfma_f32_16x16x32_bf16 v[52:55], v[174:177], v[182:185], 0
	v_mfma_f32_16x16x32_bf16 v[32:35], v[166:169], v[190:193], 0
	v_mfma_f32_16x16x32_bf16 v[36:39], v[174:177], v[190:193], 0
	v_mfma_f32_16x16x32_bf16 v[16:19], v[166:169], v[198:201], 0
	v_mfma_f32_16x16x32_bf16 v[20:23], v[174:177], v[198:201], 0
	v_mfma_f32_16x16x32_bf16 v[0:3], v[166:169], v[206:209], 0
	v_mfma_f32_16x16x32_bf16 v[4:7], v[174:177], v[206:209], 0
	v_mfma_f32_16x16x32_bf16 v[48:51], v[170:173], v[186:189], v[48:51]
	v_mfma_f32_16x16x32_bf16 v[52:55], v[178:181], v[186:189], v[52:55]
	v_mfma_f32_16x16x32_bf16 v[32:35], v[170:173], v[194:197], v[32:35]
	v_mfma_f32_16x16x32_bf16 v[36:39], v[178:181], v[194:197], v[36:39]
	v_mfma_f32_16x16x32_bf16 v[16:19], v[170:173], v[202:205], v[16:19]
	v_mfma_f32_16x16x32_bf16 v[20:23], v[178:181], v[202:205], v[20:23]
	v_mfma_f32_16x16x32_bf16 v[0:3], v[170:173], v[210:213], v[0:3]
	v_mfma_f32_16x16x32_bf16 v[4:7], v[178:181], v[210:213], v[4:7]
	s_barrier
	s_setprio 0
	s_add_i32 s44, 0, 0x18000
	s_add_i32 s45, 0, 0x1c000
	v_add_u32_e32 v162, s44, v153
	v_add_u32_e32 v178, s45, v153
	ds_read_b128 v[144:147], v162
	ds_read_b128 v[148:151], v162 offset:1024
	ds_read_b128 v[158:161], v162 offset:2048
	ds_read_b128 v[162:165], v162 offset:3072
	ds_read_b128 v[166:169], v178
	ds_read_b128 v[170:173], v178 offset:1024
	ds_read_b128 v[174:177], v178 offset:2048
	ds_read_b128 v[178:181], v178 offset:3072
	s_add_u32 s24, s24, 0x80000
	s_addc_u32 s25, s25, 0
	s_mov_b32 m0, s29
	ds_read_b128 v[182:185], v157 offset:32768
	ds_read_b128 v[186:189], v157 offset:33792
	ds_read_b128 v[190:193], v157 offset:34816
	ds_read_b128 v[194:197], v157 offset:35840
	ds_read_b128 v[198:201], v157 offset:36864
	ds_read_b128 v[202:205], v157 offset:37888
	ds_read_b128 v[206:209], v157 offset:38912
	ds_read_b128 v[210:213], v157 offset:39936
	global_load_lds_dwordx4 v128, s[24:25]
	s_mov_b32 m0, s30
	v_lshl_add_u64 v[222:223], s[24:25], 0, v[132:133]
	global_load_lds_dwordx4 v[222:223], off
	s_waitcnt vmcnt(8) lgkmcnt(0)
	s_setprio 1
	s_barrier
	v_mfma_f32_16x16x32_bf16 v[124:127], v[144:147], v[182:185], v[124:127]
	v_mfma_f32_16x16x32_bf16 v[120:123], v[158:161], v[182:185], v[120:123]
	v_mfma_f32_16x16x32_bf16 v[108:111], v[144:147], v[190:193], v[108:111]
	v_mfma_f32_16x16x32_bf16 v[104:107], v[158:161], v[190:193], v[104:107]
	v_mfma_f32_16x16x32_bf16 v[88:91], v[144:147], v[198:201], v[88:91]
	v_mfma_f32_16x16x32_bf16 v[92:95], v[158:161], v[198:201], v[92:95]
	v_mfma_f32_16x16x32_bf16 v[72:75], v[144:147], v[206:209], v[72:75]
	v_mfma_f32_16x16x32_bf16 v[76:79], v[158:161], v[206:209], v[76:79]
	v_mfma_f32_16x16x32_bf16 v[124:127], v[148:151], v[186:189], v[124:127]
	v_mfma_f32_16x16x32_bf16 v[120:123], v[162:165], v[186:189], v[120:123]
	v_mfma_f32_16x16x32_bf16 v[108:111], v[148:151], v[194:197], v[108:111]
	v_mfma_f32_16x16x32_bf16 v[104:107], v[162:165], v[194:197], v[104:107]
	v_mfma_f32_16x16x32_bf16 v[88:91], v[148:151], v[202:205], v[88:91]
	v_mfma_f32_16x16x32_bf16 v[92:95], v[162:165], v[202:205], v[92:95]
	v_mfma_f32_16x16x32_bf16 v[72:75], v[148:151], v[210:213], v[72:75]
	v_mfma_f32_16x16x32_bf16 v[76:79], v[162:165], v[210:213], v[76:79]
	v_mfma_f32_16x16x32_bf16 v[116:119], v[166:169], v[182:185], v[116:119]
	v_mfma_f32_16x16x32_bf16 v[112:115], v[174:177], v[182:185], v[112:115]
	v_mfma_f32_16x16x32_bf16 v[96:99], v[166:169], v[190:193], v[96:99]
	v_mfma_f32_16x16x32_bf16 v[100:103], v[174:177], v[190:193], v[100:103]
	v_mfma_f32_16x16x32_bf16 v[80:83], v[166:169], v[198:201], v[80:83]
	v_mfma_f32_16x16x32_bf16 v[84:87], v[174:177], v[198:201], v[84:87]
	v_mfma_f32_16x16x32_bf16 v[64:67], v[166:169], v[206:209], v[64:67]
	v_mfma_f32_16x16x32_bf16 v[68:71], v[174:177], v[206:209], v[68:71]
	v_mfma_f32_16x16x32_bf16 v[116:119], v[170:173], v[186:189], v[116:119]
	v_mfma_f32_16x16x32_bf16 v[112:115], v[178:181], v[186:189], v[112:115]
	v_mfma_f32_16x16x32_bf16 v[96:99], v[170:173], v[194:197], v[96:99]
	v_mfma_f32_16x16x32_bf16 v[100:103], v[178:181], v[194:197], v[100:103]
	v_mfma_f32_16x16x32_bf16 v[80:83], v[170:173], v[202:205], v[80:83]
	v_mfma_f32_16x16x32_bf16 v[84:87], v[178:181], v[202:205], v[84:87]
	v_mfma_f32_16x16x32_bf16 v[64:67], v[170:173], v[210:213], v[64:67]
	v_mfma_f32_16x16x32_bf16 v[68:71], v[178:181], v[210:213], v[68:71]
	s_barrier
; #define PG8_STAGE(bufoff, gbase, voff) do { _Pragma("unroll") for (int _i = 0; _i < 2; ++_i) \
;         __builtin_amdgcn_global_load_lds((const unsigned*)((const char*)(gbase) + (voff)[_i]), (PG8_LAS unsigned*)(lds + (bufoff) + ldsw + _i * 8192), 16, 0, 0); } while (0)
; #define PG8_LDA(dst, b, h) do { _Pragma("unroll") for (int m = 0; m < 4; ++m) _Pragma("unroll") for (int k = 0; k < 2; ++k) dst[m][k] = *(const PG8_LAS bf16x8*)(lds + PG8_SA(b, h) + aoff + m * 2048 + k * 1024); } while (0)
; #define PG8_LDB(dst, b, h) do { _Pragma("unroll") for (int n = 0; n < 2; ++n) _Pragma("unroll") for (int k = 0; k < 2; ++k) dst[n][k] = *(const PG8_LAS bf16x8*)(lds + PG8_SB(b, h) + boff + n * 2048 + k * 1024); } while (0)
; #define PG8_MMA(ai, bj, At, Bt) do { __builtin_amdgcn_s_setprio(1); _Pragma("unroll") for (int m = 0; m < 4; ++m) _Pragma("unroll") for (int n = 0; n < 2; ++n) _Pragma("unroll") for (int k = 0; k < 2; ++k) \
;         acc[ai][bj][m][n] = __builtin_amdgcn_mfma_f32_16x16x32_bf16(Bt[n][k], At[m][k], acc[ai][bj][m][n], 0, 0, 0); __builtin_amdgcn_s_setprio(0); } while (0)
; #define PG8_WAIT_V(n) asm volatile("s_waitcnt vmcnt(" #n ")" ::: "memory")
; #define PG8_BAR __builtin_amdgcn_s_barrier()
; template <class Epi, class Sched, bool ALIGN_EPI = false, bool SP2 = false>
; __device__ __forceinline__ void gemm_phase(PG8_LAS unsigned char* lds, const Gemm g, const Sched& S, const Epi& E) {
;     ...
;         for (int t = 0; t < nt; t += 2) {
;             const bool last = (t == nt - 2);
;             const char* a1 = cA + (size_t)(t + 1) * kstep;
;             const char* a2 = last ? nA : cA + (size_t)(t + 2) * kstep; const char* b2 = last ? nB : cB + (size_t)(t + 2) * kstep;
;             const char* a3 = a2 + kstep; const char* b3 = b2 + kstep;
;             if (last && has_next) S.a_ready(nxt);
;             if constexpr (SP2) {
;             PG8_LDB(B0, 0, 0); PG8_LDB(B1, 0, 1); PG8_SCHED; PG8_LDA(At, 0, 0); PG8_STAGE(PG8_SA(1, 1), a1 + hstep, voffA);
;             PG8_WAIT_V(8); PG8_WAIT_L(0); PG8_BAR; PG8_MMA(0, 0, At, B0); PG8_MMA(0, 1, At, B1); PG8_BAR; PG8_SCHED;
;     ...
;             PG8_LDA(At, 1, 1); PG8_STAGE(PG8_SB(1, 0), b3, voffB); PG8_STAGE(PG8_SB(1, 1), b3 + hstep, voffB); PG8_STAGE(PG8_SA(1, 0), a3, voffA);
;             PG8_WAIT_V(8); PG8_WAIT_L(0); PG8_BAR; PG8_MMA(1, 0, At, B0); PG8_MMA(1, 1, At, B1); PG8_BAR; PG8_SCHED;
	s_setprio 0
	v_lshl_add_u64 v[214:215], v[214:215], 0, s[4:5]
	s_mov_b32 m0, s100
	ds_read_b128 v[182:185], v157 offset:49152
	ds_read_b128 v[186:189], v157 offset:50176
	ds_read_b128 v[190:193], v157 offset:51200
	ds_read_b128 v[194:197], v157 offset:52224
	ds_read_b128 v[198:201], v157 offset:53248
	ds_read_b128 v[202:205], v157 offset:54272
	ds_read_b128 v[206:209], v157 offset:55296
	ds_read_b128 v[210:213], v157 offset:56320
	global_load_lds_dwordx4 v[214:215], off
	s_add_i32 m0, s100, 0x2000
	s_add_u32 s22, s22, 0x80080
	v_lshl_add_u64 v[214:215], v[216:217], 0, s[4:5]
	s_addc_u32 s23, s23, 0
	global_load_lds_dwordx4 v[214:215], off
	s_mov_b32 m0, s101
	s_nop 0
	global_load_lds_dwordx4 v130, s[22:23]
	s_add_i32 m0, s101, 0x2000
	v_lshl_add_u64 v[214:215], s[22:23], 0, v[134:135]
	global_load_lds_dwordx4 v[214:215], off
	s_mov_b32 m0, s33
	v_lshl_add_u64 v[214:215], v[218:219], 0, s[4:5]
	global_load_lds_dwordx4 v[214:215], off
	s_mov_b32 m0, s34
	v_lshl_add_u64 v[214:215], v[220:221], 0, s[4:5]
	global_load_lds_dwordx4 v[214:215], off
	s_waitcnt vmcnt(8) lgkmcnt(0)
	s_setprio 1
	s_barrier
	v_mfma_f32_16x16x32_bf16 v[56:59], v[144:147], v[182:185], v[56:59]
	v_mfma_f32_16x16x32_bf16 v[60:63], v[158:161], v[182:185], v[60:63]
	v_mfma_f32_16x16x32_bf16 v[40:43], v[144:147], v[190:193], v[40:43]
	v_mfma_f32_16x16x32_bf16 v[44:47], v[158:161], v[190:193], v[44:47]
	v_mfma_f32_16x16x32_bf16 v[24:27], v[144:147], v[198:201], v[24:27]
	v_mfma_f32_16x16x32_bf16 v[28:31], v[158:161], v[198:201], v[28:31]
	v_mfma_f32_16x16x32_bf16 v[8:11], v[144:147], v[206:209], v[8:11]
	v_mfma_f32_16x16x32_bf16 v[12:15], v[158:161], v[206:209], v[12:15]
	v_mfma_f32_16x16x32_bf16 v[56:59], v[148:151], v[186:189], v[56:59]
	v_mfma_f32_16x16x32_bf16 v[60:63], v[162:165], v[186:189], v[60:63]
	v_mfma_f32_16x16x32_bf16 v[40:43], v[148:151], v[194:197], v[40:43]
	v_mfma_f32_16x16x32_bf16 v[44:47], v[162:165], v[194:197], v[44:47]
	v_mfma_f32_16x16x32_bf16 v[24:27], v[148:151], v[202:205], v[24:27]
	v_mfma_f32_16x16x32_bf16 v[28:31], v[162:165], v[202:205], v[28:31]
	v_mfma_f32_16x16x32_bf16 v[8:11], v[148:151], v[210:213], v[8:11]
	v_mfma_f32_16x16x32_bf16 v[12:15], v[162:165], v[210:213], v[12:15]
	v_mfma_f32_16x16x32_bf16 v[48:51], v[166:169], v[182:185], v[48:51]
	v_mfma_f32_16x16x32_bf16 v[52:55], v[174:177], v[182:185], v[52:55]
	v_mfma_f32_16x16x32_bf16 v[32:35], v[166:169], v[190:193], v[32:35]
	v_mfma_f32_16x16x32_bf16 v[36:39], v[174:177], v[190:193], v[36:39]
	v_mfma_f32_16x16x32_bf16 v[16:19], v[166:169], v[198:201], v[16:19]
	v_mfma_f32_16x16x32_bf16 v[20:23], v[174:177], v[198:201], v[20:23]
	v_mfma_f32_16x16x32_bf16 v[0:3], v[166:169], v[206:209], v[0:3]
	v_mfma_f32_16x16x32_bf16 v[4:7], v[174:177], v[206:209], v[4:7]
	v_mfma_f32_16x16x32_bf16 v[48:51], v[170:173], v[186:189], v[48:51]
	v_mfma_f32_16x16x32_bf16 v[52:55], v[178:181], v[186:189], v[52:55]
	v_mfma_f32_16x16x32_bf16 v[32:35], v[170:173], v[194:197], v[32:35]
	v_mfma_f32_16x16x32_bf16 v[36:39], v[178:181], v[194:197], v[36:39]
	v_mfma_f32_16x16x32_bf16 v[16:19], v[170:173], v[202:205], v[16:19]
	v_mfma_f32_16x16x32_bf16 v[20:23], v[178:181], v[202:205], v[20:23]
	v_mfma_f32_16x16x32_bf16 v[0:3], v[170:173], v[210:213], v[0:3]
	v_mfma_f32_16x16x32_bf16 v[4:7], v[178:181], v[210:213], v[4:7]
	s_barrier
	s_setprio 0
	s_add_i32 s43, s43, 2
	s_add_u32 s20, s20, 0x100
	s_addc_u32 s21, s21, 0
	s_add_u32 s41, s41, 0x100
	s_addc_u32 s42, s42, 0
.LBB0_1549:
	ds_read_b128 v[144:147], v155
	ds_read_b128 v[148:151], v155 offset:1024
	ds_read_b128 v[158:161], v155 offset:2048
	ds_read_b128 v[162:165], v155 offset:3072
	ds_read_b128 v[166:169], v156
	ds_read_b128 v[170:173], v156 offset:1024
	ds_read_b128 v[174:177], v156 offset:2048
	ds_read_b128 v[178:181], v156 offset:3072
	s_add_u32 s22, s20, 0xfff80080
	s_addc_u32 s23, s21, -1
	s_cmp_eq_u32 s43, 28
	s_cselect_b32 s25, s13, s23
	s_cselect_b32 s24, s39, s22
	s_cselect_b32 s23, s11, s42
	s_cselect_b32 s22, s40, s41
	s_add_i32 m0, s19, 0xc000
	ds_read_b128 v[182:185], v157
	ds_read_b128 v[186:189], v157 offset:1024
	ds_read_b128 v[190:193], v157 offset:2048
	ds_read_b128 v[194:197], v157 offset:3072
	ds_read_b128 v[198:201], v157 offset:4096
	ds_read_b128 v[202:205], v157 offset:5120
	ds_read_b128 v[206:209], v157 offset:6144
	ds_read_b128 v[210:213], v157 offset:7168
	global_load_lds_dwordx4 v136, s[20:21]
	s_add_i32 m0, s19, 0xe000
	s_nop 0
	global_load_lds_dwordx4 v138, s[20:21]
	s_waitcnt vmcnt(8) lgkmcnt(0)
	s_setprio 1
	s_barrier
; #define PG8_STAGE(bufoff, gbase, voff) do { _Pragma("unroll") for (int _i = 0; _i < 2; ++_i) \
;         __builtin_amdgcn_global_load_lds((const unsigned*)((const char*)(gbase) + (voff)[_i]), (PG8_LAS unsigned*)(lds + (bufoff) + ldsw + _i * 8192), 16, 0, 0); } while (0)
; #define PG8_LDA(dst, b, h) do { _Pragma("unroll") for (int m = 0; m < 4; ++m) _Pragma("unroll") for (int k = 0; k < 2; ++k) dst[m][k] = *(const PG8_LAS bf16x8*)(lds + PG8_SA(b, h) + aoff + m * 2048 + k * 1024); } while (0)
; #define PG8_MMA(ai, bj, At, Bt) do { __builtin_amdgcn_s_setprio(1); _Pragma("unroll") for (int m = 0; m < 4; ++m) _Pragma("unroll") for (int n = 0; n < 2; ++n) _Pragma("unroll") for (int k = 0; k < 2; ++k) \
;         acc[ai][bj][m][n] = __builtin_amdgcn_mfma_f32_16x16x32_bf16(Bt[n][k], At[m][k], acc[ai][bj][m][n], 0, 0, 0); __builtin_amdgcn_s_setprio(0); } while (0)
; #define PG8_WAIT_V(n) asm volatile("s_waitcnt vmcnt(" #n ")" ::: "memory")
; #define PG8_WAIT_L(n) asm volatile("s_waitcnt lgkmcnt(" #n ")" ::: "memory")
; #define PG8_BAR __builtin_amdgcn_s_barrier()
; #define PG8_SCHED __builtin_amdgcn_sched_barrier(0)
; template <class Epi, class Sched, bool ALIGN_EPI = false, bool SP2 = false>
; __device__ __forceinline__ void gemm_phase(PG8_LAS unsigned char* lds, const Gemm g, const Sched& S, const Epi& E) {
;     ...
;             PG8_WAIT_V(8); PG8_WAIT_L(0); PG8_BAR; PG8_MMA(0, 0, At, B0); PG8_MMA(0, 1, At, B1); PG8_BAR; PG8_SCHED;
;             PG8_LDA(At, 0, 1); PG8_STAGE(PG8_SB(0, 0), b2, voffB); PG8_STAGE(PG8_SB(0, 1), b2 + hstep, voffB); PG8_STAGE(PG8_SA(0, 0), a2, voffA);
;             PG8_WAIT_V(8); PG8_WAIT_L(0); PG8_BAR; PG8_MMA(1, 0, At, B0); PG8_MMA(1, 1, At, B1); PG8_BAR; PG8_SCHED;
	v_mfma_f32_16x16x32_bf16 v[124:127], v[144:147], v[182:185], v[124:127]
	v_mfma_f32_16x16x32_bf16 v[120:123], v[158:161], v[182:185], v[120:123]
	v_mfma_f32_16x16x32_bf16 v[108:111], v[144:147], v[190:193], v[108:111]
	v_mfma_f32_16x16x32_bf16 v[104:107], v[158:161], v[190:193], v[104:107]
	v_mfma_f32_16x16x32_bf16 v[88:91], v[144:147], v[198:201], v[88:91]
	v_mfma_f32_16x16x32_bf16 v[92:95], v[158:161], v[198:201], v[92:95]
	v_mfma_f32_16x16x32_bf16 v[72:75], v[144:147], v[206:209], v[72:75]
	v_mfma_f32_16x16x32_bf16 v[76:79], v[158:161], v[206:209], v[76:79]
	v_mfma_f32_16x16x32_bf16 v[124:127], v[148:151], v[186:189], v[124:127]
	v_mfma_f32_16x16x32_bf16 v[120:123], v[162:165], v[186:189], v[120:123]
	v_mfma_f32_16x16x32_bf16 v[108:111], v[148:151], v[194:197], v[108:111]
	v_mfma_f32_16x16x32_bf16 v[104:107], v[162:165], v[194:197], v[104:107]
	v_mfma_f32_16x16x32_bf16 v[88:91], v[148:151], v[202:205], v[88:91]
	v_mfma_f32_16x16x32_bf16 v[92:95], v[162:165], v[202:205], v[92:95]
	v_mfma_f32_16x16x32_bf16 v[72:75], v[148:151], v[210:213], v[72:75]
	v_mfma_f32_16x16x32_bf16 v[76:79], v[162:165], v[210:213], v[76:79]
	v_mfma_f32_16x16x32_bf16 v[116:119], v[166:169], v[182:185], v[116:119]
	v_mfma_f32_16x16x32_bf16 v[112:115], v[174:177], v[182:185], v[112:115]
	v_mfma_f32_16x16x32_bf16 v[96:99], v[166:169], v[190:193], v[96:99]
	v_mfma_f32_16x16x32_bf16 v[100:103], v[174:177], v[190:193], v[100:103]
	v_mfma_f32_16x16x32_bf16 v[80:83], v[166:169], v[198:201], v[80:83]
	v_mfma_f32_16x16x32_bf16 v[84:87], v[174:177], v[198:201], v[84:87]
	v_mfma_f32_16x16x32_bf16 v[64:67], v[166:169], v[206:209], v[64:67]
	v_mfma_f32_16x16x32_bf16 v[68:71], v[174:177], v[206:209], v[68:71]
	v_mfma_f32_16x16x32_bf16 v[116:119], v[170:173], v[186:189], v[116:119]
	v_mfma_f32_16x16x32_bf16 v[112:115], v[178:181], v[186:189], v[112:115]
	v_mfma_f32_16x16x32_bf16 v[96:99], v[170:173], v[194:197], v[96:99]
	v_mfma_f32_16x16x32_bf16 v[100:103], v[178:181], v[194:197], v[100:103]
	v_mfma_f32_16x16x32_bf16 v[80:83], v[170:173], v[202:205], v[80:83]
	v_mfma_f32_16x16x32_bf16 v[84:87], v[178:181], v[202:205], v[84:87]
	v_mfma_f32_16x16x32_bf16 v[64:67], v[170:173], v[210:213], v[64:67]
	v_mfma_f32_16x16x32_bf16 v[68:71], v[178:181], v[210:213], v[68:71]
	s_barrier
	s_setprio 0
	v_lshl_add_u64 v[214:215], s[22:23], 0, v[130:131]
	s_mov_b32 m0, s98
	ds_read_b128 v[182:185], v157 offset:16384
	ds_read_b128 v[186:189], v157 offset:17408
	ds_read_b128 v[190:193], v157 offset:18432
	ds_read_b128 v[194:197], v157 offset:19456
	ds_read_b128 v[198:201], v157 offset:20480
	ds_read_b128 v[202:205], v157 offset:21504
	ds_read_b128 v[206:209], v157 offset:22528
	ds_read_b128 v[210:213], v157 offset:23552
	global_load_lds_dwordx4 v[214:215], off
	s_add_i32 m0, s98, 0x2000
	s_add_u32 s44, s22, 0x80000
	v_lshl_add_u64 v[216:217], s[22:23], 0, v[134:135]
	s_addc_u32 s45, s23, 0
	global_load_lds_dwordx4 v[216:217], off
	s_mov_b32 m0, s99
	v_lshl_add_u64 v[220:221], s[24:25], 0, v[132:133]
	global_load_lds_dwordx4 v130, s[44:45]
	s_add_i32 m0, s99, 0x2000
	s_nop 0
	global_load_lds_dwordx4 v134, s[44:45]
	s_mov_b32 m0, s19
	v_lshl_add_u64 v[218:219], s[24:25], 0, v[128:129]
	global_load_lds_dwordx4 v[218:219], off
	s_mov_b32 m0, s28
	s_nop 0
	global_load_lds_dwordx4 v[220:221], off
	s_waitcnt vmcnt(8) lgkmcnt(0)
	s_setprio 1
	s_barrier
	v_mfma_f32_16x16x32_bf16 v[56:59], v[144:147], v[182:185], v[56:59]
	v_mfma_f32_16x16x32_bf16 v[60:63], v[158:161], v[182:185], v[60:63]
	v_mfma_f32_16x16x32_bf16 v[40:43], v[144:147], v[190:193], v[40:43]
	v_mfma_f32_16x16x32_bf16 v[44:47], v[158:161], v[190:193], v[44:47]
	v_mfma_f32_16x16x32_bf16 v[24:27], v[144:147], v[198:201], v[24:27]
	v_mfma_f32_16x16x32_bf16 v[28:31], v[158:161], v[198:201], v[28:31]
	v_mfma_f32_16x16x32_bf16 v[8:11], v[144:147], v[206:209], v[8:11]
	v_mfma_f32_16x16x32_bf16 v[12:15], v[158:161], v[206:209], v[12:15]
	v_mfma_f32_16x16x32_bf16 v[56:59], v[148:151], v[186:189], v[56:59]
	v_mfma_f32_16x16x32_bf16 v[60:63], v[162:165], v[186:189], v[60:63]
	v_mfma_f32_16x16x32_bf16 v[40:43], v[148:151], v[194:197], v[40:43]
	v_mfma_f32_16x16x32_bf16 v[44:47], v[162:165], v[194:197], v[44:47]
	v_mfma_f32_16x16x32_bf16 v[24:27], v[148:151], v[202:205], v[24:27]
	v_mfma_f32_16x16x32_bf16 v[28:31], v[162:165], v[202:205], v[28:31]
	v_mfma_f32_16x16x32_bf16 v[8:11], v[148:151], v[210:213], v[8:11]
	v_mfma_f32_16x16x32_bf16 v[12:15], v[162:165], v[210:213], v[12:15]
	v_mfma_f32_16x16x32_bf16 v[48:51], v[166:169], v[182:185], v[48:51]
	v_mfma_f32_16x16x32_bf16 v[52:55], v[174:177], v[182:185], v[52:55]
	v_mfma_f32_16x16x32_bf16 v[32:35], v[166:169], v[190:193], v[32:35]
	v_mfma_f32_16x16x32_bf16 v[36:39], v[174:177], v[190:193], v[36:39]
	v_mfma_f32_16x16x32_bf16 v[16:19], v[166:169], v[198:201], v[16:19]
	v_mfma_f32_16x16x32_bf16 v[20:23], v[174:177], v[198:201], v[20:23]
	v_mfma_f32_16x16x32_bf16 v[0:3], v[166:169], v[206:209], v[0:3]
	v_mfma_f32_16x16x32_bf16 v[4:7], v[174:177], v[206:209], v[4:7]
	v_mfma_f32_16x16x32_bf16 v[48:51], v[170:173], v[186:189], v[48:51]
	v_mfma_f32_16x16x32_bf16 v[52:55], v[178:181], v[186:189], v[52:55]
	v_mfma_f32_16x16x32_bf16 v[32:35], v[170:173], v[194:197], v[32:35]
	v_mfma_f32_16x16x32_bf16 v[36:39], v[178:181], v[194:197], v[36:39]
	v_mfma_f32_16x16x32_bf16 v[16:19], v[170:173], v[202:205], v[16:19]
	v_mfma_f32_16x16x32_bf16 v[20:23], v[178:181], v[202:205], v[20:23]
	v_mfma_f32_16x16x32_bf16 v[0:3], v[170:173], v[210:213], v[0:3]
	v_mfma_f32_16x16x32_bf16 v[4:7], v[178:181], v[210:213], v[4:7]
	s_barrier
; #define PG8_STAGE(bufoff, gbase, voff) do { _Pragma("unroll") for (int _i = 0; _i < 2; ++_i) \
;         __builtin_amdgcn_global_load_lds((const unsigned*)((const char*)(gbase) + (voff)[_i]), (PG8_LAS unsigned*)(lds + (bufoff) + ldsw + _i * 8192), 16, 0, 0); } while (0)
; #define PG8_LDA(dst, b, h) do { _Pragma("unroll") for (int m = 0; m < 4; ++m) _Pragma("unroll") for (int k = 0; k < 2; ++k) dst[m][k] = *(const PG8_LAS bf16x8*)(lds + PG8_SA(b, h) + aoff + m * 2048 + k * 1024); } while (0)
; #define PG8_LDB(dst, b, h) do { _Pragma("unroll") for (int n = 0; n < 2; ++n) _Pragma("unroll") for (int k = 0; k < 2; ++k) dst[n][k] = *(const PG8_LAS bf16x8*)(lds + PG8_SB(b, h) + boff + n * 2048 + k * 1024); } while (0)
; #define PG8_MMA(ai, bj, At, Bt) do { __builtin_amdgcn_s_setprio(1); _Pragma("unroll") for (int m = 0; m < 4; ++m) _Pragma("unroll") for (int n = 0; n < 2; ++n) _Pragma("unroll") for (int k = 0; k < 2; ++k) \
;         acc[ai][bj][m][n] = __builtin_amdgcn_mfma_f32_16x16x32_bf16(Bt[n][k], At[m][k], acc[ai][bj][m][n], 0, 0, 0); __builtin_amdgcn_s_setprio(0); } while (0)
; #define PG8_WAIT_V(n) asm volatile("s_waitcnt vmcnt(" #n ")" ::: "memory")
; #define PG8_WAIT_L(n) asm volatile("s_waitcnt lgkmcnt(" #n ")" ::: "memory")
; #define PG8_BAR __builtin_amdgcn_s_barrier()
; #define PG8_SCHED __builtin_amdgcn_sched_barrier(0)
; template <class Epi, class Sched, bool ALIGN_EPI = false, bool SP2 = false>
; __device__ __forceinline__ void gemm_phase(PG8_LAS unsigned char* lds, const Gemm g, const Sched& S, const Epi& E) {
;     ...
;             PG8_LDB(B0, 1, 0); PG8_LDB(B1, 1, 1); PG8_SCHED; PG8_LDA(At, 1, 0); PG8_STAGE(PG8_SA(0, 1), a2 + hstep, voffA);
;             PG8_WAIT_V(8); PG8_WAIT_L(0); PG8_BAR; PG8_MMA(0, 0, At, B0); PG8_MMA(0, 1, At, B1); PG8_BAR; PG8_SCHED;
;             PG8_LDA(At, 1, 1); PG8_STAGE(PG8_SB(1, 0), b3, voffB); PG8_STAGE(PG8_SB(1, 1), b3 + hstep, voffB); PG8_STAGE(PG8_SA(1, 0), a3, voffA);
;             PG8_WAIT_V(8); PG8_WAIT_L(0); PG8_BAR; PG8_MMA(1, 0, At, B0); PG8_MMA(1, 1, At, B1); PG8_BAR; PG8_SCHED;
;     ...
;         if constexpr (ALIGN_EPI) { if (wr == 0) PG8_BAR; }
	s_setprio 0
	s_add_i32 s44, 0, 0x18000
	s_add_i32 s45, 0, 0x1c000
	v_add_u32_e32 v162, s44, v153
	v_add_u32_e32 v178, s45, v153
	ds_read_b128 v[144:147], v162
	ds_read_b128 v[148:151], v162 offset:1024
	ds_read_b128 v[158:161], v162 offset:2048
	ds_read_b128 v[162:165], v162 offset:3072
	ds_read_b128 v[166:169], v178
	ds_read_b128 v[170:173], v178 offset:1024
	ds_read_b128 v[174:177], v178 offset:2048
	ds_read_b128 v[178:181], v178 offset:3072
	s_add_u32 s24, s24, 0x80000
	s_addc_u32 s25, s25, 0
	s_mov_b32 m0, s29
	ds_read_b128 v[182:185], v157 offset:32768
	ds_read_b128 v[186:189], v157 offset:33792
	ds_read_b128 v[190:193], v157 offset:34816
	ds_read_b128 v[194:197], v157 offset:35840
	ds_read_b128 v[198:201], v157 offset:36864
	ds_read_b128 v[202:205], v157 offset:37888
	ds_read_b128 v[206:209], v157 offset:38912
	ds_read_b128 v[210:213], v157 offset:39936
	global_load_lds_dwordx4 v128, s[24:25]
	s_mov_b32 m0, s30
	s_nop 0
	global_load_lds_dwordx4 v132, s[24:25]
	s_waitcnt vmcnt(8) lgkmcnt(0)
	s_setprio 1
	s_barrier
	v_mfma_f32_16x16x32_bf16 v[124:127], v[144:147], v[182:185], v[124:127]
	v_mfma_f32_16x16x32_bf16 v[120:123], v[158:161], v[182:185], v[120:123]
	v_mfma_f32_16x16x32_bf16 v[108:111], v[144:147], v[190:193], v[108:111]
	v_mfma_f32_16x16x32_bf16 v[104:107], v[158:161], v[190:193], v[104:107]
	v_mfma_f32_16x16x32_bf16 v[88:91], v[144:147], v[198:201], v[88:91]
	v_mfma_f32_16x16x32_bf16 v[92:95], v[158:161], v[198:201], v[92:95]
	v_mfma_f32_16x16x32_bf16 v[72:75], v[144:147], v[206:209], v[72:75]
	v_mfma_f32_16x16x32_bf16 v[76:79], v[158:161], v[206:209], v[76:79]
	v_mfma_f32_16x16x32_bf16 v[124:127], v[148:151], v[186:189], v[124:127]
	v_mfma_f32_16x16x32_bf16 v[120:123], v[162:165], v[186:189], v[120:123]
	v_mfma_f32_16x16x32_bf16 v[108:111], v[148:151], v[194:197], v[108:111]
	v_mfma_f32_16x16x32_bf16 v[104:107], v[162:165], v[194:197], v[104:107]
	v_mfma_f32_16x16x32_bf16 v[88:91], v[148:151], v[202:205], v[88:91]
	v_mfma_f32_16x16x32_bf16 v[92:95], v[162:165], v[202:205], v[92:95]
	v_mfma_f32_16x16x32_bf16 v[72:75], v[148:151], v[210:213], v[72:75]
	v_mfma_f32_16x16x32_bf16 v[76:79], v[162:165], v[210:213], v[76:79]
	v_mfma_f32_16x16x32_bf16 v[116:119], v[166:169], v[182:185], v[116:119]
	v_mfma_f32_16x16x32_bf16 v[112:115], v[174:177], v[182:185], v[112:115]
	v_mfma_f32_16x16x32_bf16 v[96:99], v[166:169], v[190:193], v[96:99]
	v_mfma_f32_16x16x32_bf16 v[100:103], v[174:177], v[190:193], v[100:103]
	v_mfma_f32_16x16x32_bf16 v[80:83], v[166:169], v[198:201], v[80:83]
	v_mfma_f32_16x16x32_bf16 v[84:87], v[174:177], v[198:201], v[84:87]
	v_mfma_f32_16x16x32_bf16 v[64:67], v[166:169], v[206:209], v[64:67]
	v_mfma_f32_16x16x32_bf16 v[68:71], v[174:177], v[206:209], v[68:71]
	v_mfma_f32_16x16x32_bf16 v[116:119], v[170:173], v[186:189], v[116:119]
	v_mfma_f32_16x16x32_bf16 v[112:115], v[178:181], v[186:189], v[112:115]
	v_mfma_f32_16x16x32_bf16 v[96:99], v[170:173], v[194:197], v[96:99]
	v_mfma_f32_16x16x32_bf16 v[100:103], v[178:181], v[194:197], v[100:103]
	v_mfma_f32_16x16x32_bf16 v[80:83], v[170:173], v[202:205], v[80:83]
	v_mfma_f32_16x16x32_bf16 v[84:87], v[178:181], v[202:205], v[84:87]
	v_mfma_f32_16x16x32_bf16 v[64:67], v[170:173], v[210:213], v[64:67]
	v_mfma_f32_16x16x32_bf16 v[68:71], v[178:181], v[210:213], v[68:71]
	s_barrier
	s_setprio 0
	v_lshl_add_u64 v[214:215], v[214:215], 0, s[4:5]
	s_mov_b32 m0, s100
	ds_read_b128 v[182:185], v157 offset:49152
	ds_read_b128 v[186:189], v157 offset:50176
	ds_read_b128 v[190:193], v157 offset:51200
	ds_read_b128 v[194:197], v157 offset:52224
	ds_read_b128 v[198:201], v157 offset:53248
	ds_read_b128 v[202:205], v157 offset:54272
	ds_read_b128 v[206:209], v157 offset:55296
	ds_read_b128 v[210:213], v157 offset:56320
	global_load_lds_dwordx4 v[214:215], off
	s_add_i32 m0, s100, 0x2000
	s_add_u32 s22, s22, 0x80080
	v_lshl_add_u64 v[214:215], v[216:217], 0, s[4:5]
	s_addc_u32 s23, s23, 0
	global_load_lds_dwordx4 v[214:215], off
	s_mov_b32 m0, s101
	s_nop 0
	global_load_lds_dwordx4 v130, s[22:23]
	s_add_i32 m0, s101, 0x2000
	v_lshl_add_u64 v[214:215], s[22:23], 0, v[134:135]
	global_load_lds_dwordx4 v[214:215], off
	s_mov_b32 m0, s33
	v_lshl_add_u64 v[214:215], v[218:219], 0, s[4:5]
	global_load_lds_dwordx4 v[214:215], off
	s_mov_b32 m0, s34
	v_lshl_add_u64 v[214:215], v[220:221], 0, s[4:5]
	global_load_lds_dwordx4 v[214:215], off
	s_waitcnt vmcnt(8) lgkmcnt(0)
	s_setprio 1
	s_barrier
	v_mfma_f32_16x16x32_bf16 v[56:59], v[144:147], v[182:185], v[56:59]
	v_mfma_f32_16x16x32_bf16 v[60:63], v[158:161], v[182:185], v[60:63]
	v_mfma_f32_16x16x32_bf16 v[40:43], v[144:147], v[190:193], v[40:43]
	v_mfma_f32_16x16x32_bf16 v[44:47], v[158:161], v[190:193], v[44:47]
	v_mfma_f32_16x16x32_bf16 v[24:27], v[144:147], v[198:201], v[24:27]
	v_mfma_f32_16x16x32_bf16 v[28:31], v[158:161], v[198:201], v[28:31]
	v_mfma_f32_16x16x32_bf16 v[8:11], v[144:147], v[206:209], v[8:11]
	v_mfma_f32_16x16x32_bf16 v[12:15], v[158:161], v[206:209], v[12:15]
	v_mfma_f32_16x16x32_bf16 v[56:59], v[148:151], v[186:189], v[56:59]
	v_mfma_f32_16x16x32_bf16 v[60:63], v[162:165], v[186:189], v[60:63]
	v_mfma_f32_16x16x32_bf16 v[40:43], v[148:151], v[194:197], v[40:43]
	v_mfma_f32_16x16x32_bf16 v[44:47], v[162:165], v[194:197], v[44:47]
	v_mfma_f32_16x16x32_bf16 v[24:27], v[148:151], v[202:205], v[24:27]
	v_mfma_f32_16x16x32_bf16 v[28:31], v[162:165], v[202:205], v[28:31]
	v_mfma_f32_16x16x32_bf16 v[8:11], v[148:151], v[210:213], v[8:11]
	v_mfma_f32_16x16x32_bf16 v[12:15], v[162:165], v[210:213], v[12:15]
	v_mfma_f32_16x16x32_bf16 v[48:51], v[166:169], v[182:185], v[48:51]
	v_mfma_f32_16x16x32_bf16 v[52:55], v[174:177], v[182:185], v[52:55]
	v_mfma_f32_16x16x32_bf16 v[32:35], v[166:169], v[190:193], v[32:35]
	v_mfma_f32_16x16x32_bf16 v[36:39], v[174:177], v[190:193], v[36:39]
	v_mfma_f32_16x16x32_bf16 v[16:19], v[166:169], v[198:201], v[16:19]
	v_mfma_f32_16x16x32_bf16 v[20:23], v[174:177], v[198:201], v[20:23]
	v_mfma_f32_16x16x32_bf16 v[0:3], v[166:169], v[206:209], v[0:3]
	v_mfma_f32_16x16x32_bf16 v[4:7], v[174:177], v[206:209], v[4:7]
	v_mfma_f32_16x16x32_bf16 v[48:51], v[170:173], v[186:189], v[48:51]
	v_mfma_f32_16x16x32_bf16 v[52:55], v[178:181], v[186:189], v[52:55]
	v_mfma_f32_16x16x32_bf16 v[32:35], v[170:173], v[194:197], v[32:35]
	v_mfma_f32_16x16x32_bf16 v[36:39], v[178:181], v[194:197], v[36:39]
	v_mfma_f32_16x16x32_bf16 v[16:19], v[170:173], v[202:205], v[16:19]
	v_mfma_f32_16x16x32_bf16 v[20:23], v[178:181], v[202:205], v[20:23]
	v_mfma_f32_16x16x32_bf16 v[0:3], v[170:173], v[210:213], v[0:3]
	v_mfma_f32_16x16x32_bf16 v[4:7], v[178:181], v[210:213], v[4:7]
	s_barrier
	s_setprio 0
	s_add_i32 s43, s43, 2
	s_add_u32 s20, s20, 0x100
	s_addc_u32 s21, s21, 0
	s_add_u32 s41, s41, 0x100
	s_addc_u32 s42, s42, 0
	s_cmp_gt_u32 s43, 29
	s_cbranch_scc0 .LBB0_1549
	s_and_b64 vcc, exec, s[6:7]
	s_cbranch_vccz .LBB0_1552
	s_barrier

; __global__ void __launch_bounds__(NTHREADS, 2) hybrid_fwd(Args args) {
	.amdhsa_kernel _Z10hybrid_fwd4Args
		.amdhsa_group_segment_fixed_size 0
		.amdhsa_private_segment_fixed_size 0
		.amdhsa_kernarg_size 424
		.amdhsa_user_sgpr_count 2
		.amdhsa_user_sgpr_dispatch_ptr 0
		.amdhsa_user_sgpr_queue_ptr 0
		.amdhsa_user_sgpr_kernarg_segment_ptr 1
		.amdhsa_user_sgpr_dispatch_id 0
		.amdhsa_user_sgpr_kernarg_preload_length 0
		.amdhsa_user_sgpr_kernarg_preload_offset 0
		.amdhsa_user_sgpr_private_segment_size 0
		.amdhsa_uses_dynamic_stack 0
		.amdhsa_enable_private_segment 0
		.amdhsa_system_sgpr_workgroup_id_x 1
		.amdhsa_system_sgpr_workgroup_id_y 0
		.amdhsa_system_sgpr_workgroup_id_z 0
		.amdhsa_system_sgpr_workgroup_info 0
		.amdhsa_system_vgpr_workitem_id 2
		.amdhsa_next_free_vgpr 256
		.amdhsa_next_free_sgpr 102
		.amdhsa_accum_offset 256
		.amdhsa_reserve_vcc 1
		.amdhsa_float_round_mode_32 0
		.amdhsa_float_round_mode_16_64 0
		.amdhsa_float_denorm_mode_32 3
		.amdhsa_float_denorm_mode_16_64 3
		.amdhsa_dx10_clamp 1
		.amdhsa_ieee_mode 1
		.amdhsa_fp16_overflow 0
		.amdhsa_tg_split 0
		.amdhsa_exception_fp_ieee_invalid_op 0
		.amdhsa_exception_fp_denorm_src 0
		.amdhsa_exception_fp_ieee_div_zero 0
		.amdhsa_exception_fp_ieee_overflow 0
		.amdhsa_exception_fp_ieee_underflow 0
		.amdhsa_exception_fp_ieee_inexact 0
		.amdhsa_exception_int_div_zero 0
	.end_amdhsa_kernel

; __global__ void __launch_bounds__(NTHREADS, 2) hybrid_fwd(Args args) {
amdhsa.kernels:
  - .agpr_count:     0
    .args:
      - .offset:         0
        .size:           168
        .value_kind:     by_value
      - .offset:         168
        .size:           4
        .value_kind:     hidden_block_count_x
      - .offset:         172
        .size:           4
        .value_kind:     hidden_block_count_y
      - .offset:         176
        .size:           4
        .value_kind:     hidden_block_count_z
      - .offset:         180
        .size:           2
        .value_kind:     hidden_group_size_x
      - .offset:         182
        .size:           2
        .value_kind:     hidden_group_size_y
      - .offset:         184
        .size:           2
        .value_kind:     hidden_group_size_z
      - .offset:         186
        .size:           2
        .value_kind:     hidden_remainder_x
      - .offset:         188
        .size:           2
        .value_kind:     hidden_remainder_y
      - .offset:         190
        .size:           2
        .value_kind:     hidden_remainder_z
      - .offset:         208
        .size:           8
        .value_kind:     hidden_global_offset_x
      - .offset:         216
        .size:           8
        .value_kind:     hidden_global_offset_y
      - .offset:         224
        .size:           8
        .value_kind:     hidden_global_offset_z
      - .offset:         232
        .size:           2
        .value_kind:     hidden_grid_dims
      - .offset:         256
        .size:           8
        .value_kind:     hidden_multigrid_sync_arg
      - .offset:         288
        .size:           4
        .value_kind:     hidden_dynamic_lds_size
    .group_segment_fixed_size: 0
    .kernarg_segment_align: 8
    .kernarg_segment_size: 424
    .language:       OpenCL C
    .language_version:
      - 2
      - 0
    .max_flat_workgroup_size: 512
    .name:           _Z10hybrid_fwd4Args
    .private_segment_fixed_size: 0
    .sgpr_count:     108
    .sgpr_spill_count: 76
    .symbol:         _Z10hybrid_fwd4Args.kd
    .uniform_work_group_size: 1
    .uses_dynamic_stack: false
    .vgpr_count:     256
    .vgpr_spill_count: 0
    .wavefront_size: 64
